# hand-written PEER gather loops (clean U/V sweeps, 4 tokens in rank-lockstep per wave, own bitonic sort)
# speedup vs baseline: 1.0763x; 1.0763x over previous
; DEV float bflo(unsigned u) { return __uint_as_float(u << 16); }
; DEV float bfhi(unsigned u) { return __uint_as_float(u & 0xffff0000u); }
; DEV void sort_lists(int lane, int& myi0, int& myi1, float& myg0, float& myg1) {
; #pragma unroll
;     for (int k = 2; k <= 128; k <<= 1) {
; #pragma unroll
;       for (int j = k >> 1; j >= 1; j >>= 1) {
;         if (j == 64) {
;           const bool sw_ = myi1 < myi0;
;           const int ti = sw_ ? myi1 : myi0, tj = sw_ ? myi0 : myi1; const float tg = sw_ ? myg1 : myg0, th = sw_ ? myg0 : myg1;
;           myi0 = ti; myi1 = tj; myg0 = tg; myg1 = th;
;         } else {
;           const bool lower = (lane & j) == 0;
;           {
;             const bool up = (k == 128) ? true : ((k == 64) ? true : ((lane & k) == 0));
;             const int oi = __shfl_xor(myi0, j); const float og = __shfl_xor(myg0, j);
;             const bool take = (lower == up) ? (oi < myi0) : (oi > myi0);
;             myi0 = take ? oi : myi0; myg0 = take ? og : myg0;
;           }
;           {
;             const bool up = (k == 128) ? true : ((k == 64) ? false : ((lane & k) == 0));
;             const int oi = __shfl_xor(myi1, j); const float og = __shfl_xor(myg1, j);
;             const bool take = (lower == up) ? (oi < myi1) : (oi > myi1);
;             myi1 = take ? oi : myi1; myg1 = take ? og : myg1;
;           }
;         }
;       }
;     }
; }
; DEV void peer_gather(const Params& P, int l, int m0, const int* idxs, const float* gs) {
;     ...
;   const int row = lane >> 4, rmap = ((row & 1) << 1) | (row >> 1);
;   u32x4 nxa = *(const u32x4*)(hn + (size_t)(m0 + wid * 16) * DM + lane * 16), nxb = *(const u32x4*)(hn + (size_t)(m0 + wid * 16) * DM + lane * 16 + 8);
;   int ni0 = idxs[(wid * 16) * 128 + lane], ni1 = idxs[(wid * 16) * 128 + 64 + lane];
;   float ng0 = gs[(wid * 16) * 128 + lane], ng1 = gs[(wid * 16) * 128 + 64 + lane];
;   sort_lists(lane, ni0, ni1, ng0, ng1);
; #pragma nounroll
;   for (int i = 0; i < 16; ++i) {
;     const int tt = wid * 16 + i; const size_t tok = (size_t)(m0 + tt);
;     __syncthreads();
;     const u32x4 xa = nxa, xb = nxb;
;     f32x2_t xp[8];
; #pragma unroll
;     for (int q = 0; q < 4; ++q) { xp[q] = (f32x2_t){bflo(xa[q]), bfhi(xa[q])}; xp[4 + q] = (f32x2_t){bflo(xb[q]), bfhi(xb[q])}; }
.LBB0_313:
	s_waitcnt vmcnt(0) lgkmcnt(0)
	v_and_b32_e32 v249, 63, v176
	v_lshlrev_b32_e32 v250, 4, v249
	v_lshlrev_b32_e32 v252, 2, v249
	v_and_b32_e32 v116, 1, v249
	v_lshlrev_b32_e32 v116, 7, v116
	v_and_b32_e32 v117, 2, v249
	v_lshl_or_b32 v116, v117, 5, v116
	v_and_b32_e32 v117, 4, v249
	v_lshl_or_b32 v251, v117, 3, v116
	v_readfirstlane_b32 s33, v176
	s_lshr_b32 s33, s33, 6
	s_lshl_b32 s33, s33, 4
	v_readlane_b32 s3, v231, 30
	s_add_u32 s3, s3, s33
	s_mov_b32 s2, 0
.Lpg0_pass:
	v_readlane_b32 s82, v231, 26
	v_readlane_b32 s83, v231, 27
	s_nop 4
	s_add_u32 s98, s33, 0
	s_lshl_b32 s98, s98, 9
	v_add_u32_e32 v116, s98, v252
	global_load_dword v142, v116, s[82:83]
	global_load_dword v143, v116, s[82:83] offset:256
	s_add_u32 s98, s33, 1
	s_lshl_b32 s98, s98, 9
	v_add_u32_e32 v117, s98, v252
	global_load_dword v144, v117, s[82:83]
	global_load_dword v145, v117, s[82:83] offset:256
	s_add_u32 s98, s33, 2
	s_lshl_b32 s98, s98, 9
	v_add_u32_e32 v118, s98, v252
	global_load_dword v146, v118, s[82:83]
	global_load_dword v147, v118, s[82:83] offset:256
	s_add_u32 s98, s33, 3
	s_lshl_b32 s98, s98, 9
	v_add_u32_e32 v119, s98, v252
	global_load_dword v148, v119, s[82:83]
	global_load_dword v149, v119, s[82:83] offset:256
	v_readfirstlane_b32 s82, v128
	v_readfirstlane_b32 s83, v129
	s_nop 4
	s_add_u32 s98, s3, 0
	s_lshl_b32 s98, s98, 11
	v_lshl_add_u32 v150, v249, 5, s98
	global_load_dwordx4 v[64:67], v150, s[82:83]
	global_load_dwordx4 v[68:71], v150, s[82:83] offset:16
	s_add_u32 s98, s3, 1
	s_lshl_b32 s98, s98, 11
	v_lshl_add_u32 v151, v249, 5, s98
	global_load_dwordx4 v[72:75], v151, s[82:83]
	global_load_dwordx4 v[76:79], v151, s[82:83] offset:16
	s_add_u32 s98, s3, 2
	s_lshl_b32 s98, s98, 11
	v_lshl_add_u32 v150, v249, 5, s98
	global_load_dwordx4 v[80:83], v150, s[82:83]
	global_load_dwordx4 v[84:87], v150, s[82:83] offset:16
	s_add_u32 s98, s3, 3
	s_lshl_b32 s98, s98, 11
	v_lshl_add_u32 v151, v249, 5, s98
	global_load_dwordx4 v[88:91], v151, s[82:83]
	global_load_dwordx4 v[92:95], v151, s[82:83] offset:16
	s_waitcnt vmcnt(0)
	v_lshlrev_b32_e32 v0, 16, v64
	v_and_b32_e32 v1, 0xffff0000, v64
	v_lshlrev_b32_e32 v2, 16, v65
	v_and_b32_e32 v3, 0xffff0000, v65
	v_lshlrev_b32_e32 v4, 16, v66
	v_and_b32_e32 v5, 0xffff0000, v66
	v_lshlrev_b32_e32 v6, 16, v67
	v_and_b32_e32 v7, 0xffff0000, v67
	v_lshlrev_b32_e32 v8, 16, v68
	v_and_b32_e32 v9, 0xffff0000, v68
	v_lshlrev_b32_e32 v10, 16, v69
	v_and_b32_e32 v11, 0xffff0000, v69
	v_lshlrev_b32_e32 v12, 16, v70
	v_and_b32_e32 v13, 0xffff0000, v70
	v_lshlrev_b32_e32 v14, 16, v71
	v_and_b32_e32 v15, 0xffff0000, v71
	v_lshlrev_b32_e32 v16, 16, v72
	v_and_b32_e32 v17, 0xffff0000, v72
	v_lshlrev_b32_e32 v18, 16, v73
	v_and_b32_e32 v19, 0xffff0000, v73
	v_lshlrev_b32_e32 v20, 16, v74
	v_and_b32_e32 v21, 0xffff0000, v74
	v_lshlrev_b32_e32 v22, 16, v75
	v_and_b32_e32 v23, 0xffff0000, v75
	v_lshlrev_b32_e32 v24, 16, v76
	v_and_b32_e32 v25, 0xffff0000, v76
	v_lshlrev_b32_e32 v26, 16, v77
	v_and_b32_e32 v27, 0xffff0000, v77
	v_lshlrev_b32_e32 v28, 16, v78
	v_and_b32_e32 v29, 0xffff0000, v78
	v_lshlrev_b32_e32 v30, 16, v79
	v_and_b32_e32 v31, 0xffff0000, v79
	v_lshlrev_b32_e32 v32, 16, v80
	v_and_b32_e32 v33, 0xffff0000, v80
	v_lshlrev_b32_e32 v34, 16, v81
	v_and_b32_e32 v35, 0xffff0000, v81
	v_lshlrev_b32_e32 v36, 16, v82
	v_and_b32_e32 v37, 0xffff0000, v82
	v_lshlrev_b32_e32 v38, 16, v83
	v_and_b32_e32 v39, 0xffff0000, v83
	v_lshlrev_b32_e32 v40, 16, v84
	v_and_b32_e32 v41, 0xffff0000, v84
	v_lshlrev_b32_e32 v42, 16, v85
	v_and_b32_e32 v43, 0xffff0000, v85
	v_lshlrev_b32_e32 v44, 16, v86
	v_and_b32_e32 v45, 0xffff0000, v86
	v_lshlrev_b32_e32 v46, 16, v87
	v_and_b32_e32 v47, 0xffff0000, v87
	v_lshlrev_b32_e32 v48, 16, v88
	v_and_b32_e32 v49, 0xffff0000, v88
	v_lshlrev_b32_e32 v50, 16, v89
	v_and_b32_e32 v51, 0xffff0000, v89
	v_lshlrev_b32_e32 v52, 16, v90
	v_and_b32_e32 v53, 0xffff0000, v90
	v_lshlrev_b32_e32 v54, 16, v91
	v_and_b32_e32 v55, 0xffff0000, v91
	v_lshlrev_b32_e32 v56, 16, v92
	v_and_b32_e32 v57, 0xffff0000, v92
	v_lshlrev_b32_e32 v58, 16, v93
	v_and_b32_e32 v59, 0xffff0000, v93
	v_lshlrev_b32_e32 v60, 16, v94
	v_and_b32_e32 v61, 0xffff0000, v94
	v_lshlrev_b32_e32 v62, 16, v95
	v_and_b32_e32 v63, 0xffff0000, v95
	v_or_b32_e32 v116, 64, v249
	v_lshl_or_b32 v142, v142, 7, v249
	v_lshl_or_b32 v143, v143, 7, v116
	v_lshl_or_b32 v144, v144, 7, v249
	v_lshl_or_b32 v145, v145, 7, v116
	v_lshl_or_b32 v146, v146, 7, v249
	v_lshl_or_b32 v147, v147, 7, v116
	v_lshl_or_b32 v148, v148, 7, v249
	v_lshl_or_b32 v149, v149, 7, v116
	v_xor_b32_e32 v116, 4, v252
	ds_bpermute_b32 v64, v116, v142
	ds_bpermute_b32 v65, v116, v144
	ds_bpermute_b32 v66, v116, v146
	ds_bpermute_b32 v67, v116, v148
	ds_bpermute_b32 v68, v116, v143
	ds_bpermute_b32 v69, v116, v145
	ds_bpermute_b32 v70, v116, v147
	ds_bpermute_b32 v71, v116, v149
	s_waitcnt lgkmcnt(0)
	s_mov_b32 s88, 0x99999999
	s_mov_b32 s89, 0x99999999
	v_min_u32_e32 v96, v142, v64
	v_max_u32_e32 v97, v142, v64
	v_cndmask_b32_e64 v142, v97, v96, s[88:89]
	v_min_u32_e32 v98, v144, v65
	v_max_u32_e32 v99, v144, v65
	v_cndmask_b32_e64 v144, v99, v98, s[88:89]
	v_min_u32_e32 v96, v146, v66
	v_max_u32_e32 v97, v146, v66
	v_cndmask_b32_e64 v146, v97, v96, s[88:89]
	v_min_u32_e32 v98, v148, v67
	v_max_u32_e32 v99, v148, v67
	v_cndmask_b32_e64 v148, v99, v98, s[88:89]
	v_min_u32_e32 v96, v143, v68
	v_max_u32_e32 v97, v143, v68
	v_cndmask_b32_e64 v143, v97, v96, s[88:89]
	v_min_u32_e32 v98, v145, v69
	v_max_u32_e32 v99, v145, v69
	v_cndmask_b32_e64 v145, v99, v98, s[88:89]
	v_min_u32_e32 v96, v147, v70
	v_max_u32_e32 v97, v147, v70
	v_cndmask_b32_e64 v147, v97, v96, s[88:89]
	v_min_u32_e32 v98, v149, v71
	v_max_u32_e32 v99, v149, v71
	v_cndmask_b32_e64 v149, v99, v98, s[88:89]
	v_xor_b32_e32 v116, 8, v252
	ds_bpermute_b32 v64, v116, v142
	ds_bpermute_b32 v65, v116, v144
	ds_bpermute_b32 v66, v116, v146
	ds_bpermute_b32 v67, v116, v148
	ds_bpermute_b32 v68, v116, v143
	ds_bpermute_b32 v69, v116, v145
	ds_bpermute_b32 v70, v116, v147
	ds_bpermute_b32 v71, v116, v149
	s_waitcnt lgkmcnt(0)
; DEV void sort_lists(int lane, int& myi0, int& myi1, float& myg0, float& myg1) {
; #pragma unroll
;     for (int k = 2; k <= 128; k <<= 1) {
; #pragma unroll
;       for (int j = k >> 1; j >= 1; j >>= 1) {
;         if (j == 64) {
;           const bool sw_ = myi1 < myi0;
;           const int ti = sw_ ? myi1 : myi0, tj = sw_ ? myi0 : myi1; const float tg = sw_ ? myg1 : myg0, th = sw_ ? myg0 : myg1;
;           myi0 = ti; myi1 = tj; myg0 = tg; myg1 = th;
;         } else {
;           const bool lower = (lane & j) == 0;
;           {
;             const bool up = (k == 128) ? true : ((k == 64) ? true : ((lane & k) == 0));
;             const int oi = __shfl_xor(myi0, j); const float og = __shfl_xor(myg0, j);
;             const bool take = (lower == up) ? (oi < myi0) : (oi > myi0);
;             myi0 = take ? oi : myi0; myg0 = take ? og : myg0;
;           }
;           {
;             const bool up = (k == 128) ? true : ((k == 64) ? false : ((lane & k) == 0));
;             const int oi = __shfl_xor(myi1, j); const float og = __shfl_xor(myg1, j);
;             const bool take = (lower == up) ? (oi < myi1) : (oi > myi1);
;             myi1 = take ? oi : myi1; myg1 = take ? og : myg1;
;           }
;         }
;       }
;     }
; }
	s_mov_b32 s88, 0xc3c3c3c3
	s_mov_b32 s89, 0xc3c3c3c3
	v_min_u32_e32 v96, v142, v64
	v_max_u32_e32 v97, v142, v64
	v_cndmask_b32_e64 v142, v97, v96, s[88:89]
	v_min_u32_e32 v98, v144, v65
	v_max_u32_e32 v99, v144, v65
	v_cndmask_b32_e64 v144, v99, v98, s[88:89]
	v_min_u32_e32 v96, v146, v66
	v_max_u32_e32 v97, v146, v66
	v_cndmask_b32_e64 v146, v97, v96, s[88:89]
	v_min_u32_e32 v98, v148, v67
	v_max_u32_e32 v99, v148, v67
	v_cndmask_b32_e64 v148, v99, v98, s[88:89]
	v_min_u32_e32 v96, v143, v68
	v_max_u32_e32 v97, v143, v68
	v_cndmask_b32_e64 v143, v97, v96, s[88:89]
	v_min_u32_e32 v98, v145, v69
	v_max_u32_e32 v99, v145, v69
	v_cndmask_b32_e64 v145, v99, v98, s[88:89]
	v_min_u32_e32 v96, v147, v70
	v_max_u32_e32 v97, v147, v70
	v_cndmask_b32_e64 v147, v97, v96, s[88:89]
	v_min_u32_e32 v98, v149, v71
	v_max_u32_e32 v99, v149, v71
	v_cndmask_b32_e64 v149, v99, v98, s[88:89]
	v_xor_b32_e32 v116, 4, v252
	ds_bpermute_b32 v64, v116, v142
	ds_bpermute_b32 v65, v116, v144
	ds_bpermute_b32 v66, v116, v146
	ds_bpermute_b32 v67, v116, v148
	ds_bpermute_b32 v68, v116, v143
	ds_bpermute_b32 v69, v116, v145
	ds_bpermute_b32 v70, v116, v147
	ds_bpermute_b32 v71, v116, v149
	s_waitcnt lgkmcnt(0)
	s_mov_b32 s88, 0xa5a5a5a5
	s_mov_b32 s89, 0xa5a5a5a5
	v_min_u32_e32 v96, v142, v64
	v_max_u32_e32 v97, v142, v64
	v_cndmask_b32_e64 v142, v97, v96, s[88:89]
	v_min_u32_e32 v98, v144, v65
	v_max_u32_e32 v99, v144, v65
	v_cndmask_b32_e64 v144, v99, v98, s[88:89]
	v_min_u32_e32 v96, v146, v66
	v_max_u32_e32 v97, v146, v66
	v_cndmask_b32_e64 v146, v97, v96, s[88:89]
	v_min_u32_e32 v98, v148, v67
	v_max_u32_e32 v99, v148, v67
	v_cndmask_b32_e64 v148, v99, v98, s[88:89]
	v_min_u32_e32 v96, v143, v68
	v_max_u32_e32 v97, v143, v68
	v_cndmask_b32_e64 v143, v97, v96, s[88:89]
	v_min_u32_e32 v98, v145, v69
	v_max_u32_e32 v99, v145, v69
	v_cndmask_b32_e64 v145, v99, v98, s[88:89]
	v_min_u32_e32 v96, v147, v70
	v_max_u32_e32 v97, v147, v70
	v_cndmask_b32_e64 v147, v97, v96, s[88:89]
	v_min_u32_e32 v98, v149, v71
	v_max_u32_e32 v99, v149, v71
	v_cndmask_b32_e64 v149, v99, v98, s[88:89]
	v_xor_b32_e32 v116, 16, v252
	ds_bpermute_b32 v64, v116, v142
	ds_bpermute_b32 v65, v116, v144
	ds_bpermute_b32 v66, v116, v146
	ds_bpermute_b32 v67, v116, v148
	ds_bpermute_b32 v68, v116, v143
	ds_bpermute_b32 v69, v116, v145
	ds_bpermute_b32 v70, v116, v147
	ds_bpermute_b32 v71, v116, v149
	s_waitcnt lgkmcnt(0)
	s_mov_b32 s88, 0xf00ff00f
	s_mov_b32 s89, 0xf00ff00f
	v_min_u32_e32 v96, v142, v64
	v_max_u32_e32 v97, v142, v64
	v_cndmask_b32_e64 v142, v97, v96, s[88:89]
	v_min_u32_e32 v98, v144, v65
	v_max_u32_e32 v99, v144, v65
	v_cndmask_b32_e64 v144, v99, v98, s[88:89]
	v_min_u32_e32 v96, v146, v66
	v_max_u32_e32 v97, v146, v66
	v_cndmask_b32_e64 v146, v97, v96, s[88:89]
	v_min_u32_e32 v98, v148, v67
	v_max_u32_e32 v99, v148, v67
	v_cndmask_b32_e64 v148, v99, v98, s[88:89]
	v_min_u32_e32 v96, v143, v68
	v_max_u32_e32 v97, v143, v68
	v_cndmask_b32_e64 v143, v97, v96, s[88:89]
	v_min_u32_e32 v98, v145, v69
	v_max_u32_e32 v99, v145, v69
	v_cndmask_b32_e64 v145, v99, v98, s[88:89]
	v_min_u32_e32 v96, v147, v70
	v_max_u32_e32 v97, v147, v70
	v_cndmask_b32_e64 v147, v97, v96, s[88:89]
	v_min_u32_e32 v98, v149, v71
	v_max_u32_e32 v99, v149, v71
	v_cndmask_b32_e64 v149, v99, v98, s[88:89]
	v_xor_b32_e32 v116, 8, v252
	ds_bpermute_b32 v64, v116, v142
	ds_bpermute_b32 v65, v116, v144
	ds_bpermute_b32 v66, v116, v146
	ds_bpermute_b32 v67, v116, v148
	ds_bpermute_b32 v68, v116, v143
	ds_bpermute_b32 v69, v116, v145
	ds_bpermute_b32 v70, v116, v147
	ds_bpermute_b32 v71, v116, v149
	s_waitcnt lgkmcnt(0)
	s_mov_b32 s88, 0xcc33cc33
	s_mov_b32 s89, 0xcc33cc33
	v_min_u32_e32 v96, v142, v64
	v_max_u32_e32 v97, v142, v64
	v_cndmask_b32_e64 v142, v97, v96, s[88:89]
	v_min_u32_e32 v98, v144, v65
	v_max_u32_e32 v99, v144, v65
	v_cndmask_b32_e64 v144, v99, v98, s[88:89]
	v_min_u32_e32 v96, v146, v66
	v_max_u32_e32 v97, v146, v66
	v_cndmask_b32_e64 v146, v97, v96, s[88:89]
	v_min_u32_e32 v98, v148, v67
	v_max_u32_e32 v99, v148, v67
	v_cndmask_b32_e64 v148, v99, v98, s[88:89]
	v_min_u32_e32 v96, v143, v68
	v_max_u32_e32 v97, v143, v68
	v_cndmask_b32_e64 v143, v97, v96, s[88:89]
	v_min_u32_e32 v98, v145, v69
	v_max_u32_e32 v99, v145, v69
	v_cndmask_b32_e64 v145, v99, v98, s[88:89]
	v_min_u32_e32 v96, v147, v70
	v_max_u32_e32 v97, v147, v70
	v_cndmask_b32_e64 v147, v97, v96, s[88:89]
	v_min_u32_e32 v98, v149, v71
	v_max_u32_e32 v99, v149, v71
	v_cndmask_b32_e64 v149, v99, v98, s[88:89]
	v_xor_b32_e32 v116, 4, v252
	ds_bpermute_b32 v64, v116, v142
	ds_bpermute_b32 v65, v116, v144
	ds_bpermute_b32 v66, v116, v146
	ds_bpermute_b32 v67, v116, v148
	ds_bpermute_b32 v68, v116, v143
	ds_bpermute_b32 v69, v116, v145
	ds_bpermute_b32 v70, v116, v147
	ds_bpermute_b32 v71, v116, v149
	s_waitcnt lgkmcnt(0)
	s_mov_b32 s88, 0xaa55aa55
	s_mov_b32 s89, 0xaa55aa55
	v_min_u32_e32 v96, v142, v64
	v_max_u32_e32 v97, v142, v64
	v_cndmask_b32_e64 v142, v97, v96, s[88:89]
	v_min_u32_e32 v98, v144, v65
	v_max_u32_e32 v99, v144, v65
	v_cndmask_b32_e64 v144, v99, v98, s[88:89]
	v_min_u32_e32 v96, v146, v66
	v_max_u32_e32 v97, v146, v66
	v_cndmask_b32_e64 v146, v97, v96, s[88:89]
	v_min_u32_e32 v98, v148, v67
	v_max_u32_e32 v99, v148, v67
	v_cndmask_b32_e64 v148, v99, v98, s[88:89]
	v_min_u32_e32 v96, v143, v68
	v_max_u32_e32 v97, v143, v68
	v_cndmask_b32_e64 v143, v97, v96, s[88:89]
	v_min_u32_e32 v98, v145, v69
	v_max_u32_e32 v99, v145, v69
	v_cndmask_b32_e64 v145, v99, v98, s[88:89]
	v_min_u32_e32 v96, v147, v70
	v_max_u32_e32 v97, v147, v70
	v_cndmask_b32_e64 v147, v97, v96, s[88:89]
	v_min_u32_e32 v98, v149, v71
	v_max_u32_e32 v99, v149, v71
	v_cndmask_b32_e64 v149, v99, v98, s[88:89]
	v_xor_b32_e32 v116, 32, v252
	ds_bpermute_b32 v64, v116, v142
	ds_bpermute_b32 v65, v116, v144
	ds_bpermute_b32 v66, v116, v146
	ds_bpermute_b32 v67, v116, v148
	ds_bpermute_b32 v68, v116, v143
	ds_bpermute_b32 v69, v116, v145
	ds_bpermute_b32 v70, v116, v147
	ds_bpermute_b32 v71, v116, v149
	s_waitcnt lgkmcnt(0)
; DEV void sort_lists(int lane, int& myi0, int& myi1, float& myg0, float& myg1) {
; #pragma unroll
;     for (int k = 2; k <= 128; k <<= 1) {
; #pragma unroll
;       for (int j = k >> 1; j >= 1; j >>= 1) {
;         if (j == 64) {
;           const bool sw_ = myi1 < myi0;
;           const int ti = sw_ ? myi1 : myi0, tj = sw_ ? myi0 : myi1; const float tg = sw_ ? myg1 : myg0, th = sw_ ? myg0 : myg1;
;           myi0 = ti; myi1 = tj; myg0 = tg; myg1 = th;
;         } else {
;           const bool lower = (lane & j) == 0;
;           {
;             const bool up = (k == 128) ? true : ((k == 64) ? true : ((lane & k) == 0));
;             const int oi = __shfl_xor(myi0, j); const float og = __shfl_xor(myg0, j);
;             const bool take = (lower == up) ? (oi < myi0) : (oi > myi0);
;             myi0 = take ? oi : myi0; myg0 = take ? og : myg0;
;           }
;           {
;             const bool up = (k == 128) ? true : ((k == 64) ? false : ((lane & k) == 0));
;             const int oi = __shfl_xor(myi1, j); const float og = __shfl_xor(myg1, j);
;             const bool take = (lower == up) ? (oi < myi1) : (oi > myi1);
;             myi1 = take ? oi : myi1; myg1 = take ? og : myg1;
;           }
;         }
;       }
;     }
; }
	s_mov_b32 s88, 0xff0000ff
	s_mov_b32 s89, 0xff0000ff
	v_min_u32_e32 v96, v142, v64
	v_max_u32_e32 v97, v142, v64
	v_cndmask_b32_e64 v142, v97, v96, s[88:89]
	v_min_u32_e32 v98, v144, v65
	v_max_u32_e32 v99, v144, v65
	v_cndmask_b32_e64 v144, v99, v98, s[88:89]
	v_min_u32_e32 v96, v146, v66
	v_max_u32_e32 v97, v146, v66
	v_cndmask_b32_e64 v146, v97, v96, s[88:89]
	v_min_u32_e32 v98, v148, v67
	v_max_u32_e32 v99, v148, v67
	v_cndmask_b32_e64 v148, v99, v98, s[88:89]
	v_min_u32_e32 v96, v143, v68
	v_max_u32_e32 v97, v143, v68
	v_cndmask_b32_e64 v143, v97, v96, s[88:89]
	v_min_u32_e32 v98, v145, v69
	v_max_u32_e32 v99, v145, v69
	v_cndmask_b32_e64 v145, v99, v98, s[88:89]
	v_min_u32_e32 v96, v147, v70
	v_max_u32_e32 v97, v147, v70
	v_cndmask_b32_e64 v147, v97, v96, s[88:89]
	v_min_u32_e32 v98, v149, v71
	v_max_u32_e32 v99, v149, v71
	v_cndmask_b32_e64 v149, v99, v98, s[88:89]
	v_xor_b32_e32 v116, 16, v252
	ds_bpermute_b32 v64, v116, v142
	ds_bpermute_b32 v65, v116, v144
	ds_bpermute_b32 v66, v116, v146
	ds_bpermute_b32 v67, v116, v148
	ds_bpermute_b32 v68, v116, v143
	ds_bpermute_b32 v69, v116, v145
	ds_bpermute_b32 v70, v116, v147
	ds_bpermute_b32 v71, v116, v149
	s_waitcnt lgkmcnt(0)
	s_mov_b32 s88, 0xf0f00f0f
	s_mov_b32 s89, 0xf0f00f0f
	v_min_u32_e32 v96, v142, v64
	v_max_u32_e32 v97, v142, v64
	v_cndmask_b32_e64 v142, v97, v96, s[88:89]
	v_min_u32_e32 v98, v144, v65
	v_max_u32_e32 v99, v144, v65
	v_cndmask_b32_e64 v144, v99, v98, s[88:89]
	v_min_u32_e32 v96, v146, v66
	v_max_u32_e32 v97, v146, v66
	v_cndmask_b32_e64 v146, v97, v96, s[88:89]
	v_min_u32_e32 v98, v148, v67
	v_max_u32_e32 v99, v148, v67
	v_cndmask_b32_e64 v148, v99, v98, s[88:89]
	v_min_u32_e32 v96, v143, v68
	v_max_u32_e32 v97, v143, v68
	v_cndmask_b32_e64 v143, v97, v96, s[88:89]
	v_min_u32_e32 v98, v145, v69
	v_max_u32_e32 v99, v145, v69
	v_cndmask_b32_e64 v145, v99, v98, s[88:89]
	v_min_u32_e32 v96, v147, v70
	v_max_u32_e32 v97, v147, v70
	v_cndmask_b32_e64 v147, v97, v96, s[88:89]
	v_min_u32_e32 v98, v149, v71
	v_max_u32_e32 v99, v149, v71
	v_cndmask_b32_e64 v149, v99, v98, s[88:89]
	v_xor_b32_e32 v116, 8, v252
	ds_bpermute_b32 v64, v116, v142
	ds_bpermute_b32 v65, v116, v144
	ds_bpermute_b32 v66, v116, v146
	ds_bpermute_b32 v67, v116, v148
	ds_bpermute_b32 v68, v116, v143
	ds_bpermute_b32 v69, v116, v145
	ds_bpermute_b32 v70, v116, v147
	ds_bpermute_b32 v71, v116, v149
	s_waitcnt lgkmcnt(0)
	s_mov_b32 s88, 0xcccc3333
	s_mov_b32 s89, 0xcccc3333
	v_min_u32_e32 v96, v142, v64
	v_max_u32_e32 v97, v142, v64
	v_cndmask_b32_e64 v142, v97, v96, s[88:89]
	v_min_u32_e32 v98, v144, v65
	v_max_u32_e32 v99, v144, v65
	v_cndmask_b32_e64 v144, v99, v98, s[88:89]
	v_min_u32_e32 v96, v146, v66
	v_max_u32_e32 v97, v146, v66
	v_cndmask_b32_e64 v146, v97, v96, s[88:89]
	v_min_u32_e32 v98, v148, v67
	v_max_u32_e32 v99, v148, v67
	v_cndmask_b32_e64 v148, v99, v98, s[88:89]
	v_min_u32_e32 v96, v143, v68
	v_max_u32_e32 v97, v143, v68
	v_cndmask_b32_e64 v143, v97, v96, s[88:89]
	v_min_u32_e32 v98, v145, v69
	v_max_u32_e32 v99, v145, v69
	v_cndmask_b32_e64 v145, v99, v98, s[88:89]
	v_min_u32_e32 v96, v147, v70
	v_max_u32_e32 v97, v147, v70
	v_cndmask_b32_e64 v147, v97, v96, s[88:89]
	v_min_u32_e32 v98, v149, v71
	v_max_u32_e32 v99, v149, v71
	v_cndmask_b32_e64 v149, v99, v98, s[88:89]
	v_xor_b32_e32 v116, 4, v252
	ds_bpermute_b32 v64, v116, v142
	ds_bpermute_b32 v65, v116, v144
	ds_bpermute_b32 v66, v116, v146
	ds_bpermute_b32 v67, v116, v148
	ds_bpermute_b32 v68, v116, v143
	ds_bpermute_b32 v69, v116, v145
	ds_bpermute_b32 v70, v116, v147
	ds_bpermute_b32 v71, v116, v149
	s_waitcnt lgkmcnt(0)
	s_mov_b32 s88, 0xaaaa5555
	s_mov_b32 s89, 0xaaaa5555
	v_min_u32_e32 v96, v142, v64
	v_max_u32_e32 v97, v142, v64
	v_cndmask_b32_e64 v142, v97, v96, s[88:89]
	v_min_u32_e32 v98, v144, v65
	v_max_u32_e32 v99, v144, v65
	v_cndmask_b32_e64 v144, v99, v98, s[88:89]
	v_min_u32_e32 v96, v146, v66
	v_max_u32_e32 v97, v146, v66
	v_cndmask_b32_e64 v146, v97, v96, s[88:89]
	v_min_u32_e32 v98, v148, v67
	v_max_u32_e32 v99, v148, v67
	v_cndmask_b32_e64 v148, v99, v98, s[88:89]
	v_min_u32_e32 v96, v143, v68
	v_max_u32_e32 v97, v143, v68
	v_cndmask_b32_e64 v143, v97, v96, s[88:89]
	v_min_u32_e32 v98, v145, v69
	v_max_u32_e32 v99, v145, v69
	v_cndmask_b32_e64 v145, v99, v98, s[88:89]
	v_min_u32_e32 v96, v147, v70
	v_max_u32_e32 v97, v147, v70
	v_cndmask_b32_e64 v147, v97, v96, s[88:89]
	v_min_u32_e32 v98, v149, v71
	v_max_u32_e32 v99, v149, v71
	v_cndmask_b32_e64 v149, v99, v98, s[88:89]
	v_xor_b32_e32 v116, 64, v252
	ds_bpermute_b32 v64, v116, v142
	ds_bpermute_b32 v65, v116, v144
	ds_bpermute_b32 v66, v116, v146
	ds_bpermute_b32 v67, v116, v148
	ds_bpermute_b32 v68, v116, v143
	ds_bpermute_b32 v69, v116, v145
	ds_bpermute_b32 v70, v116, v147
	ds_bpermute_b32 v71, v116, v149
	s_waitcnt lgkmcnt(0)
	s_mov_b32 s88, 0xffff
	s_mov_b32 s89, 0xffff0000
	v_min_u32_e32 v96, v142, v64
	v_max_u32_e32 v97, v142, v64
	v_cndmask_b32_e64 v142, v97, v96, s[88:89]
	v_min_u32_e32 v98, v144, v65
	v_max_u32_e32 v99, v144, v65
	v_cndmask_b32_e64 v144, v99, v98, s[88:89]
	v_min_u32_e32 v96, v146, v66
	v_max_u32_e32 v97, v146, v66
	v_cndmask_b32_e64 v146, v97, v96, s[88:89]
	v_min_u32_e32 v98, v148, v67
	v_max_u32_e32 v99, v148, v67
	v_cndmask_b32_e64 v148, v99, v98, s[88:89]
	v_min_u32_e32 v96, v143, v68
	v_max_u32_e32 v97, v143, v68
	v_cndmask_b32_e64 v143, v97, v96, s[88:89]
	v_min_u32_e32 v98, v145, v69
	v_max_u32_e32 v99, v145, v69
	v_cndmask_b32_e64 v145, v99, v98, s[88:89]
	v_min_u32_e32 v96, v147, v70
	v_max_u32_e32 v97, v147, v70
	v_cndmask_b32_e64 v147, v97, v96, s[88:89]
	v_min_u32_e32 v98, v149, v71
	v_max_u32_e32 v99, v149, v71
	v_cndmask_b32_e64 v149, v99, v98, s[88:89]
	v_xor_b32_e32 v116, 32, v252
	ds_bpermute_b32 v64, v116, v142
	ds_bpermute_b32 v65, v116, v144
	ds_bpermute_b32 v66, v116, v146
	ds_bpermute_b32 v67, v116, v148
	ds_bpermute_b32 v68, v116, v143
	ds_bpermute_b32 v69, v116, v145
	ds_bpermute_b32 v70, v116, v147
	ds_bpermute_b32 v71, v116, v149
	s_waitcnt lgkmcnt(0)
; DEV void sort_lists(int lane, int& myi0, int& myi1, float& myg0, float& myg1) {
; #pragma unroll
;     for (int k = 2; k <= 128; k <<= 1) {
; #pragma unroll
;       for (int j = k >> 1; j >= 1; j >>= 1) {
;         if (j == 64) {
;           const bool sw_ = myi1 < myi0;
;           const int ti = sw_ ? myi1 : myi0, tj = sw_ ? myi0 : myi1; const float tg = sw_ ? myg1 : myg0, th = sw_ ? myg0 : myg1;
;           myi0 = ti; myi1 = tj; myg0 = tg; myg1 = th;
;         } else {
;           const bool lower = (lane & j) == 0;
;           {
;             const bool up = (k == 128) ? true : ((k == 64) ? true : ((lane & k) == 0));
;             const int oi = __shfl_xor(myi0, j); const float og = __shfl_xor(myg0, j);
;             const bool take = (lower == up) ? (oi < myi0) : (oi > myi0);
;             myi0 = take ? oi : myi0; myg0 = take ? og : myg0;
;           }
;           {
;             const bool up = (k == 128) ? true : ((k == 64) ? false : ((lane & k) == 0));
;             const int oi = __shfl_xor(myi1, j); const float og = __shfl_xor(myg1, j);
;             const bool take = (lower == up) ? (oi < myi1) : (oi > myi1);
;             myi1 = take ? oi : myi1; myg1 = take ? og : myg1;
;           }
;         }
;       }
;     }
; }
	s_mov_b32 s88, 0xff00ff
	s_mov_b32 s89, 0xff00ff00
	v_min_u32_e32 v96, v142, v64
	v_max_u32_e32 v97, v142, v64
	v_cndmask_b32_e64 v142, v97, v96, s[88:89]
	v_min_u32_e32 v98, v144, v65
	v_max_u32_e32 v99, v144, v65
	v_cndmask_b32_e64 v144, v99, v98, s[88:89]
	v_min_u32_e32 v96, v146, v66
	v_max_u32_e32 v97, v146, v66
	v_cndmask_b32_e64 v146, v97, v96, s[88:89]
	v_min_u32_e32 v98, v148, v67
	v_max_u32_e32 v99, v148, v67
	v_cndmask_b32_e64 v148, v99, v98, s[88:89]
	v_min_u32_e32 v96, v143, v68
	v_max_u32_e32 v97, v143, v68
	v_cndmask_b32_e64 v143, v97, v96, s[88:89]
	v_min_u32_e32 v98, v145, v69
	v_max_u32_e32 v99, v145, v69
	v_cndmask_b32_e64 v145, v99, v98, s[88:89]
	v_min_u32_e32 v96, v147, v70
	v_max_u32_e32 v97, v147, v70
	v_cndmask_b32_e64 v147, v97, v96, s[88:89]
	v_min_u32_e32 v98, v149, v71
	v_max_u32_e32 v99, v149, v71
	v_cndmask_b32_e64 v149, v99, v98, s[88:89]
	v_xor_b32_e32 v116, 16, v252
	ds_bpermute_b32 v64, v116, v142
	ds_bpermute_b32 v65, v116, v144
	ds_bpermute_b32 v66, v116, v146
	ds_bpermute_b32 v67, v116, v148
	ds_bpermute_b32 v68, v116, v143
	ds_bpermute_b32 v69, v116, v145
	ds_bpermute_b32 v70, v116, v147
	ds_bpermute_b32 v71, v116, v149
	s_waitcnt lgkmcnt(0)
	s_mov_b32 s88, 0xf0f0f0f
	s_mov_b32 s89, 0xf0f0f0f0
	v_min_u32_e32 v96, v142, v64
	v_max_u32_e32 v97, v142, v64
	v_cndmask_b32_e64 v142, v97, v96, s[88:89]
	v_min_u32_e32 v98, v144, v65
	v_max_u32_e32 v99, v144, v65
	v_cndmask_b32_e64 v144, v99, v98, s[88:89]
	v_min_u32_e32 v96, v146, v66
	v_max_u32_e32 v97, v146, v66
	v_cndmask_b32_e64 v146, v97, v96, s[88:89]
	v_min_u32_e32 v98, v148, v67
	v_max_u32_e32 v99, v148, v67
	v_cndmask_b32_e64 v148, v99, v98, s[88:89]
	v_min_u32_e32 v96, v143, v68
	v_max_u32_e32 v97, v143, v68
	v_cndmask_b32_e64 v143, v97, v96, s[88:89]
	v_min_u32_e32 v98, v145, v69
	v_max_u32_e32 v99, v145, v69
	v_cndmask_b32_e64 v145, v99, v98, s[88:89]
	v_min_u32_e32 v96, v147, v70
	v_max_u32_e32 v97, v147, v70
	v_cndmask_b32_e64 v147, v97, v96, s[88:89]
	v_min_u32_e32 v98, v149, v71
	v_max_u32_e32 v99, v149, v71
	v_cndmask_b32_e64 v149, v99, v98, s[88:89]
	v_xor_b32_e32 v116, 8, v252
	ds_bpermute_b32 v64, v116, v142
	ds_bpermute_b32 v65, v116, v144
	ds_bpermute_b32 v66, v116, v146
	ds_bpermute_b32 v67, v116, v148
	ds_bpermute_b32 v68, v116, v143
	ds_bpermute_b32 v69, v116, v145
	ds_bpermute_b32 v70, v116, v147
	ds_bpermute_b32 v71, v116, v149
	s_waitcnt lgkmcnt(0)
	s_mov_b32 s88, 0x33333333
	s_mov_b32 s89, 0xcccccccc
	v_min_u32_e32 v96, v142, v64
	v_max_u32_e32 v97, v142, v64
	v_cndmask_b32_e64 v142, v97, v96, s[88:89]
	v_min_u32_e32 v98, v144, v65
	v_max_u32_e32 v99, v144, v65
	v_cndmask_b32_e64 v144, v99, v98, s[88:89]
	v_min_u32_e32 v96, v146, v66
	v_max_u32_e32 v97, v146, v66
	v_cndmask_b32_e64 v146, v97, v96, s[88:89]
	v_min_u32_e32 v98, v148, v67
	v_max_u32_e32 v99, v148, v67
	v_cndmask_b32_e64 v148, v99, v98, s[88:89]
	v_min_u32_e32 v96, v143, v68
	v_max_u32_e32 v97, v143, v68
	v_cndmask_b32_e64 v143, v97, v96, s[88:89]
	v_min_u32_e32 v98, v145, v69
	v_max_u32_e32 v99, v145, v69
	v_cndmask_b32_e64 v145, v99, v98, s[88:89]
	v_min_u32_e32 v96, v147, v70
	v_max_u32_e32 v97, v147, v70
	v_cndmask_b32_e64 v147, v97, v96, s[88:89]
	v_min_u32_e32 v98, v149, v71
	v_max_u32_e32 v99, v149, v71
	v_cndmask_b32_e64 v149, v99, v98, s[88:89]
	v_xor_b32_e32 v116, 4, v252
	ds_bpermute_b32 v64, v116, v142
	ds_bpermute_b32 v65, v116, v144
	ds_bpermute_b32 v66, v116, v146
	ds_bpermute_b32 v67, v116, v148
	ds_bpermute_b32 v68, v116, v143
	ds_bpermute_b32 v69, v116, v145
	ds_bpermute_b32 v70, v116, v147
	ds_bpermute_b32 v71, v116, v149
	s_waitcnt lgkmcnt(0)
	s_mov_b32 s88, 0x55555555
	s_mov_b32 s89, 0xaaaaaaaa
	v_min_u32_e32 v96, v142, v64
	v_max_u32_e32 v97, v142, v64
	v_cndmask_b32_e64 v142, v97, v96, s[88:89]
	v_min_u32_e32 v98, v144, v65
	v_max_u32_e32 v99, v144, v65
	v_cndmask_b32_e64 v144, v99, v98, s[88:89]
	v_min_u32_e32 v96, v146, v66
	v_max_u32_e32 v97, v146, v66
	v_cndmask_b32_e64 v146, v97, v96, s[88:89]
	v_min_u32_e32 v98, v148, v67
	v_max_u32_e32 v99, v148, v67
	v_cndmask_b32_e64 v148, v99, v98, s[88:89]
	v_min_u32_e32 v96, v143, v68
	v_max_u32_e32 v97, v143, v68
	v_cndmask_b32_e64 v143, v97, v96, s[88:89]
	v_min_u32_e32 v98, v145, v69
	v_max_u32_e32 v99, v145, v69
	v_cndmask_b32_e64 v145, v99, v98, s[88:89]
	v_min_u32_e32 v96, v147, v70
	v_max_u32_e32 v97, v147, v70
	v_cndmask_b32_e64 v147, v97, v96, s[88:89]
	v_min_u32_e32 v98, v149, v71
	v_max_u32_e32 v99, v149, v71
	v_cndmask_b32_e64 v149, v99, v98, s[88:89]
	v_xor_b32_e32 v116, 128, v252
	ds_bpermute_b32 v64, v116, v142
	ds_bpermute_b32 v65, v116, v144
	ds_bpermute_b32 v66, v116, v146
	ds_bpermute_b32 v67, v116, v148
	ds_bpermute_b32 v68, v116, v143
	ds_bpermute_b32 v69, v116, v145
	ds_bpermute_b32 v70, v116, v147
	ds_bpermute_b32 v71, v116, v149
	s_waitcnt lgkmcnt(0)
	s_mov_b32 s88, 0xffffffff
	s_mov_b32 s89, 0x0
	v_min_u32_e32 v96, v142, v64
	v_max_u32_e32 v97, v142, v64
	v_cndmask_b32_e64 v142, v97, v96, s[88:89]
	v_min_u32_e32 v98, v144, v65
	v_max_u32_e32 v99, v144, v65
	v_cndmask_b32_e64 v144, v99, v98, s[88:89]
	v_min_u32_e32 v96, v146, v66
	v_max_u32_e32 v97, v146, v66
	v_cndmask_b32_e64 v146, v97, v96, s[88:89]
	v_min_u32_e32 v98, v148, v67
	v_max_u32_e32 v99, v148, v67
	v_cndmask_b32_e64 v148, v99, v98, s[88:89]
	s_mov_b32 s88, 0x0
	s_mov_b32 s89, 0xffffffff
	v_min_u32_e32 v96, v143, v68
	v_max_u32_e32 v97, v143, v68
	v_cndmask_b32_e64 v143, v97, v96, s[88:89]
	v_min_u32_e32 v98, v145, v69
	v_max_u32_e32 v99, v145, v69
	v_cndmask_b32_e64 v145, v99, v98, s[88:89]
	v_min_u32_e32 v96, v147, v70
	v_max_u32_e32 v97, v147, v70
	v_cndmask_b32_e64 v147, v97, v96, s[88:89]
	v_min_u32_e32 v98, v149, v71
	v_max_u32_e32 v99, v149, v71
	v_cndmask_b32_e64 v149, v99, v98, s[88:89]
	v_xor_b32_e32 v116, 64, v252
	ds_bpermute_b32 v64, v116, v142
	ds_bpermute_b32 v65, v116, v144
	ds_bpermute_b32 v66, v116, v146
	ds_bpermute_b32 v67, v116, v148
	ds_bpermute_b32 v68, v116, v143
	ds_bpermute_b32 v69, v116, v145
	ds_bpermute_b32 v70, v116, v147
	ds_bpermute_b32 v71, v116, v149
	s_waitcnt lgkmcnt(0)
; DEV void sort_lists(int lane, int& myi0, int& myi1, float& myg0, float& myg1) {
; #pragma unroll
;     for (int k = 2; k <= 128; k <<= 1) {
; #pragma unroll
;       for (int j = k >> 1; j >= 1; j >>= 1) {
;         if (j == 64) {
;           const bool sw_ = myi1 < myi0;
;           const int ti = sw_ ? myi1 : myi0, tj = sw_ ? myi0 : myi1; const float tg = sw_ ? myg1 : myg0, th = sw_ ? myg0 : myg1;
;           myi0 = ti; myi1 = tj; myg0 = tg; myg1 = th;
;         } else {
;           const bool lower = (lane & j) == 0;
;           {
;             const bool up = (k == 128) ? true : ((k == 64) ? true : ((lane & k) == 0));
;             const int oi = __shfl_xor(myi0, j); const float og = __shfl_xor(myg0, j);
;             const bool take = (lower == up) ? (oi < myi0) : (oi > myi0);
;             myi0 = take ? oi : myi0; myg0 = take ? og : myg0;
;           }
;           {
;             const bool up = (k == 128) ? true : ((k == 64) ? false : ((lane & k) == 0));
;             const int oi = __shfl_xor(myi1, j); const float og = __shfl_xor(myg1, j);
;             const bool take = (lower == up) ? (oi < myi1) : (oi > myi1);
;             myi1 = take ? oi : myi1; myg1 = take ? og : myg1;
;           }
;         }
;       }
;     }
; }
	s_mov_b32 s88, 0xffff
	s_mov_b32 s89, 0xffff
	v_min_u32_e32 v96, v142, v64
	v_max_u32_e32 v97, v142, v64
	v_cndmask_b32_e64 v142, v97, v96, s[88:89]
	v_min_u32_e32 v98, v144, v65
	v_max_u32_e32 v99, v144, v65
	v_cndmask_b32_e64 v144, v99, v98, s[88:89]
	v_min_u32_e32 v96, v146, v66
	v_max_u32_e32 v97, v146, v66
	v_cndmask_b32_e64 v146, v97, v96, s[88:89]
	v_min_u32_e32 v98, v148, v67
	v_max_u32_e32 v99, v148, v67
	v_cndmask_b32_e64 v148, v99, v98, s[88:89]
	s_mov_b32 s88, 0xffff0000
	s_mov_b32 s89, 0xffff0000
	v_min_u32_e32 v96, v143, v68
	v_max_u32_e32 v97, v143, v68
	v_cndmask_b32_e64 v143, v97, v96, s[88:89]
	v_min_u32_e32 v98, v145, v69
	v_max_u32_e32 v99, v145, v69
	v_cndmask_b32_e64 v145, v99, v98, s[88:89]
	v_min_u32_e32 v96, v147, v70
	v_max_u32_e32 v97, v147, v70
	v_cndmask_b32_e64 v147, v97, v96, s[88:89]
	v_min_u32_e32 v98, v149, v71
	v_max_u32_e32 v99, v149, v71
	v_cndmask_b32_e64 v149, v99, v98, s[88:89]
	v_xor_b32_e32 v116, 32, v252
	ds_bpermute_b32 v64, v116, v142
	ds_bpermute_b32 v65, v116, v144
	ds_bpermute_b32 v66, v116, v146
	ds_bpermute_b32 v67, v116, v148
	ds_bpermute_b32 v68, v116, v143
	ds_bpermute_b32 v69, v116, v145
	ds_bpermute_b32 v70, v116, v147
	ds_bpermute_b32 v71, v116, v149
	s_waitcnt lgkmcnt(0)
	s_mov_b32 s88, 0xff00ff
	s_mov_b32 s89, 0xff00ff
	v_min_u32_e32 v96, v142, v64
	v_max_u32_e32 v97, v142, v64
	v_cndmask_b32_e64 v142, v97, v96, s[88:89]
	v_min_u32_e32 v98, v144, v65
	v_max_u32_e32 v99, v144, v65
	v_cndmask_b32_e64 v144, v99, v98, s[88:89]
	v_min_u32_e32 v96, v146, v66
	v_max_u32_e32 v97, v146, v66
	v_cndmask_b32_e64 v146, v97, v96, s[88:89]
	v_min_u32_e32 v98, v148, v67
	v_max_u32_e32 v99, v148, v67
	v_cndmask_b32_e64 v148, v99, v98, s[88:89]
	s_mov_b32 s88, 0xff00ff00
	s_mov_b32 s89, 0xff00ff00
	v_min_u32_e32 v96, v143, v68
	v_max_u32_e32 v97, v143, v68
	v_cndmask_b32_e64 v143, v97, v96, s[88:89]
	v_min_u32_e32 v98, v145, v69
	v_max_u32_e32 v99, v145, v69
	v_cndmask_b32_e64 v145, v99, v98, s[88:89]
	v_min_u32_e32 v96, v147, v70
	v_max_u32_e32 v97, v147, v70
	v_cndmask_b32_e64 v147, v97, v96, s[88:89]
	v_min_u32_e32 v98, v149, v71
	v_max_u32_e32 v99, v149, v71
	v_cndmask_b32_e64 v149, v99, v98, s[88:89]
	v_xor_b32_e32 v116, 16, v252
	ds_bpermute_b32 v64, v116, v142
	ds_bpermute_b32 v65, v116, v144
	ds_bpermute_b32 v66, v116, v146
	ds_bpermute_b32 v67, v116, v148
	ds_bpermute_b32 v68, v116, v143
	ds_bpermute_b32 v69, v116, v145
	ds_bpermute_b32 v70, v116, v147
	ds_bpermute_b32 v71, v116, v149
	s_waitcnt lgkmcnt(0)
	s_mov_b32 s88, 0xf0f0f0f
	s_mov_b32 s89, 0xf0f0f0f
	v_min_u32_e32 v96, v142, v64
	v_max_u32_e32 v97, v142, v64
	v_cndmask_b32_e64 v142, v97, v96, s[88:89]
	v_min_u32_e32 v98, v144, v65
	v_max_u32_e32 v99, v144, v65
	v_cndmask_b32_e64 v144, v99, v98, s[88:89]
	v_min_u32_e32 v96, v146, v66
	v_max_u32_e32 v97, v146, v66
	v_cndmask_b32_e64 v146, v97, v96, s[88:89]
	v_min_u32_e32 v98, v148, v67
	v_max_u32_e32 v99, v148, v67
	v_cndmask_b32_e64 v148, v99, v98, s[88:89]
	s_mov_b32 s88, 0xf0f0f0f0
	s_mov_b32 s89, 0xf0f0f0f0
	v_min_u32_e32 v96, v143, v68
	v_max_u32_e32 v97, v143, v68
	v_cndmask_b32_e64 v143, v97, v96, s[88:89]
	v_min_u32_e32 v98, v145, v69
	v_max_u32_e32 v99, v145, v69
	v_cndmask_b32_e64 v145, v99, v98, s[88:89]
	v_min_u32_e32 v96, v147, v70
	v_max_u32_e32 v97, v147, v70
	v_cndmask_b32_e64 v147, v97, v96, s[88:89]
	v_min_u32_e32 v98, v149, v71
	v_max_u32_e32 v99, v149, v71
	v_cndmask_b32_e64 v149, v99, v98, s[88:89]
	v_xor_b32_e32 v116, 8, v252
	ds_bpermute_b32 v64, v116, v142
	ds_bpermute_b32 v65, v116, v144
	ds_bpermute_b32 v66, v116, v146
	ds_bpermute_b32 v67, v116, v148
	ds_bpermute_b32 v68, v116, v143
	ds_bpermute_b32 v69, v116, v145
	ds_bpermute_b32 v70, v116, v147
	ds_bpermute_b32 v71, v116, v149
	s_waitcnt lgkmcnt(0)
	s_mov_b32 s88, 0x33333333
	s_mov_b32 s89, 0x33333333
	v_min_u32_e32 v96, v142, v64
	v_max_u32_e32 v97, v142, v64
	v_cndmask_b32_e64 v142, v97, v96, s[88:89]
	v_min_u32_e32 v98, v144, v65
	v_max_u32_e32 v99, v144, v65
	v_cndmask_b32_e64 v144, v99, v98, s[88:89]
	v_min_u32_e32 v96, v146, v66
	v_max_u32_e32 v97, v146, v66
	v_cndmask_b32_e64 v146, v97, v96, s[88:89]
	v_min_u32_e32 v98, v148, v67
	v_max_u32_e32 v99, v148, v67
	v_cndmask_b32_e64 v148, v99, v98, s[88:89]
	s_mov_b32 s88, 0xcccccccc
	s_mov_b32 s89, 0xcccccccc
	v_min_u32_e32 v96, v143, v68
	v_max_u32_e32 v97, v143, v68
	v_cndmask_b32_e64 v143, v97, v96, s[88:89]
	v_min_u32_e32 v98, v145, v69
	v_max_u32_e32 v99, v145, v69
	v_cndmask_b32_e64 v145, v99, v98, s[88:89]
	v_min_u32_e32 v96, v147, v70
	v_max_u32_e32 v97, v147, v70
	v_cndmask_b32_e64 v147, v97, v96, s[88:89]
	v_min_u32_e32 v98, v149, v71
	v_max_u32_e32 v99, v149, v71
	v_cndmask_b32_e64 v149, v99, v98, s[88:89]
	v_xor_b32_e32 v116, 4, v252
	ds_bpermute_b32 v64, v116, v142
	ds_bpermute_b32 v65, v116, v144
	ds_bpermute_b32 v66, v116, v146
	ds_bpermute_b32 v67, v116, v148
	ds_bpermute_b32 v68, v116, v143
	ds_bpermute_b32 v69, v116, v145
	ds_bpermute_b32 v70, v116, v147
	ds_bpermute_b32 v71, v116, v149
	s_waitcnt lgkmcnt(0)
; DEV void sort_lists(int lane, int& myi0, int& myi1, float& myg0, float& myg1) {
; #pragma unroll
;     for (int k = 2; k <= 128; k <<= 1) {
; #pragma unroll
;       for (int j = k >> 1; j >= 1; j >>= 1) {
;         if (j == 64) {
;           const bool sw_ = myi1 < myi0;
;           const int ti = sw_ ? myi1 : myi0, tj = sw_ ? myi0 : myi1; const float tg = sw_ ? myg1 : myg0, th = sw_ ? myg0 : myg1;
;           myi0 = ti; myi1 = tj; myg0 = tg; myg1 = th;
;         } else {
;           const bool lower = (lane & j) == 0;
;           {
;             const bool up = (k == 128) ? true : ((k == 64) ? true : ((lane & k) == 0));
;             const int oi = __shfl_xor(myi0, j); const float og = __shfl_xor(myg0, j);
;             const bool take = (lower == up) ? (oi < myi0) : (oi > myi0);
;             myi0 = take ? oi : myi0; myg0 = take ? og : myg0;
;           }
;           {
;             const bool up = (k == 128) ? true : ((k == 64) ? false : ((lane & k) == 0));
;             const int oi = __shfl_xor(myi1, j); const float og = __shfl_xor(myg1, j);
;             const bool take = (lower == up) ? (oi < myi1) : (oi > myi1);
;             myi1 = take ? oi : myi1; myg1 = take ? og : myg1;
;           }
;         }
;       }
;     }
; }
	s_mov_b32 s88, 0x55555555
	s_mov_b32 s89, 0x55555555
	v_min_u32_e32 v96, v142, v64
	v_max_u32_e32 v97, v142, v64
	v_cndmask_b32_e64 v142, v97, v96, s[88:89]
	v_min_u32_e32 v98, v144, v65
	v_max_u32_e32 v99, v144, v65
	v_cndmask_b32_e64 v144, v99, v98, s[88:89]
	v_min_u32_e32 v96, v146, v66
	v_max_u32_e32 v97, v146, v66
	v_cndmask_b32_e64 v146, v97, v96, s[88:89]
	v_min_u32_e32 v98, v148, v67
	v_max_u32_e32 v99, v148, v67
	v_cndmask_b32_e64 v148, v99, v98, s[88:89]
	s_mov_b32 s88, 0xaaaaaaaa
	s_mov_b32 s89, 0xaaaaaaaa
	v_min_u32_e32 v96, v143, v68
	v_max_u32_e32 v97, v143, v68
	v_cndmask_b32_e64 v143, v97, v96, s[88:89]
	v_min_u32_e32 v98, v145, v69
	v_max_u32_e32 v99, v145, v69
	v_cndmask_b32_e64 v145, v99, v98, s[88:89]
	v_min_u32_e32 v96, v147, v70
	v_max_u32_e32 v97, v147, v70
	v_cndmask_b32_e64 v147, v97, v96, s[88:89]
	v_min_u32_e32 v98, v149, v71
	v_max_u32_e32 v99, v149, v71
	v_cndmask_b32_e64 v149, v99, v98, s[88:89]
	v_min_u32_e32 v96, v142, v143
	v_max_u32_e32 v143, v142, v143
	v_mov_b32_e32 v142, v96
	v_min_u32_e32 v98, v144, v145
	v_max_u32_e32 v145, v144, v145
	v_mov_b32_e32 v144, v98
	v_min_u32_e32 v96, v146, v147
	v_max_u32_e32 v147, v146, v147
	v_mov_b32_e32 v146, v96
	v_min_u32_e32 v98, v148, v149
	v_max_u32_e32 v149, v148, v149
	v_mov_b32_e32 v148, v98
	v_xor_b32_e32 v116, 128, v252
	ds_bpermute_b32 v64, v116, v142
	ds_bpermute_b32 v65, v116, v144
	ds_bpermute_b32 v66, v116, v146
	ds_bpermute_b32 v67, v116, v148
	ds_bpermute_b32 v68, v116, v143
	ds_bpermute_b32 v69, v116, v145
	ds_bpermute_b32 v70, v116, v147
	ds_bpermute_b32 v71, v116, v149
	s_waitcnt lgkmcnt(0)
	s_mov_b32 s88, 0xffffffff
	s_mov_b32 s89, 0x0
	v_min_u32_e32 v96, v142, v64
	v_max_u32_e32 v97, v142, v64
	v_cndmask_b32_e64 v142, v97, v96, s[88:89]
	v_min_u32_e32 v98, v144, v65
	v_max_u32_e32 v99, v144, v65
	v_cndmask_b32_e64 v144, v99, v98, s[88:89]
	v_min_u32_e32 v96, v146, v66
	v_max_u32_e32 v97, v146, v66
	v_cndmask_b32_e64 v146, v97, v96, s[88:89]
	v_min_u32_e32 v98, v148, v67
	v_max_u32_e32 v99, v148, v67
	v_cndmask_b32_e64 v148, v99, v98, s[88:89]
	v_min_u32_e32 v96, v143, v68
	v_max_u32_e32 v97, v143, v68
	v_cndmask_b32_e64 v143, v97, v96, s[88:89]
	v_min_u32_e32 v98, v145, v69
	v_max_u32_e32 v99, v145, v69
	v_cndmask_b32_e64 v145, v99, v98, s[88:89]
	v_min_u32_e32 v96, v147, v70
	v_max_u32_e32 v97, v147, v70
	v_cndmask_b32_e64 v147, v97, v96, s[88:89]
	v_min_u32_e32 v98, v149, v71
	v_max_u32_e32 v99, v149, v71
	v_cndmask_b32_e64 v149, v99, v98, s[88:89]
	v_xor_b32_e32 v116, 64, v252
	ds_bpermute_b32 v64, v116, v142
	ds_bpermute_b32 v65, v116, v144
	ds_bpermute_b32 v66, v116, v146
	ds_bpermute_b32 v67, v116, v148
	ds_bpermute_b32 v68, v116, v143
	ds_bpermute_b32 v69, v116, v145
	ds_bpermute_b32 v70, v116, v147
	ds_bpermute_b32 v71, v116, v149
	s_waitcnt lgkmcnt(0)
	s_mov_b32 s88, 0xffff
	s_mov_b32 s89, 0xffff
	v_min_u32_e32 v96, v142, v64
	v_max_u32_e32 v97, v142, v64
	v_cndmask_b32_e64 v142, v97, v96, s[88:89]
	v_min_u32_e32 v98, v144, v65
	v_max_u32_e32 v99, v144, v65
	v_cndmask_b32_e64 v144, v99, v98, s[88:89]
	v_min_u32_e32 v96, v146, v66
	v_max_u32_e32 v97, v146, v66
	v_cndmask_b32_e64 v146, v97, v96, s[88:89]
	v_min_u32_e32 v98, v148, v67
	v_max_u32_e32 v99, v148, v67
	v_cndmask_b32_e64 v148, v99, v98, s[88:89]
	v_min_u32_e32 v96, v143, v68
	v_max_u32_e32 v97, v143, v68
	v_cndmask_b32_e64 v143, v97, v96, s[88:89]
	v_min_u32_e32 v98, v145, v69
	v_max_u32_e32 v99, v145, v69
	v_cndmask_b32_e64 v145, v99, v98, s[88:89]
	v_min_u32_e32 v96, v147, v70
	v_max_u32_e32 v97, v147, v70
	v_cndmask_b32_e64 v147, v97, v96, s[88:89]
	v_min_u32_e32 v98, v149, v71
	v_max_u32_e32 v99, v149, v71
	v_cndmask_b32_e64 v149, v99, v98, s[88:89]
	v_xor_b32_e32 v116, 32, v252
	ds_bpermute_b32 v64, v116, v142
	ds_bpermute_b32 v65, v116, v144
	ds_bpermute_b32 v66, v116, v146
	ds_bpermute_b32 v67, v116, v148
	ds_bpermute_b32 v68, v116, v143
	ds_bpermute_b32 v69, v116, v145
	ds_bpermute_b32 v70, v116, v147
	ds_bpermute_b32 v71, v116, v149
	s_waitcnt lgkmcnt(0)
	s_mov_b32 s88, 0xff00ff
	s_mov_b32 s89, 0xff00ff
	v_min_u32_e32 v96, v142, v64
	v_max_u32_e32 v97, v142, v64
	v_cndmask_b32_e64 v142, v97, v96, s[88:89]
	v_min_u32_e32 v98, v144, v65
	v_max_u32_e32 v99, v144, v65
	v_cndmask_b32_e64 v144, v99, v98, s[88:89]
	v_min_u32_e32 v96, v146, v66
	v_max_u32_e32 v97, v146, v66
	v_cndmask_b32_e64 v146, v97, v96, s[88:89]
	v_min_u32_e32 v98, v148, v67
	v_max_u32_e32 v99, v148, v67
	v_cndmask_b32_e64 v148, v99, v98, s[88:89]
	v_min_u32_e32 v96, v143, v68
	v_max_u32_e32 v97, v143, v68
	v_cndmask_b32_e64 v143, v97, v96, s[88:89]
	v_min_u32_e32 v98, v145, v69
	v_max_u32_e32 v99, v145, v69
	v_cndmask_b32_e64 v145, v99, v98, s[88:89]
	v_min_u32_e32 v96, v147, v70
	v_max_u32_e32 v97, v147, v70
	v_cndmask_b32_e64 v147, v97, v96, s[88:89]
	v_min_u32_e32 v98, v149, v71
	v_max_u32_e32 v99, v149, v71
	v_cndmask_b32_e64 v149, v99, v98, s[88:89]
	v_xor_b32_e32 v116, 16, v252
	ds_bpermute_b32 v64, v116, v142
	ds_bpermute_b32 v65, v116, v144
	ds_bpermute_b32 v66, v116, v146
	ds_bpermute_b32 v67, v116, v148
	ds_bpermute_b32 v68, v116, v143
	ds_bpermute_b32 v69, v116, v145
	ds_bpermute_b32 v70, v116, v147
	ds_bpermute_b32 v71, v116, v149
	s_waitcnt lgkmcnt(0)
; #define PG_ISSUE(BUF, TAB, e0_) do { const int isrc_ = ((e0_) < 64) ? myi0 : myi1; \
;       _Pragma("unroll") for (int e = 0; e < 8; ++e) { const int idx_ = __builtin_amdgcn_readlane(isrc_, ((e0_) + e) & 63); \
;         BUF[e] = *(const u32x4*)((TAB) + (size_t)idx_ * 1024 + lane * 16); } } while (0)
; DEV void sort_lists(int lane, int& myi0, int& myi1, float& myg0, float& myg1) {
; #pragma unroll
;     for (int k = 2; k <= 128; k <<= 1) {
; #pragma unroll
;       for (int j = k >> 1; j >= 1; j >>= 1) {
;         if (j == 64) {
;           const bool sw_ = myi1 < myi0;
;           const int ti = sw_ ? myi1 : myi0, tj = sw_ ? myi0 : myi1; const float tg = sw_ ? myg1 : myg0, th = sw_ ? myg0 : myg1;
;           myi0 = ti; myi1 = tj; myg0 = tg; myg1 = th;
;         } else {
;           const bool lower = (lane & j) == 0;
;           {
;             const bool up = (k == 128) ? true : ((k == 64) ? true : ((lane & k) == 0));
;             const int oi = __shfl_xor(myi0, j); const float og = __shfl_xor(myg0, j);
;             const bool take = (lower == up) ? (oi < myi0) : (oi > myi0);
;             myi0 = take ? oi : myi0; myg0 = take ? og : myg0;
;           }
;           {
;             const bool up = (k == 128) ? true : ((k == 64) ? false : ((lane & k) == 0));
;             const int oi = __shfl_xor(myi1, j); const float og = __shfl_xor(myg1, j);
;             const bool take = (lower == up) ? (oi < myi1) : (oi > myi1);
;             myi1 = take ? oi : myi1; myg1 = take ? og : myg1;
;           }
;         }
;       }
;     }
; }
; DEV void peer_gather(const Params& P, int l, int m0, const int* idxs, const float* gs) {
;     ...
;   float ng0 = gs[(wid * 16) * 128 + lane], ng1 = gs[(wid * 16) * 128 + 64 + lane];
;     ...
;     PG_ISSUE(b0, U, 0);
	s_mov_b32 s88, 0xf0f0f0f
	s_mov_b32 s89, 0xf0f0f0f
	v_min_u32_e32 v96, v142, v64
	v_max_u32_e32 v97, v142, v64
	v_cndmask_b32_e64 v142, v97, v96, s[88:89]
	v_min_u32_e32 v98, v144, v65
	v_max_u32_e32 v99, v144, v65
	v_cndmask_b32_e64 v144, v99, v98, s[88:89]
	v_min_u32_e32 v96, v146, v66
	v_max_u32_e32 v97, v146, v66
	v_cndmask_b32_e64 v146, v97, v96, s[88:89]
	v_min_u32_e32 v98, v148, v67
	v_max_u32_e32 v99, v148, v67
	v_cndmask_b32_e64 v148, v99, v98, s[88:89]
	v_min_u32_e32 v96, v143, v68
	v_max_u32_e32 v97, v143, v68
	v_cndmask_b32_e64 v143, v97, v96, s[88:89]
	v_min_u32_e32 v98, v145, v69
	v_max_u32_e32 v99, v145, v69
	v_cndmask_b32_e64 v145, v99, v98, s[88:89]
	v_min_u32_e32 v96, v147, v70
	v_max_u32_e32 v97, v147, v70
	v_cndmask_b32_e64 v147, v97, v96, s[88:89]
	v_min_u32_e32 v98, v149, v71
	v_max_u32_e32 v99, v149, v71
	v_cndmask_b32_e64 v149, v99, v98, s[88:89]
	v_xor_b32_e32 v116, 8, v252
	ds_bpermute_b32 v64, v116, v142
	ds_bpermute_b32 v65, v116, v144
	ds_bpermute_b32 v66, v116, v146
	ds_bpermute_b32 v67, v116, v148
	ds_bpermute_b32 v68, v116, v143
	ds_bpermute_b32 v69, v116, v145
	ds_bpermute_b32 v70, v116, v147
	ds_bpermute_b32 v71, v116, v149
	s_waitcnt lgkmcnt(0)
	s_mov_b32 s88, 0x33333333
	s_mov_b32 s89, 0x33333333
	v_min_u32_e32 v96, v142, v64
	v_max_u32_e32 v97, v142, v64
	v_cndmask_b32_e64 v142, v97, v96, s[88:89]
	v_min_u32_e32 v98, v144, v65
	v_max_u32_e32 v99, v144, v65
	v_cndmask_b32_e64 v144, v99, v98, s[88:89]
	v_min_u32_e32 v96, v146, v66
	v_max_u32_e32 v97, v146, v66
	v_cndmask_b32_e64 v146, v97, v96, s[88:89]
	v_min_u32_e32 v98, v148, v67
	v_max_u32_e32 v99, v148, v67
	v_cndmask_b32_e64 v148, v99, v98, s[88:89]
	v_min_u32_e32 v96, v143, v68
	v_max_u32_e32 v97, v143, v68
	v_cndmask_b32_e64 v143, v97, v96, s[88:89]
	v_min_u32_e32 v98, v145, v69
	v_max_u32_e32 v99, v145, v69
	v_cndmask_b32_e64 v145, v99, v98, s[88:89]
	v_min_u32_e32 v96, v147, v70
	v_max_u32_e32 v97, v147, v70
	v_cndmask_b32_e64 v147, v97, v96, s[88:89]
	v_min_u32_e32 v98, v149, v71
	v_max_u32_e32 v99, v149, v71
	v_cndmask_b32_e64 v149, v99, v98, s[88:89]
	v_xor_b32_e32 v116, 4, v252
	ds_bpermute_b32 v64, v116, v142
	ds_bpermute_b32 v65, v116, v144
	ds_bpermute_b32 v66, v116, v146
	ds_bpermute_b32 v67, v116, v148
	ds_bpermute_b32 v68, v116, v143
	ds_bpermute_b32 v69, v116, v145
	ds_bpermute_b32 v70, v116, v147
	ds_bpermute_b32 v71, v116, v149
	s_waitcnt lgkmcnt(0)
	s_mov_b32 s88, 0x55555555
	s_mov_b32 s89, 0x55555555
	v_min_u32_e32 v96, v142, v64
	v_max_u32_e32 v97, v142, v64
	v_cndmask_b32_e64 v142, v97, v96, s[88:89]
	v_min_u32_e32 v98, v144, v65
	v_max_u32_e32 v99, v144, v65
	v_cndmask_b32_e64 v144, v99, v98, s[88:89]
	v_min_u32_e32 v96, v146, v66
	v_max_u32_e32 v97, v146, v66
	v_cndmask_b32_e64 v146, v97, v96, s[88:89]
	v_min_u32_e32 v98, v148, v67
	v_max_u32_e32 v99, v148, v67
	v_cndmask_b32_e64 v148, v99, v98, s[88:89]
	v_min_u32_e32 v96, v143, v68
	v_max_u32_e32 v97, v143, v68
	v_cndmask_b32_e64 v143, v97, v96, s[88:89]
	v_min_u32_e32 v98, v145, v69
	v_max_u32_e32 v99, v145, v69
	v_cndmask_b32_e64 v145, v99, v98, s[88:89]
	v_min_u32_e32 v96, v147, v70
	v_max_u32_e32 v97, v147, v70
	v_cndmask_b32_e64 v147, v97, v96, s[88:89]
	v_min_u32_e32 v98, v149, v71
	v_max_u32_e32 v99, v149, v71
	v_cndmask_b32_e64 v149, v99, v98, s[88:89]
	v_readlane_b32 s82, v231, 28
	v_readlane_b32 s83, v231, 29
	s_nop 4
	s_add_u32 s98, s33, 0
	s_lshl_b32 s98, s98, 9
	v_and_b32_e32 v116, 0x7f, v142
	v_lshl_add_u32 v116, v116, 2, s98
	global_load_dword v233, v116, s[82:83]
	v_lshrrev_b32_e32 v142, 7, v142
	v_and_b32_e32 v117, 0x7f, v143
	v_lshl_add_u32 v117, v117, 2, s98
	global_load_dword v234, v117, s[82:83]
	v_lshrrev_b32_e32 v143, 7, v143
	s_add_u32 s98, s33, 1
	s_lshl_b32 s98, s98, 9
	v_and_b32_e32 v118, 0x7f, v144
	v_lshl_add_u32 v118, v118, 2, s98
	global_load_dword v235, v118, s[82:83]
	v_lshrrev_b32_e32 v144, 7, v144
	v_and_b32_e32 v119, 0x7f, v145
	v_lshl_add_u32 v119, v119, 2, s98
	global_load_dword v236, v119, s[82:83]
	v_lshrrev_b32_e32 v145, 7, v145
	s_add_u32 s98, s33, 2
	s_lshl_b32 s98, s98, 9
	v_and_b32_e32 v116, 0x7f, v146
	v_lshl_add_u32 v116, v116, 2, s98
	global_load_dword v237, v116, s[82:83]
	v_lshrrev_b32_e32 v146, 7, v146
	v_and_b32_e32 v117, 0x7f, v147
	v_lshl_add_u32 v117, v117, 2, s98
	global_load_dword v238, v117, s[82:83]
	v_lshrrev_b32_e32 v147, 7, v147
	s_add_u32 s98, s33, 3
	s_lshl_b32 s98, s98, 9
	v_and_b32_e32 v118, 0x7f, v148
	v_lshl_add_u32 v118, v118, 2, s98
	global_load_dword v239, v118, s[82:83]
	v_lshrrev_b32_e32 v148, 7, v148
	v_and_b32_e32 v119, 0x7f, v149
	v_lshl_add_u32 v119, v119, 2, s98
	global_load_dword v240, v119, s[82:83]
	v_lshrrev_b32_e32 v149, 7, v149
	v_readfirstlane_b32 s80, v124
	v_readfirstlane_b32 s81, v125
	s_nop 4
	v_mov_b32_e32 v241, 0
	v_mov_b32_e32 v242, 0
	v_mov_b32_e32 v243, 0
	v_mov_b32_e32 v244, 0
	v_mov_b32_e32 v245, 0
	v_mov_b32_e32 v246, 0
	v_mov_b32_e32 v247, 0
	v_mov_b32_e32 v248, 0
	s_mov_b32 s100, 0
	s_mov_b32 s101, 0
	s_mov_b64 s[90:91], 0
	v_cndmask_b32_e64 v153, v142, v143, s[90:91]
	s_nop 0
	s_add_u32 s98, s101, 0
	v_readlane_b32 s98, v153, s98
	s_add_u32 s99, s101, 1
	v_readlane_b32 s99, v153, s99
	s_add_u32 s92, s101, 2
	v_readlane_b32 s92, v153, s92
	s_add_u32 s93, s101, 3
	v_readlane_b32 s93, v153, s93
	v_lshl_add_u32 v134, s98, 10, v250
	v_lshl_add_u32 v135, s99, 10, v250
	v_lshl_add_u32 v136, s92, 10, v250
	v_lshl_add_u32 v137, s93, 10, v250
	s_add_u32 s98, s101, 4
	v_readlane_b32 s98, v153, s98
	s_add_u32 s99, s101, 5
	v_readlane_b32 s99, v153, s99
	s_add_u32 s92, s101, 6
	v_readlane_b32 s92, v153, s92
	s_add_u32 s93, s101, 7
	v_readlane_b32 s93, v153, s93
	v_lshl_add_u32 v138, s98, 10, v250
	v_lshl_add_u32 v139, s99, 10, v250
	v_lshl_add_u32 v140, s92, 10, v250
	v_lshl_add_u32 v141, s93, 10, v250
	global_load_dwordx4 v[64:67], v134, s[80:81]
	global_load_dwordx4 v[68:71], v135, s[80:81]
	global_load_dwordx4 v[72:75], v136, s[80:81]
	global_load_dwordx4 v[76:79], v137, s[80:81]
	global_load_dwordx4 v[80:83], v138, s[80:81]
	global_load_dwordx4 v[84:87], v139, s[80:81]
	global_load_dwordx4 v[88:91], v140, s[80:81]
	global_load_dwordx4 v[92:95], v141, s[80:81]
.Lpg0_Uloop:
	s_cmp_ge_u32 s100, 8
	s_cselect_b64 s[90:91], -1, 0
	s_and_b32 s98, s100, 7
	s_lshl_b32 s98, s98, 3
	s_lshl_b64 s[88:89], 0xff, s98
	s_cmp_ge_u32 s100, 8
	s_cselect_b64 s[84:85], 0, s[88:89]
	s_cselect_b64 s[86:87], s[88:89], 0
	v_cndmask_b32_e64 v153, v144, v145, s[90:91]
	s_nop 0
	s_add_u32 s98, s101, 0
	v_readlane_b32 s98, v153, s98
	s_add_u32 s99, s101, 1
	v_readlane_b32 s99, v153, s99
	s_add_u32 s92, s101, 2
	v_readlane_b32 s92, v153, s92
	s_add_u32 s93, s101, 3
	v_readlane_b32 s93, v153, s93
	v_lshl_add_u32 v134, s98, 10, v250
	v_lshl_add_u32 v135, s99, 10, v250
	v_lshl_add_u32 v136, s92, 10, v250
	v_lshl_add_u32 v137, s93, 10, v250
	s_add_u32 s98, s101, 4
	v_readlane_b32 s98, v153, s98
	s_add_u32 s99, s101, 5
	v_readlane_b32 s99, v153, s99
	s_add_u32 s92, s101, 6
	v_readlane_b32 s92, v153, s92
	s_add_u32 s93, s101, 7
	v_readlane_b32 s93, v153, s93
	v_lshl_add_u32 v138, s98, 10, v250
	v_lshl_add_u32 v139, s99, 10, v250
	v_lshl_add_u32 v140, s92, 10, v250
	v_lshl_add_u32 v141, s93, 10, v250
	s_waitcnt vmcnt(6)
	v_cvt_pk_f32_fp8_e32 v[96:97], v64
	v_cvt_pk_f32_fp8_e32 v[100:101], v68
	v_cvt_pk_f32_fp8_sdwa v[98:99], v64 src0_sel:WORD_1
	v_cvt_pk_f32_fp8_sdwa v[102:103], v68 src0_sel:WORD_1
	v_pk_mul_f32 v[104:105], v[0:1], v[96:97]
	v_pk_mul_f32 v[106:107], v[0:1], v[100:101]
	v_pk_fma_f32 v[104:105], v[2:3], v[98:99], v[104:105]
	v_pk_fma_f32 v[106:107], v[2:3], v[102:103], v[106:107]
	v_cvt_pk_f32_fp8_e32 v[96:97], v65
	v_cvt_pk_f32_fp8_e32 v[100:101], v69
	v_cvt_pk_f32_fp8_sdwa v[98:99], v65 src0_sel:WORD_1
	v_cvt_pk_f32_fp8_sdwa v[102:103], v69 src0_sel:WORD_1
	v_pk_fma_f32 v[104:105], v[4:5], v[96:97], v[104:105]
	v_pk_fma_f32 v[106:107], v[4:5], v[100:101], v[106:107]
	v_pk_fma_f32 v[104:105], v[6:7], v[98:99], v[104:105]
	v_pk_fma_f32 v[106:107], v[6:7], v[102:103], v[106:107]
	v_cvt_pk_f32_fp8_e32 v[96:97], v66
	v_cvt_pk_f32_fp8_e32 v[100:101], v70
	v_cvt_pk_f32_fp8_sdwa v[98:99], v66 src0_sel:WORD_1
	v_cvt_pk_f32_fp8_sdwa v[102:103], v70 src0_sel:WORD_1
	v_pk_fma_f32 v[104:105], v[8:9], v[96:97], v[104:105]
	v_pk_fma_f32 v[106:107], v[8:9], v[100:101], v[106:107]
	v_pk_fma_f32 v[104:105], v[10:11], v[98:99], v[104:105]
	v_pk_fma_f32 v[106:107], v[10:11], v[102:103], v[106:107]
	v_cvt_pk_f32_fp8_e32 v[96:97], v67
	v_cvt_pk_f32_fp8_e32 v[100:101], v71
	v_cvt_pk_f32_fp8_sdwa v[98:99], v67 src0_sel:WORD_1
	v_cvt_pk_f32_fp8_sdwa v[102:103], v71 src0_sel:WORD_1
	global_load_dwordx4 v[64:67], v134, s[80:81]
	global_load_dwordx4 v[68:71], v135, s[80:81]
	v_pk_fma_f32 v[104:105], v[12:13], v[96:97], v[104:105]
	v_pk_fma_f32 v[106:107], v[12:13], v[100:101], v[106:107]
	v_pk_fma_f32 v[104:105], v[14:15], v[98:99], v[104:105]
	v_pk_fma_f32 v[106:107], v[14:15], v[102:103], v[106:107]
	s_nop 0
	v_add_f32_e32 v108, v104, v105
	v_add_f32_e32 v109, v106, v107
	s_waitcnt vmcnt(6)
	v_cvt_pk_f32_fp8_e32 v[96:97], v72
	v_cvt_pk_f32_fp8_e32 v[100:101], v76
	v_cvt_pk_f32_fp8_sdwa v[98:99], v72 src0_sel:WORD_1
	v_cvt_pk_f32_fp8_sdwa v[102:103], v76 src0_sel:WORD_1
	v_pk_mul_f32 v[104:105], v[0:1], v[96:97]
	v_pk_mul_f32 v[106:107], v[0:1], v[100:101]
	v_pk_fma_f32 v[104:105], v[2:3], v[98:99], v[104:105]
	v_pk_fma_f32 v[106:107], v[2:3], v[102:103], v[106:107]
	v_cvt_pk_f32_fp8_e32 v[96:97], v73
	v_cvt_pk_f32_fp8_e32 v[100:101], v77
	v_cvt_pk_f32_fp8_sdwa v[98:99], v73 src0_sel:WORD_1
	v_cvt_pk_f32_fp8_sdwa v[102:103], v77 src0_sel:WORD_1
	v_pk_fma_f32 v[104:105], v[4:5], v[96:97], v[104:105]
	v_pk_fma_f32 v[106:107], v[4:5], v[100:101], v[106:107]
	v_pk_fma_f32 v[104:105], v[6:7], v[98:99], v[104:105]
	v_pk_fma_f32 v[106:107], v[6:7], v[102:103], v[106:107]
	v_cvt_pk_f32_fp8_e32 v[96:97], v74
	v_cvt_pk_f32_fp8_e32 v[100:101], v78
	v_cvt_pk_f32_fp8_sdwa v[98:99], v74 src0_sel:WORD_1
	v_cvt_pk_f32_fp8_sdwa v[102:103], v78 src0_sel:WORD_1
	v_pk_fma_f32 v[104:105], v[8:9], v[96:97], v[104:105]
	v_pk_fma_f32 v[106:107], v[8:9], v[100:101], v[106:107]
	v_pk_fma_f32 v[104:105], v[10:11], v[98:99], v[104:105]
	v_pk_fma_f32 v[106:107], v[10:11], v[102:103], v[106:107]
	v_cvt_pk_f32_fp8_e32 v[96:97], v75
	v_cvt_pk_f32_fp8_e32 v[100:101], v79
	v_cvt_pk_f32_fp8_sdwa v[98:99], v75 src0_sel:WORD_1
	v_cvt_pk_f32_fp8_sdwa v[102:103], v79 src0_sel:WORD_1
	global_load_dwordx4 v[72:75], v136, s[80:81]
	global_load_dwordx4 v[76:79], v137, s[80:81]
	v_pk_fma_f32 v[104:105], v[12:13], v[96:97], v[104:105]
	v_pk_fma_f32 v[106:107], v[12:13], v[100:101], v[106:107]
	v_pk_fma_f32 v[104:105], v[14:15], v[98:99], v[104:105]
	v_pk_fma_f32 v[106:107], v[14:15], v[102:103], v[106:107]
	s_nop 0
	v_add_f32_e32 v110, v104, v105
	v_add_f32_e32 v111, v106, v107
	s_waitcnt vmcnt(6)
	v_cvt_pk_f32_fp8_e32 v[96:97], v80
	v_cvt_pk_f32_fp8_e32 v[100:101], v84
	v_cvt_pk_f32_fp8_sdwa v[98:99], v80 src0_sel:WORD_1
	v_cvt_pk_f32_fp8_sdwa v[102:103], v84 src0_sel:WORD_1
	v_pk_mul_f32 v[104:105], v[0:1], v[96:97]
	v_pk_mul_f32 v[106:107], v[0:1], v[100:101]
	v_pk_fma_f32 v[104:105], v[2:3], v[98:99], v[104:105]
	v_pk_fma_f32 v[106:107], v[2:3], v[102:103], v[106:107]
	v_cvt_pk_f32_fp8_e32 v[96:97], v81
	v_cvt_pk_f32_fp8_e32 v[100:101], v85
	v_cvt_pk_f32_fp8_sdwa v[98:99], v81 src0_sel:WORD_1
	v_cvt_pk_f32_fp8_sdwa v[102:103], v85 src0_sel:WORD_1
	v_pk_fma_f32 v[104:105], v[4:5], v[96:97], v[104:105]
	v_pk_fma_f32 v[106:107], v[4:5], v[100:101], v[106:107]
	v_pk_fma_f32 v[104:105], v[6:7], v[98:99], v[104:105]
	v_pk_fma_f32 v[106:107], v[6:7], v[102:103], v[106:107]
	v_cvt_pk_f32_fp8_e32 v[96:97], v82
	v_cvt_pk_f32_fp8_e32 v[100:101], v86
	v_cvt_pk_f32_fp8_sdwa v[98:99], v82 src0_sel:WORD_1
	v_cvt_pk_f32_fp8_sdwa v[102:103], v86 src0_sel:WORD_1
	v_pk_fma_f32 v[104:105], v[8:9], v[96:97], v[104:105]
	v_pk_fma_f32 v[106:107], v[8:9], v[100:101], v[106:107]
	v_pk_fma_f32 v[104:105], v[10:11], v[98:99], v[104:105]
	v_pk_fma_f32 v[106:107], v[10:11], v[102:103], v[106:107]
	v_cvt_pk_f32_fp8_e32 v[96:97], v83
	v_cvt_pk_f32_fp8_e32 v[100:101], v87
	v_cvt_pk_f32_fp8_sdwa v[98:99], v83 src0_sel:WORD_1
	v_cvt_pk_f32_fp8_sdwa v[102:103], v87 src0_sel:WORD_1
	global_load_dwordx4 v[80:83], v138, s[80:81]
	global_load_dwordx4 v[84:87], v139, s[80:81]
	v_pk_fma_f32 v[104:105], v[12:13], v[96:97], v[104:105]
	v_pk_fma_f32 v[106:107], v[12:13], v[100:101], v[106:107]
	v_pk_fma_f32 v[104:105], v[14:15], v[98:99], v[104:105]
	v_pk_fma_f32 v[106:107], v[14:15], v[102:103], v[106:107]
	s_nop 0
	v_add_f32_e32 v112, v104, v105
	v_add_f32_e32 v113, v106, v107
	s_waitcnt vmcnt(6)
; #define PG_ISSUE(BUF, TAB, e0_) do { const int isrc_ = ((e0_) < 64) ? myi0 : myi1; \
;       _Pragma("unroll") for (int e = 0; e < 8; ++e) { const int idx_ = __builtin_amdgcn_readlane(isrc_, ((e0_) + e) & 63); \
;         BUF[e] = *(const u32x4*)((TAB) + (size_t)idx_ * 1024 + lane * 16); } } while (0)
; DEV void peer_gather(const Params& P, int l, int m0, const int* idxs, const float* gs) {
;     ...
;     PG_ISSUE(b0, U, 0);
; #pragma nounroll
;     for (int e0 = 0; e0 < 128; e0 += 16) {
;       PG_ISSUE(b1, U, e0 + 8);
;       PG_U8(b0, 0, e0);
;       if (e0 + 16 < 128) PG_ISSUE(b0, U, e0 + 16); else PG_ISSUE(b0, V, 0);
;       PG_U8(b1, 0, e0 + 8);
;     }
	v_cvt_pk_f32_fp8_e32 v[96:97], v88
	v_cvt_pk_f32_fp8_e32 v[100:101], v92
	v_cvt_pk_f32_fp8_sdwa v[98:99], v88 src0_sel:WORD_1
	v_cvt_pk_f32_fp8_sdwa v[102:103], v92 src0_sel:WORD_1
	v_pk_mul_f32 v[104:105], v[0:1], v[96:97]
	v_pk_mul_f32 v[106:107], v[0:1], v[100:101]
	v_pk_fma_f32 v[104:105], v[2:3], v[98:99], v[104:105]
	v_pk_fma_f32 v[106:107], v[2:3], v[102:103], v[106:107]
	v_cvt_pk_f32_fp8_e32 v[96:97], v89
	v_cvt_pk_f32_fp8_e32 v[100:101], v93
	v_cvt_pk_f32_fp8_sdwa v[98:99], v89 src0_sel:WORD_1
	v_cvt_pk_f32_fp8_sdwa v[102:103], v93 src0_sel:WORD_1
	v_pk_fma_f32 v[104:105], v[4:5], v[96:97], v[104:105]
	v_pk_fma_f32 v[106:107], v[4:5], v[100:101], v[106:107]
	v_pk_fma_f32 v[104:105], v[6:7], v[98:99], v[104:105]
	v_pk_fma_f32 v[106:107], v[6:7], v[102:103], v[106:107]
	v_cvt_pk_f32_fp8_e32 v[96:97], v90
	v_cvt_pk_f32_fp8_e32 v[100:101], v94
	v_cvt_pk_f32_fp8_sdwa v[98:99], v90 src0_sel:WORD_1
	v_cvt_pk_f32_fp8_sdwa v[102:103], v94 src0_sel:WORD_1
	v_pk_fma_f32 v[104:105], v[8:9], v[96:97], v[104:105]
	v_pk_fma_f32 v[106:107], v[8:9], v[100:101], v[106:107]
	v_pk_fma_f32 v[104:105], v[10:11], v[98:99], v[104:105]
	v_pk_fma_f32 v[106:107], v[10:11], v[102:103], v[106:107]
	v_cvt_pk_f32_fp8_e32 v[96:97], v91
	v_cvt_pk_f32_fp8_e32 v[100:101], v95
	v_cvt_pk_f32_fp8_sdwa v[98:99], v91 src0_sel:WORD_1
	v_cvt_pk_f32_fp8_sdwa v[102:103], v95 src0_sel:WORD_1
	global_load_dwordx4 v[88:91], v140, s[80:81]
	global_load_dwordx4 v[92:95], v141, s[80:81]
	v_pk_fma_f32 v[104:105], v[12:13], v[96:97], v[104:105]
	v_pk_fma_f32 v[106:107], v[12:13], v[100:101], v[106:107]
	v_pk_fma_f32 v[104:105], v[14:15], v[98:99], v[104:105]
	v_pk_fma_f32 v[106:107], v[14:15], v[102:103], v[106:107]
	s_nop 0
	v_add_f32_e32 v114, v104, v105
	v_add_f32_e32 v115, v106, v107
	s_nop 1
	v_permlane32_swap_b32_e32 v108, v109
	v_permlane32_swap_b32_e32 v110, v111
	v_permlane32_swap_b32_e32 v112, v113
	v_permlane32_swap_b32_e32 v114, v115
	v_add_f32_e32 v108, v108, v109
	v_add_f32_e32 v110, v110, v111
	v_add_f32_e32 v112, v112, v113
	v_add_f32_e32 v114, v114, v115
	s_nop 1
	v_permlane16_swap_b32_e32 v108, v110
	v_permlane16_swap_b32_e32 v112, v114
	v_add_f32_e32 v108, v108, v110
	v_add_f32_e32 v112, v112, v114
	s_mov_b32 s88, 0xff00ff00
	s_mov_b32 s89, 0xff00ff00
	s_nop 0
	v_cndmask_b32_e64 v109, v108, v112, s[88:89]
	v_cndmask_b32_e64 v111, v112, v108, s[88:89]
	s_nop 1
	v_add_f32_dpp v109, v111, v109 row_ror:8 row_mask:0xf bank_mask:0xf
	s_nop 1
	v_add_f32_dpp v109, v109, v109 quad_perm:[1,0,3,2] row_mask:0xf bank_mask:0xf
	s_nop 1
	v_add_f32_dpp v109, v109, v109 quad_perm:[2,3,0,1] row_mask:0xf bank_mask:0xf
	s_nop 1
	v_add_f32_dpp v109, v109, v109 row_half_mirror row_mask:0xf bank_mask:0xf
	s_nop 0
	ds_bpermute_b32 v110, v251, v109
	s_waitcnt lgkmcnt(0)
	v_cndmask_b32_e64 v241, v241, v110, s[84:85]
	v_cndmask_b32_e64 v242, v242, v110, s[86:87]
	v_cndmask_b32_e64 v153, v146, v147, s[90:91]
	s_nop 0
	s_add_u32 s98, s101, 0
	v_readlane_b32 s98, v153, s98
	s_add_u32 s99, s101, 1
	v_readlane_b32 s99, v153, s99
	s_add_u32 s92, s101, 2
	v_readlane_b32 s92, v153, s92
	s_add_u32 s93, s101, 3
	v_readlane_b32 s93, v153, s93
	v_lshl_add_u32 v134, s98, 10, v250
	v_lshl_add_u32 v135, s99, 10, v250
	v_lshl_add_u32 v136, s92, 10, v250
	v_lshl_add_u32 v137, s93, 10, v250
	s_add_u32 s98, s101, 4
	v_readlane_b32 s98, v153, s98
	s_add_u32 s99, s101, 5
	v_readlane_b32 s99, v153, s99
	s_add_u32 s92, s101, 6
	v_readlane_b32 s92, v153, s92
	s_add_u32 s93, s101, 7
	v_readlane_b32 s93, v153, s93
	v_lshl_add_u32 v138, s98, 10, v250
	v_lshl_add_u32 v139, s99, 10, v250
	v_lshl_add_u32 v140, s92, 10, v250
	v_lshl_add_u32 v141, s93, 10, v250
	s_waitcnt vmcnt(6)
	v_cvt_pk_f32_fp8_e32 v[96:97], v64
	v_cvt_pk_f32_fp8_e32 v[100:101], v68
	v_cvt_pk_f32_fp8_sdwa v[98:99], v64 src0_sel:WORD_1
	v_cvt_pk_f32_fp8_sdwa v[102:103], v68 src0_sel:WORD_1
	v_pk_mul_f32 v[104:105], v[16:17], v[96:97]
	v_pk_mul_f32 v[106:107], v[16:17], v[100:101]
	v_pk_fma_f32 v[104:105], v[18:19], v[98:99], v[104:105]
	v_pk_fma_f32 v[106:107], v[18:19], v[102:103], v[106:107]
	v_cvt_pk_f32_fp8_e32 v[96:97], v65
	v_cvt_pk_f32_fp8_e32 v[100:101], v69
	v_cvt_pk_f32_fp8_sdwa v[98:99], v65 src0_sel:WORD_1
	v_cvt_pk_f32_fp8_sdwa v[102:103], v69 src0_sel:WORD_1
	v_pk_fma_f32 v[104:105], v[20:21], v[96:97], v[104:105]
	v_pk_fma_f32 v[106:107], v[20:21], v[100:101], v[106:107]
	v_pk_fma_f32 v[104:105], v[22:23], v[98:99], v[104:105]
	v_pk_fma_f32 v[106:107], v[22:23], v[102:103], v[106:107]
	v_cvt_pk_f32_fp8_e32 v[96:97], v66
	v_cvt_pk_f32_fp8_e32 v[100:101], v70
	v_cvt_pk_f32_fp8_sdwa v[98:99], v66 src0_sel:WORD_1
	v_cvt_pk_f32_fp8_sdwa v[102:103], v70 src0_sel:WORD_1
	v_pk_fma_f32 v[104:105], v[24:25], v[96:97], v[104:105]
	v_pk_fma_f32 v[106:107], v[24:25], v[100:101], v[106:107]
	v_pk_fma_f32 v[104:105], v[26:27], v[98:99], v[104:105]
	v_pk_fma_f32 v[106:107], v[26:27], v[102:103], v[106:107]
	v_cvt_pk_f32_fp8_e32 v[96:97], v67
	v_cvt_pk_f32_fp8_e32 v[100:101], v71
	v_cvt_pk_f32_fp8_sdwa v[98:99], v67 src0_sel:WORD_1
	v_cvt_pk_f32_fp8_sdwa v[102:103], v71 src0_sel:WORD_1
	global_load_dwordx4 v[64:67], v134, s[80:81]
	global_load_dwordx4 v[68:71], v135, s[80:81]
	v_pk_fma_f32 v[104:105], v[28:29], v[96:97], v[104:105]
	v_pk_fma_f32 v[106:107], v[28:29], v[100:101], v[106:107]
	v_pk_fma_f32 v[104:105], v[30:31], v[98:99], v[104:105]
	v_pk_fma_f32 v[106:107], v[30:31], v[102:103], v[106:107]
	s_nop 0
	v_add_f32_e32 v108, v104, v105
	v_add_f32_e32 v109, v106, v107
	s_waitcnt vmcnt(6)
; #define PG_ISSUE(BUF, TAB, e0_) do { const int isrc_ = ((e0_) < 64) ? myi0 : myi1; \
;       _Pragma("unroll") for (int e = 0; e < 8; ++e) { const int idx_ = __builtin_amdgcn_readlane(isrc_, ((e0_) + e) & 63); \
;         BUF[e] = *(const u32x4*)((TAB) + (size_t)idx_ * 1024 + lane * 16); } } while (0)
; DEV void peer_gather(const Params& P, int l, int m0, const int* idxs, const float* gs) {
;     ...
;     PG_ISSUE(b0, U, 0);
; #pragma nounroll
;     for (int e0 = 0; e0 < 128; e0 += 16) {
;       PG_ISSUE(b1, U, e0 + 8);
;       PG_U8(b0, 0, e0);
;       if (e0 + 16 < 128) PG_ISSUE(b0, U, e0 + 16); else PG_ISSUE(b0, V, 0);
;       PG_U8(b1, 0, e0 + 8);
;     }
	v_cvt_pk_f32_fp8_e32 v[96:97], v72
	v_cvt_pk_f32_fp8_e32 v[100:101], v76
	v_cvt_pk_f32_fp8_sdwa v[98:99], v72 src0_sel:WORD_1
	v_cvt_pk_f32_fp8_sdwa v[102:103], v76 src0_sel:WORD_1
	v_pk_mul_f32 v[104:105], v[16:17], v[96:97]
	v_pk_mul_f32 v[106:107], v[16:17], v[100:101]
	v_pk_fma_f32 v[104:105], v[18:19], v[98:99], v[104:105]
	v_pk_fma_f32 v[106:107], v[18:19], v[102:103], v[106:107]
	v_cvt_pk_f32_fp8_e32 v[96:97], v73
	v_cvt_pk_f32_fp8_e32 v[100:101], v77
	v_cvt_pk_f32_fp8_sdwa v[98:99], v73 src0_sel:WORD_1
	v_cvt_pk_f32_fp8_sdwa v[102:103], v77 src0_sel:WORD_1
	v_pk_fma_f32 v[104:105], v[20:21], v[96:97], v[104:105]
	v_pk_fma_f32 v[106:107], v[20:21], v[100:101], v[106:107]
	v_pk_fma_f32 v[104:105], v[22:23], v[98:99], v[104:105]
	v_pk_fma_f32 v[106:107], v[22:23], v[102:103], v[106:107]
	v_cvt_pk_f32_fp8_e32 v[96:97], v74
	v_cvt_pk_f32_fp8_e32 v[100:101], v78
	v_cvt_pk_f32_fp8_sdwa v[98:99], v74 src0_sel:WORD_1
	v_cvt_pk_f32_fp8_sdwa v[102:103], v78 src0_sel:WORD_1
	v_pk_fma_f32 v[104:105], v[24:25], v[96:97], v[104:105]
	v_pk_fma_f32 v[106:107], v[24:25], v[100:101], v[106:107]
	v_pk_fma_f32 v[104:105], v[26:27], v[98:99], v[104:105]
	v_pk_fma_f32 v[106:107], v[26:27], v[102:103], v[106:107]
	v_cvt_pk_f32_fp8_e32 v[96:97], v75
	v_cvt_pk_f32_fp8_e32 v[100:101], v79
	v_cvt_pk_f32_fp8_sdwa v[98:99], v75 src0_sel:WORD_1
	v_cvt_pk_f32_fp8_sdwa v[102:103], v79 src0_sel:WORD_1
	global_load_dwordx4 v[72:75], v136, s[80:81]
	global_load_dwordx4 v[76:79], v137, s[80:81]
	v_pk_fma_f32 v[104:105], v[28:29], v[96:97], v[104:105]
	v_pk_fma_f32 v[106:107], v[28:29], v[100:101], v[106:107]
	v_pk_fma_f32 v[104:105], v[30:31], v[98:99], v[104:105]
	v_pk_fma_f32 v[106:107], v[30:31], v[102:103], v[106:107]
	s_nop 0
	v_add_f32_e32 v110, v104, v105
	v_add_f32_e32 v111, v106, v107
	s_waitcnt vmcnt(6)
	v_cvt_pk_f32_fp8_e32 v[96:97], v80
	v_cvt_pk_f32_fp8_e32 v[100:101], v84
	v_cvt_pk_f32_fp8_sdwa v[98:99], v80 src0_sel:WORD_1
	v_cvt_pk_f32_fp8_sdwa v[102:103], v84 src0_sel:WORD_1
	v_pk_mul_f32 v[104:105], v[16:17], v[96:97]
	v_pk_mul_f32 v[106:107], v[16:17], v[100:101]
	v_pk_fma_f32 v[104:105], v[18:19], v[98:99], v[104:105]
	v_pk_fma_f32 v[106:107], v[18:19], v[102:103], v[106:107]
	v_cvt_pk_f32_fp8_e32 v[96:97], v81
	v_cvt_pk_f32_fp8_e32 v[100:101], v85
	v_cvt_pk_f32_fp8_sdwa v[98:99], v81 src0_sel:WORD_1
	v_cvt_pk_f32_fp8_sdwa v[102:103], v85 src0_sel:WORD_1
	v_pk_fma_f32 v[104:105], v[20:21], v[96:97], v[104:105]
	v_pk_fma_f32 v[106:107], v[20:21], v[100:101], v[106:107]
	v_pk_fma_f32 v[104:105], v[22:23], v[98:99], v[104:105]
	v_pk_fma_f32 v[106:107], v[22:23], v[102:103], v[106:107]
	v_cvt_pk_f32_fp8_e32 v[96:97], v82
	v_cvt_pk_f32_fp8_e32 v[100:101], v86
	v_cvt_pk_f32_fp8_sdwa v[98:99], v82 src0_sel:WORD_1
	v_cvt_pk_f32_fp8_sdwa v[102:103], v86 src0_sel:WORD_1
	v_pk_fma_f32 v[104:105], v[24:25], v[96:97], v[104:105]
	v_pk_fma_f32 v[106:107], v[24:25], v[100:101], v[106:107]
	v_pk_fma_f32 v[104:105], v[26:27], v[98:99], v[104:105]
	v_pk_fma_f32 v[106:107], v[26:27], v[102:103], v[106:107]
	v_cvt_pk_f32_fp8_e32 v[96:97], v83
	v_cvt_pk_f32_fp8_e32 v[100:101], v87
	v_cvt_pk_f32_fp8_sdwa v[98:99], v83 src0_sel:WORD_1
	v_cvt_pk_f32_fp8_sdwa v[102:103], v87 src0_sel:WORD_1
	global_load_dwordx4 v[80:83], v138, s[80:81]
	global_load_dwordx4 v[84:87], v139, s[80:81]
	v_pk_fma_f32 v[104:105], v[28:29], v[96:97], v[104:105]
	v_pk_fma_f32 v[106:107], v[28:29], v[100:101], v[106:107]
	v_pk_fma_f32 v[104:105], v[30:31], v[98:99], v[104:105]
	v_pk_fma_f32 v[106:107], v[30:31], v[102:103], v[106:107]
	s_nop 0
	v_add_f32_e32 v112, v104, v105
	v_add_f32_e32 v113, v106, v107
	s_waitcnt vmcnt(6)
	v_cvt_pk_f32_fp8_e32 v[96:97], v88
	v_cvt_pk_f32_fp8_e32 v[100:101], v92
	v_cvt_pk_f32_fp8_sdwa v[98:99], v88 src0_sel:WORD_1
	v_cvt_pk_f32_fp8_sdwa v[102:103], v92 src0_sel:WORD_1
	v_pk_mul_f32 v[104:105], v[16:17], v[96:97]
	v_pk_mul_f32 v[106:107], v[16:17], v[100:101]
	v_pk_fma_f32 v[104:105], v[18:19], v[98:99], v[104:105]
	v_pk_fma_f32 v[106:107], v[18:19], v[102:103], v[106:107]
	v_cvt_pk_f32_fp8_e32 v[96:97], v89
	v_cvt_pk_f32_fp8_e32 v[100:101], v93
	v_cvt_pk_f32_fp8_sdwa v[98:99], v89 src0_sel:WORD_1
	v_cvt_pk_f32_fp8_sdwa v[102:103], v93 src0_sel:WORD_1
	v_pk_fma_f32 v[104:105], v[20:21], v[96:97], v[104:105]
	v_pk_fma_f32 v[106:107], v[20:21], v[100:101], v[106:107]
	v_pk_fma_f32 v[104:105], v[22:23], v[98:99], v[104:105]
	v_pk_fma_f32 v[106:107], v[22:23], v[102:103], v[106:107]
	v_cvt_pk_f32_fp8_e32 v[96:97], v90
	v_cvt_pk_f32_fp8_e32 v[100:101], v94
	v_cvt_pk_f32_fp8_sdwa v[98:99], v90 src0_sel:WORD_1
	v_cvt_pk_f32_fp8_sdwa v[102:103], v94 src0_sel:WORD_1
	v_pk_fma_f32 v[104:105], v[24:25], v[96:97], v[104:105]
	v_pk_fma_f32 v[106:107], v[24:25], v[100:101], v[106:107]
	v_pk_fma_f32 v[104:105], v[26:27], v[98:99], v[104:105]
	v_pk_fma_f32 v[106:107], v[26:27], v[102:103], v[106:107]
	v_cvt_pk_f32_fp8_e32 v[96:97], v91
	v_cvt_pk_f32_fp8_e32 v[100:101], v95
	v_cvt_pk_f32_fp8_sdwa v[98:99], v91 src0_sel:WORD_1
	v_cvt_pk_f32_fp8_sdwa v[102:103], v95 src0_sel:WORD_1
	global_load_dwordx4 v[88:91], v140, s[80:81]
	global_load_dwordx4 v[92:95], v141, s[80:81]
	v_pk_fma_f32 v[104:105], v[28:29], v[96:97], v[104:105]
	v_pk_fma_f32 v[106:107], v[28:29], v[100:101], v[106:107]
	v_pk_fma_f32 v[104:105], v[30:31], v[98:99], v[104:105]
	v_pk_fma_f32 v[106:107], v[30:31], v[102:103], v[106:107]
	s_nop 0
	v_add_f32_e32 v114, v104, v105
	v_add_f32_e32 v115, v106, v107
	s_nop 1
	v_permlane32_swap_b32_e32 v108, v109
	v_permlane32_swap_b32_e32 v110, v111
	v_permlane32_swap_b32_e32 v112, v113
	v_permlane32_swap_b32_e32 v114, v115
	v_add_f32_e32 v108, v108, v109
	v_add_f32_e32 v110, v110, v111
	v_add_f32_e32 v112, v112, v113
	v_add_f32_e32 v114, v114, v115
	s_nop 1
	v_permlane16_swap_b32_e32 v108, v110
	v_permlane16_swap_b32_e32 v112, v114
	v_add_f32_e32 v108, v108, v110
	v_add_f32_e32 v112, v112, v114
	s_mov_b32 s88, 0xff00ff00
	s_mov_b32 s89, 0xff00ff00
	s_nop 0
	v_cndmask_b32_e64 v109, v108, v112, s[88:89]
	v_cndmask_b32_e64 v111, v112, v108, s[88:89]
	s_nop 1
	v_add_f32_dpp v109, v111, v109 row_ror:8 row_mask:0xf bank_mask:0xf
	s_nop 1
	v_add_f32_dpp v109, v109, v109 quad_perm:[1,0,3,2] row_mask:0xf bank_mask:0xf
	s_nop 1
	v_add_f32_dpp v109, v109, v109 quad_perm:[2,3,0,1] row_mask:0xf bank_mask:0xf
	s_nop 1
	v_add_f32_dpp v109, v109, v109 row_half_mirror row_mask:0xf bank_mask:0xf
	s_nop 0
	ds_bpermute_b32 v110, v251, v109
	s_waitcnt lgkmcnt(0)
; #define PG_ISSUE(BUF, TAB, e0_) do { const int isrc_ = ((e0_) < 64) ? myi0 : myi1; \
;       _Pragma("unroll") for (int e = 0; e < 8; ++e) { const int idx_ = __builtin_amdgcn_readlane(isrc_, ((e0_) + e) & 63); \
;         BUF[e] = *(const u32x4*)((TAB) + (size_t)idx_ * 1024 + lane * 16); } } while (0)
; DEV void peer_gather(const Params& P, int l, int m0, const int* idxs, const float* gs) {
;     ...
;     PG_ISSUE(b0, U, 0);
; #pragma nounroll
;     for (int e0 = 0; e0 < 128; e0 += 16) {
;       PG_ISSUE(b1, U, e0 + 8);
;       PG_U8(b0, 0, e0);
;       if (e0 + 16 < 128) PG_ISSUE(b0, U, e0 + 16); else PG_ISSUE(b0, V, 0);
;       PG_U8(b1, 0, e0 + 8);
;     }
	v_cndmask_b32_e64 v243, v243, v110, s[84:85]
	v_cndmask_b32_e64 v244, v244, v110, s[86:87]
	v_cndmask_b32_e64 v153, v148, v149, s[90:91]
	s_nop 0
	s_add_u32 s98, s101, 0
	v_readlane_b32 s98, v153, s98
	s_add_u32 s99, s101, 1
	v_readlane_b32 s99, v153, s99
	s_add_u32 s92, s101, 2
	v_readlane_b32 s92, v153, s92
	s_add_u32 s93, s101, 3
	v_readlane_b32 s93, v153, s93
	v_lshl_add_u32 v134, s98, 10, v250
	v_lshl_add_u32 v135, s99, 10, v250
	v_lshl_add_u32 v136, s92, 10, v250
	v_lshl_add_u32 v137, s93, 10, v250
	s_add_u32 s98, s101, 4
	v_readlane_b32 s98, v153, s98
	s_add_u32 s99, s101, 5
	v_readlane_b32 s99, v153, s99
	s_add_u32 s92, s101, 6
	v_readlane_b32 s92, v153, s92
	s_add_u32 s93, s101, 7
	v_readlane_b32 s93, v153, s93
	v_lshl_add_u32 v138, s98, 10, v250
	v_lshl_add_u32 v139, s99, 10, v250
	v_lshl_add_u32 v140, s92, 10, v250
	v_lshl_add_u32 v141, s93, 10, v250
	s_waitcnt vmcnt(6)
	v_cvt_pk_f32_fp8_e32 v[96:97], v64
	v_cvt_pk_f32_fp8_e32 v[100:101], v68
	v_cvt_pk_f32_fp8_sdwa v[98:99], v64 src0_sel:WORD_1
	v_cvt_pk_f32_fp8_sdwa v[102:103], v68 src0_sel:WORD_1
	v_pk_mul_f32 v[104:105], v[32:33], v[96:97]
	v_pk_mul_f32 v[106:107], v[32:33], v[100:101]
	v_pk_fma_f32 v[104:105], v[34:35], v[98:99], v[104:105]
	v_pk_fma_f32 v[106:107], v[34:35], v[102:103], v[106:107]
	v_cvt_pk_f32_fp8_e32 v[96:97], v65
	v_cvt_pk_f32_fp8_e32 v[100:101], v69
	v_cvt_pk_f32_fp8_sdwa v[98:99], v65 src0_sel:WORD_1
	v_cvt_pk_f32_fp8_sdwa v[102:103], v69 src0_sel:WORD_1
	v_pk_fma_f32 v[104:105], v[36:37], v[96:97], v[104:105]
	v_pk_fma_f32 v[106:107], v[36:37], v[100:101], v[106:107]
	v_pk_fma_f32 v[104:105], v[38:39], v[98:99], v[104:105]
	v_pk_fma_f32 v[106:107], v[38:39], v[102:103], v[106:107]
	v_cvt_pk_f32_fp8_e32 v[96:97], v66
	v_cvt_pk_f32_fp8_e32 v[100:101], v70
	v_cvt_pk_f32_fp8_sdwa v[98:99], v66 src0_sel:WORD_1
	v_cvt_pk_f32_fp8_sdwa v[102:103], v70 src0_sel:WORD_1
	v_pk_fma_f32 v[104:105], v[40:41], v[96:97], v[104:105]
	v_pk_fma_f32 v[106:107], v[40:41], v[100:101], v[106:107]
	v_pk_fma_f32 v[104:105], v[42:43], v[98:99], v[104:105]
	v_pk_fma_f32 v[106:107], v[42:43], v[102:103], v[106:107]
	v_cvt_pk_f32_fp8_e32 v[96:97], v67
	v_cvt_pk_f32_fp8_e32 v[100:101], v71
	v_cvt_pk_f32_fp8_sdwa v[98:99], v67 src0_sel:WORD_1
	v_cvt_pk_f32_fp8_sdwa v[102:103], v71 src0_sel:WORD_1
	global_load_dwordx4 v[64:67], v134, s[80:81]
	global_load_dwordx4 v[68:71], v135, s[80:81]
	v_pk_fma_f32 v[104:105], v[44:45], v[96:97], v[104:105]
	v_pk_fma_f32 v[106:107], v[44:45], v[100:101], v[106:107]
	v_pk_fma_f32 v[104:105], v[46:47], v[98:99], v[104:105]
	v_pk_fma_f32 v[106:107], v[46:47], v[102:103], v[106:107]
	s_nop 0
	v_add_f32_e32 v108, v104, v105
	v_add_f32_e32 v109, v106, v107
	s_waitcnt vmcnt(6)
	v_cvt_pk_f32_fp8_e32 v[96:97], v72
	v_cvt_pk_f32_fp8_e32 v[100:101], v76
	v_cvt_pk_f32_fp8_sdwa v[98:99], v72 src0_sel:WORD_1
	v_cvt_pk_f32_fp8_sdwa v[102:103], v76 src0_sel:WORD_1
	v_pk_mul_f32 v[104:105], v[32:33], v[96:97]
	v_pk_mul_f32 v[106:107], v[32:33], v[100:101]
	v_pk_fma_f32 v[104:105], v[34:35], v[98:99], v[104:105]
	v_pk_fma_f32 v[106:107], v[34:35], v[102:103], v[106:107]
	v_cvt_pk_f32_fp8_e32 v[96:97], v73
	v_cvt_pk_f32_fp8_e32 v[100:101], v77
	v_cvt_pk_f32_fp8_sdwa v[98:99], v73 src0_sel:WORD_1
	v_cvt_pk_f32_fp8_sdwa v[102:103], v77 src0_sel:WORD_1
	v_pk_fma_f32 v[104:105], v[36:37], v[96:97], v[104:105]
	v_pk_fma_f32 v[106:107], v[36:37], v[100:101], v[106:107]
	v_pk_fma_f32 v[104:105], v[38:39], v[98:99], v[104:105]
	v_pk_fma_f32 v[106:107], v[38:39], v[102:103], v[106:107]
	v_cvt_pk_f32_fp8_e32 v[96:97], v74
	v_cvt_pk_f32_fp8_e32 v[100:101], v78
	v_cvt_pk_f32_fp8_sdwa v[98:99], v74 src0_sel:WORD_1
	v_cvt_pk_f32_fp8_sdwa v[102:103], v78 src0_sel:WORD_1
	v_pk_fma_f32 v[104:105], v[40:41], v[96:97], v[104:105]
	v_pk_fma_f32 v[106:107], v[40:41], v[100:101], v[106:107]
	v_pk_fma_f32 v[104:105], v[42:43], v[98:99], v[104:105]
	v_pk_fma_f32 v[106:107], v[42:43], v[102:103], v[106:107]
	v_cvt_pk_f32_fp8_e32 v[96:97], v75
	v_cvt_pk_f32_fp8_e32 v[100:101], v79
	v_cvt_pk_f32_fp8_sdwa v[98:99], v75 src0_sel:WORD_1
	v_cvt_pk_f32_fp8_sdwa v[102:103], v79 src0_sel:WORD_1
	global_load_dwordx4 v[72:75], v136, s[80:81]
	global_load_dwordx4 v[76:79], v137, s[80:81]
	v_pk_fma_f32 v[104:105], v[44:45], v[96:97], v[104:105]
	v_pk_fma_f32 v[106:107], v[44:45], v[100:101], v[106:107]
	v_pk_fma_f32 v[104:105], v[46:47], v[98:99], v[104:105]
	v_pk_fma_f32 v[106:107], v[46:47], v[102:103], v[106:107]
	s_nop 0
	v_add_f32_e32 v110, v104, v105
	v_add_f32_e32 v111, v106, v107
	s_waitcnt vmcnt(6)
	v_cvt_pk_f32_fp8_e32 v[96:97], v80
	v_cvt_pk_f32_fp8_e32 v[100:101], v84
	v_cvt_pk_f32_fp8_sdwa v[98:99], v80 src0_sel:WORD_1
	v_cvt_pk_f32_fp8_sdwa v[102:103], v84 src0_sel:WORD_1
	v_pk_mul_f32 v[104:105], v[32:33], v[96:97]
	v_pk_mul_f32 v[106:107], v[32:33], v[100:101]
	v_pk_fma_f32 v[104:105], v[34:35], v[98:99], v[104:105]
	v_pk_fma_f32 v[106:107], v[34:35], v[102:103], v[106:107]
	v_cvt_pk_f32_fp8_e32 v[96:97], v81
	v_cvt_pk_f32_fp8_e32 v[100:101], v85
	v_cvt_pk_f32_fp8_sdwa v[98:99], v81 src0_sel:WORD_1
	v_cvt_pk_f32_fp8_sdwa v[102:103], v85 src0_sel:WORD_1
	v_pk_fma_f32 v[104:105], v[36:37], v[96:97], v[104:105]
	v_pk_fma_f32 v[106:107], v[36:37], v[100:101], v[106:107]
	v_pk_fma_f32 v[104:105], v[38:39], v[98:99], v[104:105]
	v_pk_fma_f32 v[106:107], v[38:39], v[102:103], v[106:107]
	v_cvt_pk_f32_fp8_e32 v[96:97], v82
	v_cvt_pk_f32_fp8_e32 v[100:101], v86
	v_cvt_pk_f32_fp8_sdwa v[98:99], v82 src0_sel:WORD_1
	v_cvt_pk_f32_fp8_sdwa v[102:103], v86 src0_sel:WORD_1
	v_pk_fma_f32 v[104:105], v[40:41], v[96:97], v[104:105]
	v_pk_fma_f32 v[106:107], v[40:41], v[100:101], v[106:107]
	v_pk_fma_f32 v[104:105], v[42:43], v[98:99], v[104:105]
	v_pk_fma_f32 v[106:107], v[42:43], v[102:103], v[106:107]
	v_cvt_pk_f32_fp8_e32 v[96:97], v83
	v_cvt_pk_f32_fp8_e32 v[100:101], v87
	v_cvt_pk_f32_fp8_sdwa v[98:99], v83 src0_sel:WORD_1
	v_cvt_pk_f32_fp8_sdwa v[102:103], v87 src0_sel:WORD_1
	global_load_dwordx4 v[80:83], v138, s[80:81]
	global_load_dwordx4 v[84:87], v139, s[80:81]
	v_pk_fma_f32 v[104:105], v[44:45], v[96:97], v[104:105]
	v_pk_fma_f32 v[106:107], v[44:45], v[100:101], v[106:107]
	v_pk_fma_f32 v[104:105], v[46:47], v[98:99], v[104:105]
	v_pk_fma_f32 v[106:107], v[46:47], v[102:103], v[106:107]
	s_nop 0
	v_add_f32_e32 v112, v104, v105
	v_add_f32_e32 v113, v106, v107
	s_waitcnt vmcnt(6)
; #define PG_ISSUE(BUF, TAB, e0_) do { const int isrc_ = ((e0_) < 64) ? myi0 : myi1; \
;       _Pragma("unroll") for (int e = 0; e < 8; ++e) { const int idx_ = __builtin_amdgcn_readlane(isrc_, ((e0_) + e) & 63); \
;         BUF[e] = *(const u32x4*)((TAB) + (size_t)idx_ * 1024 + lane * 16); } } while (0)
; DEV void peer_gather(const Params& P, int l, int m0, const int* idxs, const float* gs) {
;     ...
;     PG_ISSUE(b0, U, 0);
; #pragma nounroll
;     for (int e0 = 0; e0 < 128; e0 += 16) {
;       PG_ISSUE(b1, U, e0 + 8);
;       PG_U8(b0, 0, e0);
;       if (e0 + 16 < 128) PG_ISSUE(b0, U, e0 + 16); else PG_ISSUE(b0, V, 0);
;       PG_U8(b1, 0, e0 + 8);
;     }
	v_cvt_pk_f32_fp8_e32 v[96:97], v88
	v_cvt_pk_f32_fp8_e32 v[100:101], v92
	v_cvt_pk_f32_fp8_sdwa v[98:99], v88 src0_sel:WORD_1
	v_cvt_pk_f32_fp8_sdwa v[102:103], v92 src0_sel:WORD_1
	v_pk_mul_f32 v[104:105], v[32:33], v[96:97]
	v_pk_mul_f32 v[106:107], v[32:33], v[100:101]
	v_pk_fma_f32 v[104:105], v[34:35], v[98:99], v[104:105]
	v_pk_fma_f32 v[106:107], v[34:35], v[102:103], v[106:107]
	v_cvt_pk_f32_fp8_e32 v[96:97], v89
	v_cvt_pk_f32_fp8_e32 v[100:101], v93
	v_cvt_pk_f32_fp8_sdwa v[98:99], v89 src0_sel:WORD_1
	v_cvt_pk_f32_fp8_sdwa v[102:103], v93 src0_sel:WORD_1
	v_pk_fma_f32 v[104:105], v[36:37], v[96:97], v[104:105]
	v_pk_fma_f32 v[106:107], v[36:37], v[100:101], v[106:107]
	v_pk_fma_f32 v[104:105], v[38:39], v[98:99], v[104:105]
	v_pk_fma_f32 v[106:107], v[38:39], v[102:103], v[106:107]
	v_cvt_pk_f32_fp8_e32 v[96:97], v90
	v_cvt_pk_f32_fp8_e32 v[100:101], v94
	v_cvt_pk_f32_fp8_sdwa v[98:99], v90 src0_sel:WORD_1
	v_cvt_pk_f32_fp8_sdwa v[102:103], v94 src0_sel:WORD_1
	v_pk_fma_f32 v[104:105], v[40:41], v[96:97], v[104:105]
	v_pk_fma_f32 v[106:107], v[40:41], v[100:101], v[106:107]
	v_pk_fma_f32 v[104:105], v[42:43], v[98:99], v[104:105]
	v_pk_fma_f32 v[106:107], v[42:43], v[102:103], v[106:107]
	v_cvt_pk_f32_fp8_e32 v[96:97], v91
	v_cvt_pk_f32_fp8_e32 v[100:101], v95
	v_cvt_pk_f32_fp8_sdwa v[98:99], v91 src0_sel:WORD_1
	v_cvt_pk_f32_fp8_sdwa v[102:103], v95 src0_sel:WORD_1
	global_load_dwordx4 v[88:91], v140, s[80:81]
	global_load_dwordx4 v[92:95], v141, s[80:81]
	v_pk_fma_f32 v[104:105], v[44:45], v[96:97], v[104:105]
	v_pk_fma_f32 v[106:107], v[44:45], v[100:101], v[106:107]
	v_pk_fma_f32 v[104:105], v[46:47], v[98:99], v[104:105]
	v_pk_fma_f32 v[106:107], v[46:47], v[102:103], v[106:107]
	s_nop 0
	v_add_f32_e32 v114, v104, v105
	v_add_f32_e32 v115, v106, v107
	s_nop 1
	v_permlane32_swap_b32_e32 v108, v109
	v_permlane32_swap_b32_e32 v110, v111
	v_permlane32_swap_b32_e32 v112, v113
	v_permlane32_swap_b32_e32 v114, v115
	v_add_f32_e32 v108, v108, v109
	v_add_f32_e32 v110, v110, v111
	v_add_f32_e32 v112, v112, v113
	v_add_f32_e32 v114, v114, v115
	s_nop 1
	v_permlane16_swap_b32_e32 v108, v110
	v_permlane16_swap_b32_e32 v112, v114
	v_add_f32_e32 v108, v108, v110
	v_add_f32_e32 v112, v112, v114
	s_mov_b32 s88, 0xff00ff00
	s_mov_b32 s89, 0xff00ff00
	s_nop 0
	v_cndmask_b32_e64 v109, v108, v112, s[88:89]
	v_cndmask_b32_e64 v111, v112, v108, s[88:89]
	s_nop 1
	v_add_f32_dpp v109, v111, v109 row_ror:8 row_mask:0xf bank_mask:0xf
	s_nop 1
	v_add_f32_dpp v109, v109, v109 quad_perm:[1,0,3,2] row_mask:0xf bank_mask:0xf
	s_nop 1
	v_add_f32_dpp v109, v109, v109 quad_perm:[2,3,0,1] row_mask:0xf bank_mask:0xf
	s_nop 1
	v_add_f32_dpp v109, v109, v109 row_half_mirror row_mask:0xf bank_mask:0xf
	s_nop 0
	ds_bpermute_b32 v110, v251, v109
	s_waitcnt lgkmcnt(0)
	v_cndmask_b32_e64 v245, v245, v110, s[84:85]
	v_cndmask_b32_e64 v246, v246, v110, s[86:87]
	s_add_u32 s98, s100, 1
	s_min_u32 s98, s98, 15
	s_cmp_ge_u32 s98, 8
	s_cselect_b64 s[88:89], -1, 0
	s_lshl_b32 s99, s98, 3
	s_and_b32 s99, s99, 63
	s_mov_b32 vcc_lo, s99
	v_cndmask_b32_e64 v153, v142, v143, s[88:89]
	s_nop 0
	s_add_u32 s98, vcc_lo, 0
	v_readlane_b32 s98, v153, s98
	s_add_u32 s99, vcc_lo, 1
	v_readlane_b32 s99, v153, s99
	s_add_u32 s92, vcc_lo, 2
	v_readlane_b32 s92, v153, s92
	s_add_u32 s93, vcc_lo, 3
	v_readlane_b32 s93, v153, s93
	v_lshl_add_u32 v134, s98, 10, v250
	v_lshl_add_u32 v135, s99, 10, v250
	v_lshl_add_u32 v136, s92, 10, v250
	v_lshl_add_u32 v137, s93, 10, v250
	s_add_u32 s98, vcc_lo, 4
	v_readlane_b32 s98, v153, s98
	s_add_u32 s99, vcc_lo, 5
	v_readlane_b32 s99, v153, s99
	s_add_u32 s92, vcc_lo, 6
	v_readlane_b32 s92, v153, s92
	s_add_u32 s93, vcc_lo, 7
	v_readlane_b32 s93, v153, s93
	v_lshl_add_u32 v138, s98, 10, v250
	v_lshl_add_u32 v139, s99, 10, v250
	v_lshl_add_u32 v140, s92, 10, v250
	v_lshl_add_u32 v141, s93, 10, v250
	s_waitcnt vmcnt(6)
	v_cvt_pk_f32_fp8_e32 v[96:97], v64
	v_cvt_pk_f32_fp8_e32 v[100:101], v68
	v_cvt_pk_f32_fp8_sdwa v[98:99], v64 src0_sel:WORD_1
	v_cvt_pk_f32_fp8_sdwa v[102:103], v68 src0_sel:WORD_1
	v_pk_mul_f32 v[104:105], v[48:49], v[96:97]
	v_pk_mul_f32 v[106:107], v[48:49], v[100:101]
	v_pk_fma_f32 v[104:105], v[50:51], v[98:99], v[104:105]
	v_pk_fma_f32 v[106:107], v[50:51], v[102:103], v[106:107]
	v_cvt_pk_f32_fp8_e32 v[96:97], v65
	v_cvt_pk_f32_fp8_e32 v[100:101], v69
	v_cvt_pk_f32_fp8_sdwa v[98:99], v65 src0_sel:WORD_1
	v_cvt_pk_f32_fp8_sdwa v[102:103], v69 src0_sel:WORD_1
	v_pk_fma_f32 v[104:105], v[52:53], v[96:97], v[104:105]
	v_pk_fma_f32 v[106:107], v[52:53], v[100:101], v[106:107]
	v_pk_fma_f32 v[104:105], v[54:55], v[98:99], v[104:105]
	v_pk_fma_f32 v[106:107], v[54:55], v[102:103], v[106:107]
	v_cvt_pk_f32_fp8_e32 v[96:97], v66
	v_cvt_pk_f32_fp8_e32 v[100:101], v70
	v_cvt_pk_f32_fp8_sdwa v[98:99], v66 src0_sel:WORD_1
	v_cvt_pk_f32_fp8_sdwa v[102:103], v70 src0_sel:WORD_1
	v_pk_fma_f32 v[104:105], v[56:57], v[96:97], v[104:105]
	v_pk_fma_f32 v[106:107], v[56:57], v[100:101], v[106:107]
	v_pk_fma_f32 v[104:105], v[58:59], v[98:99], v[104:105]
	v_pk_fma_f32 v[106:107], v[58:59], v[102:103], v[106:107]
	v_cvt_pk_f32_fp8_e32 v[96:97], v67
	v_cvt_pk_f32_fp8_e32 v[100:101], v71
	v_cvt_pk_f32_fp8_sdwa v[98:99], v67 src0_sel:WORD_1
	v_cvt_pk_f32_fp8_sdwa v[102:103], v71 src0_sel:WORD_1
	global_load_dwordx4 v[64:67], v134, s[80:81]
	global_load_dwordx4 v[68:71], v135, s[80:81]
	v_pk_fma_f32 v[104:105], v[60:61], v[96:97], v[104:105]
	v_pk_fma_f32 v[106:107], v[60:61], v[100:101], v[106:107]
	v_pk_fma_f32 v[104:105], v[62:63], v[98:99], v[104:105]
	v_pk_fma_f32 v[106:107], v[62:63], v[102:103], v[106:107]
	s_nop 0
	v_add_f32_e32 v108, v104, v105
	v_add_f32_e32 v109, v106, v107
	s_waitcnt vmcnt(6)
; #define PG_ISSUE(BUF, TAB, e0_) do { const int isrc_ = ((e0_) < 64) ? myi0 : myi1; \
;       _Pragma("unroll") for (int e = 0; e < 8; ++e) { const int idx_ = __builtin_amdgcn_readlane(isrc_, ((e0_) + e) & 63); \
;         BUF[e] = *(const u32x4*)((TAB) + (size_t)idx_ * 1024 + lane * 16); } } while (0)
; DEV void peer_gather(const Params& P, int l, int m0, const int* idxs, const float* gs) {
;     ...
;     PG_ISSUE(b0, U, 0);
; #pragma nounroll
;     for (int e0 = 0; e0 < 128; e0 += 16) {
;       PG_ISSUE(b1, U, e0 + 8);
;       PG_U8(b0, 0, e0);
;       if (e0 + 16 < 128) PG_ISSUE(b0, U, e0 + 16); else PG_ISSUE(b0, V, 0);
;       PG_U8(b1, 0, e0 + 8);
;     }
	v_cvt_pk_f32_fp8_e32 v[96:97], v72
	v_cvt_pk_f32_fp8_e32 v[100:101], v76
	v_cvt_pk_f32_fp8_sdwa v[98:99], v72 src0_sel:WORD_1
	v_cvt_pk_f32_fp8_sdwa v[102:103], v76 src0_sel:WORD_1
	v_pk_mul_f32 v[104:105], v[48:49], v[96:97]
	v_pk_mul_f32 v[106:107], v[48:49], v[100:101]
	v_pk_fma_f32 v[104:105], v[50:51], v[98:99], v[104:105]
	v_pk_fma_f32 v[106:107], v[50:51], v[102:103], v[106:107]
	v_cvt_pk_f32_fp8_e32 v[96:97], v73
	v_cvt_pk_f32_fp8_e32 v[100:101], v77
	v_cvt_pk_f32_fp8_sdwa v[98:99], v73 src0_sel:WORD_1
	v_cvt_pk_f32_fp8_sdwa v[102:103], v77 src0_sel:WORD_1
	v_pk_fma_f32 v[104:105], v[52:53], v[96:97], v[104:105]
	v_pk_fma_f32 v[106:107], v[52:53], v[100:101], v[106:107]
	v_pk_fma_f32 v[104:105], v[54:55], v[98:99], v[104:105]
	v_pk_fma_f32 v[106:107], v[54:55], v[102:103], v[106:107]
	v_cvt_pk_f32_fp8_e32 v[96:97], v74
	v_cvt_pk_f32_fp8_e32 v[100:101], v78
	v_cvt_pk_f32_fp8_sdwa v[98:99], v74 src0_sel:WORD_1
	v_cvt_pk_f32_fp8_sdwa v[102:103], v78 src0_sel:WORD_1
	v_pk_fma_f32 v[104:105], v[56:57], v[96:97], v[104:105]
	v_pk_fma_f32 v[106:107], v[56:57], v[100:101], v[106:107]
	v_pk_fma_f32 v[104:105], v[58:59], v[98:99], v[104:105]
	v_pk_fma_f32 v[106:107], v[58:59], v[102:103], v[106:107]
	v_cvt_pk_f32_fp8_e32 v[96:97], v75
	v_cvt_pk_f32_fp8_e32 v[100:101], v79
	v_cvt_pk_f32_fp8_sdwa v[98:99], v75 src0_sel:WORD_1
	v_cvt_pk_f32_fp8_sdwa v[102:103], v79 src0_sel:WORD_1
	global_load_dwordx4 v[72:75], v136, s[80:81]
	global_load_dwordx4 v[76:79], v137, s[80:81]
	v_pk_fma_f32 v[104:105], v[60:61], v[96:97], v[104:105]
	v_pk_fma_f32 v[106:107], v[60:61], v[100:101], v[106:107]
	v_pk_fma_f32 v[104:105], v[62:63], v[98:99], v[104:105]
	v_pk_fma_f32 v[106:107], v[62:63], v[102:103], v[106:107]
	s_nop 0
	v_add_f32_e32 v110, v104, v105
	v_add_f32_e32 v111, v106, v107
	s_waitcnt vmcnt(6)
	v_cvt_pk_f32_fp8_e32 v[96:97], v80
	v_cvt_pk_f32_fp8_e32 v[100:101], v84
	v_cvt_pk_f32_fp8_sdwa v[98:99], v80 src0_sel:WORD_1
	v_cvt_pk_f32_fp8_sdwa v[102:103], v84 src0_sel:WORD_1
	v_pk_mul_f32 v[104:105], v[48:49], v[96:97]
	v_pk_mul_f32 v[106:107], v[48:49], v[100:101]
	v_pk_fma_f32 v[104:105], v[50:51], v[98:99], v[104:105]
	v_pk_fma_f32 v[106:107], v[50:51], v[102:103], v[106:107]
	v_cvt_pk_f32_fp8_e32 v[96:97], v81
	v_cvt_pk_f32_fp8_e32 v[100:101], v85
	v_cvt_pk_f32_fp8_sdwa v[98:99], v81 src0_sel:WORD_1
	v_cvt_pk_f32_fp8_sdwa v[102:103], v85 src0_sel:WORD_1
	v_pk_fma_f32 v[104:105], v[52:53], v[96:97], v[104:105]
	v_pk_fma_f32 v[106:107], v[52:53], v[100:101], v[106:107]
	v_pk_fma_f32 v[104:105], v[54:55], v[98:99], v[104:105]
	v_pk_fma_f32 v[106:107], v[54:55], v[102:103], v[106:107]
	v_cvt_pk_f32_fp8_e32 v[96:97], v82
	v_cvt_pk_f32_fp8_e32 v[100:101], v86
	v_cvt_pk_f32_fp8_sdwa v[98:99], v82 src0_sel:WORD_1
	v_cvt_pk_f32_fp8_sdwa v[102:103], v86 src0_sel:WORD_1
	v_pk_fma_f32 v[104:105], v[56:57], v[96:97], v[104:105]
	v_pk_fma_f32 v[106:107], v[56:57], v[100:101], v[106:107]
	v_pk_fma_f32 v[104:105], v[58:59], v[98:99], v[104:105]
	v_pk_fma_f32 v[106:107], v[58:59], v[102:103], v[106:107]
	v_cvt_pk_f32_fp8_e32 v[96:97], v83
	v_cvt_pk_f32_fp8_e32 v[100:101], v87
	v_cvt_pk_f32_fp8_sdwa v[98:99], v83 src0_sel:WORD_1
	v_cvt_pk_f32_fp8_sdwa v[102:103], v87 src0_sel:WORD_1
	global_load_dwordx4 v[80:83], v138, s[80:81]
	global_load_dwordx4 v[84:87], v139, s[80:81]
	v_pk_fma_f32 v[104:105], v[60:61], v[96:97], v[104:105]
	v_pk_fma_f32 v[106:107], v[60:61], v[100:101], v[106:107]
	v_pk_fma_f32 v[104:105], v[62:63], v[98:99], v[104:105]
	v_pk_fma_f32 v[106:107], v[62:63], v[102:103], v[106:107]
	s_nop 0
	v_add_f32_e32 v112, v104, v105
	v_add_f32_e32 v113, v106, v107
	s_waitcnt vmcnt(6)
	v_cvt_pk_f32_fp8_e32 v[96:97], v88
	v_cvt_pk_f32_fp8_e32 v[100:101], v92
	v_cvt_pk_f32_fp8_sdwa v[98:99], v88 src0_sel:WORD_1
	v_cvt_pk_f32_fp8_sdwa v[102:103], v92 src0_sel:WORD_1
	v_pk_mul_f32 v[104:105], v[48:49], v[96:97]
	v_pk_mul_f32 v[106:107], v[48:49], v[100:101]
	v_pk_fma_f32 v[104:105], v[50:51], v[98:99], v[104:105]
	v_pk_fma_f32 v[106:107], v[50:51], v[102:103], v[106:107]
	v_cvt_pk_f32_fp8_e32 v[96:97], v89
	v_cvt_pk_f32_fp8_e32 v[100:101], v93
	v_cvt_pk_f32_fp8_sdwa v[98:99], v89 src0_sel:WORD_1
	v_cvt_pk_f32_fp8_sdwa v[102:103], v93 src0_sel:WORD_1
	v_pk_fma_f32 v[104:105], v[52:53], v[96:97], v[104:105]
	v_pk_fma_f32 v[106:107], v[52:53], v[100:101], v[106:107]
	v_pk_fma_f32 v[104:105], v[54:55], v[98:99], v[104:105]
	v_pk_fma_f32 v[106:107], v[54:55], v[102:103], v[106:107]
	v_cvt_pk_f32_fp8_e32 v[96:97], v90
	v_cvt_pk_f32_fp8_e32 v[100:101], v94
	v_cvt_pk_f32_fp8_sdwa v[98:99], v90 src0_sel:WORD_1
	v_cvt_pk_f32_fp8_sdwa v[102:103], v94 src0_sel:WORD_1
	v_pk_fma_f32 v[104:105], v[56:57], v[96:97], v[104:105]
	v_pk_fma_f32 v[106:107], v[56:57], v[100:101], v[106:107]
	v_pk_fma_f32 v[104:105], v[58:59], v[98:99], v[104:105]
	v_pk_fma_f32 v[106:107], v[58:59], v[102:103], v[106:107]
	v_cvt_pk_f32_fp8_e32 v[96:97], v91
	v_cvt_pk_f32_fp8_e32 v[100:101], v95
	v_cvt_pk_f32_fp8_sdwa v[98:99], v91 src0_sel:WORD_1
	v_cvt_pk_f32_fp8_sdwa v[102:103], v95 src0_sel:WORD_1
	global_load_dwordx4 v[88:91], v140, s[80:81]
	global_load_dwordx4 v[92:95], v141, s[80:81]
	v_pk_fma_f32 v[104:105], v[60:61], v[96:97], v[104:105]
	v_pk_fma_f32 v[106:107], v[60:61], v[100:101], v[106:107]
	v_pk_fma_f32 v[104:105], v[62:63], v[98:99], v[104:105]
	v_pk_fma_f32 v[106:107], v[62:63], v[102:103], v[106:107]
	s_nop 0
	v_add_f32_e32 v114, v104, v105
	v_add_f32_e32 v115, v106, v107
	s_nop 1
	v_permlane32_swap_b32_e32 v108, v109
	v_permlane32_swap_b32_e32 v110, v111
	v_permlane32_swap_b32_e32 v112, v113
	v_permlane32_swap_b32_e32 v114, v115
	v_add_f32_e32 v108, v108, v109
	v_add_f32_e32 v110, v110, v111
	v_add_f32_e32 v112, v112, v113
	v_add_f32_e32 v114, v114, v115
	s_nop 1
	v_permlane16_swap_b32_e32 v108, v110
	v_permlane16_swap_b32_e32 v112, v114
	v_add_f32_e32 v108, v108, v110
	v_add_f32_e32 v112, v112, v114
	s_mov_b32 s88, 0xff00ff00
	s_mov_b32 s89, 0xff00ff00
	s_nop 0
	v_cndmask_b32_e64 v109, v108, v112, s[88:89]
	v_cndmask_b32_e64 v111, v112, v108, s[88:89]
	s_nop 1
	v_add_f32_dpp v109, v111, v109 row_ror:8 row_mask:0xf bank_mask:0xf
	s_nop 1
	v_add_f32_dpp v109, v109, v109 quad_perm:[1,0,3,2] row_mask:0xf bank_mask:0xf
	s_nop 1
	v_add_f32_dpp v109, v109, v109 quad_perm:[2,3,0,1] row_mask:0xf bank_mask:0xf
	s_nop 1
	v_add_f32_dpp v109, v109, v109 row_half_mirror row_mask:0xf bank_mask:0xf
	s_nop 0
	ds_bpermute_b32 v110, v251, v109
	s_waitcnt lgkmcnt(0)
	v_cndmask_b32_e64 v247, v247, v110, s[84:85]
	v_cndmask_b32_e64 v248, v248, v110, s[86:87]
	s_add_u32 s100, s100, 1
	s_add_u32 s101, s101, 8
	s_and_b32 s101, s101, 63
	s_cmp_lt_u32 s100, 16
	s_cbranch_scc1 .Lpg0_Uloop
; #define PG_ISSUE(BUF, TAB, e0_) do { const int isrc_ = ((e0_) < 64) ? myi0 : myi1; \
;       _Pragma("unroll") for (int e = 0; e < 8; ++e) { const int idx_ = __builtin_amdgcn_readlane(isrc_, ((e0_) + e) & 63); \
;         BUF[e] = *(const u32x4*)((TAB) + (size_t)idx_ * 1024 + lane * 16); } } while (0)
; DEV void peer_gather(const Params& P, int l, int m0, const int* idxs, const float* gs) {
;     ...
;     f32x2_t acc[8];
; #pragma unroll
;     for (int q = 0; q < 8; ++q) acc[q] = (f32x2_t){0.f, 0.f};
;     float wr0 = 0.f, wr1 = 0.f;
;     u32x4 b0[8], b1[8];
;     ...
;     PG_ISSUE(b0, U, 0);
; #pragma nounroll
;     for (int e0 = 0; e0 < 128; e0 += 16) {
;       PG_ISSUE(b1, U, e0 + 8);
;       PG_U8(b0, 0, e0);
;       if (e0 + 16 < 128) PG_ISSUE(b0, U, e0 + 16); else PG_ISSUE(b0, V, 0);
	s_waitcnt vmcnt(0)
	s_waitcnt vmcnt(0)
	v_mul_f32_e32 v72, 0x3c800000, v241
	v_mul_f32_e32 v73, 0x3c800000, v242
	v_mul_f32_e32 v74, 0x3c800000, v243
	v_mul_f32_e32 v75, 0x3c800000, v244
	v_mul_f32_e32 v76, 0x3c800000, v245
	v_mul_f32_e32 v77, 0x3c800000, v246
	v_mul_f32_e32 v78, 0x3c800000, v247
	v_mul_f32_e32 v79, 0x3c800000, v248
	v_mul_f32_e32 v64, 0x3d372713, v72
	v_mul_f32_e32 v65, 0x3d372713, v73
	v_mul_f32_e32 v66, 0x3d372713, v74
	v_mul_f32_e32 v67, 0x3d372713, v75
	v_mul_f32_e32 v68, 0x3d372713, v76
	v_mul_f32_e32 v69, 0x3d372713, v77
	v_mul_f32_e32 v70, 0x3d372713, v78
	v_mul_f32_e32 v71, 0x3d372713, v79
	v_mul_f32_e32 v64, v72, v64
	v_mul_f32_e32 v65, v73, v65
	v_mul_f32_e32 v66, v74, v66
	v_mul_f32_e32 v67, v75, v67
	v_mul_f32_e32 v68, v76, v68
	v_mul_f32_e32 v69, v77, v69
	v_mul_f32_e32 v70, v78, v70
	v_mul_f32_e32 v71, v79, v71
	v_fma_f32 v64, v72, v64, v72
	v_fma_f32 v65, v73, v65, v73
	v_fma_f32 v66, v74, v66, v74
	v_fma_f32 v67, v75, v67, v75
	v_fma_f32 v68, v76, v68, v76
	v_fma_f32 v69, v77, v69, v77
	v_fma_f32 v70, v78, v70, v78
	v_fma_f32 v71, v79, v71, v79
	v_mul_f32_e32 v64, 0xbfcc422a, v64
	v_mul_f32_e32 v65, 0xbfcc422a, v65
	v_mul_f32_e32 v66, 0xbfcc422a, v66
	v_mul_f32_e32 v67, 0xbfcc422a, v67
	v_mul_f32_e32 v68, 0xbfcc422a, v68
	v_mul_f32_e32 v69, 0xbfcc422a, v69
	v_mul_f32_e32 v70, 0xbfcc422a, v70
	v_mul_f32_e32 v71, 0xbfcc422a, v71
	v_mul_f32_e32 v64, 0x3fb8aa3b, v64
	v_mul_f32_e32 v65, 0x3fb8aa3b, v65
	v_mul_f32_e32 v66, 0x3fb8aa3b, v66
	v_mul_f32_e32 v67, 0x3fb8aa3b, v67
	v_mul_f32_e32 v68, 0x3fb8aa3b, v68
	v_mul_f32_e32 v69, 0x3fb8aa3b, v69
	v_mul_f32_e32 v70, 0x3fb8aa3b, v70
	v_mul_f32_e32 v71, 0x3fb8aa3b, v71
	v_exp_f32_e32 v64, v64
	v_exp_f32_e32 v65, v65
	v_exp_f32_e32 v66, v66
	v_exp_f32_e32 v67, v67
	v_exp_f32_e32 v68, v68
	v_exp_f32_e32 v69, v69
	v_exp_f32_e32 v70, v70
	v_exp_f32_e32 v71, v71
	s_nop 0
	v_add_f32_e32 v64, 1.0, v64
	v_add_f32_e32 v65, 1.0, v65
	v_add_f32_e32 v66, 1.0, v66
	v_add_f32_e32 v67, 1.0, v67
	v_add_f32_e32 v68, 1.0, v68
	v_add_f32_e32 v69, 1.0, v69
	v_add_f32_e32 v70, 1.0, v70
	v_add_f32_e32 v71, 1.0, v71
	v_rcp_f32_e32 v64, v64
	v_rcp_f32_e32 v65, v65
	v_rcp_f32_e32 v66, v66
	v_rcp_f32_e32 v67, v67
	v_rcp_f32_e32 v68, v68
	v_rcp_f32_e32 v69, v69
	v_rcp_f32_e32 v70, v70
	v_rcp_f32_e32 v71, v71
	s_nop 0
	v_mul_f32_e32 v64, v72, v64
	v_mul_f32_e32 v65, v73, v65
	v_mul_f32_e32 v66, v74, v66
	v_mul_f32_e32 v67, v75, v67
	v_mul_f32_e32 v68, v76, v68
	v_mul_f32_e32 v69, v77, v69
	v_mul_f32_e32 v70, v78, v70
	v_mul_f32_e32 v71, v79, v71
	v_mul_f32_e32 v241, v64, v233
	v_mul_f32_e32 v242, v65, v234
	v_mul_f32_e32 v243, v66, v235
	v_mul_f32_e32 v244, v67, v236
	v_mul_f32_e32 v245, v68, v237
	v_mul_f32_e32 v246, v69, v238
	v_mul_f32_e32 v247, v70, v239
	v_mul_f32_e32 v248, v71, v240
	v_readfirstlane_b32 s80, v126
	v_readfirstlane_b32 s81, v127
	s_nop 4
	v_mov_b32_e32 v0, 0
	v_mov_b32_e32 v1, 0
	v_mov_b32_e32 v2, 0
	v_mov_b32_e32 v3, 0
	v_mov_b32_e32 v4, 0
	v_mov_b32_e32 v5, 0
	v_mov_b32_e32 v6, 0
	v_mov_b32_e32 v7, 0
	v_mov_b32_e32 v8, 0
	v_mov_b32_e32 v9, 0
	v_mov_b32_e32 v10, 0
	v_mov_b32_e32 v11, 0
	v_mov_b32_e32 v12, 0
	v_mov_b32_e32 v13, 0
	v_mov_b32_e32 v14, 0
	v_mov_b32_e32 v15, 0
	v_mov_b32_e32 v16, 0
	v_mov_b32_e32 v17, 0
	v_mov_b32_e32 v18, 0
	v_mov_b32_e32 v19, 0
	v_mov_b32_e32 v20, 0
	v_mov_b32_e32 v21, 0
	v_mov_b32_e32 v22, 0
	v_mov_b32_e32 v23, 0
	v_mov_b32_e32 v24, 0
	v_mov_b32_e32 v25, 0
	v_mov_b32_e32 v26, 0
	v_mov_b32_e32 v27, 0
	v_mov_b32_e32 v28, 0
	v_mov_b32_e32 v29, 0
	v_mov_b32_e32 v30, 0
	v_mov_b32_e32 v31, 0
	v_mov_b32_e32 v32, 0
	v_mov_b32_e32 v33, 0
	v_mov_b32_e32 v34, 0
	v_mov_b32_e32 v35, 0
	v_mov_b32_e32 v36, 0
	v_mov_b32_e32 v37, 0
	v_mov_b32_e32 v38, 0
	v_mov_b32_e32 v39, 0
	v_mov_b32_e32 v40, 0
	v_mov_b32_e32 v41, 0
	v_mov_b32_e32 v42, 0
	v_mov_b32_e32 v43, 0
	v_mov_b32_e32 v44, 0
	v_mov_b32_e32 v45, 0
	v_mov_b32_e32 v46, 0
	v_mov_b32_e32 v47, 0
	v_mov_b32_e32 v48, 0
	v_mov_b32_e32 v49, 0
	v_mov_b32_e32 v50, 0
	v_mov_b32_e32 v51, 0
	v_mov_b32_e32 v52, 0
	v_mov_b32_e32 v53, 0
	v_mov_b32_e32 v54, 0
	v_mov_b32_e32 v55, 0
	v_mov_b32_e32 v56, 0
	v_mov_b32_e32 v57, 0
	v_mov_b32_e32 v58, 0
	v_mov_b32_e32 v59, 0
	v_mov_b32_e32 v60, 0
	v_mov_b32_e32 v61, 0
	v_mov_b32_e32 v62, 0
	v_mov_b32_e32 v63, 0
	s_mov_b32 s100, 0
	s_mov_b32 s101, 0
	s_mov_b64 s[90:91], 0
	v_cndmask_b32_e64 v153, v142, v143, s[90:91]
	s_nop 0
	s_add_u32 s98, s101, 0
	v_readlane_b32 s98, v153, s98
	s_add_u32 s99, s101, 1
	v_readlane_b32 s99, v153, s99
	s_add_u32 s92, s101, 2
	v_readlane_b32 s92, v153, s92
	s_add_u32 s93, s101, 3
	v_readlane_b32 s93, v153, s93
	v_lshl_add_u32 v134, s98, 10, v250
	v_lshl_add_u32 v135, s99, 10, v250
	v_lshl_add_u32 v136, s92, 10, v250
	v_lshl_add_u32 v137, s93, 10, v250
	s_add_u32 s98, s101, 4
	v_readlane_b32 s98, v153, s98
	s_add_u32 s99, s101, 5
	v_readlane_b32 s99, v153, s99
	s_add_u32 s92, s101, 6
	v_readlane_b32 s92, v153, s92
	s_add_u32 s93, s101, 7
	v_readlane_b32 s93, v153, s93
	v_lshl_add_u32 v138, s98, 10, v250
	v_lshl_add_u32 v139, s99, 10, v250
	v_lshl_add_u32 v140, s92, 10, v250
	v_lshl_add_u32 v141, s93, 10, v250
	global_load_dwordx4 v[64:67], v134, s[80:81]
	global_load_dwordx4 v[68:71], v135, s[80:81]
	global_load_dwordx4 v[72:75], v136, s[80:81]
	global_load_dwordx4 v[76:79], v137, s[80:81]
	global_load_dwordx4 v[80:83], v138, s[80:81]
	global_load_dwordx4 v[84:87], v139, s[80:81]
	global_load_dwordx4 v[88:91], v140, s[80:81]
	global_load_dwordx4 v[92:95], v141, s[80:81]
; #define PG_ISSUE(BUF, TAB, e0_) do { const int isrc_ = ((e0_) < 64) ? myi0 : myi1; \
;       _Pragma("unroll") for (int e = 0; e < 8; ++e) { const int idx_ = __builtin_amdgcn_readlane(isrc_, ((e0_) + e) & 63); \
;         BUF[e] = *(const u32x4*)((TAB) + (size_t)idx_ * 1024 + lane * 16); } } while (0)
; DEV void peer_gather(const Params& P, int l, int m0, const int* idxs, const float* gs) {
;     ...
;     PG_ISSUE(b0, U, 0);
; #pragma nounroll
;     for (int e0 = 0; e0 < 128; e0 += 16) {
;       PG_ISSUE(b1, U, e0 + 8);
;       PG_U8(b0, 0, e0);
;       if (e0 + 16 < 128) PG_ISSUE(b0, U, e0 + 16); else PG_ISSUE(b0, V, 0);
;       PG_U8(b1, 0, e0 + 8);
;     }
;     float* hrow = P.out + tok * DM + lane * 16;
;     f32x4 hv[4];
; #pragma unroll
;     for (int q = 0; q < 4; ++q) hv[q] = *(const f32x4*)(hrow + 4 * q);
;     if (i + 1 < 16) {
;       const int tn = tt + 1;
;       nxa = *(const u32x4*)(hn + (size_t)(m0 + tn) * DM + lane * 16); nxb = *(const u32x4*)(hn + (size_t)(m0 + tn) * DM + lane * 16 + 8);
;       ni0 = idxs[tn * 128 + lane]; ni1 = idxs[tn * 128 + 64 + lane]; ng0 = gs[tn * 128 + lane]; ng1 = gs[tn * 128 + 64 + lane];
;     }
; #pragma nounroll
;     for (int e0 = 0; e0 < 128; e0 += 16) {
;       PG_ISSUE(b1, V, e0 + 8);
;       if (e0 == 64 && i + 1 < 16) sort_lists(lane, ni0, ni1, ng0, ng1);
;       PG_V16(b0, e0);
;       if (e0 + 16 < 128) PG_ISSUE(b0, V, e0 + 16);
;       PG_V16(b1, e0 + 8);
;     }
.Lpg0_Vloop:
	s_cmp_ge_u32 s100, 8
	s_cselect_b64 s[90:91], -1, 0
	v_cndmask_b32_e64 v153, v144, v145, s[90:91]
	s_nop 0
	s_add_u32 s98, s101, 0
	v_readlane_b32 s98, v153, s98
	s_add_u32 s99, s101, 1
	v_readlane_b32 s99, v153, s99
	s_add_u32 s92, s101, 2
	v_readlane_b32 s92, v153, s92
	s_add_u32 s93, s101, 3
	v_readlane_b32 s93, v153, s93
	v_lshl_add_u32 v134, s98, 10, v250
	v_lshl_add_u32 v135, s99, 10, v250
	v_lshl_add_u32 v136, s92, 10, v250
	v_lshl_add_u32 v137, s93, 10, v250
	s_add_u32 s98, s101, 4
	v_readlane_b32 s98, v153, s98
	s_add_u32 s99, s101, 5
	v_readlane_b32 s99, v153, s99
	s_add_u32 s92, s101, 6
	v_readlane_b32 s92, v153, s92
	s_add_u32 s93, s101, 7
	v_readlane_b32 s93, v153, s93
	v_lshl_add_u32 v138, s98, 10, v250
	v_lshl_add_u32 v139, s99, 10, v250
	v_lshl_add_u32 v140, s92, 10, v250
	v_lshl_add_u32 v141, s93, 10, v250
	v_cndmask_b32_e64 v152, v241, v242, s[90:91]
	s_add_u32 s98, s101, 0
	s_add_u32 s99, s101, 1
	v_readlane_b32 s84, v152, s98
	v_readlane_b32 s86, v152, s99
	s_waitcnt vmcnt(6)
	v_cvt_pk_f32_fp8_e32 v[96:97], v64
	v_cvt_pk_f32_fp8_sdwa v[98:99], v64 src0_sel:WORD_1
	v_cvt_pk_f32_fp8_e32 v[100:101], v68
	v_cvt_pk_f32_fp8_sdwa v[102:103], v68 src0_sel:WORD_1
	v_pk_fma_f32 v[0:1], v[96:97], s[84:85], v[0:1] op_sel_hi:[1,0,1]
	v_pk_fma_f32 v[2:3], v[98:99], s[84:85], v[2:3] op_sel_hi:[1,0,1]
	v_pk_fma_f32 v[0:1], v[100:101], s[86:87], v[0:1] op_sel_hi:[1,0,1]
	v_pk_fma_f32 v[2:3], v[102:103], s[86:87], v[2:3] op_sel_hi:[1,0,1]
	v_cvt_pk_f32_fp8_e32 v[96:97], v65
	v_cvt_pk_f32_fp8_sdwa v[98:99], v65 src0_sel:WORD_1
	v_cvt_pk_f32_fp8_e32 v[100:101], v69
	v_cvt_pk_f32_fp8_sdwa v[102:103], v69 src0_sel:WORD_1
	v_pk_fma_f32 v[4:5], v[96:97], s[84:85], v[4:5] op_sel_hi:[1,0,1]
	v_pk_fma_f32 v[6:7], v[98:99], s[84:85], v[6:7] op_sel_hi:[1,0,1]
	v_pk_fma_f32 v[4:5], v[100:101], s[86:87], v[4:5] op_sel_hi:[1,0,1]
	v_pk_fma_f32 v[6:7], v[102:103], s[86:87], v[6:7] op_sel_hi:[1,0,1]
	v_cvt_pk_f32_fp8_e32 v[96:97], v66
	v_cvt_pk_f32_fp8_sdwa v[98:99], v66 src0_sel:WORD_1
	v_cvt_pk_f32_fp8_e32 v[100:101], v70
	v_cvt_pk_f32_fp8_sdwa v[102:103], v70 src0_sel:WORD_1
	v_pk_fma_f32 v[8:9], v[96:97], s[84:85], v[8:9] op_sel_hi:[1,0,1]
	v_pk_fma_f32 v[10:11], v[98:99], s[84:85], v[10:11] op_sel_hi:[1,0,1]
	v_pk_fma_f32 v[8:9], v[100:101], s[86:87], v[8:9] op_sel_hi:[1,0,1]
	v_pk_fma_f32 v[10:11], v[102:103], s[86:87], v[10:11] op_sel_hi:[1,0,1]
	v_cvt_pk_f32_fp8_e32 v[96:97], v67
	v_cvt_pk_f32_fp8_sdwa v[98:99], v67 src0_sel:WORD_1
	v_cvt_pk_f32_fp8_e32 v[100:101], v71
	v_cvt_pk_f32_fp8_sdwa v[102:103], v71 src0_sel:WORD_1
	global_load_dwordx4 v[64:67], v134, s[80:81]
	global_load_dwordx4 v[68:71], v135, s[80:81]
	v_pk_fma_f32 v[12:13], v[96:97], s[84:85], v[12:13] op_sel_hi:[1,0,1]
	v_pk_fma_f32 v[14:15], v[98:99], s[84:85], v[14:15] op_sel_hi:[1,0,1]
	v_pk_fma_f32 v[12:13], v[100:101], s[86:87], v[12:13] op_sel_hi:[1,0,1]
	v_pk_fma_f32 v[14:15], v[102:103], s[86:87], v[14:15] op_sel_hi:[1,0,1]
	s_add_u32 s98, s101, 2
	s_add_u32 s99, s101, 3
	v_readlane_b32 s84, v152, s98
	v_readlane_b32 s86, v152, s99
	s_waitcnt vmcnt(6)
	v_cvt_pk_f32_fp8_e32 v[96:97], v72
	v_cvt_pk_f32_fp8_sdwa v[98:99], v72 src0_sel:WORD_1
	v_cvt_pk_f32_fp8_e32 v[100:101], v76
	v_cvt_pk_f32_fp8_sdwa v[102:103], v76 src0_sel:WORD_1
	v_pk_fma_f32 v[0:1], v[96:97], s[84:85], v[0:1] op_sel_hi:[1,0,1]
	v_pk_fma_f32 v[2:3], v[98:99], s[84:85], v[2:3] op_sel_hi:[1,0,1]
	v_pk_fma_f32 v[0:1], v[100:101], s[86:87], v[0:1] op_sel_hi:[1,0,1]
	v_pk_fma_f32 v[2:3], v[102:103], s[86:87], v[2:3] op_sel_hi:[1,0,1]
	v_cvt_pk_f32_fp8_e32 v[96:97], v73
	v_cvt_pk_f32_fp8_sdwa v[98:99], v73 src0_sel:WORD_1
	v_cvt_pk_f32_fp8_e32 v[100:101], v77
	v_cvt_pk_f32_fp8_sdwa v[102:103], v77 src0_sel:WORD_1
	v_pk_fma_f32 v[4:5], v[96:97], s[84:85], v[4:5] op_sel_hi:[1,0,1]
	v_pk_fma_f32 v[6:7], v[98:99], s[84:85], v[6:7] op_sel_hi:[1,0,1]
	v_pk_fma_f32 v[4:5], v[100:101], s[86:87], v[4:5] op_sel_hi:[1,0,1]
	v_pk_fma_f32 v[6:7], v[102:103], s[86:87], v[6:7] op_sel_hi:[1,0,1]
	v_cvt_pk_f32_fp8_e32 v[96:97], v74
	v_cvt_pk_f32_fp8_sdwa v[98:99], v74 src0_sel:WORD_1
	v_cvt_pk_f32_fp8_e32 v[100:101], v78
	v_cvt_pk_f32_fp8_sdwa v[102:103], v78 src0_sel:WORD_1
	v_pk_fma_f32 v[8:9], v[96:97], s[84:85], v[8:9] op_sel_hi:[1,0,1]
	v_pk_fma_f32 v[10:11], v[98:99], s[84:85], v[10:11] op_sel_hi:[1,0,1]
	v_pk_fma_f32 v[8:9], v[100:101], s[86:87], v[8:9] op_sel_hi:[1,0,1]
	v_pk_fma_f32 v[10:11], v[102:103], s[86:87], v[10:11] op_sel_hi:[1,0,1]
	v_cvt_pk_f32_fp8_e32 v[96:97], v75
	v_cvt_pk_f32_fp8_sdwa v[98:99], v75 src0_sel:WORD_1
	v_cvt_pk_f32_fp8_e32 v[100:101], v79
	v_cvt_pk_f32_fp8_sdwa v[102:103], v79 src0_sel:WORD_1
	global_load_dwordx4 v[72:75], v136, s[80:81]
	global_load_dwordx4 v[76:79], v137, s[80:81]
	v_pk_fma_f32 v[12:13], v[96:97], s[84:85], v[12:13] op_sel_hi:[1,0,1]
	v_pk_fma_f32 v[14:15], v[98:99], s[84:85], v[14:15] op_sel_hi:[1,0,1]
	v_pk_fma_f32 v[12:13], v[100:101], s[86:87], v[12:13] op_sel_hi:[1,0,1]
	v_pk_fma_f32 v[14:15], v[102:103], s[86:87], v[14:15] op_sel_hi:[1,0,1]
	s_add_u32 s98, s101, 4
	s_add_u32 s99, s101, 5
	v_readlane_b32 s84, v152, s98
	v_readlane_b32 s86, v152, s99
	s_waitcnt vmcnt(6)
; #define PG_ISSUE(BUF, TAB, e0_) do { const int isrc_ = ((e0_) < 64) ? myi0 : myi1; \
;       _Pragma("unroll") for (int e = 0; e < 8; ++e) { const int idx_ = __builtin_amdgcn_readlane(isrc_, ((e0_) + e) & 63); \
;         BUF[e] = *(const u32x4*)((TAB) + (size_t)idx_ * 1024 + lane * 16); } } while (0)
; DEV void peer_gather(const Params& P, int l, int m0, const int* idxs, const float* gs) {
;     ...
;     PG_ISSUE(b0, U, 0);
; #pragma nounroll
;     for (int e0 = 0; e0 < 128; e0 += 16) {
;       PG_ISSUE(b1, U, e0 + 8);
;       PG_U8(b0, 0, e0);
;       if (e0 + 16 < 128) PG_ISSUE(b0, U, e0 + 16); else PG_ISSUE(b0, V, 0);
;       PG_U8(b1, 0, e0 + 8);
;     }
;     float* hrow = P.out + tok * DM + lane * 16;
;     f32x4 hv[4];
; #pragma unroll
;     for (int q = 0; q < 4; ++q) hv[q] = *(const f32x4*)(hrow + 4 * q);
;     if (i + 1 < 16) {
;       const int tn = tt + 1;
;       nxa = *(const u32x4*)(hn + (size_t)(m0 + tn) * DM + lane * 16); nxb = *(const u32x4*)(hn + (size_t)(m0 + tn) * DM + lane * 16 + 8);
;       ni0 = idxs[tn * 128 + lane]; ni1 = idxs[tn * 128 + 64 + lane]; ng0 = gs[tn * 128 + lane]; ng1 = gs[tn * 128 + 64 + lane];
;     }
; #pragma nounroll
;     for (int e0 = 0; e0 < 128; e0 += 16) {
;       PG_ISSUE(b1, V, e0 + 8);
;       if (e0 == 64 && i + 1 < 16) sort_lists(lane, ni0, ni1, ng0, ng1);
;       PG_V16(b0, e0);
;       if (e0 + 16 < 128) PG_ISSUE(b0, V, e0 + 16);
;       PG_V16(b1, e0 + 8);
;     }
	v_cvt_pk_f32_fp8_e32 v[96:97], v80
	v_cvt_pk_f32_fp8_sdwa v[98:99], v80 src0_sel:WORD_1
	v_cvt_pk_f32_fp8_e32 v[100:101], v84
	v_cvt_pk_f32_fp8_sdwa v[102:103], v84 src0_sel:WORD_1
	v_pk_fma_f32 v[0:1], v[96:97], s[84:85], v[0:1] op_sel_hi:[1,0,1]
	v_pk_fma_f32 v[2:3], v[98:99], s[84:85], v[2:3] op_sel_hi:[1,0,1]
	v_pk_fma_f32 v[0:1], v[100:101], s[86:87], v[0:1] op_sel_hi:[1,0,1]
	v_pk_fma_f32 v[2:3], v[102:103], s[86:87], v[2:3] op_sel_hi:[1,0,1]
	v_cvt_pk_f32_fp8_e32 v[96:97], v81
	v_cvt_pk_f32_fp8_sdwa v[98:99], v81 src0_sel:WORD_1
	v_cvt_pk_f32_fp8_e32 v[100:101], v85
	v_cvt_pk_f32_fp8_sdwa v[102:103], v85 src0_sel:WORD_1
	v_pk_fma_f32 v[4:5], v[96:97], s[84:85], v[4:5] op_sel_hi:[1,0,1]
	v_pk_fma_f32 v[6:7], v[98:99], s[84:85], v[6:7] op_sel_hi:[1,0,1]
	v_pk_fma_f32 v[4:5], v[100:101], s[86:87], v[4:5] op_sel_hi:[1,0,1]
	v_pk_fma_f32 v[6:7], v[102:103], s[86:87], v[6:7] op_sel_hi:[1,0,1]
	v_cvt_pk_f32_fp8_e32 v[96:97], v82
	v_cvt_pk_f32_fp8_sdwa v[98:99], v82 src0_sel:WORD_1
	v_cvt_pk_f32_fp8_e32 v[100:101], v86
	v_cvt_pk_f32_fp8_sdwa v[102:103], v86 src0_sel:WORD_1
	v_pk_fma_f32 v[8:9], v[96:97], s[84:85], v[8:9] op_sel_hi:[1,0,1]
	v_pk_fma_f32 v[10:11], v[98:99], s[84:85], v[10:11] op_sel_hi:[1,0,1]
	v_pk_fma_f32 v[8:9], v[100:101], s[86:87], v[8:9] op_sel_hi:[1,0,1]
	v_pk_fma_f32 v[10:11], v[102:103], s[86:87], v[10:11] op_sel_hi:[1,0,1]
	v_cvt_pk_f32_fp8_e32 v[96:97], v83
	v_cvt_pk_f32_fp8_sdwa v[98:99], v83 src0_sel:WORD_1
	v_cvt_pk_f32_fp8_e32 v[100:101], v87
	v_cvt_pk_f32_fp8_sdwa v[102:103], v87 src0_sel:WORD_1
	global_load_dwordx4 v[80:83], v138, s[80:81]
	global_load_dwordx4 v[84:87], v139, s[80:81]
	v_pk_fma_f32 v[12:13], v[96:97], s[84:85], v[12:13] op_sel_hi:[1,0,1]
	v_pk_fma_f32 v[14:15], v[98:99], s[84:85], v[14:15] op_sel_hi:[1,0,1]
	v_pk_fma_f32 v[12:13], v[100:101], s[86:87], v[12:13] op_sel_hi:[1,0,1]
	v_pk_fma_f32 v[14:15], v[102:103], s[86:87], v[14:15] op_sel_hi:[1,0,1]
	s_add_u32 s98, s101, 6
	s_add_u32 s99, s101, 7
	v_readlane_b32 s84, v152, s98
	v_readlane_b32 s86, v152, s99
	s_waitcnt vmcnt(6)
	v_cvt_pk_f32_fp8_e32 v[96:97], v88
	v_cvt_pk_f32_fp8_sdwa v[98:99], v88 src0_sel:WORD_1
	v_cvt_pk_f32_fp8_e32 v[100:101], v92
	v_cvt_pk_f32_fp8_sdwa v[102:103], v92 src0_sel:WORD_1
	v_pk_fma_f32 v[0:1], v[96:97], s[84:85], v[0:1] op_sel_hi:[1,0,1]
	v_pk_fma_f32 v[2:3], v[98:99], s[84:85], v[2:3] op_sel_hi:[1,0,1]
	v_pk_fma_f32 v[0:1], v[100:101], s[86:87], v[0:1] op_sel_hi:[1,0,1]
	v_pk_fma_f32 v[2:3], v[102:103], s[86:87], v[2:3] op_sel_hi:[1,0,1]
	v_cvt_pk_f32_fp8_e32 v[96:97], v89
	v_cvt_pk_f32_fp8_sdwa v[98:99], v89 src0_sel:WORD_1
	v_cvt_pk_f32_fp8_e32 v[100:101], v93
	v_cvt_pk_f32_fp8_sdwa v[102:103], v93 src0_sel:WORD_1
	v_pk_fma_f32 v[4:5], v[96:97], s[84:85], v[4:5] op_sel_hi:[1,0,1]
	v_pk_fma_f32 v[6:7], v[98:99], s[84:85], v[6:7] op_sel_hi:[1,0,1]
	v_pk_fma_f32 v[4:5], v[100:101], s[86:87], v[4:5] op_sel_hi:[1,0,1]
	v_pk_fma_f32 v[6:7], v[102:103], s[86:87], v[6:7] op_sel_hi:[1,0,1]
	v_cvt_pk_f32_fp8_e32 v[96:97], v90
	v_cvt_pk_f32_fp8_sdwa v[98:99], v90 src0_sel:WORD_1
	v_cvt_pk_f32_fp8_e32 v[100:101], v94
	v_cvt_pk_f32_fp8_sdwa v[102:103], v94 src0_sel:WORD_1
	v_pk_fma_f32 v[8:9], v[96:97], s[84:85], v[8:9] op_sel_hi:[1,0,1]
	v_pk_fma_f32 v[10:11], v[98:99], s[84:85], v[10:11] op_sel_hi:[1,0,1]
	v_pk_fma_f32 v[8:9], v[100:101], s[86:87], v[8:9] op_sel_hi:[1,0,1]
	v_pk_fma_f32 v[10:11], v[102:103], s[86:87], v[10:11] op_sel_hi:[1,0,1]
	v_cvt_pk_f32_fp8_e32 v[96:97], v91
	v_cvt_pk_f32_fp8_sdwa v[98:99], v91 src0_sel:WORD_1
	v_cvt_pk_f32_fp8_e32 v[100:101], v95
	v_cvt_pk_f32_fp8_sdwa v[102:103], v95 src0_sel:WORD_1
	global_load_dwordx4 v[88:91], v140, s[80:81]
	global_load_dwordx4 v[92:95], v141, s[80:81]
	v_pk_fma_f32 v[12:13], v[96:97], s[84:85], v[12:13] op_sel_hi:[1,0,1]
	v_pk_fma_f32 v[14:15], v[98:99], s[84:85], v[14:15] op_sel_hi:[1,0,1]
	v_pk_fma_f32 v[12:13], v[100:101], s[86:87], v[12:13] op_sel_hi:[1,0,1]
	v_pk_fma_f32 v[14:15], v[102:103], s[86:87], v[14:15] op_sel_hi:[1,0,1]
	v_cndmask_b32_e64 v153, v146, v147, s[90:91]
	s_nop 0
	s_add_u32 s98, s101, 0
	v_readlane_b32 s98, v153, s98
	s_add_u32 s99, s101, 1
	v_readlane_b32 s99, v153, s99
	s_add_u32 s92, s101, 2
	v_readlane_b32 s92, v153, s92
	s_add_u32 s93, s101, 3
	v_readlane_b32 s93, v153, s93
	v_lshl_add_u32 v134, s98, 10, v250
	v_lshl_add_u32 v135, s99, 10, v250
	v_lshl_add_u32 v136, s92, 10, v250
	v_lshl_add_u32 v137, s93, 10, v250
	s_add_u32 s98, s101, 4
	v_readlane_b32 s98, v153, s98
	s_add_u32 s99, s101, 5
	v_readlane_b32 s99, v153, s99
	s_add_u32 s92, s101, 6
	v_readlane_b32 s92, v153, s92
	s_add_u32 s93, s101, 7
	v_readlane_b32 s93, v153, s93
	v_lshl_add_u32 v138, s98, 10, v250
	v_lshl_add_u32 v139, s99, 10, v250
	v_lshl_add_u32 v140, s92, 10, v250
	v_lshl_add_u32 v141, s93, 10, v250
	v_cndmask_b32_e64 v152, v243, v244, s[90:91]
	s_add_u32 s98, s101, 0
	s_add_u32 s99, s101, 1
	v_readlane_b32 s84, v152, s98
	v_readlane_b32 s86, v152, s99
	s_waitcnt vmcnt(6)
; #define PG_ISSUE(BUF, TAB, e0_) do { const int isrc_ = ((e0_) < 64) ? myi0 : myi1; \
;       _Pragma("unroll") for (int e = 0; e < 8; ++e) { const int idx_ = __builtin_amdgcn_readlane(isrc_, ((e0_) + e) & 63); \
;         BUF[e] = *(const u32x4*)((TAB) + (size_t)idx_ * 1024 + lane * 16); } } while (0)
; DEV void peer_gather(const Params& P, int l, int m0, const int* idxs, const float* gs) {
;     ...
;     PG_ISSUE(b0, U, 0);
; #pragma nounroll
;     for (int e0 = 0; e0 < 128; e0 += 16) {
;       PG_ISSUE(b1, U, e0 + 8);
;       PG_U8(b0, 0, e0);
;       if (e0 + 16 < 128) PG_ISSUE(b0, U, e0 + 16); else PG_ISSUE(b0, V, 0);
;       PG_U8(b1, 0, e0 + 8);
;     }
;     float* hrow = P.out + tok * DM + lane * 16;
;     f32x4 hv[4];
; #pragma unroll
;     for (int q = 0; q < 4; ++q) hv[q] = *(const f32x4*)(hrow + 4 * q);
;     if (i + 1 < 16) {
;       const int tn = tt + 1;
;       nxa = *(const u32x4*)(hn + (size_t)(m0 + tn) * DM + lane * 16); nxb = *(const u32x4*)(hn + (size_t)(m0 + tn) * DM + lane * 16 + 8);
;       ni0 = idxs[tn * 128 + lane]; ni1 = idxs[tn * 128 + 64 + lane]; ng0 = gs[tn * 128 + lane]; ng1 = gs[tn * 128 + 64 + lane];
;     }
; #pragma nounroll
;     for (int e0 = 0; e0 < 128; e0 += 16) {
;       PG_ISSUE(b1, V, e0 + 8);
;       if (e0 == 64 && i + 1 < 16) sort_lists(lane, ni0, ni1, ng0, ng1);
;       PG_V16(b0, e0);
;       if (e0 + 16 < 128) PG_ISSUE(b0, V, e0 + 16);
;       PG_V16(b1, e0 + 8);
;     }
	v_cvt_pk_f32_fp8_e32 v[96:97], v64
	v_cvt_pk_f32_fp8_sdwa v[98:99], v64 src0_sel:WORD_1
	v_cvt_pk_f32_fp8_e32 v[100:101], v68
	v_cvt_pk_f32_fp8_sdwa v[102:103], v68 src0_sel:WORD_1
	v_pk_fma_f32 v[16:17], v[96:97], s[84:85], v[16:17] op_sel_hi:[1,0,1]
	v_pk_fma_f32 v[18:19], v[98:99], s[84:85], v[18:19] op_sel_hi:[1,0,1]
	v_pk_fma_f32 v[16:17], v[100:101], s[86:87], v[16:17] op_sel_hi:[1,0,1]
	v_pk_fma_f32 v[18:19], v[102:103], s[86:87], v[18:19] op_sel_hi:[1,0,1]
	v_cvt_pk_f32_fp8_e32 v[96:97], v65
	v_cvt_pk_f32_fp8_sdwa v[98:99], v65 src0_sel:WORD_1
	v_cvt_pk_f32_fp8_e32 v[100:101], v69
	v_cvt_pk_f32_fp8_sdwa v[102:103], v69 src0_sel:WORD_1
	v_pk_fma_f32 v[20:21], v[96:97], s[84:85], v[20:21] op_sel_hi:[1,0,1]
	v_pk_fma_f32 v[22:23], v[98:99], s[84:85], v[22:23] op_sel_hi:[1,0,1]
	v_pk_fma_f32 v[20:21], v[100:101], s[86:87], v[20:21] op_sel_hi:[1,0,1]
	v_pk_fma_f32 v[22:23], v[102:103], s[86:87], v[22:23] op_sel_hi:[1,0,1]
	v_cvt_pk_f32_fp8_e32 v[96:97], v66
	v_cvt_pk_f32_fp8_sdwa v[98:99], v66 src0_sel:WORD_1
	v_cvt_pk_f32_fp8_e32 v[100:101], v70
	v_cvt_pk_f32_fp8_sdwa v[102:103], v70 src0_sel:WORD_1
	v_pk_fma_f32 v[24:25], v[96:97], s[84:85], v[24:25] op_sel_hi:[1,0,1]
	v_pk_fma_f32 v[26:27], v[98:99], s[84:85], v[26:27] op_sel_hi:[1,0,1]
	v_pk_fma_f32 v[24:25], v[100:101], s[86:87], v[24:25] op_sel_hi:[1,0,1]
	v_pk_fma_f32 v[26:27], v[102:103], s[86:87], v[26:27] op_sel_hi:[1,0,1]
	v_cvt_pk_f32_fp8_e32 v[96:97], v67
	v_cvt_pk_f32_fp8_sdwa v[98:99], v67 src0_sel:WORD_1
	v_cvt_pk_f32_fp8_e32 v[100:101], v71
	v_cvt_pk_f32_fp8_sdwa v[102:103], v71 src0_sel:WORD_1
	global_load_dwordx4 v[64:67], v134, s[80:81]
	global_load_dwordx4 v[68:71], v135, s[80:81]
	v_pk_fma_f32 v[28:29], v[96:97], s[84:85], v[28:29] op_sel_hi:[1,0,1]
	v_pk_fma_f32 v[30:31], v[98:99], s[84:85], v[30:31] op_sel_hi:[1,0,1]
	v_pk_fma_f32 v[28:29], v[100:101], s[86:87], v[28:29] op_sel_hi:[1,0,1]
	v_pk_fma_f32 v[30:31], v[102:103], s[86:87], v[30:31] op_sel_hi:[1,0,1]
	s_add_u32 s98, s101, 2
	s_add_u32 s99, s101, 3
	v_readlane_b32 s84, v152, s98
	v_readlane_b32 s86, v152, s99
	s_waitcnt vmcnt(6)
	v_cvt_pk_f32_fp8_e32 v[96:97], v72
	v_cvt_pk_f32_fp8_sdwa v[98:99], v72 src0_sel:WORD_1
	v_cvt_pk_f32_fp8_e32 v[100:101], v76
	v_cvt_pk_f32_fp8_sdwa v[102:103], v76 src0_sel:WORD_1
	v_pk_fma_f32 v[16:17], v[96:97], s[84:85], v[16:17] op_sel_hi:[1,0,1]
	v_pk_fma_f32 v[18:19], v[98:99], s[84:85], v[18:19] op_sel_hi:[1,0,1]
	v_pk_fma_f32 v[16:17], v[100:101], s[86:87], v[16:17] op_sel_hi:[1,0,1]
	v_pk_fma_f32 v[18:19], v[102:103], s[86:87], v[18:19] op_sel_hi:[1,0,1]
	v_cvt_pk_f32_fp8_e32 v[96:97], v73
	v_cvt_pk_f32_fp8_sdwa v[98:99], v73 src0_sel:WORD_1
	v_cvt_pk_f32_fp8_e32 v[100:101], v77
	v_cvt_pk_f32_fp8_sdwa v[102:103], v77 src0_sel:WORD_1
	v_pk_fma_f32 v[20:21], v[96:97], s[84:85], v[20:21] op_sel_hi:[1,0,1]
	v_pk_fma_f32 v[22:23], v[98:99], s[84:85], v[22:23] op_sel_hi:[1,0,1]
	v_pk_fma_f32 v[20:21], v[100:101], s[86:87], v[20:21] op_sel_hi:[1,0,1]
	v_pk_fma_f32 v[22:23], v[102:103], s[86:87], v[22:23] op_sel_hi:[1,0,1]
	v_cvt_pk_f32_fp8_e32 v[96:97], v74
	v_cvt_pk_f32_fp8_sdwa v[98:99], v74 src0_sel:WORD_1
	v_cvt_pk_f32_fp8_e32 v[100:101], v78
	v_cvt_pk_f32_fp8_sdwa v[102:103], v78 src0_sel:WORD_1
	v_pk_fma_f32 v[24:25], v[96:97], s[84:85], v[24:25] op_sel_hi:[1,0,1]
	v_pk_fma_f32 v[26:27], v[98:99], s[84:85], v[26:27] op_sel_hi:[1,0,1]
	v_pk_fma_f32 v[24:25], v[100:101], s[86:87], v[24:25] op_sel_hi:[1,0,1]
	v_pk_fma_f32 v[26:27], v[102:103], s[86:87], v[26:27] op_sel_hi:[1,0,1]
	v_cvt_pk_f32_fp8_e32 v[96:97], v75
	v_cvt_pk_f32_fp8_sdwa v[98:99], v75 src0_sel:WORD_1
	v_cvt_pk_f32_fp8_e32 v[100:101], v79
	v_cvt_pk_f32_fp8_sdwa v[102:103], v79 src0_sel:WORD_1
	global_load_dwordx4 v[72:75], v136, s[80:81]
	global_load_dwordx4 v[76:79], v137, s[80:81]
	v_pk_fma_f32 v[28:29], v[96:97], s[84:85], v[28:29] op_sel_hi:[1,0,1]
	v_pk_fma_f32 v[30:31], v[98:99], s[84:85], v[30:31] op_sel_hi:[1,0,1]
	v_pk_fma_f32 v[28:29], v[100:101], s[86:87], v[28:29] op_sel_hi:[1,0,1]
	v_pk_fma_f32 v[30:31], v[102:103], s[86:87], v[30:31] op_sel_hi:[1,0,1]
	s_add_u32 s98, s101, 4
	s_add_u32 s99, s101, 5
	v_readlane_b32 s84, v152, s98
	v_readlane_b32 s86, v152, s99
	s_waitcnt vmcnt(6)
	v_cvt_pk_f32_fp8_e32 v[96:97], v80
	v_cvt_pk_f32_fp8_sdwa v[98:99], v80 src0_sel:WORD_1
	v_cvt_pk_f32_fp8_e32 v[100:101], v84
	v_cvt_pk_f32_fp8_sdwa v[102:103], v84 src0_sel:WORD_1
	v_pk_fma_f32 v[16:17], v[96:97], s[84:85], v[16:17] op_sel_hi:[1,0,1]
	v_pk_fma_f32 v[18:19], v[98:99], s[84:85], v[18:19] op_sel_hi:[1,0,1]
	v_pk_fma_f32 v[16:17], v[100:101], s[86:87], v[16:17] op_sel_hi:[1,0,1]
	v_pk_fma_f32 v[18:19], v[102:103], s[86:87], v[18:19] op_sel_hi:[1,0,1]
	v_cvt_pk_f32_fp8_e32 v[96:97], v81
	v_cvt_pk_f32_fp8_sdwa v[98:99], v81 src0_sel:WORD_1
	v_cvt_pk_f32_fp8_e32 v[100:101], v85
	v_cvt_pk_f32_fp8_sdwa v[102:103], v85 src0_sel:WORD_1
	v_pk_fma_f32 v[20:21], v[96:97], s[84:85], v[20:21] op_sel_hi:[1,0,1]
	v_pk_fma_f32 v[22:23], v[98:99], s[84:85], v[22:23] op_sel_hi:[1,0,1]
	v_pk_fma_f32 v[20:21], v[100:101], s[86:87], v[20:21] op_sel_hi:[1,0,1]
	v_pk_fma_f32 v[22:23], v[102:103], s[86:87], v[22:23] op_sel_hi:[1,0,1]
	v_cvt_pk_f32_fp8_e32 v[96:97], v82
	v_cvt_pk_f32_fp8_sdwa v[98:99], v82 src0_sel:WORD_1
	v_cvt_pk_f32_fp8_e32 v[100:101], v86
	v_cvt_pk_f32_fp8_sdwa v[102:103], v86 src0_sel:WORD_1
	v_pk_fma_f32 v[24:25], v[96:97], s[84:85], v[24:25] op_sel_hi:[1,0,1]
	v_pk_fma_f32 v[26:27], v[98:99], s[84:85], v[26:27] op_sel_hi:[1,0,1]
	v_pk_fma_f32 v[24:25], v[100:101], s[86:87], v[24:25] op_sel_hi:[1,0,1]
	v_pk_fma_f32 v[26:27], v[102:103], s[86:87], v[26:27] op_sel_hi:[1,0,1]
	v_cvt_pk_f32_fp8_e32 v[96:97], v83
	v_cvt_pk_f32_fp8_sdwa v[98:99], v83 src0_sel:WORD_1
	v_cvt_pk_f32_fp8_e32 v[100:101], v87
	v_cvt_pk_f32_fp8_sdwa v[102:103], v87 src0_sel:WORD_1
	global_load_dwordx4 v[80:83], v138, s[80:81]
	global_load_dwordx4 v[84:87], v139, s[80:81]
	v_pk_fma_f32 v[28:29], v[96:97], s[84:85], v[28:29] op_sel_hi:[1,0,1]
	v_pk_fma_f32 v[30:31], v[98:99], s[84:85], v[30:31] op_sel_hi:[1,0,1]
	v_pk_fma_f32 v[28:29], v[100:101], s[86:87], v[28:29] op_sel_hi:[1,0,1]
	v_pk_fma_f32 v[30:31], v[102:103], s[86:87], v[30:31] op_sel_hi:[1,0,1]
	s_add_u32 s98, s101, 6
	s_add_u32 s99, s101, 7
	v_readlane_b32 s84, v152, s98
	v_readlane_b32 s86, v152, s99
	s_waitcnt vmcnt(6)
; #define PG_ISSUE(BUF, TAB, e0_) do { const int isrc_ = ((e0_) < 64) ? myi0 : myi1; \
;       _Pragma("unroll") for (int e = 0; e < 8; ++e) { const int idx_ = __builtin_amdgcn_readlane(isrc_, ((e0_) + e) & 63); \
;         BUF[e] = *(const u32x4*)((TAB) + (size_t)idx_ * 1024 + lane * 16); } } while (0)
; DEV void peer_gather(const Params& P, int l, int m0, const int* idxs, const float* gs) {
;     ...
;     PG_ISSUE(b0, U, 0);
; #pragma nounroll
;     for (int e0 = 0; e0 < 128; e0 += 16) {
;       PG_ISSUE(b1, U, e0 + 8);
;       PG_U8(b0, 0, e0);
;       if (e0 + 16 < 128) PG_ISSUE(b0, U, e0 + 16); else PG_ISSUE(b0, V, 0);
;       PG_U8(b1, 0, e0 + 8);
;     }
;     float* hrow = P.out + tok * DM + lane * 16;
;     f32x4 hv[4];
; #pragma unroll
;     for (int q = 0; q < 4; ++q) hv[q] = *(const f32x4*)(hrow + 4 * q);
;     if (i + 1 < 16) {
;       const int tn = tt + 1;
;       nxa = *(const u32x4*)(hn + (size_t)(m0 + tn) * DM + lane * 16); nxb = *(const u32x4*)(hn + (size_t)(m0 + tn) * DM + lane * 16 + 8);
;       ni0 = idxs[tn * 128 + lane]; ni1 = idxs[tn * 128 + 64 + lane]; ng0 = gs[tn * 128 + lane]; ng1 = gs[tn * 128 + 64 + lane];
;     }
; #pragma nounroll
;     for (int e0 = 0; e0 < 128; e0 += 16) {
;       PG_ISSUE(b1, V, e0 + 8);
;       if (e0 == 64 && i + 1 < 16) sort_lists(lane, ni0, ni1, ng0, ng1);
;       PG_V16(b0, e0);
;       if (e0 + 16 < 128) PG_ISSUE(b0, V, e0 + 16);
;       PG_V16(b1, e0 + 8);
;     }
	v_cvt_pk_f32_fp8_e32 v[96:97], v88
	v_cvt_pk_f32_fp8_sdwa v[98:99], v88 src0_sel:WORD_1
	v_cvt_pk_f32_fp8_e32 v[100:101], v92
	v_cvt_pk_f32_fp8_sdwa v[102:103], v92 src0_sel:WORD_1
	v_pk_fma_f32 v[16:17], v[96:97], s[84:85], v[16:17] op_sel_hi:[1,0,1]
	v_pk_fma_f32 v[18:19], v[98:99], s[84:85], v[18:19] op_sel_hi:[1,0,1]
	v_pk_fma_f32 v[16:17], v[100:101], s[86:87], v[16:17] op_sel_hi:[1,0,1]
	v_pk_fma_f32 v[18:19], v[102:103], s[86:87], v[18:19] op_sel_hi:[1,0,1]
	v_cvt_pk_f32_fp8_e32 v[96:97], v89
	v_cvt_pk_f32_fp8_sdwa v[98:99], v89 src0_sel:WORD_1
	v_cvt_pk_f32_fp8_e32 v[100:101], v93
	v_cvt_pk_f32_fp8_sdwa v[102:103], v93 src0_sel:WORD_1
	v_pk_fma_f32 v[20:21], v[96:97], s[84:85], v[20:21] op_sel_hi:[1,0,1]
	v_pk_fma_f32 v[22:23], v[98:99], s[84:85], v[22:23] op_sel_hi:[1,0,1]
	v_pk_fma_f32 v[20:21], v[100:101], s[86:87], v[20:21] op_sel_hi:[1,0,1]
	v_pk_fma_f32 v[22:23], v[102:103], s[86:87], v[22:23] op_sel_hi:[1,0,1]
	v_cvt_pk_f32_fp8_e32 v[96:97], v90
	v_cvt_pk_f32_fp8_sdwa v[98:99], v90 src0_sel:WORD_1
	v_cvt_pk_f32_fp8_e32 v[100:101], v94
	v_cvt_pk_f32_fp8_sdwa v[102:103], v94 src0_sel:WORD_1
	v_pk_fma_f32 v[24:25], v[96:97], s[84:85], v[24:25] op_sel_hi:[1,0,1]
	v_pk_fma_f32 v[26:27], v[98:99], s[84:85], v[26:27] op_sel_hi:[1,0,1]
	v_pk_fma_f32 v[24:25], v[100:101], s[86:87], v[24:25] op_sel_hi:[1,0,1]
	v_pk_fma_f32 v[26:27], v[102:103], s[86:87], v[26:27] op_sel_hi:[1,0,1]
	v_cvt_pk_f32_fp8_e32 v[96:97], v91
	v_cvt_pk_f32_fp8_sdwa v[98:99], v91 src0_sel:WORD_1
	v_cvt_pk_f32_fp8_e32 v[100:101], v95
	v_cvt_pk_f32_fp8_sdwa v[102:103], v95 src0_sel:WORD_1
	global_load_dwordx4 v[88:91], v140, s[80:81]
	global_load_dwordx4 v[92:95], v141, s[80:81]
	v_pk_fma_f32 v[28:29], v[96:97], s[84:85], v[28:29] op_sel_hi:[1,0,1]
	v_pk_fma_f32 v[30:31], v[98:99], s[84:85], v[30:31] op_sel_hi:[1,0,1]
	v_pk_fma_f32 v[28:29], v[100:101], s[86:87], v[28:29] op_sel_hi:[1,0,1]
	v_pk_fma_f32 v[30:31], v[102:103], s[86:87], v[30:31] op_sel_hi:[1,0,1]
	v_cndmask_b32_e64 v153, v148, v149, s[90:91]
	s_nop 0
	s_add_u32 s98, s101, 0
	v_readlane_b32 s98, v153, s98
	s_add_u32 s99, s101, 1
	v_readlane_b32 s99, v153, s99
	s_add_u32 s92, s101, 2
	v_readlane_b32 s92, v153, s92
	s_add_u32 s93, s101, 3
	v_readlane_b32 s93, v153, s93
	v_lshl_add_u32 v134, s98, 10, v250
	v_lshl_add_u32 v135, s99, 10, v250
	v_lshl_add_u32 v136, s92, 10, v250
	v_lshl_add_u32 v137, s93, 10, v250
	s_add_u32 s98, s101, 4
	v_readlane_b32 s98, v153, s98
	s_add_u32 s99, s101, 5
	v_readlane_b32 s99, v153, s99
	s_add_u32 s92, s101, 6
	v_readlane_b32 s92, v153, s92
	s_add_u32 s93, s101, 7
	v_readlane_b32 s93, v153, s93
	v_lshl_add_u32 v138, s98, 10, v250
	v_lshl_add_u32 v139, s99, 10, v250
	v_lshl_add_u32 v140, s92, 10, v250
	v_lshl_add_u32 v141, s93, 10, v250
	v_cndmask_b32_e64 v152, v245, v246, s[90:91]
	s_add_u32 s98, s101, 0
	s_add_u32 s99, s101, 1
	v_readlane_b32 s84, v152, s98
	v_readlane_b32 s86, v152, s99
	s_waitcnt vmcnt(6)
	v_cvt_pk_f32_fp8_e32 v[96:97], v64
	v_cvt_pk_f32_fp8_sdwa v[98:99], v64 src0_sel:WORD_1
	v_cvt_pk_f32_fp8_e32 v[100:101], v68
	v_cvt_pk_f32_fp8_sdwa v[102:103], v68 src0_sel:WORD_1
	v_pk_fma_f32 v[32:33], v[96:97], s[84:85], v[32:33] op_sel_hi:[1,0,1]
	v_pk_fma_f32 v[34:35], v[98:99], s[84:85], v[34:35] op_sel_hi:[1,0,1]
	v_pk_fma_f32 v[32:33], v[100:101], s[86:87], v[32:33] op_sel_hi:[1,0,1]
	v_pk_fma_f32 v[34:35], v[102:103], s[86:87], v[34:35] op_sel_hi:[1,0,1]
	v_cvt_pk_f32_fp8_e32 v[96:97], v65
	v_cvt_pk_f32_fp8_sdwa v[98:99], v65 src0_sel:WORD_1
	v_cvt_pk_f32_fp8_e32 v[100:101], v69
	v_cvt_pk_f32_fp8_sdwa v[102:103], v69 src0_sel:WORD_1
	v_pk_fma_f32 v[36:37], v[96:97], s[84:85], v[36:37] op_sel_hi:[1,0,1]
	v_pk_fma_f32 v[38:39], v[98:99], s[84:85], v[38:39] op_sel_hi:[1,0,1]
	v_pk_fma_f32 v[36:37], v[100:101], s[86:87], v[36:37] op_sel_hi:[1,0,1]
	v_pk_fma_f32 v[38:39], v[102:103], s[86:87], v[38:39] op_sel_hi:[1,0,1]
	v_cvt_pk_f32_fp8_e32 v[96:97], v66
	v_cvt_pk_f32_fp8_sdwa v[98:99], v66 src0_sel:WORD_1
	v_cvt_pk_f32_fp8_e32 v[100:101], v70
	v_cvt_pk_f32_fp8_sdwa v[102:103], v70 src0_sel:WORD_1
	v_pk_fma_f32 v[40:41], v[96:97], s[84:85], v[40:41] op_sel_hi:[1,0,1]
	v_pk_fma_f32 v[42:43], v[98:99], s[84:85], v[42:43] op_sel_hi:[1,0,1]
	v_pk_fma_f32 v[40:41], v[100:101], s[86:87], v[40:41] op_sel_hi:[1,0,1]
	v_pk_fma_f32 v[42:43], v[102:103], s[86:87], v[42:43] op_sel_hi:[1,0,1]
	v_cvt_pk_f32_fp8_e32 v[96:97], v67
	v_cvt_pk_f32_fp8_sdwa v[98:99], v67 src0_sel:WORD_1
	v_cvt_pk_f32_fp8_e32 v[100:101], v71
	v_cvt_pk_f32_fp8_sdwa v[102:103], v71 src0_sel:WORD_1
	global_load_dwordx4 v[64:67], v134, s[80:81]
	global_load_dwordx4 v[68:71], v135, s[80:81]
	v_pk_fma_f32 v[44:45], v[96:97], s[84:85], v[44:45] op_sel_hi:[1,0,1]
	v_pk_fma_f32 v[46:47], v[98:99], s[84:85], v[46:47] op_sel_hi:[1,0,1]
	v_pk_fma_f32 v[44:45], v[100:101], s[86:87], v[44:45] op_sel_hi:[1,0,1]
	v_pk_fma_f32 v[46:47], v[102:103], s[86:87], v[46:47] op_sel_hi:[1,0,1]
	s_add_u32 s98, s101, 2
	s_add_u32 s99, s101, 3
	v_readlane_b32 s84, v152, s98
	v_readlane_b32 s86, v152, s99
	s_waitcnt vmcnt(6)
; #define PG_ISSUE(BUF, TAB, e0_) do { const int isrc_ = ((e0_) < 64) ? myi0 : myi1; \
;       _Pragma("unroll") for (int e = 0; e < 8; ++e) { const int idx_ = __builtin_amdgcn_readlane(isrc_, ((e0_) + e) & 63); \
;         BUF[e] = *(const u32x4*)((TAB) + (size_t)idx_ * 1024 + lane * 16); } } while (0)
; DEV void peer_gather(const Params& P, int l, int m0, const int* idxs, const float* gs) {
;     ...
;     PG_ISSUE(b0, U, 0);
; #pragma nounroll
;     for (int e0 = 0; e0 < 128; e0 += 16) {
;       PG_ISSUE(b1, U, e0 + 8);
;       PG_U8(b0, 0, e0);
;       if (e0 + 16 < 128) PG_ISSUE(b0, U, e0 + 16); else PG_ISSUE(b0, V, 0);
;       PG_U8(b1, 0, e0 + 8);
;     }
;     float* hrow = P.out + tok * DM + lane * 16;
;     f32x4 hv[4];
; #pragma unroll
;     for (int q = 0; q < 4; ++q) hv[q] = *(const f32x4*)(hrow + 4 * q);
;     if (i + 1 < 16) {
;       const int tn = tt + 1;
;       nxa = *(const u32x4*)(hn + (size_t)(m0 + tn) * DM + lane * 16); nxb = *(const u32x4*)(hn + (size_t)(m0 + tn) * DM + lane * 16 + 8);
;       ni0 = idxs[tn * 128 + lane]; ni1 = idxs[tn * 128 + 64 + lane]; ng0 = gs[tn * 128 + lane]; ng1 = gs[tn * 128 + 64 + lane];
;     }
; #pragma nounroll
;     for (int e0 = 0; e0 < 128; e0 += 16) {
;       PG_ISSUE(b1, V, e0 + 8);
;       if (e0 == 64 && i + 1 < 16) sort_lists(lane, ni0, ni1, ng0, ng1);
;       PG_V16(b0, e0);
;       if (e0 + 16 < 128) PG_ISSUE(b0, V, e0 + 16);
;       PG_V16(b1, e0 + 8);
;     }
	v_cvt_pk_f32_fp8_e32 v[96:97], v72
	v_cvt_pk_f32_fp8_sdwa v[98:99], v72 src0_sel:WORD_1
	v_cvt_pk_f32_fp8_e32 v[100:101], v76
	v_cvt_pk_f32_fp8_sdwa v[102:103], v76 src0_sel:WORD_1
	v_pk_fma_f32 v[32:33], v[96:97], s[84:85], v[32:33] op_sel_hi:[1,0,1]
	v_pk_fma_f32 v[34:35], v[98:99], s[84:85], v[34:35] op_sel_hi:[1,0,1]
	v_pk_fma_f32 v[32:33], v[100:101], s[86:87], v[32:33] op_sel_hi:[1,0,1]
	v_pk_fma_f32 v[34:35], v[102:103], s[86:87], v[34:35] op_sel_hi:[1,0,1]
	v_cvt_pk_f32_fp8_e32 v[96:97], v73
	v_cvt_pk_f32_fp8_sdwa v[98:99], v73 src0_sel:WORD_1
	v_cvt_pk_f32_fp8_e32 v[100:101], v77
	v_cvt_pk_f32_fp8_sdwa v[102:103], v77 src0_sel:WORD_1
	v_pk_fma_f32 v[36:37], v[96:97], s[84:85], v[36:37] op_sel_hi:[1,0,1]
	v_pk_fma_f32 v[38:39], v[98:99], s[84:85], v[38:39] op_sel_hi:[1,0,1]
	v_pk_fma_f32 v[36:37], v[100:101], s[86:87], v[36:37] op_sel_hi:[1,0,1]
	v_pk_fma_f32 v[38:39], v[102:103], s[86:87], v[38:39] op_sel_hi:[1,0,1]
	v_cvt_pk_f32_fp8_e32 v[96:97], v74
	v_cvt_pk_f32_fp8_sdwa v[98:99], v74 src0_sel:WORD_1
	v_cvt_pk_f32_fp8_e32 v[100:101], v78
	v_cvt_pk_f32_fp8_sdwa v[102:103], v78 src0_sel:WORD_1
	v_pk_fma_f32 v[40:41], v[96:97], s[84:85], v[40:41] op_sel_hi:[1,0,1]
	v_pk_fma_f32 v[42:43], v[98:99], s[84:85], v[42:43] op_sel_hi:[1,0,1]
	v_pk_fma_f32 v[40:41], v[100:101], s[86:87], v[40:41] op_sel_hi:[1,0,1]
	v_pk_fma_f32 v[42:43], v[102:103], s[86:87], v[42:43] op_sel_hi:[1,0,1]
	v_cvt_pk_f32_fp8_e32 v[96:97], v75
	v_cvt_pk_f32_fp8_sdwa v[98:99], v75 src0_sel:WORD_1
	v_cvt_pk_f32_fp8_e32 v[100:101], v79
	v_cvt_pk_f32_fp8_sdwa v[102:103], v79 src0_sel:WORD_1
	global_load_dwordx4 v[72:75], v136, s[80:81]
	global_load_dwordx4 v[76:79], v137, s[80:81]
	v_pk_fma_f32 v[44:45], v[96:97], s[84:85], v[44:45] op_sel_hi:[1,0,1]
	v_pk_fma_f32 v[46:47], v[98:99], s[84:85], v[46:47] op_sel_hi:[1,0,1]
	v_pk_fma_f32 v[44:45], v[100:101], s[86:87], v[44:45] op_sel_hi:[1,0,1]
	v_pk_fma_f32 v[46:47], v[102:103], s[86:87], v[46:47] op_sel_hi:[1,0,1]
	s_add_u32 s98, s101, 4
	s_add_u32 s99, s101, 5
	v_readlane_b32 s84, v152, s98
	v_readlane_b32 s86, v152, s99
	s_waitcnt vmcnt(6)
	v_cvt_pk_f32_fp8_e32 v[96:97], v80
	v_cvt_pk_f32_fp8_sdwa v[98:99], v80 src0_sel:WORD_1
	v_cvt_pk_f32_fp8_e32 v[100:101], v84
	v_cvt_pk_f32_fp8_sdwa v[102:103], v84 src0_sel:WORD_1
	v_pk_fma_f32 v[32:33], v[96:97], s[84:85], v[32:33] op_sel_hi:[1,0,1]
	v_pk_fma_f32 v[34:35], v[98:99], s[84:85], v[34:35] op_sel_hi:[1,0,1]
	v_pk_fma_f32 v[32:33], v[100:101], s[86:87], v[32:33] op_sel_hi:[1,0,1]
	v_pk_fma_f32 v[34:35], v[102:103], s[86:87], v[34:35] op_sel_hi:[1,0,1]
	v_cvt_pk_f32_fp8_e32 v[96:97], v81
	v_cvt_pk_f32_fp8_sdwa v[98:99], v81 src0_sel:WORD_1
	v_cvt_pk_f32_fp8_e32 v[100:101], v85
	v_cvt_pk_f32_fp8_sdwa v[102:103], v85 src0_sel:WORD_1
	v_pk_fma_f32 v[36:37], v[96:97], s[84:85], v[36:37] op_sel_hi:[1,0,1]
	v_pk_fma_f32 v[38:39], v[98:99], s[84:85], v[38:39] op_sel_hi:[1,0,1]
	v_pk_fma_f32 v[36:37], v[100:101], s[86:87], v[36:37] op_sel_hi:[1,0,1]
	v_pk_fma_f32 v[38:39], v[102:103], s[86:87], v[38:39] op_sel_hi:[1,0,1]
	v_cvt_pk_f32_fp8_e32 v[96:97], v82
	v_cvt_pk_f32_fp8_sdwa v[98:99], v82 src0_sel:WORD_1
	v_cvt_pk_f32_fp8_e32 v[100:101], v86
	v_cvt_pk_f32_fp8_sdwa v[102:103], v86 src0_sel:WORD_1
	v_pk_fma_f32 v[40:41], v[96:97], s[84:85], v[40:41] op_sel_hi:[1,0,1]
	v_pk_fma_f32 v[42:43], v[98:99], s[84:85], v[42:43] op_sel_hi:[1,0,1]
	v_pk_fma_f32 v[40:41], v[100:101], s[86:87], v[40:41] op_sel_hi:[1,0,1]
	v_pk_fma_f32 v[42:43], v[102:103], s[86:87], v[42:43] op_sel_hi:[1,0,1]
	v_cvt_pk_f32_fp8_e32 v[96:97], v83
	v_cvt_pk_f32_fp8_sdwa v[98:99], v83 src0_sel:WORD_1
	v_cvt_pk_f32_fp8_e32 v[100:101], v87
	v_cvt_pk_f32_fp8_sdwa v[102:103], v87 src0_sel:WORD_1
	global_load_dwordx4 v[80:83], v138, s[80:81]
	global_load_dwordx4 v[84:87], v139, s[80:81]
	v_pk_fma_f32 v[44:45], v[96:97], s[84:85], v[44:45] op_sel_hi:[1,0,1]
	v_pk_fma_f32 v[46:47], v[98:99], s[84:85], v[46:47] op_sel_hi:[1,0,1]
	v_pk_fma_f32 v[44:45], v[100:101], s[86:87], v[44:45] op_sel_hi:[1,0,1]
	v_pk_fma_f32 v[46:47], v[102:103], s[86:87], v[46:47] op_sel_hi:[1,0,1]
	s_add_u32 s98, s101, 6
	s_add_u32 s99, s101, 7
	v_readlane_b32 s84, v152, s98
	v_readlane_b32 s86, v152, s99
	s_waitcnt vmcnt(6)
	v_cvt_pk_f32_fp8_e32 v[96:97], v88
	v_cvt_pk_f32_fp8_sdwa v[98:99], v88 src0_sel:WORD_1
	v_cvt_pk_f32_fp8_e32 v[100:101], v92
	v_cvt_pk_f32_fp8_sdwa v[102:103], v92 src0_sel:WORD_1
	v_pk_fma_f32 v[32:33], v[96:97], s[84:85], v[32:33] op_sel_hi:[1,0,1]
	v_pk_fma_f32 v[34:35], v[98:99], s[84:85], v[34:35] op_sel_hi:[1,0,1]
	v_pk_fma_f32 v[32:33], v[100:101], s[86:87], v[32:33] op_sel_hi:[1,0,1]
	v_pk_fma_f32 v[34:35], v[102:103], s[86:87], v[34:35] op_sel_hi:[1,0,1]
	v_cvt_pk_f32_fp8_e32 v[96:97], v89
	v_cvt_pk_f32_fp8_sdwa v[98:99], v89 src0_sel:WORD_1
	v_cvt_pk_f32_fp8_e32 v[100:101], v93
	v_cvt_pk_f32_fp8_sdwa v[102:103], v93 src0_sel:WORD_1
	v_pk_fma_f32 v[36:37], v[96:97], s[84:85], v[36:37] op_sel_hi:[1,0,1]
	v_pk_fma_f32 v[38:39], v[98:99], s[84:85], v[38:39] op_sel_hi:[1,0,1]
	v_pk_fma_f32 v[36:37], v[100:101], s[86:87], v[36:37] op_sel_hi:[1,0,1]
	v_pk_fma_f32 v[38:39], v[102:103], s[86:87], v[38:39] op_sel_hi:[1,0,1]
	v_cvt_pk_f32_fp8_e32 v[96:97], v90
	v_cvt_pk_f32_fp8_sdwa v[98:99], v90 src0_sel:WORD_1
	v_cvt_pk_f32_fp8_e32 v[100:101], v94
	v_cvt_pk_f32_fp8_sdwa v[102:103], v94 src0_sel:WORD_1
	v_pk_fma_f32 v[40:41], v[96:97], s[84:85], v[40:41] op_sel_hi:[1,0,1]
	v_pk_fma_f32 v[42:43], v[98:99], s[84:85], v[42:43] op_sel_hi:[1,0,1]
	v_pk_fma_f32 v[40:41], v[100:101], s[86:87], v[40:41] op_sel_hi:[1,0,1]
	v_pk_fma_f32 v[42:43], v[102:103], s[86:87], v[42:43] op_sel_hi:[1,0,1]
	v_cvt_pk_f32_fp8_e32 v[96:97], v91
; #define PG_ISSUE(BUF, TAB, e0_) do { const int isrc_ = ((e0_) < 64) ? myi0 : myi1; \
;       _Pragma("unroll") for (int e = 0; e < 8; ++e) { const int idx_ = __builtin_amdgcn_readlane(isrc_, ((e0_) + e) & 63); \
;         BUF[e] = *(const u32x4*)((TAB) + (size_t)idx_ * 1024 + lane * 16); } } while (0)
; DEV void peer_gather(const Params& P, int l, int m0, const int* idxs, const float* gs) {
;     ...
;     PG_ISSUE(b0, U, 0);
; #pragma nounroll
;     for (int e0 = 0; e0 < 128; e0 += 16) {
;       PG_ISSUE(b1, U, e0 + 8);
;       PG_U8(b0, 0, e0);
;       if (e0 + 16 < 128) PG_ISSUE(b0, U, e0 + 16); else PG_ISSUE(b0, V, 0);
;       PG_U8(b1, 0, e0 + 8);
;     }
;     float* hrow = P.out + tok * DM + lane * 16;
;     f32x4 hv[4];
; #pragma unroll
;     for (int q = 0; q < 4; ++q) hv[q] = *(const f32x4*)(hrow + 4 * q);
;     if (i + 1 < 16) {
;       const int tn = tt + 1;
;       nxa = *(const u32x4*)(hn + (size_t)(m0 + tn) * DM + lane * 16); nxb = *(const u32x4*)(hn + (size_t)(m0 + tn) * DM + lane * 16 + 8);
;       ni0 = idxs[tn * 128 + lane]; ni1 = idxs[tn * 128 + 64 + lane]; ng0 = gs[tn * 128 + lane]; ng1 = gs[tn * 128 + 64 + lane];
;     }
; #pragma nounroll
;     for (int e0 = 0; e0 < 128; e0 += 16) {
;       PG_ISSUE(b1, V, e0 + 8);
;       if (e0 == 64 && i + 1 < 16) sort_lists(lane, ni0, ni1, ng0, ng1);
;       PG_V16(b0, e0);
;       if (e0 + 16 < 128) PG_ISSUE(b0, V, e0 + 16);
;       PG_V16(b1, e0 + 8);
;     }
	v_cvt_pk_f32_fp8_sdwa v[98:99], v91 src0_sel:WORD_1
	v_cvt_pk_f32_fp8_e32 v[100:101], v95
	v_cvt_pk_f32_fp8_sdwa v[102:103], v95 src0_sel:WORD_1
	global_load_dwordx4 v[88:91], v140, s[80:81]
	global_load_dwordx4 v[92:95], v141, s[80:81]
	v_pk_fma_f32 v[44:45], v[96:97], s[84:85], v[44:45] op_sel_hi:[1,0,1]
	v_pk_fma_f32 v[46:47], v[98:99], s[84:85], v[46:47] op_sel_hi:[1,0,1]
	v_pk_fma_f32 v[44:45], v[100:101], s[86:87], v[44:45] op_sel_hi:[1,0,1]
	v_pk_fma_f32 v[46:47], v[102:103], s[86:87], v[46:47] op_sel_hi:[1,0,1]
	s_add_u32 s98, s100, 1
	s_min_u32 s98, s98, 15
	s_cmp_ge_u32 s98, 8
	s_cselect_b64 s[88:89], -1, 0
	s_lshl_b32 s99, s98, 3
	s_and_b32 s99, s99, 63
	s_mov_b32 vcc_lo, s99
	v_cndmask_b32_e64 v153, v142, v143, s[88:89]
	s_nop 0
	s_add_u32 s98, vcc_lo, 0
	v_readlane_b32 s98, v153, s98
	s_add_u32 s99, vcc_lo, 1
	v_readlane_b32 s99, v153, s99
	s_add_u32 s92, vcc_lo, 2
	v_readlane_b32 s92, v153, s92
	s_add_u32 s93, vcc_lo, 3
	v_readlane_b32 s93, v153, s93
	v_lshl_add_u32 v134, s98, 10, v250
	v_lshl_add_u32 v135, s99, 10, v250
	v_lshl_add_u32 v136, s92, 10, v250
	v_lshl_add_u32 v137, s93, 10, v250
	s_add_u32 s98, vcc_lo, 4
	v_readlane_b32 s98, v153, s98
	s_add_u32 s99, vcc_lo, 5
	v_readlane_b32 s99, v153, s99
	s_add_u32 s92, vcc_lo, 6
	v_readlane_b32 s92, v153, s92
	s_add_u32 s93, vcc_lo, 7
	v_readlane_b32 s93, v153, s93
	v_lshl_add_u32 v138, s98, 10, v250
	v_lshl_add_u32 v139, s99, 10, v250
	v_lshl_add_u32 v140, s92, 10, v250
	v_lshl_add_u32 v141, s93, 10, v250
	v_cndmask_b32_e64 v152, v247, v248, s[90:91]
	s_add_u32 s98, s101, 0
	s_add_u32 s99, s101, 1
	v_readlane_b32 s84, v152, s98
	v_readlane_b32 s86, v152, s99
	s_waitcnt vmcnt(6)
	v_cvt_pk_f32_fp8_e32 v[96:97], v64
	v_cvt_pk_f32_fp8_sdwa v[98:99], v64 src0_sel:WORD_1
	v_cvt_pk_f32_fp8_e32 v[100:101], v68
	v_cvt_pk_f32_fp8_sdwa v[102:103], v68 src0_sel:WORD_1
	v_pk_fma_f32 v[48:49], v[96:97], s[84:85], v[48:49] op_sel_hi:[1,0,1]
	v_pk_fma_f32 v[50:51], v[98:99], s[84:85], v[50:51] op_sel_hi:[1,0,1]
	v_pk_fma_f32 v[48:49], v[100:101], s[86:87], v[48:49] op_sel_hi:[1,0,1]
	v_pk_fma_f32 v[50:51], v[102:103], s[86:87], v[50:51] op_sel_hi:[1,0,1]
	v_cvt_pk_f32_fp8_e32 v[96:97], v65
	v_cvt_pk_f32_fp8_sdwa v[98:99], v65 src0_sel:WORD_1
	v_cvt_pk_f32_fp8_e32 v[100:101], v69
	v_cvt_pk_f32_fp8_sdwa v[102:103], v69 src0_sel:WORD_1
	v_pk_fma_f32 v[52:53], v[96:97], s[84:85], v[52:53] op_sel_hi:[1,0,1]
	v_pk_fma_f32 v[54:55], v[98:99], s[84:85], v[54:55] op_sel_hi:[1,0,1]
	v_pk_fma_f32 v[52:53], v[100:101], s[86:87], v[52:53] op_sel_hi:[1,0,1]
	v_pk_fma_f32 v[54:55], v[102:103], s[86:87], v[54:55] op_sel_hi:[1,0,1]
	v_cvt_pk_f32_fp8_e32 v[96:97], v66
	v_cvt_pk_f32_fp8_sdwa v[98:99], v66 src0_sel:WORD_1
	v_cvt_pk_f32_fp8_e32 v[100:101], v70
	v_cvt_pk_f32_fp8_sdwa v[102:103], v70 src0_sel:WORD_1
	v_pk_fma_f32 v[56:57], v[96:97], s[84:85], v[56:57] op_sel_hi:[1,0,1]
	v_pk_fma_f32 v[58:59], v[98:99], s[84:85], v[58:59] op_sel_hi:[1,0,1]
	v_pk_fma_f32 v[56:57], v[100:101], s[86:87], v[56:57] op_sel_hi:[1,0,1]
	v_pk_fma_f32 v[58:59], v[102:103], s[86:87], v[58:59] op_sel_hi:[1,0,1]
	v_cvt_pk_f32_fp8_e32 v[96:97], v67
	v_cvt_pk_f32_fp8_sdwa v[98:99], v67 src0_sel:WORD_1
	v_cvt_pk_f32_fp8_e32 v[100:101], v71
	v_cvt_pk_f32_fp8_sdwa v[102:103], v71 src0_sel:WORD_1
	global_load_dwordx4 v[64:67], v134, s[80:81]
	global_load_dwordx4 v[68:71], v135, s[80:81]
	v_pk_fma_f32 v[60:61], v[96:97], s[84:85], v[60:61] op_sel_hi:[1,0,1]
	v_pk_fma_f32 v[62:63], v[98:99], s[84:85], v[62:63] op_sel_hi:[1,0,1]
	v_pk_fma_f32 v[60:61], v[100:101], s[86:87], v[60:61] op_sel_hi:[1,0,1]
	v_pk_fma_f32 v[62:63], v[102:103], s[86:87], v[62:63] op_sel_hi:[1,0,1]
	s_add_u32 s98, s101, 2
	s_add_u32 s99, s101, 3
	v_readlane_b32 s84, v152, s98
	v_readlane_b32 s86, v152, s99
	s_waitcnt vmcnt(6)
	v_cvt_pk_f32_fp8_e32 v[96:97], v72
	v_cvt_pk_f32_fp8_sdwa v[98:99], v72 src0_sel:WORD_1
	v_cvt_pk_f32_fp8_e32 v[100:101], v76
	v_cvt_pk_f32_fp8_sdwa v[102:103], v76 src0_sel:WORD_1
	v_pk_fma_f32 v[48:49], v[96:97], s[84:85], v[48:49] op_sel_hi:[1,0,1]
	v_pk_fma_f32 v[50:51], v[98:99], s[84:85], v[50:51] op_sel_hi:[1,0,1]
	v_pk_fma_f32 v[48:49], v[100:101], s[86:87], v[48:49] op_sel_hi:[1,0,1]
	v_pk_fma_f32 v[50:51], v[102:103], s[86:87], v[50:51] op_sel_hi:[1,0,1]
	v_cvt_pk_f32_fp8_e32 v[96:97], v73
	v_cvt_pk_f32_fp8_sdwa v[98:99], v73 src0_sel:WORD_1
	v_cvt_pk_f32_fp8_e32 v[100:101], v77
	v_cvt_pk_f32_fp8_sdwa v[102:103], v77 src0_sel:WORD_1
	v_pk_fma_f32 v[52:53], v[96:97], s[84:85], v[52:53] op_sel_hi:[1,0,1]
	v_pk_fma_f32 v[54:55], v[98:99], s[84:85], v[54:55] op_sel_hi:[1,0,1]
	v_pk_fma_f32 v[52:53], v[100:101], s[86:87], v[52:53] op_sel_hi:[1,0,1]
	v_pk_fma_f32 v[54:55], v[102:103], s[86:87], v[54:55] op_sel_hi:[1,0,1]
	v_cvt_pk_f32_fp8_e32 v[96:97], v74
	v_cvt_pk_f32_fp8_sdwa v[98:99], v74 src0_sel:WORD_1
	v_cvt_pk_f32_fp8_e32 v[100:101], v78
	v_cvt_pk_f32_fp8_sdwa v[102:103], v78 src0_sel:WORD_1
	v_pk_fma_f32 v[56:57], v[96:97], s[84:85], v[56:57] op_sel_hi:[1,0,1]
	v_pk_fma_f32 v[58:59], v[98:99], s[84:85], v[58:59] op_sel_hi:[1,0,1]
	v_pk_fma_f32 v[56:57], v[100:101], s[86:87], v[56:57] op_sel_hi:[1,0,1]
	v_pk_fma_f32 v[58:59], v[102:103], s[86:87], v[58:59] op_sel_hi:[1,0,1]
	v_cvt_pk_f32_fp8_e32 v[96:97], v75
	v_cvt_pk_f32_fp8_sdwa v[98:99], v75 src0_sel:WORD_1
	v_cvt_pk_f32_fp8_e32 v[100:101], v79
	v_cvt_pk_f32_fp8_sdwa v[102:103], v79 src0_sel:WORD_1
	global_load_dwordx4 v[72:75], v136, s[80:81]
	global_load_dwordx4 v[76:79], v137, s[80:81]
	v_pk_fma_f32 v[60:61], v[96:97], s[84:85], v[60:61] op_sel_hi:[1,0,1]
	v_pk_fma_f32 v[62:63], v[98:99], s[84:85], v[62:63] op_sel_hi:[1,0,1]
	v_pk_fma_f32 v[60:61], v[100:101], s[86:87], v[60:61] op_sel_hi:[1,0,1]
	v_pk_fma_f32 v[62:63], v[102:103], s[86:87], v[62:63] op_sel_hi:[1,0,1]
	s_add_u32 s98, s101, 4
	s_add_u32 s99, s101, 5
	v_readlane_b32 s84, v152, s98
	v_readlane_b32 s86, v152, s99
	s_waitcnt vmcnt(6)
; #define PG_ISSUE(BUF, TAB, e0_) do { const int isrc_ = ((e0_) < 64) ? myi0 : myi1; \
;       _Pragma("unroll") for (int e = 0; e < 8; ++e) { const int idx_ = __builtin_amdgcn_readlane(isrc_, ((e0_) + e) & 63); \
;         BUF[e] = *(const u32x4*)((TAB) + (size_t)idx_ * 1024 + lane * 16); } } while (0)
; DEV void peer_gather(const Params& P, int l, int m0, const int* idxs, const float* gs) {
;     ...
;     PG_ISSUE(b0, U, 0);
; #pragma nounroll
;     for (int e0 = 0; e0 < 128; e0 += 16) {
;       PG_ISSUE(b1, U, e0 + 8);
;       PG_U8(b0, 0, e0);
;       if (e0 + 16 < 128) PG_ISSUE(b0, U, e0 + 16); else PG_ISSUE(b0, V, 0);
;       PG_U8(b1, 0, e0 + 8);
;     }
;     float* hrow = P.out + tok * DM + lane * 16;
;     f32x4 hv[4];
; #pragma unroll
;     for (int q = 0; q < 4; ++q) hv[q] = *(const f32x4*)(hrow + 4 * q);
;     if (i + 1 < 16) {
;       const int tn = tt + 1;
;       nxa = *(const u32x4*)(hn + (size_t)(m0 + tn) * DM + lane * 16); nxb = *(const u32x4*)(hn + (size_t)(m0 + tn) * DM + lane * 16 + 8);
;       ni0 = idxs[tn * 128 + lane]; ni1 = idxs[tn * 128 + 64 + lane]; ng0 = gs[tn * 128 + lane]; ng1 = gs[tn * 128 + 64 + lane];
;     }
; #pragma nounroll
;     for (int e0 = 0; e0 < 128; e0 += 16) {
;       PG_ISSUE(b1, V, e0 + 8);
;       if (e0 == 64 && i + 1 < 16) sort_lists(lane, ni0, ni1, ng0, ng1);
;       PG_V16(b0, e0);
;       if (e0 + 16 < 128) PG_ISSUE(b0, V, e0 + 16);
;       PG_V16(b1, e0 + 8);
;     }
	v_cvt_pk_f32_fp8_e32 v[96:97], v80
	v_cvt_pk_f32_fp8_sdwa v[98:99], v80 src0_sel:WORD_1
	v_cvt_pk_f32_fp8_e32 v[100:101], v84
	v_cvt_pk_f32_fp8_sdwa v[102:103], v84 src0_sel:WORD_1
	v_pk_fma_f32 v[48:49], v[96:97], s[84:85], v[48:49] op_sel_hi:[1,0,1]
	v_pk_fma_f32 v[50:51], v[98:99], s[84:85], v[50:51] op_sel_hi:[1,0,1]
	v_pk_fma_f32 v[48:49], v[100:101], s[86:87], v[48:49] op_sel_hi:[1,0,1]
	v_pk_fma_f32 v[50:51], v[102:103], s[86:87], v[50:51] op_sel_hi:[1,0,1]
	v_cvt_pk_f32_fp8_e32 v[96:97], v81
	v_cvt_pk_f32_fp8_sdwa v[98:99], v81 src0_sel:WORD_1
	v_cvt_pk_f32_fp8_e32 v[100:101], v85
	v_cvt_pk_f32_fp8_sdwa v[102:103], v85 src0_sel:WORD_1
	v_pk_fma_f32 v[52:53], v[96:97], s[84:85], v[52:53] op_sel_hi:[1,0,1]
	v_pk_fma_f32 v[54:55], v[98:99], s[84:85], v[54:55] op_sel_hi:[1,0,1]
	v_pk_fma_f32 v[52:53], v[100:101], s[86:87], v[52:53] op_sel_hi:[1,0,1]
	v_pk_fma_f32 v[54:55], v[102:103], s[86:87], v[54:55] op_sel_hi:[1,0,1]
	v_cvt_pk_f32_fp8_e32 v[96:97], v82
	v_cvt_pk_f32_fp8_sdwa v[98:99], v82 src0_sel:WORD_1
	v_cvt_pk_f32_fp8_e32 v[100:101], v86
	v_cvt_pk_f32_fp8_sdwa v[102:103], v86 src0_sel:WORD_1
	v_pk_fma_f32 v[56:57], v[96:97], s[84:85], v[56:57] op_sel_hi:[1,0,1]
	v_pk_fma_f32 v[58:59], v[98:99], s[84:85], v[58:59] op_sel_hi:[1,0,1]
	v_pk_fma_f32 v[56:57], v[100:101], s[86:87], v[56:57] op_sel_hi:[1,0,1]
	v_pk_fma_f32 v[58:59], v[102:103], s[86:87], v[58:59] op_sel_hi:[1,0,1]
	v_cvt_pk_f32_fp8_e32 v[96:97], v83
	v_cvt_pk_f32_fp8_sdwa v[98:99], v83 src0_sel:WORD_1
	v_cvt_pk_f32_fp8_e32 v[100:101], v87
	v_cvt_pk_f32_fp8_sdwa v[102:103], v87 src0_sel:WORD_1
	global_load_dwordx4 v[80:83], v138, s[80:81]
	global_load_dwordx4 v[84:87], v139, s[80:81]
	v_pk_fma_f32 v[60:61], v[96:97], s[84:85], v[60:61] op_sel_hi:[1,0,1]
	v_pk_fma_f32 v[62:63], v[98:99], s[84:85], v[62:63] op_sel_hi:[1,0,1]
	v_pk_fma_f32 v[60:61], v[100:101], s[86:87], v[60:61] op_sel_hi:[1,0,1]
	v_pk_fma_f32 v[62:63], v[102:103], s[86:87], v[62:63] op_sel_hi:[1,0,1]
	s_add_u32 s98, s101, 6
	s_add_u32 s99, s101, 7
	v_readlane_b32 s84, v152, s98
	v_readlane_b32 s86, v152, s99
	s_waitcnt vmcnt(6)
	v_cvt_pk_f32_fp8_e32 v[96:97], v88
	v_cvt_pk_f32_fp8_sdwa v[98:99], v88 src0_sel:WORD_1
	v_cvt_pk_f32_fp8_e32 v[100:101], v92
	v_cvt_pk_f32_fp8_sdwa v[102:103], v92 src0_sel:WORD_1
	v_pk_fma_f32 v[48:49], v[96:97], s[84:85], v[48:49] op_sel_hi:[1,0,1]
	v_pk_fma_f32 v[50:51], v[98:99], s[84:85], v[50:51] op_sel_hi:[1,0,1]
	v_pk_fma_f32 v[48:49], v[100:101], s[86:87], v[48:49] op_sel_hi:[1,0,1]
	v_pk_fma_f32 v[50:51], v[102:103], s[86:87], v[50:51] op_sel_hi:[1,0,1]
	v_cvt_pk_f32_fp8_e32 v[96:97], v89
	v_cvt_pk_f32_fp8_sdwa v[98:99], v89 src0_sel:WORD_1
	v_cvt_pk_f32_fp8_e32 v[100:101], v93
	v_cvt_pk_f32_fp8_sdwa v[102:103], v93 src0_sel:WORD_1
	v_pk_fma_f32 v[52:53], v[96:97], s[84:85], v[52:53] op_sel_hi:[1,0,1]
	v_pk_fma_f32 v[54:55], v[98:99], s[84:85], v[54:55] op_sel_hi:[1,0,1]
	v_pk_fma_f32 v[52:53], v[100:101], s[86:87], v[52:53] op_sel_hi:[1,0,1]
	v_pk_fma_f32 v[54:55], v[102:103], s[86:87], v[54:55] op_sel_hi:[1,0,1]
	v_cvt_pk_f32_fp8_e32 v[96:97], v90
	v_cvt_pk_f32_fp8_sdwa v[98:99], v90 src0_sel:WORD_1
	v_cvt_pk_f32_fp8_e32 v[100:101], v94
	v_cvt_pk_f32_fp8_sdwa v[102:103], v94 src0_sel:WORD_1
	v_pk_fma_f32 v[56:57], v[96:97], s[84:85], v[56:57] op_sel_hi:[1,0,1]
	v_pk_fma_f32 v[58:59], v[98:99], s[84:85], v[58:59] op_sel_hi:[1,0,1]
	v_pk_fma_f32 v[56:57], v[100:101], s[86:87], v[56:57] op_sel_hi:[1,0,1]
	v_pk_fma_f32 v[58:59], v[102:103], s[86:87], v[58:59] op_sel_hi:[1,0,1]
	v_cvt_pk_f32_fp8_e32 v[96:97], v91
	v_cvt_pk_f32_fp8_sdwa v[98:99], v91 src0_sel:WORD_1
	v_cvt_pk_f32_fp8_e32 v[100:101], v95
	v_cvt_pk_f32_fp8_sdwa v[102:103], v95 src0_sel:WORD_1
	global_load_dwordx4 v[88:91], v140, s[80:81]
	global_load_dwordx4 v[92:95], v141, s[80:81]
	v_pk_fma_f32 v[60:61], v[96:97], s[84:85], v[60:61] op_sel_hi:[1,0,1]
	v_pk_fma_f32 v[62:63], v[98:99], s[84:85], v[62:63] op_sel_hi:[1,0,1]
	v_pk_fma_f32 v[60:61], v[100:101], s[86:87], v[60:61] op_sel_hi:[1,0,1]
	v_pk_fma_f32 v[62:63], v[102:103], s[86:87], v[62:63] op_sel_hi:[1,0,1]
	s_add_u32 s100, s100, 1
	s_add_u32 s101, s101, 8
	s_and_b32 s101, s101, 63
	s_cmp_lt_u32 s100, 16
	s_cbranch_scc1 .Lpg0_Vloop
	s_waitcnt vmcnt(0)
	v_readfirstlane_b32 s82, v132
	v_readfirstlane_b32 s83, v133
	s_nop 4
	s_add_u32 s98, s3, 0
	s_lshl_b32 s99, s98, 12
	v_lshl_add_u32 v116, v249, 6, s99
	global_load_dwordx4 v[64:67], v116, s[82:83] offset:0
	global_load_dwordx4 v[68:71], v116, s[82:83] offset:16
	global_load_dwordx4 v[72:75], v116, s[82:83] offset:32
	global_load_dwordx4 v[76:79], v116, s[82:83] offset:48
	v_readfirstlane_b32 s88, v130
	v_readfirstlane_b32 s89, v131
	s_nop 4
	v_lshlrev_b32_e32 v117, 6, v249
	global_load_dwordx4 v[80:83], v117, s[88:89] offset:0
	global_load_dwordx4 v[84:87], v117, s[88:89] offset:16
	global_load_dwordx4 v[88:91], v117, s[88:89] offset:32
	global_load_dwordx4 v[92:95], v117, s[88:89] offset:48
	s_mov_b32 s90, 0x3c800000
	s_waitcnt vmcnt(4)
; DEV unsigned pk2(float lo, float hi) { f32x2_t v = {lo, hi}; bf16x2_t b = __builtin_convertvector(v, bf16x2_t); return __builtin_bit_cast(unsigned, b); }
; #define PG_ISSUE(BUF, TAB, e0_) do { const int isrc_ = ((e0_) < 64) ? myi0 : myi1; \
;       _Pragma("unroll") for (int e = 0; e < 8; ++e) { const int idx_ = __builtin_amdgcn_readlane(isrc_, ((e0_) + e) & 63); \
;         BUF[e] = *(const u32x4*)((TAB) + (size_t)idx_ * 1024 + lane * 16); } } while (0)
; DEV void peer_gather(const Params& P, int l, int m0, const int* idxs, const float* gs) {
;     ...
;     float* hrow = P.out + tok * DM + lane * 16;
;     f32x4 hv[4];
; #pragma unroll
;     for (int q = 0; q < 4; ++q) hv[q] = *(const f32x4*)(hrow + 4 * q);
;     if (i + 1 < 16) {
;       const int tn = tt + 1;
;       nxa = *(const u32x4*)(hn + (size_t)(m0 + tn) * DM + lane * 16); nxb = *(const u32x4*)(hn + (size_t)(m0 + tn) * DM + lane * 16 + 8);
;       ni0 = idxs[tn * 128 + lane]; ni1 = idxs[tn * 128 + 64 + lane]; ng0 = gs[tn * 128 + lane]; ng1 = gs[tn * 128 + 64 + lane];
;     }
; #pragma nounroll
;     for (int e0 = 0; e0 < 128; e0 += 16) {
;       PG_ISSUE(b1, V, e0 + 8);
;       if (e0 == 64 && i + 1 < 16) sort_lists(lane, ni0, ni1, ng0, ng1);
;       PG_V16(b0, e0);
;       if (e0 + 16 < 128) PG_ISSUE(b0, V, e0 + 16);
;       PG_V16(b1, e0 + 8);
;     }
;     ...
;     float ss = 0.f;
; #pragma unroll
;     for (int q = 0; q < 4; ++q) {
;       hv[q][0] += acc[2 * q][0] * TAB_INV; hv[q][1] += acc[2 * q][1] * TAB_INV; hv[q][2] += acc[2 * q + 1][0] * TAB_INV; hv[q][3] += acc[2 * q + 1][1] * TAB_INV;
;       ss += hv[q][0] * hv[q][0] + hv[q][1] * hv[q][1] + hv[q][2] * hv[q][2] + hv[q][3] * hv[q][3];
;       *(f32x4*)(hrow + 4 * q) = hv[q];
;     }
;     const float rstd = rsqrtf(wave_sum(ss) * (1.f / DM) + EPS);
;     u32x4 oa, ob;
; #pragma unroll
;     for (int q = 0; q < 4; ++q) {
;       const f32x4 g = *(const f32x4*)(gp + lane * 16 + 4 * q);
;       const unsigned p0 = pk2(hv[q][0] * rstd * g[0], hv[q][1] * rstd * g[1]), p1 = pk2(hv[q][2] * rstd * g[2], hv[q][3] * rstd * g[3]);
;       if (q < 2) { oa[2 * q] = p0; oa[2 * q + 1] = p1; } else { ob[2 * (q - 2)] = p0; ob[2 * (q - 2) + 1] = p1; }
;     }
;     *(u32x4*)(hn + tok * DM + lane * 16) = oa; *(u32x4*)(hn + tok * DM + lane * 16 + 8) = ob;
	v_pk_fma_f32 v[64:65], v[0:1], s[90:91], v[64:65] op_sel_hi:[1,0,1]
	v_pk_fma_f32 v[66:67], v[2:3], s[90:91], v[66:67] op_sel_hi:[1,0,1]
	v_pk_fma_f32 v[68:69], v[4:5], s[90:91], v[68:69] op_sel_hi:[1,0,1]
	v_pk_fma_f32 v[70:71], v[6:7], s[90:91], v[70:71] op_sel_hi:[1,0,1]
	v_pk_fma_f32 v[72:73], v[8:9], s[90:91], v[72:73] op_sel_hi:[1,0,1]
	v_pk_fma_f32 v[74:75], v[10:11], s[90:91], v[74:75] op_sel_hi:[1,0,1]
	v_pk_fma_f32 v[76:77], v[12:13], s[90:91], v[76:77] op_sel_hi:[1,0,1]
	v_pk_fma_f32 v[78:79], v[14:15], s[90:91], v[78:79] op_sel_hi:[1,0,1]
	global_store_dwordx4 v116, v[64:67], s[82:83] offset:0
	global_store_dwordx4 v116, v[68:71], s[82:83] offset:16
	global_store_dwordx4 v116, v[72:75], s[82:83] offset:32
	global_store_dwordx4 v116, v[76:79], s[82:83] offset:48
	v_pk_mul_f32 v[96:97], v[64:65], v[64:65]
	v_pk_fma_f32 v[96:97], v[66:67], v[66:67], v[96:97]
	v_pk_fma_f32 v[96:97], v[68:69], v[68:69], v[96:97]
	v_pk_fma_f32 v[96:97], v[70:71], v[70:71], v[96:97]
	v_pk_fma_f32 v[96:97], v[72:73], v[72:73], v[96:97]
	v_pk_fma_f32 v[96:97], v[74:75], v[74:75], v[96:97]
	v_pk_fma_f32 v[96:97], v[76:77], v[76:77], v[96:97]
	v_pk_fma_f32 v[96:97], v[78:79], v[78:79], v[96:97]
	s_nop 0
	v_add_f32_e32 v118, v96, v97
	s_nop 1
	v_add_f32_dpp v118, v118, v118 quad_perm:[1,0,3,2] row_mask:0xf bank_mask:0xf
	s_nop 1
	v_add_f32_dpp v118, v118, v118 quad_perm:[2,3,0,1] row_mask:0xf bank_mask:0xf
	s_nop 1
	v_add_f32_dpp v118, v118, v118 row_half_mirror row_mask:0xf bank_mask:0xf
	s_nop 1
	v_add_f32_dpp v118, v118, v118 row_mirror row_mask:0xf bank_mask:0xf
	v_xor_b32_e32 v119, 64, v252
	ds_bpermute_b32 v119, v119, v118
	s_waitcnt lgkmcnt(0)
	v_add_f32_e32 v118, v118, v119
	v_xor_b32_e32 v119, 128, v252
	ds_bpermute_b32 v119, v119, v118
	s_waitcnt lgkmcnt(0)
	v_add_f32_e32 v118, v118, v119
	v_mov_b32_e32 v119, 0x358637bd
	v_fmac_f32_e32 v119, 0x3a800000, v118
	v_rsq_f32_e32 v98, v119
	s_waitcnt vmcnt(4)
	s_nop 0
	v_pk_mul_f32 v[64:65], v[64:65], v[98:99] op_sel_hi:[1,0]
	v_pk_mul_f32 v[66:67], v[66:67], v[98:99] op_sel_hi:[1,0]
	v_pk_mul_f32 v[68:69], v[68:69], v[98:99] op_sel_hi:[1,0]
	v_pk_mul_f32 v[70:71], v[70:71], v[98:99] op_sel_hi:[1,0]
	v_pk_mul_f32 v[72:73], v[72:73], v[98:99] op_sel_hi:[1,0]
	v_pk_mul_f32 v[74:75], v[74:75], v[98:99] op_sel_hi:[1,0]
	v_pk_mul_f32 v[76:77], v[76:77], v[98:99] op_sel_hi:[1,0]
	v_pk_mul_f32 v[78:79], v[78:79], v[98:99] op_sel_hi:[1,0]
	v_pk_mul_f32 v[64:65], v[80:81], v[64:65]
	v_pk_mul_f32 v[66:67], v[82:83], v[66:67]
	v_pk_mul_f32 v[68:69], v[84:85], v[68:69]
	v_pk_mul_f32 v[70:71], v[86:87], v[70:71]
	v_pk_mul_f32 v[72:73], v[88:89], v[72:73]
	v_pk_mul_f32 v[74:75], v[90:91], v[74:75]
	v_pk_mul_f32 v[76:77], v[92:93], v[76:77]
	v_pk_mul_f32 v[78:79], v[94:95], v[78:79]
	v_cvt_pk_bf16_f32 v80, v64, v65
	v_cvt_pk_bf16_f32 v81, v66, v67
	v_cvt_pk_bf16_f32 v82, v68, v69
	v_cvt_pk_bf16_f32 v83, v70, v71
	v_cvt_pk_bf16_f32 v84, v72, v73
	v_cvt_pk_bf16_f32 v85, v74, v75
	v_cvt_pk_bf16_f32 v86, v76, v77
	v_cvt_pk_bf16_f32 v87, v78, v79
	v_readfirstlane_b32 s82, v128
	v_readfirstlane_b32 s83, v129
	s_nop 4
	s_lshl_b32 s99, s98, 11
	v_lshl_add_u32 v116, v249, 5, s99
	global_store_dwordx4 v116, v[80:83], s[82:83]
	global_store_dwordx4 v116, v[84:87], s[82:83] offset:16
	s_nop 1
	v_readfirstlane_b32 s82, v132
	v_readfirstlane_b32 s83, v133
	s_nop 4
	s_add_u32 s98, s3, 1
	s_lshl_b32 s99, s98, 12
	v_lshl_add_u32 v116, v249, 6, s99
	global_load_dwordx4 v[64:67], v116, s[82:83] offset:0
	global_load_dwordx4 v[68:71], v116, s[82:83] offset:16
	global_load_dwordx4 v[72:75], v116, s[82:83] offset:32
	global_load_dwordx4 v[76:79], v116, s[82:83] offset:48
	v_readfirstlane_b32 s88, v130
	v_readfirstlane_b32 s89, v131
	s_nop 4
	v_lshlrev_b32_e32 v117, 6, v249
	global_load_dwordx4 v[80:83], v117, s[88:89] offset:0
	global_load_dwordx4 v[84:87], v117, s[88:89] offset:16
	global_load_dwordx4 v[88:91], v117, s[88:89] offset:32
	global_load_dwordx4 v[92:95], v117, s[88:89] offset:48
	s_mov_b32 s90, 0x3c800000
	s_waitcnt vmcnt(4)
	v_pk_fma_f32 v[64:65], v[16:17], s[90:91], v[64:65] op_sel_hi:[1,0,1]
	v_pk_fma_f32 v[66:67], v[18:19], s[90:91], v[66:67] op_sel_hi:[1,0,1]
	v_pk_fma_f32 v[68:69], v[20:21], s[90:91], v[68:69] op_sel_hi:[1,0,1]
	v_pk_fma_f32 v[70:71], v[22:23], s[90:91], v[70:71] op_sel_hi:[1,0,1]
	v_pk_fma_f32 v[72:73], v[24:25], s[90:91], v[72:73] op_sel_hi:[1,0,1]
	v_pk_fma_f32 v[74:75], v[26:27], s[90:91], v[74:75] op_sel_hi:[1,0,1]
	v_pk_fma_f32 v[76:77], v[28:29], s[90:91], v[76:77] op_sel_hi:[1,0,1]
	v_pk_fma_f32 v[78:79], v[30:31], s[90:91], v[78:79] op_sel_hi:[1,0,1]
	global_store_dwordx4 v116, v[64:67], s[82:83] offset:0
	global_store_dwordx4 v116, v[68:71], s[82:83] offset:16
	global_store_dwordx4 v116, v[72:75], s[82:83] offset:32
	global_store_dwordx4 v116, v[76:79], s[82:83] offset:48
	v_pk_mul_f32 v[96:97], v[64:65], v[64:65]
	v_pk_fma_f32 v[96:97], v[66:67], v[66:67], v[96:97]
	v_pk_fma_f32 v[96:97], v[68:69], v[68:69], v[96:97]
	v_pk_fma_f32 v[96:97], v[70:71], v[70:71], v[96:97]
	v_pk_fma_f32 v[96:97], v[72:73], v[72:73], v[96:97]
	v_pk_fma_f32 v[96:97], v[74:75], v[74:75], v[96:97]
	v_pk_fma_f32 v[96:97], v[76:77], v[76:77], v[96:97]
	v_pk_fma_f32 v[96:97], v[78:79], v[78:79], v[96:97]
	s_nop 0
	v_add_f32_e32 v118, v96, v97
	s_nop 1
	v_add_f32_dpp v118, v118, v118 quad_perm:[1,0,3,2] row_mask:0xf bank_mask:0xf
	s_nop 1
	v_add_f32_dpp v118, v118, v118 quad_perm:[2,3,0,1] row_mask:0xf bank_mask:0xf
	s_nop 1
	v_add_f32_dpp v118, v118, v118 row_half_mirror row_mask:0xf bank_mask:0xf
	s_nop 1
	v_add_f32_dpp v118, v118, v118 row_mirror row_mask:0xf bank_mask:0xf
	v_xor_b32_e32 v119, 64, v252
	ds_bpermute_b32 v119, v119, v118
	s_waitcnt lgkmcnt(0)
; DEV unsigned pk2(float lo, float hi) { f32x2_t v = {lo, hi}; bf16x2_t b = __builtin_convertvector(v, bf16x2_t); return __builtin_bit_cast(unsigned, b); }
; #define PG_ISSUE(BUF, TAB, e0_) do { const int isrc_ = ((e0_) < 64) ? myi0 : myi1; \
;       _Pragma("unroll") for (int e = 0; e < 8; ++e) { const int idx_ = __builtin_amdgcn_readlane(isrc_, ((e0_) + e) & 63); \
;         BUF[e] = *(const u32x4*)((TAB) + (size_t)idx_ * 1024 + lane * 16); } } while (0)
; DEV void peer_gather(const Params& P, int l, int m0, const int* idxs, const float* gs) {
;     ...
;     float* hrow = P.out + tok * DM + lane * 16;
;     f32x4 hv[4];
; #pragma unroll
;     for (int q = 0; q < 4; ++q) hv[q] = *(const f32x4*)(hrow + 4 * q);
;     if (i + 1 < 16) {
;       const int tn = tt + 1;
;       nxa = *(const u32x4*)(hn + (size_t)(m0 + tn) * DM + lane * 16); nxb = *(const u32x4*)(hn + (size_t)(m0 + tn) * DM + lane * 16 + 8);
;       ni0 = idxs[tn * 128 + lane]; ni1 = idxs[tn * 128 + 64 + lane]; ng0 = gs[tn * 128 + lane]; ng1 = gs[tn * 128 + 64 + lane];
;     }
; #pragma nounroll
;     for (int e0 = 0; e0 < 128; e0 += 16) {
;       PG_ISSUE(b1, V, e0 + 8);
;       if (e0 == 64 && i + 1 < 16) sort_lists(lane, ni0, ni1, ng0, ng1);
;       PG_V16(b0, e0);
;       if (e0 + 16 < 128) PG_ISSUE(b0, V, e0 + 16);
;       PG_V16(b1, e0 + 8);
;     }
;     ...
;     float ss = 0.f;
; #pragma unroll
;     for (int q = 0; q < 4; ++q) {
;       hv[q][0] += acc[2 * q][0] * TAB_INV; hv[q][1] += acc[2 * q][1] * TAB_INV; hv[q][2] += acc[2 * q + 1][0] * TAB_INV; hv[q][3] += acc[2 * q + 1][1] * TAB_INV;
;       ss += hv[q][0] * hv[q][0] + hv[q][1] * hv[q][1] + hv[q][2] * hv[q][2] + hv[q][3] * hv[q][3];
;       *(f32x4*)(hrow + 4 * q) = hv[q];
;     }
;     const float rstd = rsqrtf(wave_sum(ss) * (1.f / DM) + EPS);
;     u32x4 oa, ob;
; #pragma unroll
;     for (int q = 0; q < 4; ++q) {
;       const f32x4 g = *(const f32x4*)(gp + lane * 16 + 4 * q);
;       const unsigned p0 = pk2(hv[q][0] * rstd * g[0], hv[q][1] * rstd * g[1]), p1 = pk2(hv[q][2] * rstd * g[2], hv[q][3] * rstd * g[3]);
;       if (q < 2) { oa[2 * q] = p0; oa[2 * q + 1] = p1; } else { ob[2 * (q - 2)] = p0; ob[2 * (q - 2) + 1] = p1; }
;     }
;     *(u32x4*)(hn + tok * DM + lane * 16) = oa; *(u32x4*)(hn + tok * DM + lane * 16 + 8) = ob;
	v_add_f32_e32 v118, v118, v119
	v_xor_b32_e32 v119, 128, v252
	ds_bpermute_b32 v119, v119, v118
	s_waitcnt lgkmcnt(0)
	v_add_f32_e32 v118, v118, v119
	v_mov_b32_e32 v119, 0x358637bd
	v_fmac_f32_e32 v119, 0x3a800000, v118
	v_rsq_f32_e32 v98, v119
	s_waitcnt vmcnt(4)
	s_nop 0
	v_pk_mul_f32 v[64:65], v[64:65], v[98:99] op_sel_hi:[1,0]
	v_pk_mul_f32 v[66:67], v[66:67], v[98:99] op_sel_hi:[1,0]
	v_pk_mul_f32 v[68:69], v[68:69], v[98:99] op_sel_hi:[1,0]
	v_pk_mul_f32 v[70:71], v[70:71], v[98:99] op_sel_hi:[1,0]
	v_pk_mul_f32 v[72:73], v[72:73], v[98:99] op_sel_hi:[1,0]
	v_pk_mul_f32 v[74:75], v[74:75], v[98:99] op_sel_hi:[1,0]
	v_pk_mul_f32 v[76:77], v[76:77], v[98:99] op_sel_hi:[1,0]
	v_pk_mul_f32 v[78:79], v[78:79], v[98:99] op_sel_hi:[1,0]
	v_pk_mul_f32 v[64:65], v[80:81], v[64:65]
	v_pk_mul_f32 v[66:67], v[82:83], v[66:67]
	v_pk_mul_f32 v[68:69], v[84:85], v[68:69]
	v_pk_mul_f32 v[70:71], v[86:87], v[70:71]
	v_pk_mul_f32 v[72:73], v[88:89], v[72:73]
	v_pk_mul_f32 v[74:75], v[90:91], v[74:75]
	v_pk_mul_f32 v[76:77], v[92:93], v[76:77]
	v_pk_mul_f32 v[78:79], v[94:95], v[78:79]
	v_cvt_pk_bf16_f32 v80, v64, v65
	v_cvt_pk_bf16_f32 v81, v66, v67
	v_cvt_pk_bf16_f32 v82, v68, v69
	v_cvt_pk_bf16_f32 v83, v70, v71
	v_cvt_pk_bf16_f32 v84, v72, v73
	v_cvt_pk_bf16_f32 v85, v74, v75
	v_cvt_pk_bf16_f32 v86, v76, v77
	v_cvt_pk_bf16_f32 v87, v78, v79
	v_readfirstlane_b32 s82, v128
	v_readfirstlane_b32 s83, v129
	s_nop 4
	s_lshl_b32 s99, s98, 11
	v_lshl_add_u32 v116, v249, 5, s99
	global_store_dwordx4 v116, v[80:83], s[82:83]
	global_store_dwordx4 v116, v[84:87], s[82:83] offset:16
	s_nop 1
	v_readfirstlane_b32 s82, v132
	v_readfirstlane_b32 s83, v133
	s_nop 4
	s_add_u32 s98, s3, 2
	s_lshl_b32 s99, s98, 12
	v_lshl_add_u32 v116, v249, 6, s99
	global_load_dwordx4 v[64:67], v116, s[82:83] offset:0
	global_load_dwordx4 v[68:71], v116, s[82:83] offset:16
	global_load_dwordx4 v[72:75], v116, s[82:83] offset:32
	global_load_dwordx4 v[76:79], v116, s[82:83] offset:48
	v_readfirstlane_b32 s88, v130
	v_readfirstlane_b32 s89, v131
	s_nop 4
	v_lshlrev_b32_e32 v117, 6, v249
	global_load_dwordx4 v[80:83], v117, s[88:89] offset:0
	global_load_dwordx4 v[84:87], v117, s[88:89] offset:16
	global_load_dwordx4 v[88:91], v117, s[88:89] offset:32
	global_load_dwordx4 v[92:95], v117, s[88:89] offset:48
	s_mov_b32 s90, 0x3c800000
	s_waitcnt vmcnt(4)
	v_pk_fma_f32 v[64:65], v[32:33], s[90:91], v[64:65] op_sel_hi:[1,0,1]
	v_pk_fma_f32 v[66:67], v[34:35], s[90:91], v[66:67] op_sel_hi:[1,0,1]
	v_pk_fma_f32 v[68:69], v[36:37], s[90:91], v[68:69] op_sel_hi:[1,0,1]
	v_pk_fma_f32 v[70:71], v[38:39], s[90:91], v[70:71] op_sel_hi:[1,0,1]
	v_pk_fma_f32 v[72:73], v[40:41], s[90:91], v[72:73] op_sel_hi:[1,0,1]
	v_pk_fma_f32 v[74:75], v[42:43], s[90:91], v[74:75] op_sel_hi:[1,0,1]
	v_pk_fma_f32 v[76:77], v[44:45], s[90:91], v[76:77] op_sel_hi:[1,0,1]
	v_pk_fma_f32 v[78:79], v[46:47], s[90:91], v[78:79] op_sel_hi:[1,0,1]
	global_store_dwordx4 v116, v[64:67], s[82:83] offset:0
	global_store_dwordx4 v116, v[68:71], s[82:83] offset:16
	global_store_dwordx4 v116, v[72:75], s[82:83] offset:32
	global_store_dwordx4 v116, v[76:79], s[82:83] offset:48
	v_pk_mul_f32 v[96:97], v[64:65], v[64:65]
	v_pk_fma_f32 v[96:97], v[66:67], v[66:67], v[96:97]
	v_pk_fma_f32 v[96:97], v[68:69], v[68:69], v[96:97]
	v_pk_fma_f32 v[96:97], v[70:71], v[70:71], v[96:97]
	v_pk_fma_f32 v[96:97], v[72:73], v[72:73], v[96:97]
	v_pk_fma_f32 v[96:97], v[74:75], v[74:75], v[96:97]
	v_pk_fma_f32 v[96:97], v[76:77], v[76:77], v[96:97]
	v_pk_fma_f32 v[96:97], v[78:79], v[78:79], v[96:97]
	s_nop 0
	v_add_f32_e32 v118, v96, v97
	s_nop 1
	v_add_f32_dpp v118, v118, v118 quad_perm:[1,0,3,2] row_mask:0xf bank_mask:0xf
	s_nop 1
	v_add_f32_dpp v118, v118, v118 quad_perm:[2,3,0,1] row_mask:0xf bank_mask:0xf
	s_nop 1
	v_add_f32_dpp v118, v118, v118 row_half_mirror row_mask:0xf bank_mask:0xf
	s_nop 1
	v_add_f32_dpp v118, v118, v118 row_mirror row_mask:0xf bank_mask:0xf
	v_xor_b32_e32 v119, 64, v252
	ds_bpermute_b32 v119, v119, v118
	s_waitcnt lgkmcnt(0)
	v_add_f32_e32 v118, v118, v119
	v_xor_b32_e32 v119, 128, v252
	ds_bpermute_b32 v119, v119, v118
	s_waitcnt lgkmcnt(0)
	v_add_f32_e32 v118, v118, v119
	v_mov_b32_e32 v119, 0x358637bd
	v_fmac_f32_e32 v119, 0x3a800000, v118
	v_rsq_f32_e32 v98, v119
	s_waitcnt vmcnt(4)
; DEV unsigned pk2(float lo, float hi) { f32x2_t v = {lo, hi}; bf16x2_t b = __builtin_convertvector(v, bf16x2_t); return __builtin_bit_cast(unsigned, b); }
; #define PG_ISSUE(BUF, TAB, e0_) do { const int isrc_ = ((e0_) < 64) ? myi0 : myi1; \
;       _Pragma("unroll") for (int e = 0; e < 8; ++e) { const int idx_ = __builtin_amdgcn_readlane(isrc_, ((e0_) + e) & 63); \
;         BUF[e] = *(const u32x4*)((TAB) + (size_t)idx_ * 1024 + lane * 16); } } while (0)
; DEV void peer_gather(const Params& P, int l, int m0, const int* idxs, const float* gs) {
;     ...
;     float* hrow = P.out + tok * DM + lane * 16;
;     f32x4 hv[4];
; #pragma unroll
;     for (int q = 0; q < 4; ++q) hv[q] = *(const f32x4*)(hrow + 4 * q);
;     if (i + 1 < 16) {
;       const int tn = tt + 1;
;       nxa = *(const u32x4*)(hn + (size_t)(m0 + tn) * DM + lane * 16); nxb = *(const u32x4*)(hn + (size_t)(m0 + tn) * DM + lane * 16 + 8);
;       ni0 = idxs[tn * 128 + lane]; ni1 = idxs[tn * 128 + 64 + lane]; ng0 = gs[tn * 128 + lane]; ng1 = gs[tn * 128 + 64 + lane];
;     }
; #pragma nounroll
;     for (int e0 = 0; e0 < 128; e0 += 16) {
;       PG_ISSUE(b1, V, e0 + 8);
;       if (e0 == 64 && i + 1 < 16) sort_lists(lane, ni0, ni1, ng0, ng1);
;       PG_V16(b0, e0);
;       if (e0 + 16 < 128) PG_ISSUE(b0, V, e0 + 16);
;       PG_V16(b1, e0 + 8);
;     }
;     ...
;     float ss = 0.f;
; #pragma unroll
;     for (int q = 0; q < 4; ++q) {
;       hv[q][0] += acc[2 * q][0] * TAB_INV; hv[q][1] += acc[2 * q][1] * TAB_INV; hv[q][2] += acc[2 * q + 1][0] * TAB_INV; hv[q][3] += acc[2 * q + 1][1] * TAB_INV;
;       ss += hv[q][0] * hv[q][0] + hv[q][1] * hv[q][1] + hv[q][2] * hv[q][2] + hv[q][3] * hv[q][3];
;       *(f32x4*)(hrow + 4 * q) = hv[q];
;     }
;     const float rstd = rsqrtf(wave_sum(ss) * (1.f / DM) + EPS);
;     u32x4 oa, ob;
; #pragma unroll
;     for (int q = 0; q < 4; ++q) {
;       const f32x4 g = *(const f32x4*)(gp + lane * 16 + 4 * q);
;       const unsigned p0 = pk2(hv[q][0] * rstd * g[0], hv[q][1] * rstd * g[1]), p1 = pk2(hv[q][2] * rstd * g[2], hv[q][3] * rstd * g[3]);
;       if (q < 2) { oa[2 * q] = p0; oa[2 * q + 1] = p1; } else { ob[2 * (q - 2)] = p0; ob[2 * (q - 2) + 1] = p1; }
;     }
;     *(u32x4*)(hn + tok * DM + lane * 16) = oa; *(u32x4*)(hn + tok * DM + lane * 16 + 8) = ob;
	s_nop 0
	v_pk_mul_f32 v[64:65], v[64:65], v[98:99] op_sel_hi:[1,0]
	v_pk_mul_f32 v[66:67], v[66:67], v[98:99] op_sel_hi:[1,0]
	v_pk_mul_f32 v[68:69], v[68:69], v[98:99] op_sel_hi:[1,0]
	v_pk_mul_f32 v[70:71], v[70:71], v[98:99] op_sel_hi:[1,0]
	v_pk_mul_f32 v[72:73], v[72:73], v[98:99] op_sel_hi:[1,0]
	v_pk_mul_f32 v[74:75], v[74:75], v[98:99] op_sel_hi:[1,0]
	v_pk_mul_f32 v[76:77], v[76:77], v[98:99] op_sel_hi:[1,0]
	v_pk_mul_f32 v[78:79], v[78:79], v[98:99] op_sel_hi:[1,0]
	v_pk_mul_f32 v[64:65], v[80:81], v[64:65]
	v_pk_mul_f32 v[66:67], v[82:83], v[66:67]
	v_pk_mul_f32 v[68:69], v[84:85], v[68:69]
	v_pk_mul_f32 v[70:71], v[86:87], v[70:71]
	v_pk_mul_f32 v[72:73], v[88:89], v[72:73]
	v_pk_mul_f32 v[74:75], v[90:91], v[74:75]
	v_pk_mul_f32 v[76:77], v[92:93], v[76:77]
	v_pk_mul_f32 v[78:79], v[94:95], v[78:79]
	v_cvt_pk_bf16_f32 v80, v64, v65
	v_cvt_pk_bf16_f32 v81, v66, v67
	v_cvt_pk_bf16_f32 v82, v68, v69
	v_cvt_pk_bf16_f32 v83, v70, v71
	v_cvt_pk_bf16_f32 v84, v72, v73
	v_cvt_pk_bf16_f32 v85, v74, v75
	v_cvt_pk_bf16_f32 v86, v76, v77
	v_cvt_pk_bf16_f32 v87, v78, v79
	v_readfirstlane_b32 s82, v128
	v_readfirstlane_b32 s83, v129
	s_nop 4
	s_lshl_b32 s99, s98, 11
	v_lshl_add_u32 v116, v249, 5, s99
	global_store_dwordx4 v116, v[80:83], s[82:83]
	global_store_dwordx4 v116, v[84:87], s[82:83] offset:16
	s_nop 1
	v_readfirstlane_b32 s82, v132
	v_readfirstlane_b32 s83, v133
	s_nop 4
	s_add_u32 s98, s3, 3
	s_lshl_b32 s99, s98, 12
	v_lshl_add_u32 v116, v249, 6, s99
	global_load_dwordx4 v[64:67], v116, s[82:83] offset:0
	global_load_dwordx4 v[68:71], v116, s[82:83] offset:16
	global_load_dwordx4 v[72:75], v116, s[82:83] offset:32
	global_load_dwordx4 v[76:79], v116, s[82:83] offset:48
	v_readfirstlane_b32 s88, v130
	v_readfirstlane_b32 s89, v131
	s_nop 4
	v_lshlrev_b32_e32 v117, 6, v249
	global_load_dwordx4 v[80:83], v117, s[88:89] offset:0
	global_load_dwordx4 v[84:87], v117, s[88:89] offset:16
	global_load_dwordx4 v[88:91], v117, s[88:89] offset:32
	global_load_dwordx4 v[92:95], v117, s[88:89] offset:48
	s_mov_b32 s90, 0x3c800000
	s_waitcnt vmcnt(4)
	v_pk_fma_f32 v[64:65], v[48:49], s[90:91], v[64:65] op_sel_hi:[1,0,1]
	v_pk_fma_f32 v[66:67], v[50:51], s[90:91], v[66:67] op_sel_hi:[1,0,1]
	v_pk_fma_f32 v[68:69], v[52:53], s[90:91], v[68:69] op_sel_hi:[1,0,1]
	v_pk_fma_f32 v[70:71], v[54:55], s[90:91], v[70:71] op_sel_hi:[1,0,1]
	v_pk_fma_f32 v[72:73], v[56:57], s[90:91], v[72:73] op_sel_hi:[1,0,1]
	v_pk_fma_f32 v[74:75], v[58:59], s[90:91], v[74:75] op_sel_hi:[1,0,1]
	v_pk_fma_f32 v[76:77], v[60:61], s[90:91], v[76:77] op_sel_hi:[1,0,1]
	v_pk_fma_f32 v[78:79], v[62:63], s[90:91], v[78:79] op_sel_hi:[1,0,1]
	global_store_dwordx4 v116, v[64:67], s[82:83] offset:0
	global_store_dwordx4 v116, v[68:71], s[82:83] offset:16
	global_store_dwordx4 v116, v[72:75], s[82:83] offset:32
	global_store_dwordx4 v116, v[76:79], s[82:83] offset:48
	v_pk_mul_f32 v[96:97], v[64:65], v[64:65]
	v_pk_fma_f32 v[96:97], v[66:67], v[66:67], v[96:97]
	v_pk_fma_f32 v[96:97], v[68:69], v[68:69], v[96:97]
	v_pk_fma_f32 v[96:97], v[70:71], v[70:71], v[96:97]
	v_pk_fma_f32 v[96:97], v[72:73], v[72:73], v[96:97]
	v_pk_fma_f32 v[96:97], v[74:75], v[74:75], v[96:97]
	v_pk_fma_f32 v[96:97], v[76:77], v[76:77], v[96:97]
	v_pk_fma_f32 v[96:97], v[78:79], v[78:79], v[96:97]
	s_nop 0
	v_add_f32_e32 v118, v96, v97
	s_nop 1
	v_add_f32_dpp v118, v118, v118 quad_perm:[1,0,3,2] row_mask:0xf bank_mask:0xf
	s_nop 1
	v_add_f32_dpp v118, v118, v118 quad_perm:[2,3,0,1] row_mask:0xf bank_mask:0xf
	s_nop 1
	v_add_f32_dpp v118, v118, v118 row_half_mirror row_mask:0xf bank_mask:0xf
	s_nop 1
	v_add_f32_dpp v118, v118, v118 row_mirror row_mask:0xf bank_mask:0xf
	v_xor_b32_e32 v119, 64, v252
	ds_bpermute_b32 v119, v119, v118
	s_waitcnt lgkmcnt(0)
	v_add_f32_e32 v118, v118, v119
	v_xor_b32_e32 v119, 128, v252
	ds_bpermute_b32 v119, v119, v118
	s_waitcnt lgkmcnt(0)
	v_add_f32_e32 v118, v118, v119
	v_mov_b32_e32 v119, 0x358637bd
	v_fmac_f32_e32 v119, 0x3a800000, v118
	v_rsq_f32_e32 v98, v119
	s_waitcnt vmcnt(4)
	s_nop 0
	v_pk_mul_f32 v[64:65], v[64:65], v[98:99] op_sel_hi:[1,0]
	v_pk_mul_f32 v[66:67], v[66:67], v[98:99] op_sel_hi:[1,0]
	v_pk_mul_f32 v[68:69], v[68:69], v[98:99] op_sel_hi:[1,0]
	v_pk_mul_f32 v[70:71], v[70:71], v[98:99] op_sel_hi:[1,0]
	v_pk_mul_f32 v[72:73], v[72:73], v[98:99] op_sel_hi:[1,0]
	v_pk_mul_f32 v[74:75], v[74:75], v[98:99] op_sel_hi:[1,0]
	v_pk_mul_f32 v[76:77], v[76:77], v[98:99] op_sel_hi:[1,0]
	v_pk_mul_f32 v[78:79], v[78:79], v[98:99] op_sel_hi:[1,0]
	v_pk_mul_f32 v[64:65], v[80:81], v[64:65]
	v_pk_mul_f32 v[66:67], v[82:83], v[66:67]
	v_pk_mul_f32 v[68:69], v[84:85], v[68:69]
	v_pk_mul_f32 v[70:71], v[86:87], v[70:71]
	v_pk_mul_f32 v[72:73], v[88:89], v[72:73]
	v_pk_mul_f32 v[74:75], v[90:91], v[74:75]
	v_pk_mul_f32 v[76:77], v[92:93], v[76:77]
	v_pk_mul_f32 v[78:79], v[94:95], v[78:79]
	v_cvt_pk_bf16_f32 v80, v64, v65
	v_cvt_pk_bf16_f32 v81, v66, v67
	v_cvt_pk_bf16_f32 v82, v68, v69
	v_cvt_pk_bf16_f32 v83, v70, v71
	v_cvt_pk_bf16_f32 v84, v72, v73
	v_cvt_pk_bf16_f32 v85, v74, v75
	v_cvt_pk_bf16_f32 v86, v76, v77
	v_cvt_pk_bf16_f32 v87, v78, v79
	v_readfirstlane_b32 s82, v128
	v_readfirstlane_b32 s83, v129
	s_nop 4
	s_lshl_b32 s99, s98, 11
	v_lshl_add_u32 v116, v249, 5, s99
	global_store_dwordx4 v116, v[80:83], s[82:83]
	global_store_dwordx4 v116, v[84:87], s[82:83] offset:16
	s_nop 1
	s_add_u32 s3, s3, 4
	s_add_u32 s33, s33, 4
	s_add_u32 s2, s2, 1
	s_cmp_lt_u32 s2, 4
	s_cbranch_scc1 .Lpg0_pass
	s_waitcnt vmcnt(0) lgkmcnt(0)
	v_readlane_b32 s90, v231, 30
	v_readlane_b32 s91, v231, 31

; DEV void sort_lists(int lane, int& myi0, int& myi1, float& myg0, float& myg1) {
; #pragma unroll
;     for (int k = 2; k <= 128; k <<= 1) {
; #pragma unroll
;       for (int j = k >> 1; j >= 1; j >>= 1) {
;         if (j == 64) {
;           const bool sw_ = myi1 < myi0;
;           const int ti = sw_ ? myi1 : myi0, tj = sw_ ? myi0 : myi1; const float tg = sw_ ? myg1 : myg0, th = sw_ ? myg0 : myg1;
;           myi0 = ti; myi1 = tj; myg0 = tg; myg1 = th;
;         } else {
;           const bool lower = (lane & j) == 0;
;           {
;             const bool up = (k == 128) ? true : ((k == 64) ? true : ((lane & k) == 0));
;             const int oi = __shfl_xor(myi0, j); const float og = __shfl_xor(myg0, j);
;             const bool take = (lower == up) ? (oi < myi0) : (oi > myi0);
;             myi0 = take ? oi : myi0; myg0 = take ? og : myg0;
;           }
;           {
;             const bool up = (k == 128) ? true : ((k == 64) ? false : ((lane & k) == 0));
;             const int oi = __shfl_xor(myi1, j); const float og = __shfl_xor(myg1, j);
;             const bool take = (lower == up) ? (oi < myi1) : (oi > myi1);
;             myi1 = take ? oi : myi1; myg1 = take ? og : myg1;
;           }
;         }
;       }
;     }
; }
; DEV void peer_gather(const Params& P, int l, int m0, const int* idxs, const float* gs) {
;   const int tid = tid_l(), lane = tid & 63, wid = tid >> 6;
;   const unsigned char* U = P.ws + WS_TAB + (size_t)l * 32 * MB;
;   const unsigned char* V = U + 16 * MB;
;   bf16_t* hn = (bf16_t*)(P.ws + WS_HN);
;   const float* gp = P.norm_ple + l * DM;
;   const int row = lane >> 4, rmap = ((row & 1) << 1) | (row >> 1);
;   u32x4 nxa = *(const u32x4*)(hn + (size_t)(m0 + wid * 16) * DM + lane * 16), nxb = *(const u32x4*)(hn + (size_t)(m0 + wid * 16) * DM + lane * 16 + 8);
;   int ni0 = idxs[(wid * 16) * 128 + lane], ni1 = idxs[(wid * 16) * 128 + 64 + lane];
;   float ng0 = gs[(wid * 16) * 128 + lane], ng1 = gs[(wid * 16) * 128 + 64 + lane];
;   sort_lists(lane, ni0, ni1, ng0, ng1);
; #pragma nounroll
;   for (int i = 0; i < 16; ++i) {
;     const int tt = wid * 16 + i; const size_t tok = (size_t)(m0 + tt);
;     __syncthreads();
;     const u32x4 xa = nxa, xb = nxb;
;     f32x2_t xp[8];
; #pragma unroll
;     for (int q = 0; q < 4; ++q) { xp[q] = (f32x2_t){bflo(xa[q]), bfhi(xa[q])}; xp[4 + q] = (f32x2_t){bflo(xb[q]), bfhi(xb[q])}; }
.LBB0_752:
	s_waitcnt vmcnt(0) lgkmcnt(0)
	v_and_b32_e32 v249, 63, v176
	v_lshlrev_b32_e32 v250, 4, v249
	v_lshlrev_b32_e32 v252, 2, v249
	v_and_b32_e32 v116, 1, v249
	v_lshlrev_b32_e32 v116, 7, v116
	v_and_b32_e32 v117, 2, v249
	v_lshl_or_b32 v116, v117, 5, v116
	v_and_b32_e32 v117, 4, v249
	v_lshl_or_b32 v251, v117, 3, v116
	v_readfirstlane_b32 s33, v176
	s_lshr_b32 s33, s33, 6
	s_lshl_b32 s33, s33, 4
	v_readlane_b32 s3, v231, 15
	s_add_u32 s3, s3, s33
	s_mov_b32 s2, 0
.Lpg1_pass:
	v_readlane_b32 s82, v231, 13
	v_readlane_b32 s83, v231, 14
	s_nop 4
	s_add_u32 s98, s33, 0
	s_lshl_b32 s98, s98, 9
	v_add_u32_e32 v116, s98, v252
	global_load_dword v142, v116, s[82:83]
	global_load_dword v143, v116, s[82:83] offset:256
	s_add_u32 s98, s33, 1
	s_lshl_b32 s98, s98, 9
	v_add_u32_e32 v117, s98, v252
	global_load_dword v144, v117, s[82:83]
	global_load_dword v145, v117, s[82:83] offset:256
	s_add_u32 s98, s33, 2
	s_lshl_b32 s98, s98, 9
	v_add_u32_e32 v118, s98, v252
	global_load_dword v146, v118, s[82:83]
	global_load_dword v147, v118, s[82:83] offset:256
	s_add_u32 s98, s33, 3
	s_lshl_b32 s98, s98, 9
	v_add_u32_e32 v119, s98, v252
	global_load_dword v148, v119, s[82:83]
	global_load_dword v149, v119, s[82:83] offset:256
	v_readfirstlane_b32 s82, v122
	v_readfirstlane_b32 s83, v123
	s_nop 4
	s_add_u32 s98, s3, 0
	s_lshl_b32 s98, s98, 11
	v_lshl_add_u32 v150, v249, 5, s98
	global_load_dwordx4 v[64:67], v150, s[82:83]
	global_load_dwordx4 v[68:71], v150, s[82:83] offset:16
	s_add_u32 s98, s3, 1
	s_lshl_b32 s98, s98, 11
	v_lshl_add_u32 v151, v249, 5, s98
	global_load_dwordx4 v[72:75], v151, s[82:83]
	global_load_dwordx4 v[76:79], v151, s[82:83] offset:16
	s_add_u32 s98, s3, 2
	s_lshl_b32 s98, s98, 11
	v_lshl_add_u32 v150, v249, 5, s98
	global_load_dwordx4 v[80:83], v150, s[82:83]
	global_load_dwordx4 v[84:87], v150, s[82:83] offset:16
	s_add_u32 s98, s3, 3
	s_lshl_b32 s98, s98, 11
	v_lshl_add_u32 v151, v249, 5, s98
	global_load_dwordx4 v[88:91], v151, s[82:83]
	global_load_dwordx4 v[92:95], v151, s[82:83] offset:16
	s_waitcnt vmcnt(0)
	v_lshlrev_b32_e32 v0, 16, v64
	v_and_b32_e32 v1, 0xffff0000, v64
	v_lshlrev_b32_e32 v2, 16, v65
	v_and_b32_e32 v3, 0xffff0000, v65
	v_lshlrev_b32_e32 v4, 16, v66
	v_and_b32_e32 v5, 0xffff0000, v66
	v_lshlrev_b32_e32 v6, 16, v67
	v_and_b32_e32 v7, 0xffff0000, v67
	v_lshlrev_b32_e32 v8, 16, v68
	v_and_b32_e32 v9, 0xffff0000, v68
	v_lshlrev_b32_e32 v10, 16, v69
	v_and_b32_e32 v11, 0xffff0000, v69
	v_lshlrev_b32_e32 v12, 16, v70
	v_and_b32_e32 v13, 0xffff0000, v70
	v_lshlrev_b32_e32 v14, 16, v71
	v_and_b32_e32 v15, 0xffff0000, v71
	v_lshlrev_b32_e32 v16, 16, v72
	v_and_b32_e32 v17, 0xffff0000, v72
	v_lshlrev_b32_e32 v18, 16, v73
	v_and_b32_e32 v19, 0xffff0000, v73
	v_lshlrev_b32_e32 v20, 16, v74
	v_and_b32_e32 v21, 0xffff0000, v74
	v_lshlrev_b32_e32 v22, 16, v75
	v_and_b32_e32 v23, 0xffff0000, v75
	v_lshlrev_b32_e32 v24, 16, v76
	v_and_b32_e32 v25, 0xffff0000, v76
	v_lshlrev_b32_e32 v26, 16, v77
	v_and_b32_e32 v27, 0xffff0000, v77
	v_lshlrev_b32_e32 v28, 16, v78
	v_and_b32_e32 v29, 0xffff0000, v78
	v_lshlrev_b32_e32 v30, 16, v79
	v_and_b32_e32 v31, 0xffff0000, v79
	v_lshlrev_b32_e32 v32, 16, v80
	v_and_b32_e32 v33, 0xffff0000, v80
	v_lshlrev_b32_e32 v34, 16, v81
	v_and_b32_e32 v35, 0xffff0000, v81
	v_lshlrev_b32_e32 v36, 16, v82
	v_and_b32_e32 v37, 0xffff0000, v82
	v_lshlrev_b32_e32 v38, 16, v83
	v_and_b32_e32 v39, 0xffff0000, v83
	v_lshlrev_b32_e32 v40, 16, v84
	v_and_b32_e32 v41, 0xffff0000, v84
	v_lshlrev_b32_e32 v42, 16, v85
	v_and_b32_e32 v43, 0xffff0000, v85
	v_lshlrev_b32_e32 v44, 16, v86
	v_and_b32_e32 v45, 0xffff0000, v86
	v_lshlrev_b32_e32 v46, 16, v87
	v_and_b32_e32 v47, 0xffff0000, v87
	v_lshlrev_b32_e32 v48, 16, v88
	v_and_b32_e32 v49, 0xffff0000, v88
	v_lshlrev_b32_e32 v50, 16, v89
	v_and_b32_e32 v51, 0xffff0000, v89
	v_lshlrev_b32_e32 v52, 16, v90
	v_and_b32_e32 v53, 0xffff0000, v90
	v_lshlrev_b32_e32 v54, 16, v91
	v_and_b32_e32 v55, 0xffff0000, v91
	v_lshlrev_b32_e32 v56, 16, v92
	v_and_b32_e32 v57, 0xffff0000, v92
	v_lshlrev_b32_e32 v58, 16, v93
	v_and_b32_e32 v59, 0xffff0000, v93
	v_lshlrev_b32_e32 v60, 16, v94
	v_and_b32_e32 v61, 0xffff0000, v94
	v_lshlrev_b32_e32 v62, 16, v95
	v_and_b32_e32 v63, 0xffff0000, v95
	v_or_b32_e32 v116, 64, v249
	v_lshl_or_b32 v142, v142, 7, v249
	v_lshl_or_b32 v143, v143, 7, v116
	v_lshl_or_b32 v144, v144, 7, v249
	v_lshl_or_b32 v145, v145, 7, v116
	v_lshl_or_b32 v146, v146, 7, v249
	v_lshl_or_b32 v147, v147, 7, v116
	v_lshl_or_b32 v148, v148, 7, v249
	v_lshl_or_b32 v149, v149, 7, v116
	v_xor_b32_e32 v116, 4, v252
	ds_bpermute_b32 v64, v116, v142
	ds_bpermute_b32 v65, v116, v144
	ds_bpermute_b32 v66, v116, v146
	ds_bpermute_b32 v67, v116, v148
	ds_bpermute_b32 v68, v116, v143
	ds_bpermute_b32 v69, v116, v145
	ds_bpermute_b32 v70, v116, v147
	ds_bpermute_b32 v71, v116, v149
	s_waitcnt lgkmcnt(0)
	s_mov_b32 s88, 0x99999999
	s_mov_b32 s89, 0x99999999
	v_min_u32_e32 v96, v142, v64
	v_max_u32_e32 v97, v142, v64
	v_cndmask_b32_e64 v142, v97, v96, s[88:89]
	v_min_u32_e32 v98, v144, v65
	v_max_u32_e32 v99, v144, v65
	v_cndmask_b32_e64 v144, v99, v98, s[88:89]
	v_min_u32_e32 v96, v146, v66
	v_max_u32_e32 v97, v146, v66
	v_cndmask_b32_e64 v146, v97, v96, s[88:89]
	v_min_u32_e32 v98, v148, v67
	v_max_u32_e32 v99, v148, v67
	v_cndmask_b32_e64 v148, v99, v98, s[88:89]
	v_min_u32_e32 v96, v143, v68
	v_max_u32_e32 v97, v143, v68
	v_cndmask_b32_e64 v143, v97, v96, s[88:89]
	v_min_u32_e32 v98, v145, v69
	v_max_u32_e32 v99, v145, v69
	v_cndmask_b32_e64 v145, v99, v98, s[88:89]
	v_min_u32_e32 v96, v147, v70
	v_max_u32_e32 v97, v147, v70
	v_cndmask_b32_e64 v147, v97, v96, s[88:89]
	v_min_u32_e32 v98, v149, v71
	v_max_u32_e32 v99, v149, v71
	v_cndmask_b32_e64 v149, v99, v98, s[88:89]
	v_xor_b32_e32 v116, 8, v252
	ds_bpermute_b32 v64, v116, v142
	ds_bpermute_b32 v65, v116, v144
	ds_bpermute_b32 v66, v116, v146
	ds_bpermute_b32 v67, v116, v148
	ds_bpermute_b32 v68, v116, v143
	ds_bpermute_b32 v69, v116, v145
	ds_bpermute_b32 v70, v116, v147
	ds_bpermute_b32 v71, v116, v149
	s_waitcnt lgkmcnt(0)
; DEV void sort_lists(int lane, int& myi0, int& myi1, float& myg0, float& myg1) {
; #pragma unroll
;     for (int k = 2; k <= 128; k <<= 1) {
; #pragma unroll
;       for (int j = k >> 1; j >= 1; j >>= 1) {
;         if (j == 64) {
;           const bool sw_ = myi1 < myi0;
;           const int ti = sw_ ? myi1 : myi0, tj = sw_ ? myi0 : myi1; const float tg = sw_ ? myg1 : myg0, th = sw_ ? myg0 : myg1;
;           myi0 = ti; myi1 = tj; myg0 = tg; myg1 = th;
;         } else {
;           const bool lower = (lane & j) == 0;
;           {
;             const bool up = (k == 128) ? true : ((k == 64) ? true : ((lane & k) == 0));
;             const int oi = __shfl_xor(myi0, j); const float og = __shfl_xor(myg0, j);
;             const bool take = (lower == up) ? (oi < myi0) : (oi > myi0);
;             myi0 = take ? oi : myi0; myg0 = take ? og : myg0;
;           }
;           {
;             const bool up = (k == 128) ? true : ((k == 64) ? false : ((lane & k) == 0));
;             const int oi = __shfl_xor(myi1, j); const float og = __shfl_xor(myg1, j);
;             const bool take = (lower == up) ? (oi < myi1) : (oi > myi1);
;             myi1 = take ? oi : myi1; myg1 = take ? og : myg1;
;           }
;         }
;       }
;     }
; }
	s_mov_b32 s88, 0xc3c3c3c3
	s_mov_b32 s89, 0xc3c3c3c3
	v_min_u32_e32 v96, v142, v64
	v_max_u32_e32 v97, v142, v64
	v_cndmask_b32_e64 v142, v97, v96, s[88:89]
	v_min_u32_e32 v98, v144, v65
	v_max_u32_e32 v99, v144, v65
	v_cndmask_b32_e64 v144, v99, v98, s[88:89]
	v_min_u32_e32 v96, v146, v66
	v_max_u32_e32 v97, v146, v66
	v_cndmask_b32_e64 v146, v97, v96, s[88:89]
	v_min_u32_e32 v98, v148, v67
	v_max_u32_e32 v99, v148, v67
	v_cndmask_b32_e64 v148, v99, v98, s[88:89]
	v_min_u32_e32 v96, v143, v68
	v_max_u32_e32 v97, v143, v68
	v_cndmask_b32_e64 v143, v97, v96, s[88:89]
	v_min_u32_e32 v98, v145, v69
	v_max_u32_e32 v99, v145, v69
	v_cndmask_b32_e64 v145, v99, v98, s[88:89]
	v_min_u32_e32 v96, v147, v70
	v_max_u32_e32 v97, v147, v70
	v_cndmask_b32_e64 v147, v97, v96, s[88:89]
	v_min_u32_e32 v98, v149, v71
	v_max_u32_e32 v99, v149, v71
	v_cndmask_b32_e64 v149, v99, v98, s[88:89]
	v_xor_b32_e32 v116, 4, v252
	ds_bpermute_b32 v64, v116, v142
	ds_bpermute_b32 v65, v116, v144
	ds_bpermute_b32 v66, v116, v146
	ds_bpermute_b32 v67, v116, v148
	ds_bpermute_b32 v68, v116, v143
	ds_bpermute_b32 v69, v116, v145
	ds_bpermute_b32 v70, v116, v147
	ds_bpermute_b32 v71, v116, v149
	s_waitcnt lgkmcnt(0)
	s_mov_b32 s88, 0xa5a5a5a5
	s_mov_b32 s89, 0xa5a5a5a5
	v_min_u32_e32 v96, v142, v64
	v_max_u32_e32 v97, v142, v64
	v_cndmask_b32_e64 v142, v97, v96, s[88:89]
	v_min_u32_e32 v98, v144, v65
	v_max_u32_e32 v99, v144, v65
	v_cndmask_b32_e64 v144, v99, v98, s[88:89]
	v_min_u32_e32 v96, v146, v66
	v_max_u32_e32 v97, v146, v66
	v_cndmask_b32_e64 v146, v97, v96, s[88:89]
	v_min_u32_e32 v98, v148, v67
	v_max_u32_e32 v99, v148, v67
	v_cndmask_b32_e64 v148, v99, v98, s[88:89]
	v_min_u32_e32 v96, v143, v68
	v_max_u32_e32 v97, v143, v68
	v_cndmask_b32_e64 v143, v97, v96, s[88:89]
	v_min_u32_e32 v98, v145, v69
	v_max_u32_e32 v99, v145, v69
	v_cndmask_b32_e64 v145, v99, v98, s[88:89]
	v_min_u32_e32 v96, v147, v70
	v_max_u32_e32 v97, v147, v70
	v_cndmask_b32_e64 v147, v97, v96, s[88:89]
	v_min_u32_e32 v98, v149, v71
	v_max_u32_e32 v99, v149, v71
	v_cndmask_b32_e64 v149, v99, v98, s[88:89]
	v_xor_b32_e32 v116, 16, v252
	ds_bpermute_b32 v64, v116, v142
	ds_bpermute_b32 v65, v116, v144
	ds_bpermute_b32 v66, v116, v146
	ds_bpermute_b32 v67, v116, v148
	ds_bpermute_b32 v68, v116, v143
	ds_bpermute_b32 v69, v116, v145
	ds_bpermute_b32 v70, v116, v147
	ds_bpermute_b32 v71, v116, v149
	s_waitcnt lgkmcnt(0)
	s_mov_b32 s88, 0xf00ff00f
	s_mov_b32 s89, 0xf00ff00f
	v_min_u32_e32 v96, v142, v64
	v_max_u32_e32 v97, v142, v64
	v_cndmask_b32_e64 v142, v97, v96, s[88:89]
	v_min_u32_e32 v98, v144, v65
	v_max_u32_e32 v99, v144, v65
	v_cndmask_b32_e64 v144, v99, v98, s[88:89]
	v_min_u32_e32 v96, v146, v66
	v_max_u32_e32 v97, v146, v66
	v_cndmask_b32_e64 v146, v97, v96, s[88:89]
	v_min_u32_e32 v98, v148, v67
	v_max_u32_e32 v99, v148, v67
	v_cndmask_b32_e64 v148, v99, v98, s[88:89]
	v_min_u32_e32 v96, v143, v68
	v_max_u32_e32 v97, v143, v68
	v_cndmask_b32_e64 v143, v97, v96, s[88:89]
	v_min_u32_e32 v98, v145, v69
	v_max_u32_e32 v99, v145, v69
	v_cndmask_b32_e64 v145, v99, v98, s[88:89]
	v_min_u32_e32 v96, v147, v70
	v_max_u32_e32 v97, v147, v70
	v_cndmask_b32_e64 v147, v97, v96, s[88:89]
	v_min_u32_e32 v98, v149, v71
	v_max_u32_e32 v99, v149, v71
	v_cndmask_b32_e64 v149, v99, v98, s[88:89]
	v_xor_b32_e32 v116, 8, v252
	ds_bpermute_b32 v64, v116, v142
	ds_bpermute_b32 v65, v116, v144
	ds_bpermute_b32 v66, v116, v146
	ds_bpermute_b32 v67, v116, v148
	ds_bpermute_b32 v68, v116, v143
	ds_bpermute_b32 v69, v116, v145
	ds_bpermute_b32 v70, v116, v147
	ds_bpermute_b32 v71, v116, v149
	s_waitcnt lgkmcnt(0)
	s_mov_b32 s88, 0xcc33cc33
	s_mov_b32 s89, 0xcc33cc33
	v_min_u32_e32 v96, v142, v64
	v_max_u32_e32 v97, v142, v64
	v_cndmask_b32_e64 v142, v97, v96, s[88:89]
	v_min_u32_e32 v98, v144, v65
	v_max_u32_e32 v99, v144, v65
	v_cndmask_b32_e64 v144, v99, v98, s[88:89]
	v_min_u32_e32 v96, v146, v66
	v_max_u32_e32 v97, v146, v66
	v_cndmask_b32_e64 v146, v97, v96, s[88:89]
	v_min_u32_e32 v98, v148, v67
	v_max_u32_e32 v99, v148, v67
	v_cndmask_b32_e64 v148, v99, v98, s[88:89]
	v_min_u32_e32 v96, v143, v68
	v_max_u32_e32 v97, v143, v68
	v_cndmask_b32_e64 v143, v97, v96, s[88:89]
	v_min_u32_e32 v98, v145, v69
	v_max_u32_e32 v99, v145, v69
	v_cndmask_b32_e64 v145, v99, v98, s[88:89]
	v_min_u32_e32 v96, v147, v70
	v_max_u32_e32 v97, v147, v70
	v_cndmask_b32_e64 v147, v97, v96, s[88:89]
	v_min_u32_e32 v98, v149, v71
	v_max_u32_e32 v99, v149, v71
	v_cndmask_b32_e64 v149, v99, v98, s[88:89]
	v_xor_b32_e32 v116, 4, v252
	ds_bpermute_b32 v64, v116, v142
	ds_bpermute_b32 v65, v116, v144
	ds_bpermute_b32 v66, v116, v146
	ds_bpermute_b32 v67, v116, v148
	ds_bpermute_b32 v68, v116, v143
	ds_bpermute_b32 v69, v116, v145
	ds_bpermute_b32 v70, v116, v147
	ds_bpermute_b32 v71, v116, v149
	s_waitcnt lgkmcnt(0)
	s_mov_b32 s88, 0xaa55aa55
	s_mov_b32 s89, 0xaa55aa55
	v_min_u32_e32 v96, v142, v64
	v_max_u32_e32 v97, v142, v64
	v_cndmask_b32_e64 v142, v97, v96, s[88:89]
	v_min_u32_e32 v98, v144, v65
	v_max_u32_e32 v99, v144, v65
	v_cndmask_b32_e64 v144, v99, v98, s[88:89]
	v_min_u32_e32 v96, v146, v66
	v_max_u32_e32 v97, v146, v66
	v_cndmask_b32_e64 v146, v97, v96, s[88:89]
	v_min_u32_e32 v98, v148, v67
	v_max_u32_e32 v99, v148, v67
	v_cndmask_b32_e64 v148, v99, v98, s[88:89]
	v_min_u32_e32 v96, v143, v68
	v_max_u32_e32 v97, v143, v68
	v_cndmask_b32_e64 v143, v97, v96, s[88:89]
	v_min_u32_e32 v98, v145, v69
	v_max_u32_e32 v99, v145, v69
	v_cndmask_b32_e64 v145, v99, v98, s[88:89]
	v_min_u32_e32 v96, v147, v70
	v_max_u32_e32 v97, v147, v70
	v_cndmask_b32_e64 v147, v97, v96, s[88:89]
	v_min_u32_e32 v98, v149, v71
	v_max_u32_e32 v99, v149, v71
	v_cndmask_b32_e64 v149, v99, v98, s[88:89]
	v_xor_b32_e32 v116, 32, v252
	ds_bpermute_b32 v64, v116, v142
	ds_bpermute_b32 v65, v116, v144
	ds_bpermute_b32 v66, v116, v146
	ds_bpermute_b32 v67, v116, v148
	ds_bpermute_b32 v68, v116, v143
	ds_bpermute_b32 v69, v116, v145
	ds_bpermute_b32 v70, v116, v147
	ds_bpermute_b32 v71, v116, v149
	s_waitcnt lgkmcnt(0)
; DEV void sort_lists(int lane, int& myi0, int& myi1, float& myg0, float& myg1) {
; #pragma unroll
;     for (int k = 2; k <= 128; k <<= 1) {
; #pragma unroll
;       for (int j = k >> 1; j >= 1; j >>= 1) {
;         if (j == 64) {
;           const bool sw_ = myi1 < myi0;
;           const int ti = sw_ ? myi1 : myi0, tj = sw_ ? myi0 : myi1; const float tg = sw_ ? myg1 : myg0, th = sw_ ? myg0 : myg1;
;           myi0 = ti; myi1 = tj; myg0 = tg; myg1 = th;
;         } else {
;           const bool lower = (lane & j) == 0;
;           {
;             const bool up = (k == 128) ? true : ((k == 64) ? true : ((lane & k) == 0));
;             const int oi = __shfl_xor(myi0, j); const float og = __shfl_xor(myg0, j);
;             const bool take = (lower == up) ? (oi < myi0) : (oi > myi0);
;             myi0 = take ? oi : myi0; myg0 = take ? og : myg0;
;           }
;           {
;             const bool up = (k == 128) ? true : ((k == 64) ? false : ((lane & k) == 0));
;             const int oi = __shfl_xor(myi1, j); const float og = __shfl_xor(myg1, j);
;             const bool take = (lower == up) ? (oi < myi1) : (oi > myi1);
;             myi1 = take ? oi : myi1; myg1 = take ? og : myg1;
;           }
;         }
;       }
;     }
; }
	s_mov_b32 s88, 0xff0000ff
	s_mov_b32 s89, 0xff0000ff
	v_min_u32_e32 v96, v142, v64
	v_max_u32_e32 v97, v142, v64
	v_cndmask_b32_e64 v142, v97, v96, s[88:89]
	v_min_u32_e32 v98, v144, v65
	v_max_u32_e32 v99, v144, v65
	v_cndmask_b32_e64 v144, v99, v98, s[88:89]
	v_min_u32_e32 v96, v146, v66
	v_max_u32_e32 v97, v146, v66
	v_cndmask_b32_e64 v146, v97, v96, s[88:89]
	v_min_u32_e32 v98, v148, v67
	v_max_u32_e32 v99, v148, v67
	v_cndmask_b32_e64 v148, v99, v98, s[88:89]
	v_min_u32_e32 v96, v143, v68
	v_max_u32_e32 v97, v143, v68
	v_cndmask_b32_e64 v143, v97, v96, s[88:89]
	v_min_u32_e32 v98, v145, v69
	v_max_u32_e32 v99, v145, v69
	v_cndmask_b32_e64 v145, v99, v98, s[88:89]
	v_min_u32_e32 v96, v147, v70
	v_max_u32_e32 v97, v147, v70
	v_cndmask_b32_e64 v147, v97, v96, s[88:89]
	v_min_u32_e32 v98, v149, v71
	v_max_u32_e32 v99, v149, v71
	v_cndmask_b32_e64 v149, v99, v98, s[88:89]
	v_xor_b32_e32 v116, 16, v252
	ds_bpermute_b32 v64, v116, v142
	ds_bpermute_b32 v65, v116, v144
	ds_bpermute_b32 v66, v116, v146
	ds_bpermute_b32 v67, v116, v148
	ds_bpermute_b32 v68, v116, v143
	ds_bpermute_b32 v69, v116, v145
	ds_bpermute_b32 v70, v116, v147
	ds_bpermute_b32 v71, v116, v149
	s_waitcnt lgkmcnt(0)
	s_mov_b32 s88, 0xf0f00f0f
	s_mov_b32 s89, 0xf0f00f0f
	v_min_u32_e32 v96, v142, v64
	v_max_u32_e32 v97, v142, v64
	v_cndmask_b32_e64 v142, v97, v96, s[88:89]
	v_min_u32_e32 v98, v144, v65
	v_max_u32_e32 v99, v144, v65
	v_cndmask_b32_e64 v144, v99, v98, s[88:89]
	v_min_u32_e32 v96, v146, v66
	v_max_u32_e32 v97, v146, v66
	v_cndmask_b32_e64 v146, v97, v96, s[88:89]
	v_min_u32_e32 v98, v148, v67
	v_max_u32_e32 v99, v148, v67
	v_cndmask_b32_e64 v148, v99, v98, s[88:89]
	v_min_u32_e32 v96, v143, v68
	v_max_u32_e32 v97, v143, v68
	v_cndmask_b32_e64 v143, v97, v96, s[88:89]
	v_min_u32_e32 v98, v145, v69
	v_max_u32_e32 v99, v145, v69
	v_cndmask_b32_e64 v145, v99, v98, s[88:89]
	v_min_u32_e32 v96, v147, v70
	v_max_u32_e32 v97, v147, v70
	v_cndmask_b32_e64 v147, v97, v96, s[88:89]
	v_min_u32_e32 v98, v149, v71
	v_max_u32_e32 v99, v149, v71
	v_cndmask_b32_e64 v149, v99, v98, s[88:89]
	v_xor_b32_e32 v116, 8, v252
	ds_bpermute_b32 v64, v116, v142
	ds_bpermute_b32 v65, v116, v144
	ds_bpermute_b32 v66, v116, v146
	ds_bpermute_b32 v67, v116, v148
	ds_bpermute_b32 v68, v116, v143
	ds_bpermute_b32 v69, v116, v145
	ds_bpermute_b32 v70, v116, v147
	ds_bpermute_b32 v71, v116, v149
	s_waitcnt lgkmcnt(0)
	s_mov_b32 s88, 0xcccc3333
	s_mov_b32 s89, 0xcccc3333
	v_min_u32_e32 v96, v142, v64
	v_max_u32_e32 v97, v142, v64
	v_cndmask_b32_e64 v142, v97, v96, s[88:89]
	v_min_u32_e32 v98, v144, v65
	v_max_u32_e32 v99, v144, v65
	v_cndmask_b32_e64 v144, v99, v98, s[88:89]
	v_min_u32_e32 v96, v146, v66
	v_max_u32_e32 v97, v146, v66
	v_cndmask_b32_e64 v146, v97, v96, s[88:89]
	v_min_u32_e32 v98, v148, v67
	v_max_u32_e32 v99, v148, v67
	v_cndmask_b32_e64 v148, v99, v98, s[88:89]
	v_min_u32_e32 v96, v143, v68
	v_max_u32_e32 v97, v143, v68
	v_cndmask_b32_e64 v143, v97, v96, s[88:89]
	v_min_u32_e32 v98, v145, v69
	v_max_u32_e32 v99, v145, v69
	v_cndmask_b32_e64 v145, v99, v98, s[88:89]
	v_min_u32_e32 v96, v147, v70
	v_max_u32_e32 v97, v147, v70
	v_cndmask_b32_e64 v147, v97, v96, s[88:89]
	v_min_u32_e32 v98, v149, v71
	v_max_u32_e32 v99, v149, v71
	v_cndmask_b32_e64 v149, v99, v98, s[88:89]
	v_xor_b32_e32 v116, 4, v252
	ds_bpermute_b32 v64, v116, v142
	ds_bpermute_b32 v65, v116, v144
	ds_bpermute_b32 v66, v116, v146
	ds_bpermute_b32 v67, v116, v148
	ds_bpermute_b32 v68, v116, v143
	ds_bpermute_b32 v69, v116, v145
	ds_bpermute_b32 v70, v116, v147
	ds_bpermute_b32 v71, v116, v149
	s_waitcnt lgkmcnt(0)
	s_mov_b32 s88, 0xaaaa5555
	s_mov_b32 s89, 0xaaaa5555
	v_min_u32_e32 v96, v142, v64
	v_max_u32_e32 v97, v142, v64
	v_cndmask_b32_e64 v142, v97, v96, s[88:89]
	v_min_u32_e32 v98, v144, v65
	v_max_u32_e32 v99, v144, v65
	v_cndmask_b32_e64 v144, v99, v98, s[88:89]
	v_min_u32_e32 v96, v146, v66
	v_max_u32_e32 v97, v146, v66
	v_cndmask_b32_e64 v146, v97, v96, s[88:89]
	v_min_u32_e32 v98, v148, v67
	v_max_u32_e32 v99, v148, v67
	v_cndmask_b32_e64 v148, v99, v98, s[88:89]
	v_min_u32_e32 v96, v143, v68
	v_max_u32_e32 v97, v143, v68
	v_cndmask_b32_e64 v143, v97, v96, s[88:89]
	v_min_u32_e32 v98, v145, v69
	v_max_u32_e32 v99, v145, v69
	v_cndmask_b32_e64 v145, v99, v98, s[88:89]
	v_min_u32_e32 v96, v147, v70
	v_max_u32_e32 v97, v147, v70
	v_cndmask_b32_e64 v147, v97, v96, s[88:89]
	v_min_u32_e32 v98, v149, v71
	v_max_u32_e32 v99, v149, v71
	v_cndmask_b32_e64 v149, v99, v98, s[88:89]
	v_xor_b32_e32 v116, 64, v252
	ds_bpermute_b32 v64, v116, v142
	ds_bpermute_b32 v65, v116, v144
	ds_bpermute_b32 v66, v116, v146
	ds_bpermute_b32 v67, v116, v148
	ds_bpermute_b32 v68, v116, v143
	ds_bpermute_b32 v69, v116, v145
	ds_bpermute_b32 v70, v116, v147
	ds_bpermute_b32 v71, v116, v149
	s_waitcnt lgkmcnt(0)
	s_mov_b32 s88, 0xffff
	s_mov_b32 s89, 0xffff0000
	v_min_u32_e32 v96, v142, v64
	v_max_u32_e32 v97, v142, v64
	v_cndmask_b32_e64 v142, v97, v96, s[88:89]
	v_min_u32_e32 v98, v144, v65
	v_max_u32_e32 v99, v144, v65
	v_cndmask_b32_e64 v144, v99, v98, s[88:89]
	v_min_u32_e32 v96, v146, v66
	v_max_u32_e32 v97, v146, v66
	v_cndmask_b32_e64 v146, v97, v96, s[88:89]
	v_min_u32_e32 v98, v148, v67
	v_max_u32_e32 v99, v148, v67
	v_cndmask_b32_e64 v148, v99, v98, s[88:89]
	v_min_u32_e32 v96, v143, v68
	v_max_u32_e32 v97, v143, v68
	v_cndmask_b32_e64 v143, v97, v96, s[88:89]
	v_min_u32_e32 v98, v145, v69
	v_max_u32_e32 v99, v145, v69
	v_cndmask_b32_e64 v145, v99, v98, s[88:89]
	v_min_u32_e32 v96, v147, v70
	v_max_u32_e32 v97, v147, v70
	v_cndmask_b32_e64 v147, v97, v96, s[88:89]
	v_min_u32_e32 v98, v149, v71
	v_max_u32_e32 v99, v149, v71
	v_cndmask_b32_e64 v149, v99, v98, s[88:89]
	v_xor_b32_e32 v116, 32, v252
	ds_bpermute_b32 v64, v116, v142
	ds_bpermute_b32 v65, v116, v144
	ds_bpermute_b32 v66, v116, v146
	ds_bpermute_b32 v67, v116, v148
	ds_bpermute_b32 v68, v116, v143
	ds_bpermute_b32 v69, v116, v145
	ds_bpermute_b32 v70, v116, v147
	ds_bpermute_b32 v71, v116, v149
	s_waitcnt lgkmcnt(0)
; DEV void sort_lists(int lane, int& myi0, int& myi1, float& myg0, float& myg1) {
; #pragma unroll
;     for (int k = 2; k <= 128; k <<= 1) {
; #pragma unroll
;       for (int j = k >> 1; j >= 1; j >>= 1) {
;         if (j == 64) {
;           const bool sw_ = myi1 < myi0;
;           const int ti = sw_ ? myi1 : myi0, tj = sw_ ? myi0 : myi1; const float tg = sw_ ? myg1 : myg0, th = sw_ ? myg0 : myg1;
;           myi0 = ti; myi1 = tj; myg0 = tg; myg1 = th;
;         } else {
;           const bool lower = (lane & j) == 0;
;           {
;             const bool up = (k == 128) ? true : ((k == 64) ? true : ((lane & k) == 0));
;             const int oi = __shfl_xor(myi0, j); const float og = __shfl_xor(myg0, j);
;             const bool take = (lower == up) ? (oi < myi0) : (oi > myi0);
;             myi0 = take ? oi : myi0; myg0 = take ? og : myg0;
;           }
;           {
;             const bool up = (k == 128) ? true : ((k == 64) ? false : ((lane & k) == 0));
;             const int oi = __shfl_xor(myi1, j); const float og = __shfl_xor(myg1, j);
;             const bool take = (lower == up) ? (oi < myi1) : (oi > myi1);
;             myi1 = take ? oi : myi1; myg1 = take ? og : myg1;
;           }
;         }
;       }
;     }
; }
	s_mov_b32 s88, 0xff00ff
	s_mov_b32 s89, 0xff00ff00
	v_min_u32_e32 v96, v142, v64
	v_max_u32_e32 v97, v142, v64
	v_cndmask_b32_e64 v142, v97, v96, s[88:89]
	v_min_u32_e32 v98, v144, v65
	v_max_u32_e32 v99, v144, v65
	v_cndmask_b32_e64 v144, v99, v98, s[88:89]
	v_min_u32_e32 v96, v146, v66
	v_max_u32_e32 v97, v146, v66
	v_cndmask_b32_e64 v146, v97, v96, s[88:89]
	v_min_u32_e32 v98, v148, v67
	v_max_u32_e32 v99, v148, v67
	v_cndmask_b32_e64 v148, v99, v98, s[88:89]
	v_min_u32_e32 v96, v143, v68
	v_max_u32_e32 v97, v143, v68
	v_cndmask_b32_e64 v143, v97, v96, s[88:89]
	v_min_u32_e32 v98, v145, v69
	v_max_u32_e32 v99, v145, v69
	v_cndmask_b32_e64 v145, v99, v98, s[88:89]
	v_min_u32_e32 v96, v147, v70
	v_max_u32_e32 v97, v147, v70
	v_cndmask_b32_e64 v147, v97, v96, s[88:89]
	v_min_u32_e32 v98, v149, v71
	v_max_u32_e32 v99, v149, v71
	v_cndmask_b32_e64 v149, v99, v98, s[88:89]
	v_xor_b32_e32 v116, 16, v252
	ds_bpermute_b32 v64, v116, v142
	ds_bpermute_b32 v65, v116, v144
	ds_bpermute_b32 v66, v116, v146
	ds_bpermute_b32 v67, v116, v148
	ds_bpermute_b32 v68, v116, v143
	ds_bpermute_b32 v69, v116, v145
	ds_bpermute_b32 v70, v116, v147
	ds_bpermute_b32 v71, v116, v149
	s_waitcnt lgkmcnt(0)
	s_mov_b32 s88, 0xf0f0f0f
	s_mov_b32 s89, 0xf0f0f0f0
	v_min_u32_e32 v96, v142, v64
	v_max_u32_e32 v97, v142, v64
	v_cndmask_b32_e64 v142, v97, v96, s[88:89]
	v_min_u32_e32 v98, v144, v65
	v_max_u32_e32 v99, v144, v65
	v_cndmask_b32_e64 v144, v99, v98, s[88:89]
	v_min_u32_e32 v96, v146, v66
	v_max_u32_e32 v97, v146, v66
	v_cndmask_b32_e64 v146, v97, v96, s[88:89]
	v_min_u32_e32 v98, v148, v67
	v_max_u32_e32 v99, v148, v67
	v_cndmask_b32_e64 v148, v99, v98, s[88:89]
	v_min_u32_e32 v96, v143, v68
	v_max_u32_e32 v97, v143, v68
	v_cndmask_b32_e64 v143, v97, v96, s[88:89]
	v_min_u32_e32 v98, v145, v69
	v_max_u32_e32 v99, v145, v69
	v_cndmask_b32_e64 v145, v99, v98, s[88:89]
	v_min_u32_e32 v96, v147, v70
	v_max_u32_e32 v97, v147, v70
	v_cndmask_b32_e64 v147, v97, v96, s[88:89]
	v_min_u32_e32 v98, v149, v71
	v_max_u32_e32 v99, v149, v71
	v_cndmask_b32_e64 v149, v99, v98, s[88:89]
	v_xor_b32_e32 v116, 8, v252
	ds_bpermute_b32 v64, v116, v142
	ds_bpermute_b32 v65, v116, v144
	ds_bpermute_b32 v66, v116, v146
	ds_bpermute_b32 v67, v116, v148
	ds_bpermute_b32 v68, v116, v143
	ds_bpermute_b32 v69, v116, v145
	ds_bpermute_b32 v70, v116, v147
	ds_bpermute_b32 v71, v116, v149
	s_waitcnt lgkmcnt(0)
	s_mov_b32 s88, 0x33333333
	s_mov_b32 s89, 0xcccccccc
	v_min_u32_e32 v96, v142, v64
	v_max_u32_e32 v97, v142, v64
	v_cndmask_b32_e64 v142, v97, v96, s[88:89]
	v_min_u32_e32 v98, v144, v65
	v_max_u32_e32 v99, v144, v65
	v_cndmask_b32_e64 v144, v99, v98, s[88:89]
	v_min_u32_e32 v96, v146, v66
	v_max_u32_e32 v97, v146, v66
	v_cndmask_b32_e64 v146, v97, v96, s[88:89]
	v_min_u32_e32 v98, v148, v67
	v_max_u32_e32 v99, v148, v67
	v_cndmask_b32_e64 v148, v99, v98, s[88:89]
	v_min_u32_e32 v96, v143, v68
	v_max_u32_e32 v97, v143, v68
	v_cndmask_b32_e64 v143, v97, v96, s[88:89]
	v_min_u32_e32 v98, v145, v69
	v_max_u32_e32 v99, v145, v69
	v_cndmask_b32_e64 v145, v99, v98, s[88:89]
	v_min_u32_e32 v96, v147, v70
	v_max_u32_e32 v97, v147, v70
	v_cndmask_b32_e64 v147, v97, v96, s[88:89]
	v_min_u32_e32 v98, v149, v71
	v_max_u32_e32 v99, v149, v71
	v_cndmask_b32_e64 v149, v99, v98, s[88:89]
	v_xor_b32_e32 v116, 4, v252
	ds_bpermute_b32 v64, v116, v142
	ds_bpermute_b32 v65, v116, v144
	ds_bpermute_b32 v66, v116, v146
	ds_bpermute_b32 v67, v116, v148
	ds_bpermute_b32 v68, v116, v143
	ds_bpermute_b32 v69, v116, v145
	ds_bpermute_b32 v70, v116, v147
	ds_bpermute_b32 v71, v116, v149
	s_waitcnt lgkmcnt(0)
	s_mov_b32 s88, 0x55555555
	s_mov_b32 s89, 0xaaaaaaaa
	v_min_u32_e32 v96, v142, v64
	v_max_u32_e32 v97, v142, v64
	v_cndmask_b32_e64 v142, v97, v96, s[88:89]
	v_min_u32_e32 v98, v144, v65
	v_max_u32_e32 v99, v144, v65
	v_cndmask_b32_e64 v144, v99, v98, s[88:89]
	v_min_u32_e32 v96, v146, v66
	v_max_u32_e32 v97, v146, v66
	v_cndmask_b32_e64 v146, v97, v96, s[88:89]
	v_min_u32_e32 v98, v148, v67
	v_max_u32_e32 v99, v148, v67
	v_cndmask_b32_e64 v148, v99, v98, s[88:89]
	v_min_u32_e32 v96, v143, v68
	v_max_u32_e32 v97, v143, v68
	v_cndmask_b32_e64 v143, v97, v96, s[88:89]
	v_min_u32_e32 v98, v145, v69
	v_max_u32_e32 v99, v145, v69
	v_cndmask_b32_e64 v145, v99, v98, s[88:89]
	v_min_u32_e32 v96, v147, v70
	v_max_u32_e32 v97, v147, v70
	v_cndmask_b32_e64 v147, v97, v96, s[88:89]
	v_min_u32_e32 v98, v149, v71
	v_max_u32_e32 v99, v149, v71
	v_cndmask_b32_e64 v149, v99, v98, s[88:89]
	v_xor_b32_e32 v116, 128, v252
	ds_bpermute_b32 v64, v116, v142
	ds_bpermute_b32 v65, v116, v144
	ds_bpermute_b32 v66, v116, v146
	ds_bpermute_b32 v67, v116, v148
	ds_bpermute_b32 v68, v116, v143
	ds_bpermute_b32 v69, v116, v145
	ds_bpermute_b32 v70, v116, v147
	ds_bpermute_b32 v71, v116, v149
	s_waitcnt lgkmcnt(0)
	s_mov_b32 s88, 0xffffffff
	s_mov_b32 s89, 0x0
	v_min_u32_e32 v96, v142, v64
	v_max_u32_e32 v97, v142, v64
	v_cndmask_b32_e64 v142, v97, v96, s[88:89]
	v_min_u32_e32 v98, v144, v65
	v_max_u32_e32 v99, v144, v65
	v_cndmask_b32_e64 v144, v99, v98, s[88:89]
	v_min_u32_e32 v96, v146, v66
	v_max_u32_e32 v97, v146, v66
	v_cndmask_b32_e64 v146, v97, v96, s[88:89]
	v_min_u32_e32 v98, v148, v67
	v_max_u32_e32 v99, v148, v67
	v_cndmask_b32_e64 v148, v99, v98, s[88:89]
	s_mov_b32 s88, 0x0
	s_mov_b32 s89, 0xffffffff
	v_min_u32_e32 v96, v143, v68
	v_max_u32_e32 v97, v143, v68
	v_cndmask_b32_e64 v143, v97, v96, s[88:89]
	v_min_u32_e32 v98, v145, v69
	v_max_u32_e32 v99, v145, v69
	v_cndmask_b32_e64 v145, v99, v98, s[88:89]
	v_min_u32_e32 v96, v147, v70
	v_max_u32_e32 v97, v147, v70
	v_cndmask_b32_e64 v147, v97, v96, s[88:89]
	v_min_u32_e32 v98, v149, v71
	v_max_u32_e32 v99, v149, v71
	v_cndmask_b32_e64 v149, v99, v98, s[88:89]
	v_xor_b32_e32 v116, 64, v252
	ds_bpermute_b32 v64, v116, v142
	ds_bpermute_b32 v65, v116, v144
	ds_bpermute_b32 v66, v116, v146
	ds_bpermute_b32 v67, v116, v148
	ds_bpermute_b32 v68, v116, v143
	ds_bpermute_b32 v69, v116, v145
	ds_bpermute_b32 v70, v116, v147
	ds_bpermute_b32 v71, v116, v149
	s_waitcnt lgkmcnt(0)
; DEV void sort_lists(int lane, int& myi0, int& myi1, float& myg0, float& myg1) {
; #pragma unroll
;     for (int k = 2; k <= 128; k <<= 1) {
; #pragma unroll
;       for (int j = k >> 1; j >= 1; j >>= 1) {
;         if (j == 64) {
;           const bool sw_ = myi1 < myi0;
;           const int ti = sw_ ? myi1 : myi0, tj = sw_ ? myi0 : myi1; const float tg = sw_ ? myg1 : myg0, th = sw_ ? myg0 : myg1;
;           myi0 = ti; myi1 = tj; myg0 = tg; myg1 = th;
;         } else {
;           const bool lower = (lane & j) == 0;
;           {
;             const bool up = (k == 128) ? true : ((k == 64) ? true : ((lane & k) == 0));
;             const int oi = __shfl_xor(myi0, j); const float og = __shfl_xor(myg0, j);
;             const bool take = (lower == up) ? (oi < myi0) : (oi > myi0);
;             myi0 = take ? oi : myi0; myg0 = take ? og : myg0;
;           }
;           {
;             const bool up = (k == 128) ? true : ((k == 64) ? false : ((lane & k) == 0));
;             const int oi = __shfl_xor(myi1, j); const float og = __shfl_xor(myg1, j);
;             const bool take = (lower == up) ? (oi < myi1) : (oi > myi1);
;             myi1 = take ? oi : myi1; myg1 = take ? og : myg1;
;           }
;         }
;       }
;     }
; }
	s_mov_b32 s88, 0xffff
	s_mov_b32 s89, 0xffff
	v_min_u32_e32 v96, v142, v64
	v_max_u32_e32 v97, v142, v64
	v_cndmask_b32_e64 v142, v97, v96, s[88:89]
	v_min_u32_e32 v98, v144, v65
	v_max_u32_e32 v99, v144, v65
	v_cndmask_b32_e64 v144, v99, v98, s[88:89]
	v_min_u32_e32 v96, v146, v66
	v_max_u32_e32 v97, v146, v66
	v_cndmask_b32_e64 v146, v97, v96, s[88:89]
	v_min_u32_e32 v98, v148, v67
	v_max_u32_e32 v99, v148, v67
	v_cndmask_b32_e64 v148, v99, v98, s[88:89]
	s_mov_b32 s88, 0xffff0000
	s_mov_b32 s89, 0xffff0000
	v_min_u32_e32 v96, v143, v68
	v_max_u32_e32 v97, v143, v68
	v_cndmask_b32_e64 v143, v97, v96, s[88:89]
	v_min_u32_e32 v98, v145, v69
	v_max_u32_e32 v99, v145, v69
	v_cndmask_b32_e64 v145, v99, v98, s[88:89]
	v_min_u32_e32 v96, v147, v70
	v_max_u32_e32 v97, v147, v70
	v_cndmask_b32_e64 v147, v97, v96, s[88:89]
	v_min_u32_e32 v98, v149, v71
	v_max_u32_e32 v99, v149, v71
	v_cndmask_b32_e64 v149, v99, v98, s[88:89]
	v_xor_b32_e32 v116, 32, v252
	ds_bpermute_b32 v64, v116, v142
	ds_bpermute_b32 v65, v116, v144
	ds_bpermute_b32 v66, v116, v146
	ds_bpermute_b32 v67, v116, v148
	ds_bpermute_b32 v68, v116, v143
	ds_bpermute_b32 v69, v116, v145
	ds_bpermute_b32 v70, v116, v147
	ds_bpermute_b32 v71, v116, v149
	s_waitcnt lgkmcnt(0)
	s_mov_b32 s88, 0xff00ff
	s_mov_b32 s89, 0xff00ff
	v_min_u32_e32 v96, v142, v64
	v_max_u32_e32 v97, v142, v64
	v_cndmask_b32_e64 v142, v97, v96, s[88:89]
	v_min_u32_e32 v98, v144, v65
	v_max_u32_e32 v99, v144, v65
	v_cndmask_b32_e64 v144, v99, v98, s[88:89]
	v_min_u32_e32 v96, v146, v66
	v_max_u32_e32 v97, v146, v66
	v_cndmask_b32_e64 v146, v97, v96, s[88:89]
	v_min_u32_e32 v98, v148, v67
	v_max_u32_e32 v99, v148, v67
	v_cndmask_b32_e64 v148, v99, v98, s[88:89]
	s_mov_b32 s88, 0xff00ff00
	s_mov_b32 s89, 0xff00ff00
	v_min_u32_e32 v96, v143, v68
	v_max_u32_e32 v97, v143, v68
	v_cndmask_b32_e64 v143, v97, v96, s[88:89]
	v_min_u32_e32 v98, v145, v69
	v_max_u32_e32 v99, v145, v69
	v_cndmask_b32_e64 v145, v99, v98, s[88:89]
	v_min_u32_e32 v96, v147, v70
	v_max_u32_e32 v97, v147, v70
	v_cndmask_b32_e64 v147, v97, v96, s[88:89]
	v_min_u32_e32 v98, v149, v71
	v_max_u32_e32 v99, v149, v71
	v_cndmask_b32_e64 v149, v99, v98, s[88:89]
	v_xor_b32_e32 v116, 16, v252
	ds_bpermute_b32 v64, v116, v142
	ds_bpermute_b32 v65, v116, v144
	ds_bpermute_b32 v66, v116, v146
	ds_bpermute_b32 v67, v116, v148
	ds_bpermute_b32 v68, v116, v143
	ds_bpermute_b32 v69, v116, v145
	ds_bpermute_b32 v70, v116, v147
	ds_bpermute_b32 v71, v116, v149
	s_waitcnt lgkmcnt(0)
	s_mov_b32 s88, 0xf0f0f0f
	s_mov_b32 s89, 0xf0f0f0f
	v_min_u32_e32 v96, v142, v64
	v_max_u32_e32 v97, v142, v64
	v_cndmask_b32_e64 v142, v97, v96, s[88:89]
	v_min_u32_e32 v98, v144, v65
	v_max_u32_e32 v99, v144, v65
	v_cndmask_b32_e64 v144, v99, v98, s[88:89]
	v_min_u32_e32 v96, v146, v66
	v_max_u32_e32 v97, v146, v66
	v_cndmask_b32_e64 v146, v97, v96, s[88:89]
	v_min_u32_e32 v98, v148, v67
	v_max_u32_e32 v99, v148, v67
	v_cndmask_b32_e64 v148, v99, v98, s[88:89]
	s_mov_b32 s88, 0xf0f0f0f0
	s_mov_b32 s89, 0xf0f0f0f0
	v_min_u32_e32 v96, v143, v68
	v_max_u32_e32 v97, v143, v68
	v_cndmask_b32_e64 v143, v97, v96, s[88:89]
	v_min_u32_e32 v98, v145, v69
	v_max_u32_e32 v99, v145, v69
	v_cndmask_b32_e64 v145, v99, v98, s[88:89]
	v_min_u32_e32 v96, v147, v70
	v_max_u32_e32 v97, v147, v70
	v_cndmask_b32_e64 v147, v97, v96, s[88:89]
	v_min_u32_e32 v98, v149, v71
	v_max_u32_e32 v99, v149, v71
	v_cndmask_b32_e64 v149, v99, v98, s[88:89]
	v_xor_b32_e32 v116, 8, v252
	ds_bpermute_b32 v64, v116, v142
	ds_bpermute_b32 v65, v116, v144
	ds_bpermute_b32 v66, v116, v146
	ds_bpermute_b32 v67, v116, v148
	ds_bpermute_b32 v68, v116, v143
	ds_bpermute_b32 v69, v116, v145
	ds_bpermute_b32 v70, v116, v147
	ds_bpermute_b32 v71, v116, v149
	s_waitcnt lgkmcnt(0)
	s_mov_b32 s88, 0x33333333
	s_mov_b32 s89, 0x33333333
	v_min_u32_e32 v96, v142, v64
	v_max_u32_e32 v97, v142, v64
	v_cndmask_b32_e64 v142, v97, v96, s[88:89]
	v_min_u32_e32 v98, v144, v65
	v_max_u32_e32 v99, v144, v65
	v_cndmask_b32_e64 v144, v99, v98, s[88:89]
	v_min_u32_e32 v96, v146, v66
	v_max_u32_e32 v97, v146, v66
	v_cndmask_b32_e64 v146, v97, v96, s[88:89]
	v_min_u32_e32 v98, v148, v67
	v_max_u32_e32 v99, v148, v67
	v_cndmask_b32_e64 v148, v99, v98, s[88:89]
	s_mov_b32 s88, 0xcccccccc
	s_mov_b32 s89, 0xcccccccc
	v_min_u32_e32 v96, v143, v68
	v_max_u32_e32 v97, v143, v68
	v_cndmask_b32_e64 v143, v97, v96, s[88:89]
	v_min_u32_e32 v98, v145, v69
	v_max_u32_e32 v99, v145, v69
	v_cndmask_b32_e64 v145, v99, v98, s[88:89]
	v_min_u32_e32 v96, v147, v70
	v_max_u32_e32 v97, v147, v70
	v_cndmask_b32_e64 v147, v97, v96, s[88:89]
	v_min_u32_e32 v98, v149, v71
	v_max_u32_e32 v99, v149, v71
	v_cndmask_b32_e64 v149, v99, v98, s[88:89]
	v_xor_b32_e32 v116, 4, v252
	ds_bpermute_b32 v64, v116, v142
	ds_bpermute_b32 v65, v116, v144
	ds_bpermute_b32 v66, v116, v146
	ds_bpermute_b32 v67, v116, v148
	ds_bpermute_b32 v68, v116, v143
	ds_bpermute_b32 v69, v116, v145
	ds_bpermute_b32 v70, v116, v147
	ds_bpermute_b32 v71, v116, v149
	s_waitcnt lgkmcnt(0)
; DEV void sort_lists(int lane, int& myi0, int& myi1, float& myg0, float& myg1) {
; #pragma unroll
;     for (int k = 2; k <= 128; k <<= 1) {
; #pragma unroll
;       for (int j = k >> 1; j >= 1; j >>= 1) {
;         if (j == 64) {
;           const bool sw_ = myi1 < myi0;
;           const int ti = sw_ ? myi1 : myi0, tj = sw_ ? myi0 : myi1; const float tg = sw_ ? myg1 : myg0, th = sw_ ? myg0 : myg1;
;           myi0 = ti; myi1 = tj; myg0 = tg; myg1 = th;
;         } else {
;           const bool lower = (lane & j) == 0;
;           {
;             const bool up = (k == 128) ? true : ((k == 64) ? true : ((lane & k) == 0));
;             const int oi = __shfl_xor(myi0, j); const float og = __shfl_xor(myg0, j);
;             const bool take = (lower == up) ? (oi < myi0) : (oi > myi0);
;             myi0 = take ? oi : myi0; myg0 = take ? og : myg0;
;           }
;           {
;             const bool up = (k == 128) ? true : ((k == 64) ? false : ((lane & k) == 0));
;             const int oi = __shfl_xor(myi1, j); const float og = __shfl_xor(myg1, j);
;             const bool take = (lower == up) ? (oi < myi1) : (oi > myi1);
;             myi1 = take ? oi : myi1; myg1 = take ? og : myg1;
;           }
;         }
;       }
;     }
; }
	s_mov_b32 s88, 0x55555555
	s_mov_b32 s89, 0x55555555
	v_min_u32_e32 v96, v142, v64
	v_max_u32_e32 v97, v142, v64
	v_cndmask_b32_e64 v142, v97, v96, s[88:89]
	v_min_u32_e32 v98, v144, v65
	v_max_u32_e32 v99, v144, v65
	v_cndmask_b32_e64 v144, v99, v98, s[88:89]
	v_min_u32_e32 v96, v146, v66
	v_max_u32_e32 v97, v146, v66
	v_cndmask_b32_e64 v146, v97, v96, s[88:89]
	v_min_u32_e32 v98, v148, v67
	v_max_u32_e32 v99, v148, v67
	v_cndmask_b32_e64 v148, v99, v98, s[88:89]
	s_mov_b32 s88, 0xaaaaaaaa
	s_mov_b32 s89, 0xaaaaaaaa
	v_min_u32_e32 v96, v143, v68
	v_max_u32_e32 v97, v143, v68
	v_cndmask_b32_e64 v143, v97, v96, s[88:89]
	v_min_u32_e32 v98, v145, v69
	v_max_u32_e32 v99, v145, v69
	v_cndmask_b32_e64 v145, v99, v98, s[88:89]
	v_min_u32_e32 v96, v147, v70
	v_max_u32_e32 v97, v147, v70
	v_cndmask_b32_e64 v147, v97, v96, s[88:89]
	v_min_u32_e32 v98, v149, v71
	v_max_u32_e32 v99, v149, v71
	v_cndmask_b32_e64 v149, v99, v98, s[88:89]
	v_min_u32_e32 v96, v142, v143
	v_max_u32_e32 v143, v142, v143
	v_mov_b32_e32 v142, v96
	v_min_u32_e32 v98, v144, v145
	v_max_u32_e32 v145, v144, v145
	v_mov_b32_e32 v144, v98
	v_min_u32_e32 v96, v146, v147
	v_max_u32_e32 v147, v146, v147
	v_mov_b32_e32 v146, v96
	v_min_u32_e32 v98, v148, v149
	v_max_u32_e32 v149, v148, v149
	v_mov_b32_e32 v148, v98
	v_xor_b32_e32 v116, 128, v252
	ds_bpermute_b32 v64, v116, v142
	ds_bpermute_b32 v65, v116, v144
	ds_bpermute_b32 v66, v116, v146
	ds_bpermute_b32 v67, v116, v148
	ds_bpermute_b32 v68, v116, v143
	ds_bpermute_b32 v69, v116, v145
	ds_bpermute_b32 v70, v116, v147
	ds_bpermute_b32 v71, v116, v149
	s_waitcnt lgkmcnt(0)
	s_mov_b32 s88, 0xffffffff
	s_mov_b32 s89, 0x0
	v_min_u32_e32 v96, v142, v64
	v_max_u32_e32 v97, v142, v64
	v_cndmask_b32_e64 v142, v97, v96, s[88:89]
	v_min_u32_e32 v98, v144, v65
	v_max_u32_e32 v99, v144, v65
	v_cndmask_b32_e64 v144, v99, v98, s[88:89]
	v_min_u32_e32 v96, v146, v66
	v_max_u32_e32 v97, v146, v66
	v_cndmask_b32_e64 v146, v97, v96, s[88:89]
	v_min_u32_e32 v98, v148, v67
	v_max_u32_e32 v99, v148, v67
	v_cndmask_b32_e64 v148, v99, v98, s[88:89]
	v_min_u32_e32 v96, v143, v68
	v_max_u32_e32 v97, v143, v68
	v_cndmask_b32_e64 v143, v97, v96, s[88:89]
	v_min_u32_e32 v98, v145, v69
	v_max_u32_e32 v99, v145, v69
	v_cndmask_b32_e64 v145, v99, v98, s[88:89]
	v_min_u32_e32 v96, v147, v70
	v_max_u32_e32 v97, v147, v70
	v_cndmask_b32_e64 v147, v97, v96, s[88:89]
	v_min_u32_e32 v98, v149, v71
	v_max_u32_e32 v99, v149, v71
	v_cndmask_b32_e64 v149, v99, v98, s[88:89]
	v_xor_b32_e32 v116, 64, v252
	ds_bpermute_b32 v64, v116, v142
	ds_bpermute_b32 v65, v116, v144
	ds_bpermute_b32 v66, v116, v146
	ds_bpermute_b32 v67, v116, v148
	ds_bpermute_b32 v68, v116, v143
	ds_bpermute_b32 v69, v116, v145
	ds_bpermute_b32 v70, v116, v147
	ds_bpermute_b32 v71, v116, v149
	s_waitcnt lgkmcnt(0)
	s_mov_b32 s88, 0xffff
	s_mov_b32 s89, 0xffff
	v_min_u32_e32 v96, v142, v64
	v_max_u32_e32 v97, v142, v64
	v_cndmask_b32_e64 v142, v97, v96, s[88:89]
	v_min_u32_e32 v98, v144, v65
	v_max_u32_e32 v99, v144, v65
	v_cndmask_b32_e64 v144, v99, v98, s[88:89]
	v_min_u32_e32 v96, v146, v66
	v_max_u32_e32 v97, v146, v66
	v_cndmask_b32_e64 v146, v97, v96, s[88:89]
	v_min_u32_e32 v98, v148, v67
	v_max_u32_e32 v99, v148, v67
	v_cndmask_b32_e64 v148, v99, v98, s[88:89]
	v_min_u32_e32 v96, v143, v68
	v_max_u32_e32 v97, v143, v68
	v_cndmask_b32_e64 v143, v97, v96, s[88:89]
	v_min_u32_e32 v98, v145, v69
	v_max_u32_e32 v99, v145, v69
	v_cndmask_b32_e64 v145, v99, v98, s[88:89]
	v_min_u32_e32 v96, v147, v70
	v_max_u32_e32 v97, v147, v70
	v_cndmask_b32_e64 v147, v97, v96, s[88:89]
	v_min_u32_e32 v98, v149, v71
	v_max_u32_e32 v99, v149, v71
	v_cndmask_b32_e64 v149, v99, v98, s[88:89]
	v_xor_b32_e32 v116, 32, v252
	ds_bpermute_b32 v64, v116, v142
	ds_bpermute_b32 v65, v116, v144
	ds_bpermute_b32 v66, v116, v146
	ds_bpermute_b32 v67, v116, v148
	ds_bpermute_b32 v68, v116, v143
	ds_bpermute_b32 v69, v116, v145
	ds_bpermute_b32 v70, v116, v147
	ds_bpermute_b32 v71, v116, v149
	s_waitcnt lgkmcnt(0)
	s_mov_b32 s88, 0xff00ff
	s_mov_b32 s89, 0xff00ff
	v_min_u32_e32 v96, v142, v64
	v_max_u32_e32 v97, v142, v64
	v_cndmask_b32_e64 v142, v97, v96, s[88:89]
	v_min_u32_e32 v98, v144, v65
	v_max_u32_e32 v99, v144, v65
	v_cndmask_b32_e64 v144, v99, v98, s[88:89]
	v_min_u32_e32 v96, v146, v66
	v_max_u32_e32 v97, v146, v66
	v_cndmask_b32_e64 v146, v97, v96, s[88:89]
	v_min_u32_e32 v98, v148, v67
	v_max_u32_e32 v99, v148, v67
	v_cndmask_b32_e64 v148, v99, v98, s[88:89]
	v_min_u32_e32 v96, v143, v68
	v_max_u32_e32 v97, v143, v68
	v_cndmask_b32_e64 v143, v97, v96, s[88:89]
	v_min_u32_e32 v98, v145, v69
	v_max_u32_e32 v99, v145, v69
	v_cndmask_b32_e64 v145, v99, v98, s[88:89]
	v_min_u32_e32 v96, v147, v70
	v_max_u32_e32 v97, v147, v70
	v_cndmask_b32_e64 v147, v97, v96, s[88:89]
	v_min_u32_e32 v98, v149, v71
	v_max_u32_e32 v99, v149, v71
	v_cndmask_b32_e64 v149, v99, v98, s[88:89]
	v_xor_b32_e32 v116, 16, v252
	ds_bpermute_b32 v64, v116, v142
	ds_bpermute_b32 v65, v116, v144
	ds_bpermute_b32 v66, v116, v146
	ds_bpermute_b32 v67, v116, v148
	ds_bpermute_b32 v68, v116, v143
	ds_bpermute_b32 v69, v116, v145
	ds_bpermute_b32 v70, v116, v147
	ds_bpermute_b32 v71, v116, v149
	s_waitcnt lgkmcnt(0)
; #define PG_ISSUE(BUF, TAB, e0_) do { const int isrc_ = ((e0_) < 64) ? myi0 : myi1; \
;       _Pragma("unroll") for (int e = 0; e < 8; ++e) { const int idx_ = __builtin_amdgcn_readlane(isrc_, ((e0_) + e) & 63); \
;         BUF[e] = *(const u32x4*)((TAB) + (size_t)idx_ * 1024 + lane * 16); } } while (0)
; DEV void sort_lists(int lane, int& myi0, int& myi1, float& myg0, float& myg1) {
; #pragma unroll
;     for (int k = 2; k <= 128; k <<= 1) {
; #pragma unroll
;       for (int j = k >> 1; j >= 1; j >>= 1) {
;         if (j == 64) {
;           const bool sw_ = myi1 < myi0;
;           const int ti = sw_ ? myi1 : myi0, tj = sw_ ? myi0 : myi1; const float tg = sw_ ? myg1 : myg0, th = sw_ ? myg0 : myg1;
;           myi0 = ti; myi1 = tj; myg0 = tg; myg1 = th;
;         } else {
;           const bool lower = (lane & j) == 0;
;           {
;             const bool up = (k == 128) ? true : ((k == 64) ? true : ((lane & k) == 0));
;             const int oi = __shfl_xor(myi0, j); const float og = __shfl_xor(myg0, j);
;             const bool take = (lower == up) ? (oi < myi0) : (oi > myi0);
;             myi0 = take ? oi : myi0; myg0 = take ? og : myg0;
;           }
;           {
;             const bool up = (k == 128) ? true : ((k == 64) ? false : ((lane & k) == 0));
;             const int oi = __shfl_xor(myi1, j); const float og = __shfl_xor(myg1, j);
;             const bool take = (lower == up) ? (oi < myi1) : (oi > myi1);
;             myi1 = take ? oi : myi1; myg1 = take ? og : myg1;
;           }
;         }
;       }
;     }
; }
; DEV void peer_gather(const Params& P, int l, int m0, const int* idxs, const float* gs) {
;     ...
;     PG_ISSUE(b0, U, 0);
	s_mov_b32 s88, 0xf0f0f0f
	s_mov_b32 s89, 0xf0f0f0f
	v_min_u32_e32 v96, v142, v64
	v_max_u32_e32 v97, v142, v64
	v_cndmask_b32_e64 v142, v97, v96, s[88:89]
	v_min_u32_e32 v98, v144, v65
	v_max_u32_e32 v99, v144, v65
	v_cndmask_b32_e64 v144, v99, v98, s[88:89]
	v_min_u32_e32 v96, v146, v66
	v_max_u32_e32 v97, v146, v66
	v_cndmask_b32_e64 v146, v97, v96, s[88:89]
	v_min_u32_e32 v98, v148, v67
	v_max_u32_e32 v99, v148, v67
	v_cndmask_b32_e64 v148, v99, v98, s[88:89]
	v_min_u32_e32 v96, v143, v68
	v_max_u32_e32 v97, v143, v68
	v_cndmask_b32_e64 v143, v97, v96, s[88:89]
	v_min_u32_e32 v98, v145, v69
	v_max_u32_e32 v99, v145, v69
	v_cndmask_b32_e64 v145, v99, v98, s[88:89]
	v_min_u32_e32 v96, v147, v70
	v_max_u32_e32 v97, v147, v70
	v_cndmask_b32_e64 v147, v97, v96, s[88:89]
	v_min_u32_e32 v98, v149, v71
	v_max_u32_e32 v99, v149, v71
	v_cndmask_b32_e64 v149, v99, v98, s[88:89]
	v_xor_b32_e32 v116, 8, v252
	ds_bpermute_b32 v64, v116, v142
	ds_bpermute_b32 v65, v116, v144
	ds_bpermute_b32 v66, v116, v146
	ds_bpermute_b32 v67, v116, v148
	ds_bpermute_b32 v68, v116, v143
	ds_bpermute_b32 v69, v116, v145
	ds_bpermute_b32 v70, v116, v147
	ds_bpermute_b32 v71, v116, v149
	s_waitcnt lgkmcnt(0)
	s_mov_b32 s88, 0x33333333
	s_mov_b32 s89, 0x33333333
	v_min_u32_e32 v96, v142, v64
	v_max_u32_e32 v97, v142, v64
	v_cndmask_b32_e64 v142, v97, v96, s[88:89]
	v_min_u32_e32 v98, v144, v65
	v_max_u32_e32 v99, v144, v65
	v_cndmask_b32_e64 v144, v99, v98, s[88:89]
	v_min_u32_e32 v96, v146, v66
	v_max_u32_e32 v97, v146, v66
	v_cndmask_b32_e64 v146, v97, v96, s[88:89]
	v_min_u32_e32 v98, v148, v67
	v_max_u32_e32 v99, v148, v67
	v_cndmask_b32_e64 v148, v99, v98, s[88:89]
	v_min_u32_e32 v96, v143, v68
	v_max_u32_e32 v97, v143, v68
	v_cndmask_b32_e64 v143, v97, v96, s[88:89]
	v_min_u32_e32 v98, v145, v69
	v_max_u32_e32 v99, v145, v69
	v_cndmask_b32_e64 v145, v99, v98, s[88:89]
	v_min_u32_e32 v96, v147, v70
	v_max_u32_e32 v97, v147, v70
	v_cndmask_b32_e64 v147, v97, v96, s[88:89]
	v_min_u32_e32 v98, v149, v71
	v_max_u32_e32 v99, v149, v71
	v_cndmask_b32_e64 v149, v99, v98, s[88:89]
	v_xor_b32_e32 v116, 4, v252
	ds_bpermute_b32 v64, v116, v142
	ds_bpermute_b32 v65, v116, v144
	ds_bpermute_b32 v66, v116, v146
	ds_bpermute_b32 v67, v116, v148
	ds_bpermute_b32 v68, v116, v143
	ds_bpermute_b32 v69, v116, v145
	ds_bpermute_b32 v70, v116, v147
	ds_bpermute_b32 v71, v116, v149
	s_waitcnt lgkmcnt(0)
	s_mov_b32 s88, 0x55555555
	s_mov_b32 s89, 0x55555555
	v_min_u32_e32 v96, v142, v64
	v_max_u32_e32 v97, v142, v64
	v_cndmask_b32_e64 v142, v97, v96, s[88:89]
	v_min_u32_e32 v98, v144, v65
	v_max_u32_e32 v99, v144, v65
	v_cndmask_b32_e64 v144, v99, v98, s[88:89]
	v_min_u32_e32 v96, v146, v66
	v_max_u32_e32 v97, v146, v66
	v_cndmask_b32_e64 v146, v97, v96, s[88:89]
	v_min_u32_e32 v98, v148, v67
	v_max_u32_e32 v99, v148, v67
	v_cndmask_b32_e64 v148, v99, v98, s[88:89]
	v_min_u32_e32 v96, v143, v68
	v_max_u32_e32 v97, v143, v68
	v_cndmask_b32_e64 v143, v97, v96, s[88:89]
	v_min_u32_e32 v98, v145, v69
	v_max_u32_e32 v99, v145, v69
	v_cndmask_b32_e64 v145, v99, v98, s[88:89]
	v_min_u32_e32 v96, v147, v70
	v_max_u32_e32 v97, v147, v70
	v_cndmask_b32_e64 v147, v97, v96, s[88:89]
	v_min_u32_e32 v98, v149, v71
	v_max_u32_e32 v99, v149, v71
	v_cndmask_b32_e64 v149, v99, v98, s[88:89]
	v_readlane_b32 s82, v232, 1
	v_readlane_b32 s83, v232, 2
	s_nop 4
	s_add_u32 s98, s33, 0
	s_lshl_b32 s98, s98, 9
	v_and_b32_e32 v116, 0x7f, v142
	v_lshl_add_u32 v116, v116, 2, s98
	global_load_dword v233, v116, s[82:83]
	v_lshrrev_b32_e32 v142, 7, v142
	v_and_b32_e32 v117, 0x7f, v143
	v_lshl_add_u32 v117, v117, 2, s98
	global_load_dword v234, v117, s[82:83]
	v_lshrrev_b32_e32 v143, 7, v143
	s_add_u32 s98, s33, 1
	s_lshl_b32 s98, s98, 9
	v_and_b32_e32 v118, 0x7f, v144
	v_lshl_add_u32 v118, v118, 2, s98
	global_load_dword v235, v118, s[82:83]
	v_lshrrev_b32_e32 v144, 7, v144
	v_and_b32_e32 v119, 0x7f, v145
	v_lshl_add_u32 v119, v119, 2, s98
	global_load_dword v236, v119, s[82:83]
	v_lshrrev_b32_e32 v145, 7, v145
	s_add_u32 s98, s33, 2
	s_lshl_b32 s98, s98, 9
	v_and_b32_e32 v116, 0x7f, v146
	v_lshl_add_u32 v116, v116, 2, s98
	global_load_dword v237, v116, s[82:83]
	v_lshrrev_b32_e32 v146, 7, v146
	v_and_b32_e32 v117, 0x7f, v147
	v_lshl_add_u32 v117, v117, 2, s98
	global_load_dword v238, v117, s[82:83]
	v_lshrrev_b32_e32 v147, 7, v147
	s_add_u32 s98, s33, 3
	s_lshl_b32 s98, s98, 9
	v_and_b32_e32 v118, 0x7f, v148
	v_lshl_add_u32 v118, v118, 2, s98
	global_load_dword v239, v118, s[82:83]
	v_lshrrev_b32_e32 v148, 7, v148
	v_and_b32_e32 v119, 0x7f, v149
	v_lshl_add_u32 v119, v119, 2, s98
	global_load_dword v240, v119, s[82:83]
	v_lshrrev_b32_e32 v149, 7, v149
	v_readfirstlane_b32 s80, v126
	v_readfirstlane_b32 s81, v127
	s_nop 4
	v_mov_b32_e32 v241, 0
	v_mov_b32_e32 v242, 0
	v_mov_b32_e32 v243, 0
	v_mov_b32_e32 v244, 0
	v_mov_b32_e32 v245, 0
	v_mov_b32_e32 v246, 0
	v_mov_b32_e32 v247, 0
	v_mov_b32_e32 v248, 0
	s_mov_b32 s100, 0
	s_mov_b32 s101, 0
	s_mov_b64 s[90:91], 0
	v_cndmask_b32_e64 v153, v142, v143, s[90:91]
	s_nop 0
	s_add_u32 s98, s101, 0
	v_readlane_b32 s98, v153, s98
	s_add_u32 s99, s101, 1
	v_readlane_b32 s99, v153, s99
	s_add_u32 s92, s101, 2
	v_readlane_b32 s92, v153, s92
	s_add_u32 s93, s101, 3
	v_readlane_b32 s93, v153, s93
	v_lshl_add_u32 v134, s98, 10, v250
	v_lshl_add_u32 v135, s99, 10, v250
	v_lshl_add_u32 v136, s92, 10, v250
	v_lshl_add_u32 v137, s93, 10, v250
	s_add_u32 s98, s101, 4
	v_readlane_b32 s98, v153, s98
	s_add_u32 s99, s101, 5
	v_readlane_b32 s99, v153, s99
	s_add_u32 s92, s101, 6
	v_readlane_b32 s92, v153, s92
	s_add_u32 s93, s101, 7
	v_readlane_b32 s93, v153, s93
	v_lshl_add_u32 v138, s98, 10, v250
	v_lshl_add_u32 v139, s99, 10, v250
	v_lshl_add_u32 v140, s92, 10, v250
	v_lshl_add_u32 v141, s93, 10, v250
	global_load_dwordx4 v[64:67], v134, s[80:81]
	global_load_dwordx4 v[68:71], v135, s[80:81]
	global_load_dwordx4 v[72:75], v136, s[80:81]
	global_load_dwordx4 v[76:79], v137, s[80:81]
	global_load_dwordx4 v[80:83], v138, s[80:81]
	global_load_dwordx4 v[84:87], v139, s[80:81]
	global_load_dwordx4 v[88:91], v140, s[80:81]
	global_load_dwordx4 v[92:95], v141, s[80:81]
; #define PG_ISSUE(BUF, TAB, e0_) do { const int isrc_ = ((e0_) < 64) ? myi0 : myi1; \
;       _Pragma("unroll") for (int e = 0; e < 8; ++e) { const int idx_ = __builtin_amdgcn_readlane(isrc_, ((e0_) + e) & 63); \
;         BUF[e] = *(const u32x4*)((TAB) + (size_t)idx_ * 1024 + lane * 16); } } while (0)
; DEV void peer_gather(const Params& P, int l, int m0, const int* idxs, const float* gs) {
;     ...
;     PG_ISSUE(b0, U, 0);
; #pragma nounroll
;     for (int e0 = 0; e0 < 128; e0 += 16) {
;       PG_ISSUE(b1, U, e0 + 8);
;       PG_U8(b0, 0, e0);
;       if (e0 + 16 < 128) PG_ISSUE(b0, U, e0 + 16); else PG_ISSUE(b0, V, 0);
;       PG_U8(b1, 0, e0 + 8);
;     }
.Lpg1_Uloop:
	s_cmp_ge_u32 s100, 8
	s_cselect_b64 s[90:91], -1, 0
	s_and_b32 s98, s100, 7
	s_lshl_b32 s98, s98, 3
	s_lshl_b64 s[88:89], 0xff, s98
	s_cmp_ge_u32 s100, 8
	s_cselect_b64 s[84:85], 0, s[88:89]
	s_cselect_b64 s[86:87], s[88:89], 0
	v_cndmask_b32_e64 v153, v144, v145, s[90:91]
	s_nop 0
	s_add_u32 s98, s101, 0
	v_readlane_b32 s98, v153, s98
	s_add_u32 s99, s101, 1
	v_readlane_b32 s99, v153, s99
	s_add_u32 s92, s101, 2
	v_readlane_b32 s92, v153, s92
	s_add_u32 s93, s101, 3
	v_readlane_b32 s93, v153, s93
	v_lshl_add_u32 v134, s98, 10, v250
	v_lshl_add_u32 v135, s99, 10, v250
	v_lshl_add_u32 v136, s92, 10, v250
	v_lshl_add_u32 v137, s93, 10, v250
	s_add_u32 s98, s101, 4
	v_readlane_b32 s98, v153, s98
	s_add_u32 s99, s101, 5
	v_readlane_b32 s99, v153, s99
	s_add_u32 s92, s101, 6
	v_readlane_b32 s92, v153, s92
	s_add_u32 s93, s101, 7
	v_readlane_b32 s93, v153, s93
	v_lshl_add_u32 v138, s98, 10, v250
	v_lshl_add_u32 v139, s99, 10, v250
	v_lshl_add_u32 v140, s92, 10, v250
	v_lshl_add_u32 v141, s93, 10, v250
	s_waitcnt vmcnt(6)
	v_cvt_pk_f32_fp8_e32 v[96:97], v64
	v_cvt_pk_f32_fp8_e32 v[100:101], v68
	v_cvt_pk_f32_fp8_sdwa v[98:99], v64 src0_sel:WORD_1
	v_cvt_pk_f32_fp8_sdwa v[102:103], v68 src0_sel:WORD_1
	v_pk_mul_f32 v[104:105], v[0:1], v[96:97]
	v_pk_mul_f32 v[106:107], v[0:1], v[100:101]
	v_pk_fma_f32 v[104:105], v[2:3], v[98:99], v[104:105]
	v_pk_fma_f32 v[106:107], v[2:3], v[102:103], v[106:107]
	v_cvt_pk_f32_fp8_e32 v[96:97], v65
	v_cvt_pk_f32_fp8_e32 v[100:101], v69
	v_cvt_pk_f32_fp8_sdwa v[98:99], v65 src0_sel:WORD_1
	v_cvt_pk_f32_fp8_sdwa v[102:103], v69 src0_sel:WORD_1
	v_pk_fma_f32 v[104:105], v[4:5], v[96:97], v[104:105]
	v_pk_fma_f32 v[106:107], v[4:5], v[100:101], v[106:107]
	v_pk_fma_f32 v[104:105], v[6:7], v[98:99], v[104:105]
	v_pk_fma_f32 v[106:107], v[6:7], v[102:103], v[106:107]
	v_cvt_pk_f32_fp8_e32 v[96:97], v66
	v_cvt_pk_f32_fp8_e32 v[100:101], v70
	v_cvt_pk_f32_fp8_sdwa v[98:99], v66 src0_sel:WORD_1
	v_cvt_pk_f32_fp8_sdwa v[102:103], v70 src0_sel:WORD_1
	v_pk_fma_f32 v[104:105], v[8:9], v[96:97], v[104:105]
	v_pk_fma_f32 v[106:107], v[8:9], v[100:101], v[106:107]
	v_pk_fma_f32 v[104:105], v[10:11], v[98:99], v[104:105]
	v_pk_fma_f32 v[106:107], v[10:11], v[102:103], v[106:107]
	v_cvt_pk_f32_fp8_e32 v[96:97], v67
	v_cvt_pk_f32_fp8_e32 v[100:101], v71
	v_cvt_pk_f32_fp8_sdwa v[98:99], v67 src0_sel:WORD_1
	v_cvt_pk_f32_fp8_sdwa v[102:103], v71 src0_sel:WORD_1
	global_load_dwordx4 v[64:67], v134, s[80:81]
	global_load_dwordx4 v[68:71], v135, s[80:81]
	v_pk_fma_f32 v[104:105], v[12:13], v[96:97], v[104:105]
	v_pk_fma_f32 v[106:107], v[12:13], v[100:101], v[106:107]
	v_pk_fma_f32 v[104:105], v[14:15], v[98:99], v[104:105]
	v_pk_fma_f32 v[106:107], v[14:15], v[102:103], v[106:107]
	s_nop 0
	v_add_f32_e32 v108, v104, v105
	v_add_f32_e32 v109, v106, v107
	s_waitcnt vmcnt(6)
	v_cvt_pk_f32_fp8_e32 v[96:97], v72
	v_cvt_pk_f32_fp8_e32 v[100:101], v76
	v_cvt_pk_f32_fp8_sdwa v[98:99], v72 src0_sel:WORD_1
	v_cvt_pk_f32_fp8_sdwa v[102:103], v76 src0_sel:WORD_1
	v_pk_mul_f32 v[104:105], v[0:1], v[96:97]
	v_pk_mul_f32 v[106:107], v[0:1], v[100:101]
	v_pk_fma_f32 v[104:105], v[2:3], v[98:99], v[104:105]
	v_pk_fma_f32 v[106:107], v[2:3], v[102:103], v[106:107]
	v_cvt_pk_f32_fp8_e32 v[96:97], v73
	v_cvt_pk_f32_fp8_e32 v[100:101], v77
	v_cvt_pk_f32_fp8_sdwa v[98:99], v73 src0_sel:WORD_1
	v_cvt_pk_f32_fp8_sdwa v[102:103], v77 src0_sel:WORD_1
	v_pk_fma_f32 v[104:105], v[4:5], v[96:97], v[104:105]
	v_pk_fma_f32 v[106:107], v[4:5], v[100:101], v[106:107]
	v_pk_fma_f32 v[104:105], v[6:7], v[98:99], v[104:105]
	v_pk_fma_f32 v[106:107], v[6:7], v[102:103], v[106:107]
	v_cvt_pk_f32_fp8_e32 v[96:97], v74
	v_cvt_pk_f32_fp8_e32 v[100:101], v78
	v_cvt_pk_f32_fp8_sdwa v[98:99], v74 src0_sel:WORD_1
	v_cvt_pk_f32_fp8_sdwa v[102:103], v78 src0_sel:WORD_1
	v_pk_fma_f32 v[104:105], v[8:9], v[96:97], v[104:105]
	v_pk_fma_f32 v[106:107], v[8:9], v[100:101], v[106:107]
	v_pk_fma_f32 v[104:105], v[10:11], v[98:99], v[104:105]
	v_pk_fma_f32 v[106:107], v[10:11], v[102:103], v[106:107]
	v_cvt_pk_f32_fp8_e32 v[96:97], v75
	v_cvt_pk_f32_fp8_e32 v[100:101], v79
	v_cvt_pk_f32_fp8_sdwa v[98:99], v75 src0_sel:WORD_1
	v_cvt_pk_f32_fp8_sdwa v[102:103], v79 src0_sel:WORD_1
	global_load_dwordx4 v[72:75], v136, s[80:81]
	global_load_dwordx4 v[76:79], v137, s[80:81]
	v_pk_fma_f32 v[104:105], v[12:13], v[96:97], v[104:105]
	v_pk_fma_f32 v[106:107], v[12:13], v[100:101], v[106:107]
	v_pk_fma_f32 v[104:105], v[14:15], v[98:99], v[104:105]
	v_pk_fma_f32 v[106:107], v[14:15], v[102:103], v[106:107]
	s_nop 0
	v_add_f32_e32 v110, v104, v105
	v_add_f32_e32 v111, v106, v107
	s_waitcnt vmcnt(6)
	v_cvt_pk_f32_fp8_e32 v[96:97], v80
	v_cvt_pk_f32_fp8_e32 v[100:101], v84
	v_cvt_pk_f32_fp8_sdwa v[98:99], v80 src0_sel:WORD_1
	v_cvt_pk_f32_fp8_sdwa v[102:103], v84 src0_sel:WORD_1
	v_pk_mul_f32 v[104:105], v[0:1], v[96:97]
	v_pk_mul_f32 v[106:107], v[0:1], v[100:101]
	v_pk_fma_f32 v[104:105], v[2:3], v[98:99], v[104:105]
	v_pk_fma_f32 v[106:107], v[2:3], v[102:103], v[106:107]
	v_cvt_pk_f32_fp8_e32 v[96:97], v81
	v_cvt_pk_f32_fp8_e32 v[100:101], v85
	v_cvt_pk_f32_fp8_sdwa v[98:99], v81 src0_sel:WORD_1
	v_cvt_pk_f32_fp8_sdwa v[102:103], v85 src0_sel:WORD_1
	v_pk_fma_f32 v[104:105], v[4:5], v[96:97], v[104:105]
	v_pk_fma_f32 v[106:107], v[4:5], v[100:101], v[106:107]
	v_pk_fma_f32 v[104:105], v[6:7], v[98:99], v[104:105]
	v_pk_fma_f32 v[106:107], v[6:7], v[102:103], v[106:107]
	v_cvt_pk_f32_fp8_e32 v[96:97], v82
	v_cvt_pk_f32_fp8_e32 v[100:101], v86
	v_cvt_pk_f32_fp8_sdwa v[98:99], v82 src0_sel:WORD_1
	v_cvt_pk_f32_fp8_sdwa v[102:103], v86 src0_sel:WORD_1
	v_pk_fma_f32 v[104:105], v[8:9], v[96:97], v[104:105]
	v_pk_fma_f32 v[106:107], v[8:9], v[100:101], v[106:107]
	v_pk_fma_f32 v[104:105], v[10:11], v[98:99], v[104:105]
	v_pk_fma_f32 v[106:107], v[10:11], v[102:103], v[106:107]
	v_cvt_pk_f32_fp8_e32 v[96:97], v83
	v_cvt_pk_f32_fp8_e32 v[100:101], v87
	v_cvt_pk_f32_fp8_sdwa v[98:99], v83 src0_sel:WORD_1
	v_cvt_pk_f32_fp8_sdwa v[102:103], v87 src0_sel:WORD_1
	global_load_dwordx4 v[80:83], v138, s[80:81]
	global_load_dwordx4 v[84:87], v139, s[80:81]
	v_pk_fma_f32 v[104:105], v[12:13], v[96:97], v[104:105]
	v_pk_fma_f32 v[106:107], v[12:13], v[100:101], v[106:107]
	v_pk_fma_f32 v[104:105], v[14:15], v[98:99], v[104:105]
	v_pk_fma_f32 v[106:107], v[14:15], v[102:103], v[106:107]
	s_nop 0
	v_add_f32_e32 v112, v104, v105
	v_add_f32_e32 v113, v106, v107
	s_waitcnt vmcnt(6)
; #define PG_ISSUE(BUF, TAB, e0_) do { const int isrc_ = ((e0_) < 64) ? myi0 : myi1; \
;       _Pragma("unroll") for (int e = 0; e < 8; ++e) { const int idx_ = __builtin_amdgcn_readlane(isrc_, ((e0_) + e) & 63); \
;         BUF[e] = *(const u32x4*)((TAB) + (size_t)idx_ * 1024 + lane * 16); } } while (0)
; DEV void peer_gather(const Params& P, int l, int m0, const int* idxs, const float* gs) {
;     ...
;     PG_ISSUE(b0, U, 0);
; #pragma nounroll
;     for (int e0 = 0; e0 < 128; e0 += 16) {
;       PG_ISSUE(b1, U, e0 + 8);
;       PG_U8(b0, 0, e0);
;       if (e0 + 16 < 128) PG_ISSUE(b0, U, e0 + 16); else PG_ISSUE(b0, V, 0);
;       PG_U8(b1, 0, e0 + 8);
;     }
	v_cvt_pk_f32_fp8_e32 v[96:97], v88
	v_cvt_pk_f32_fp8_e32 v[100:101], v92
	v_cvt_pk_f32_fp8_sdwa v[98:99], v88 src0_sel:WORD_1
	v_cvt_pk_f32_fp8_sdwa v[102:103], v92 src0_sel:WORD_1
	v_pk_mul_f32 v[104:105], v[0:1], v[96:97]
	v_pk_mul_f32 v[106:107], v[0:1], v[100:101]
	v_pk_fma_f32 v[104:105], v[2:3], v[98:99], v[104:105]
	v_pk_fma_f32 v[106:107], v[2:3], v[102:103], v[106:107]
	v_cvt_pk_f32_fp8_e32 v[96:97], v89
	v_cvt_pk_f32_fp8_e32 v[100:101], v93
	v_cvt_pk_f32_fp8_sdwa v[98:99], v89 src0_sel:WORD_1
	v_cvt_pk_f32_fp8_sdwa v[102:103], v93 src0_sel:WORD_1
	v_pk_fma_f32 v[104:105], v[4:5], v[96:97], v[104:105]
	v_pk_fma_f32 v[106:107], v[4:5], v[100:101], v[106:107]
	v_pk_fma_f32 v[104:105], v[6:7], v[98:99], v[104:105]
	v_pk_fma_f32 v[106:107], v[6:7], v[102:103], v[106:107]
	v_cvt_pk_f32_fp8_e32 v[96:97], v90
	v_cvt_pk_f32_fp8_e32 v[100:101], v94
	v_cvt_pk_f32_fp8_sdwa v[98:99], v90 src0_sel:WORD_1
	v_cvt_pk_f32_fp8_sdwa v[102:103], v94 src0_sel:WORD_1
	v_pk_fma_f32 v[104:105], v[8:9], v[96:97], v[104:105]
	v_pk_fma_f32 v[106:107], v[8:9], v[100:101], v[106:107]
	v_pk_fma_f32 v[104:105], v[10:11], v[98:99], v[104:105]
	v_pk_fma_f32 v[106:107], v[10:11], v[102:103], v[106:107]
	v_cvt_pk_f32_fp8_e32 v[96:97], v91
	v_cvt_pk_f32_fp8_e32 v[100:101], v95
	v_cvt_pk_f32_fp8_sdwa v[98:99], v91 src0_sel:WORD_1
	v_cvt_pk_f32_fp8_sdwa v[102:103], v95 src0_sel:WORD_1
	global_load_dwordx4 v[88:91], v140, s[80:81]
	global_load_dwordx4 v[92:95], v141, s[80:81]
	v_pk_fma_f32 v[104:105], v[12:13], v[96:97], v[104:105]
	v_pk_fma_f32 v[106:107], v[12:13], v[100:101], v[106:107]
	v_pk_fma_f32 v[104:105], v[14:15], v[98:99], v[104:105]
	v_pk_fma_f32 v[106:107], v[14:15], v[102:103], v[106:107]
	s_nop 0
	v_add_f32_e32 v114, v104, v105
	v_add_f32_e32 v115, v106, v107
	s_nop 1
	v_permlane32_swap_b32_e32 v108, v109
	v_permlane32_swap_b32_e32 v110, v111
	v_permlane32_swap_b32_e32 v112, v113
	v_permlane32_swap_b32_e32 v114, v115
	v_add_f32_e32 v108, v108, v109
	v_add_f32_e32 v110, v110, v111
	v_add_f32_e32 v112, v112, v113
	v_add_f32_e32 v114, v114, v115
	s_nop 1
	v_permlane16_swap_b32_e32 v108, v110
	v_permlane16_swap_b32_e32 v112, v114
	v_add_f32_e32 v108, v108, v110
	v_add_f32_e32 v112, v112, v114
	s_mov_b32 s88, 0xff00ff00
	s_mov_b32 s89, 0xff00ff00
	s_nop 0
	v_cndmask_b32_e64 v109, v108, v112, s[88:89]
	v_cndmask_b32_e64 v111, v112, v108, s[88:89]
	s_nop 1
	v_add_f32_dpp v109, v111, v109 row_ror:8 row_mask:0xf bank_mask:0xf
	s_nop 1
	v_add_f32_dpp v109, v109, v109 quad_perm:[1,0,3,2] row_mask:0xf bank_mask:0xf
	s_nop 1
	v_add_f32_dpp v109, v109, v109 quad_perm:[2,3,0,1] row_mask:0xf bank_mask:0xf
	s_nop 1
	v_add_f32_dpp v109, v109, v109 row_half_mirror row_mask:0xf bank_mask:0xf
	s_nop 0
	ds_bpermute_b32 v110, v251, v109
	s_waitcnt lgkmcnt(0)
	v_cndmask_b32_e64 v241, v241, v110, s[84:85]
	v_cndmask_b32_e64 v242, v242, v110, s[86:87]
	v_cndmask_b32_e64 v153, v146, v147, s[90:91]
	s_nop 0
	s_add_u32 s98, s101, 0
	v_readlane_b32 s98, v153, s98
	s_add_u32 s99, s101, 1
	v_readlane_b32 s99, v153, s99
	s_add_u32 s92, s101, 2
	v_readlane_b32 s92, v153, s92
	s_add_u32 s93, s101, 3
	v_readlane_b32 s93, v153, s93
	v_lshl_add_u32 v134, s98, 10, v250
	v_lshl_add_u32 v135, s99, 10, v250
	v_lshl_add_u32 v136, s92, 10, v250
	v_lshl_add_u32 v137, s93, 10, v250
	s_add_u32 s98, s101, 4
	v_readlane_b32 s98, v153, s98
	s_add_u32 s99, s101, 5
	v_readlane_b32 s99, v153, s99
	s_add_u32 s92, s101, 6
	v_readlane_b32 s92, v153, s92
	s_add_u32 s93, s101, 7
	v_readlane_b32 s93, v153, s93
	v_lshl_add_u32 v138, s98, 10, v250
	v_lshl_add_u32 v139, s99, 10, v250
	v_lshl_add_u32 v140, s92, 10, v250
	v_lshl_add_u32 v141, s93, 10, v250
	s_waitcnt vmcnt(6)
	v_cvt_pk_f32_fp8_e32 v[96:97], v64
	v_cvt_pk_f32_fp8_e32 v[100:101], v68
	v_cvt_pk_f32_fp8_sdwa v[98:99], v64 src0_sel:WORD_1
	v_cvt_pk_f32_fp8_sdwa v[102:103], v68 src0_sel:WORD_1
	v_pk_mul_f32 v[104:105], v[16:17], v[96:97]
	v_pk_mul_f32 v[106:107], v[16:17], v[100:101]
	v_pk_fma_f32 v[104:105], v[18:19], v[98:99], v[104:105]
	v_pk_fma_f32 v[106:107], v[18:19], v[102:103], v[106:107]
	v_cvt_pk_f32_fp8_e32 v[96:97], v65
	v_cvt_pk_f32_fp8_e32 v[100:101], v69
	v_cvt_pk_f32_fp8_sdwa v[98:99], v65 src0_sel:WORD_1
	v_cvt_pk_f32_fp8_sdwa v[102:103], v69 src0_sel:WORD_1
	v_pk_fma_f32 v[104:105], v[20:21], v[96:97], v[104:105]
	v_pk_fma_f32 v[106:107], v[20:21], v[100:101], v[106:107]
	v_pk_fma_f32 v[104:105], v[22:23], v[98:99], v[104:105]
	v_pk_fma_f32 v[106:107], v[22:23], v[102:103], v[106:107]
	v_cvt_pk_f32_fp8_e32 v[96:97], v66
	v_cvt_pk_f32_fp8_e32 v[100:101], v70
	v_cvt_pk_f32_fp8_sdwa v[98:99], v66 src0_sel:WORD_1
	v_cvt_pk_f32_fp8_sdwa v[102:103], v70 src0_sel:WORD_1
	v_pk_fma_f32 v[104:105], v[24:25], v[96:97], v[104:105]
	v_pk_fma_f32 v[106:107], v[24:25], v[100:101], v[106:107]
	v_pk_fma_f32 v[104:105], v[26:27], v[98:99], v[104:105]
	v_pk_fma_f32 v[106:107], v[26:27], v[102:103], v[106:107]
	v_cvt_pk_f32_fp8_e32 v[96:97], v67
	v_cvt_pk_f32_fp8_e32 v[100:101], v71
	v_cvt_pk_f32_fp8_sdwa v[98:99], v67 src0_sel:WORD_1
	v_cvt_pk_f32_fp8_sdwa v[102:103], v71 src0_sel:WORD_1
	global_load_dwordx4 v[64:67], v134, s[80:81]
	global_load_dwordx4 v[68:71], v135, s[80:81]
	v_pk_fma_f32 v[104:105], v[28:29], v[96:97], v[104:105]
	v_pk_fma_f32 v[106:107], v[28:29], v[100:101], v[106:107]
	v_pk_fma_f32 v[104:105], v[30:31], v[98:99], v[104:105]
	v_pk_fma_f32 v[106:107], v[30:31], v[102:103], v[106:107]
	s_nop 0
	v_add_f32_e32 v108, v104, v105
	v_add_f32_e32 v109, v106, v107
	s_waitcnt vmcnt(6)
; #define PG_ISSUE(BUF, TAB, e0_) do { const int isrc_ = ((e0_) < 64) ? myi0 : myi1; \
;       _Pragma("unroll") for (int e = 0; e < 8; ++e) { const int idx_ = __builtin_amdgcn_readlane(isrc_, ((e0_) + e) & 63); \
;         BUF[e] = *(const u32x4*)((TAB) + (size_t)idx_ * 1024 + lane * 16); } } while (0)
; DEV void peer_gather(const Params& P, int l, int m0, const int* idxs, const float* gs) {
;     ...
;     PG_ISSUE(b0, U, 0);
; #pragma nounroll
;     for (int e0 = 0; e0 < 128; e0 += 16) {
;       PG_ISSUE(b1, U, e0 + 8);
;       PG_U8(b0, 0, e0);
;       if (e0 + 16 < 128) PG_ISSUE(b0, U, e0 + 16); else PG_ISSUE(b0, V, 0);
;       PG_U8(b1, 0, e0 + 8);
;     }
	v_cvt_pk_f32_fp8_e32 v[96:97], v72
	v_cvt_pk_f32_fp8_e32 v[100:101], v76
	v_cvt_pk_f32_fp8_sdwa v[98:99], v72 src0_sel:WORD_1
	v_cvt_pk_f32_fp8_sdwa v[102:103], v76 src0_sel:WORD_1
	v_pk_mul_f32 v[104:105], v[16:17], v[96:97]
	v_pk_mul_f32 v[106:107], v[16:17], v[100:101]
	v_pk_fma_f32 v[104:105], v[18:19], v[98:99], v[104:105]
	v_pk_fma_f32 v[106:107], v[18:19], v[102:103], v[106:107]
	v_cvt_pk_f32_fp8_e32 v[96:97], v73
	v_cvt_pk_f32_fp8_e32 v[100:101], v77
	v_cvt_pk_f32_fp8_sdwa v[98:99], v73 src0_sel:WORD_1
	v_cvt_pk_f32_fp8_sdwa v[102:103], v77 src0_sel:WORD_1
	v_pk_fma_f32 v[104:105], v[20:21], v[96:97], v[104:105]
	v_pk_fma_f32 v[106:107], v[20:21], v[100:101], v[106:107]
	v_pk_fma_f32 v[104:105], v[22:23], v[98:99], v[104:105]
	v_pk_fma_f32 v[106:107], v[22:23], v[102:103], v[106:107]
	v_cvt_pk_f32_fp8_e32 v[96:97], v74
	v_cvt_pk_f32_fp8_e32 v[100:101], v78
	v_cvt_pk_f32_fp8_sdwa v[98:99], v74 src0_sel:WORD_1
	v_cvt_pk_f32_fp8_sdwa v[102:103], v78 src0_sel:WORD_1
	v_pk_fma_f32 v[104:105], v[24:25], v[96:97], v[104:105]
	v_pk_fma_f32 v[106:107], v[24:25], v[100:101], v[106:107]
	v_pk_fma_f32 v[104:105], v[26:27], v[98:99], v[104:105]
	v_pk_fma_f32 v[106:107], v[26:27], v[102:103], v[106:107]
	v_cvt_pk_f32_fp8_e32 v[96:97], v75
	v_cvt_pk_f32_fp8_e32 v[100:101], v79
	v_cvt_pk_f32_fp8_sdwa v[98:99], v75 src0_sel:WORD_1
	v_cvt_pk_f32_fp8_sdwa v[102:103], v79 src0_sel:WORD_1
	global_load_dwordx4 v[72:75], v136, s[80:81]
	global_load_dwordx4 v[76:79], v137, s[80:81]
	v_pk_fma_f32 v[104:105], v[28:29], v[96:97], v[104:105]
	v_pk_fma_f32 v[106:107], v[28:29], v[100:101], v[106:107]
	v_pk_fma_f32 v[104:105], v[30:31], v[98:99], v[104:105]
	v_pk_fma_f32 v[106:107], v[30:31], v[102:103], v[106:107]
	s_nop 0
	v_add_f32_e32 v110, v104, v105
	v_add_f32_e32 v111, v106, v107
	s_waitcnt vmcnt(6)
	v_cvt_pk_f32_fp8_e32 v[96:97], v80
	v_cvt_pk_f32_fp8_e32 v[100:101], v84
	v_cvt_pk_f32_fp8_sdwa v[98:99], v80 src0_sel:WORD_1
	v_cvt_pk_f32_fp8_sdwa v[102:103], v84 src0_sel:WORD_1
	v_pk_mul_f32 v[104:105], v[16:17], v[96:97]
	v_pk_mul_f32 v[106:107], v[16:17], v[100:101]
	v_pk_fma_f32 v[104:105], v[18:19], v[98:99], v[104:105]
	v_pk_fma_f32 v[106:107], v[18:19], v[102:103], v[106:107]
	v_cvt_pk_f32_fp8_e32 v[96:97], v81
	v_cvt_pk_f32_fp8_e32 v[100:101], v85
	v_cvt_pk_f32_fp8_sdwa v[98:99], v81 src0_sel:WORD_1
	v_cvt_pk_f32_fp8_sdwa v[102:103], v85 src0_sel:WORD_1
	v_pk_fma_f32 v[104:105], v[20:21], v[96:97], v[104:105]
	v_pk_fma_f32 v[106:107], v[20:21], v[100:101], v[106:107]
	v_pk_fma_f32 v[104:105], v[22:23], v[98:99], v[104:105]
	v_pk_fma_f32 v[106:107], v[22:23], v[102:103], v[106:107]
	v_cvt_pk_f32_fp8_e32 v[96:97], v82
	v_cvt_pk_f32_fp8_e32 v[100:101], v86
	v_cvt_pk_f32_fp8_sdwa v[98:99], v82 src0_sel:WORD_1
	v_cvt_pk_f32_fp8_sdwa v[102:103], v86 src0_sel:WORD_1
	v_pk_fma_f32 v[104:105], v[24:25], v[96:97], v[104:105]
	v_pk_fma_f32 v[106:107], v[24:25], v[100:101], v[106:107]
	v_pk_fma_f32 v[104:105], v[26:27], v[98:99], v[104:105]
	v_pk_fma_f32 v[106:107], v[26:27], v[102:103], v[106:107]
	v_cvt_pk_f32_fp8_e32 v[96:97], v83
	v_cvt_pk_f32_fp8_e32 v[100:101], v87
	v_cvt_pk_f32_fp8_sdwa v[98:99], v83 src0_sel:WORD_1
	v_cvt_pk_f32_fp8_sdwa v[102:103], v87 src0_sel:WORD_1
	global_load_dwordx4 v[80:83], v138, s[80:81]
	global_load_dwordx4 v[84:87], v139, s[80:81]
	v_pk_fma_f32 v[104:105], v[28:29], v[96:97], v[104:105]
	v_pk_fma_f32 v[106:107], v[28:29], v[100:101], v[106:107]
	v_pk_fma_f32 v[104:105], v[30:31], v[98:99], v[104:105]
	v_pk_fma_f32 v[106:107], v[30:31], v[102:103], v[106:107]
	s_nop 0
	v_add_f32_e32 v112, v104, v105
	v_add_f32_e32 v113, v106, v107
	s_waitcnt vmcnt(6)
	v_cvt_pk_f32_fp8_e32 v[96:97], v88
	v_cvt_pk_f32_fp8_e32 v[100:101], v92
	v_cvt_pk_f32_fp8_sdwa v[98:99], v88 src0_sel:WORD_1
	v_cvt_pk_f32_fp8_sdwa v[102:103], v92 src0_sel:WORD_1
	v_pk_mul_f32 v[104:105], v[16:17], v[96:97]
	v_pk_mul_f32 v[106:107], v[16:17], v[100:101]
	v_pk_fma_f32 v[104:105], v[18:19], v[98:99], v[104:105]
	v_pk_fma_f32 v[106:107], v[18:19], v[102:103], v[106:107]
	v_cvt_pk_f32_fp8_e32 v[96:97], v89
	v_cvt_pk_f32_fp8_e32 v[100:101], v93
	v_cvt_pk_f32_fp8_sdwa v[98:99], v89 src0_sel:WORD_1
	v_cvt_pk_f32_fp8_sdwa v[102:103], v93 src0_sel:WORD_1
	v_pk_fma_f32 v[104:105], v[20:21], v[96:97], v[104:105]
	v_pk_fma_f32 v[106:107], v[20:21], v[100:101], v[106:107]
	v_pk_fma_f32 v[104:105], v[22:23], v[98:99], v[104:105]
	v_pk_fma_f32 v[106:107], v[22:23], v[102:103], v[106:107]
	v_cvt_pk_f32_fp8_e32 v[96:97], v90
	v_cvt_pk_f32_fp8_e32 v[100:101], v94
	v_cvt_pk_f32_fp8_sdwa v[98:99], v90 src0_sel:WORD_1
	v_cvt_pk_f32_fp8_sdwa v[102:103], v94 src0_sel:WORD_1
	v_pk_fma_f32 v[104:105], v[24:25], v[96:97], v[104:105]
	v_pk_fma_f32 v[106:107], v[24:25], v[100:101], v[106:107]
	v_pk_fma_f32 v[104:105], v[26:27], v[98:99], v[104:105]
	v_pk_fma_f32 v[106:107], v[26:27], v[102:103], v[106:107]
	v_cvt_pk_f32_fp8_e32 v[96:97], v91
	v_cvt_pk_f32_fp8_e32 v[100:101], v95
	v_cvt_pk_f32_fp8_sdwa v[98:99], v91 src0_sel:WORD_1
	v_cvt_pk_f32_fp8_sdwa v[102:103], v95 src0_sel:WORD_1
	global_load_dwordx4 v[88:91], v140, s[80:81]
	global_load_dwordx4 v[92:95], v141, s[80:81]
	v_pk_fma_f32 v[104:105], v[28:29], v[96:97], v[104:105]
	v_pk_fma_f32 v[106:107], v[28:29], v[100:101], v[106:107]
	v_pk_fma_f32 v[104:105], v[30:31], v[98:99], v[104:105]
	v_pk_fma_f32 v[106:107], v[30:31], v[102:103], v[106:107]
	s_nop 0
	v_add_f32_e32 v114, v104, v105
	v_add_f32_e32 v115, v106, v107
	s_nop 1
	v_permlane32_swap_b32_e32 v108, v109
	v_permlane32_swap_b32_e32 v110, v111
	v_permlane32_swap_b32_e32 v112, v113
	v_permlane32_swap_b32_e32 v114, v115
	v_add_f32_e32 v108, v108, v109
	v_add_f32_e32 v110, v110, v111
	v_add_f32_e32 v112, v112, v113
	v_add_f32_e32 v114, v114, v115
	s_nop 1
	v_permlane16_swap_b32_e32 v108, v110
	v_permlane16_swap_b32_e32 v112, v114
	v_add_f32_e32 v108, v108, v110
	v_add_f32_e32 v112, v112, v114
	s_mov_b32 s88, 0xff00ff00
	s_mov_b32 s89, 0xff00ff00
	s_nop 0
	v_cndmask_b32_e64 v109, v108, v112, s[88:89]
	v_cndmask_b32_e64 v111, v112, v108, s[88:89]
	s_nop 1
	v_add_f32_dpp v109, v111, v109 row_ror:8 row_mask:0xf bank_mask:0xf
	s_nop 1
	v_add_f32_dpp v109, v109, v109 quad_perm:[1,0,3,2] row_mask:0xf bank_mask:0xf
	s_nop 1
	v_add_f32_dpp v109, v109, v109 quad_perm:[2,3,0,1] row_mask:0xf bank_mask:0xf
	s_nop 1
	v_add_f32_dpp v109, v109, v109 row_half_mirror row_mask:0xf bank_mask:0xf
	s_nop 0
	ds_bpermute_b32 v110, v251, v109
	s_waitcnt lgkmcnt(0)
; #define PG_ISSUE(BUF, TAB, e0_) do { const int isrc_ = ((e0_) < 64) ? myi0 : myi1; \
;       _Pragma("unroll") for (int e = 0; e < 8; ++e) { const int idx_ = __builtin_amdgcn_readlane(isrc_, ((e0_) + e) & 63); \
;         BUF[e] = *(const u32x4*)((TAB) + (size_t)idx_ * 1024 + lane * 16); } } while (0)
; DEV void peer_gather(const Params& P, int l, int m0, const int* idxs, const float* gs) {
;     ...
;     PG_ISSUE(b0, U, 0);
; #pragma nounroll
;     for (int e0 = 0; e0 < 128; e0 += 16) {
;       PG_ISSUE(b1, U, e0 + 8);
;       PG_U8(b0, 0, e0);
;       if (e0 + 16 < 128) PG_ISSUE(b0, U, e0 + 16); else PG_ISSUE(b0, V, 0);
;       PG_U8(b1, 0, e0 + 8);
;     }
	v_cndmask_b32_e64 v243, v243, v110, s[84:85]
	v_cndmask_b32_e64 v244, v244, v110, s[86:87]
	v_cndmask_b32_e64 v153, v148, v149, s[90:91]
	s_nop 0
	s_add_u32 s98, s101, 0
	v_readlane_b32 s98, v153, s98
	s_add_u32 s99, s101, 1
	v_readlane_b32 s99, v153, s99
	s_add_u32 s92, s101, 2
	v_readlane_b32 s92, v153, s92
	s_add_u32 s93, s101, 3
	v_readlane_b32 s93, v153, s93
	v_lshl_add_u32 v134, s98, 10, v250
	v_lshl_add_u32 v135, s99, 10, v250
	v_lshl_add_u32 v136, s92, 10, v250
	v_lshl_add_u32 v137, s93, 10, v250
	s_add_u32 s98, s101, 4
	v_readlane_b32 s98, v153, s98
	s_add_u32 s99, s101, 5
	v_readlane_b32 s99, v153, s99
	s_add_u32 s92, s101, 6
	v_readlane_b32 s92, v153, s92
	s_add_u32 s93, s101, 7
	v_readlane_b32 s93, v153, s93
	v_lshl_add_u32 v138, s98, 10, v250
	v_lshl_add_u32 v139, s99, 10, v250
	v_lshl_add_u32 v140, s92, 10, v250
	v_lshl_add_u32 v141, s93, 10, v250
	s_waitcnt vmcnt(6)
	v_cvt_pk_f32_fp8_e32 v[96:97], v64
	v_cvt_pk_f32_fp8_e32 v[100:101], v68
	v_cvt_pk_f32_fp8_sdwa v[98:99], v64 src0_sel:WORD_1
	v_cvt_pk_f32_fp8_sdwa v[102:103], v68 src0_sel:WORD_1
	v_pk_mul_f32 v[104:105], v[32:33], v[96:97]
	v_pk_mul_f32 v[106:107], v[32:33], v[100:101]
	v_pk_fma_f32 v[104:105], v[34:35], v[98:99], v[104:105]
	v_pk_fma_f32 v[106:107], v[34:35], v[102:103], v[106:107]
	v_cvt_pk_f32_fp8_e32 v[96:97], v65
	v_cvt_pk_f32_fp8_e32 v[100:101], v69
	v_cvt_pk_f32_fp8_sdwa v[98:99], v65 src0_sel:WORD_1
	v_cvt_pk_f32_fp8_sdwa v[102:103], v69 src0_sel:WORD_1
	v_pk_fma_f32 v[104:105], v[36:37], v[96:97], v[104:105]
	v_pk_fma_f32 v[106:107], v[36:37], v[100:101], v[106:107]
	v_pk_fma_f32 v[104:105], v[38:39], v[98:99], v[104:105]
	v_pk_fma_f32 v[106:107], v[38:39], v[102:103], v[106:107]
	v_cvt_pk_f32_fp8_e32 v[96:97], v66
	v_cvt_pk_f32_fp8_e32 v[100:101], v70
	v_cvt_pk_f32_fp8_sdwa v[98:99], v66 src0_sel:WORD_1
	v_cvt_pk_f32_fp8_sdwa v[102:103], v70 src0_sel:WORD_1
	v_pk_fma_f32 v[104:105], v[40:41], v[96:97], v[104:105]
	v_pk_fma_f32 v[106:107], v[40:41], v[100:101], v[106:107]
	v_pk_fma_f32 v[104:105], v[42:43], v[98:99], v[104:105]
	v_pk_fma_f32 v[106:107], v[42:43], v[102:103], v[106:107]
	v_cvt_pk_f32_fp8_e32 v[96:97], v67
	v_cvt_pk_f32_fp8_e32 v[100:101], v71
	v_cvt_pk_f32_fp8_sdwa v[98:99], v67 src0_sel:WORD_1
	v_cvt_pk_f32_fp8_sdwa v[102:103], v71 src0_sel:WORD_1
	global_load_dwordx4 v[64:67], v134, s[80:81]
	global_load_dwordx4 v[68:71], v135, s[80:81]
	v_pk_fma_f32 v[104:105], v[44:45], v[96:97], v[104:105]
	v_pk_fma_f32 v[106:107], v[44:45], v[100:101], v[106:107]
	v_pk_fma_f32 v[104:105], v[46:47], v[98:99], v[104:105]
	v_pk_fma_f32 v[106:107], v[46:47], v[102:103], v[106:107]
	s_nop 0
	v_add_f32_e32 v108, v104, v105
	v_add_f32_e32 v109, v106, v107
	s_waitcnt vmcnt(6)
	v_cvt_pk_f32_fp8_e32 v[96:97], v72
	v_cvt_pk_f32_fp8_e32 v[100:101], v76
	v_cvt_pk_f32_fp8_sdwa v[98:99], v72 src0_sel:WORD_1
	v_cvt_pk_f32_fp8_sdwa v[102:103], v76 src0_sel:WORD_1
	v_pk_mul_f32 v[104:105], v[32:33], v[96:97]
	v_pk_mul_f32 v[106:107], v[32:33], v[100:101]
	v_pk_fma_f32 v[104:105], v[34:35], v[98:99], v[104:105]
	v_pk_fma_f32 v[106:107], v[34:35], v[102:103], v[106:107]
	v_cvt_pk_f32_fp8_e32 v[96:97], v73
	v_cvt_pk_f32_fp8_e32 v[100:101], v77
	v_cvt_pk_f32_fp8_sdwa v[98:99], v73 src0_sel:WORD_1
	v_cvt_pk_f32_fp8_sdwa v[102:103], v77 src0_sel:WORD_1
	v_pk_fma_f32 v[104:105], v[36:37], v[96:97], v[104:105]
	v_pk_fma_f32 v[106:107], v[36:37], v[100:101], v[106:107]
	v_pk_fma_f32 v[104:105], v[38:39], v[98:99], v[104:105]
	v_pk_fma_f32 v[106:107], v[38:39], v[102:103], v[106:107]
	v_cvt_pk_f32_fp8_e32 v[96:97], v74
	v_cvt_pk_f32_fp8_e32 v[100:101], v78
	v_cvt_pk_f32_fp8_sdwa v[98:99], v74 src0_sel:WORD_1
	v_cvt_pk_f32_fp8_sdwa v[102:103], v78 src0_sel:WORD_1
	v_pk_fma_f32 v[104:105], v[40:41], v[96:97], v[104:105]
	v_pk_fma_f32 v[106:107], v[40:41], v[100:101], v[106:107]
	v_pk_fma_f32 v[104:105], v[42:43], v[98:99], v[104:105]
	v_pk_fma_f32 v[106:107], v[42:43], v[102:103], v[106:107]
	v_cvt_pk_f32_fp8_e32 v[96:97], v75
	v_cvt_pk_f32_fp8_e32 v[100:101], v79
	v_cvt_pk_f32_fp8_sdwa v[98:99], v75 src0_sel:WORD_1
	v_cvt_pk_f32_fp8_sdwa v[102:103], v79 src0_sel:WORD_1
	global_load_dwordx4 v[72:75], v136, s[80:81]
	global_load_dwordx4 v[76:79], v137, s[80:81]
	v_pk_fma_f32 v[104:105], v[44:45], v[96:97], v[104:105]
	v_pk_fma_f32 v[106:107], v[44:45], v[100:101], v[106:107]
	v_pk_fma_f32 v[104:105], v[46:47], v[98:99], v[104:105]
	v_pk_fma_f32 v[106:107], v[46:47], v[102:103], v[106:107]
	s_nop 0
	v_add_f32_e32 v110, v104, v105
	v_add_f32_e32 v111, v106, v107
	s_waitcnt vmcnt(6)
	v_cvt_pk_f32_fp8_e32 v[96:97], v80
	v_cvt_pk_f32_fp8_e32 v[100:101], v84
	v_cvt_pk_f32_fp8_sdwa v[98:99], v80 src0_sel:WORD_1
	v_cvt_pk_f32_fp8_sdwa v[102:103], v84 src0_sel:WORD_1
	v_pk_mul_f32 v[104:105], v[32:33], v[96:97]
	v_pk_mul_f32 v[106:107], v[32:33], v[100:101]
	v_pk_fma_f32 v[104:105], v[34:35], v[98:99], v[104:105]
	v_pk_fma_f32 v[106:107], v[34:35], v[102:103], v[106:107]
	v_cvt_pk_f32_fp8_e32 v[96:97], v81
	v_cvt_pk_f32_fp8_e32 v[100:101], v85
	v_cvt_pk_f32_fp8_sdwa v[98:99], v81 src0_sel:WORD_1
	v_cvt_pk_f32_fp8_sdwa v[102:103], v85 src0_sel:WORD_1
	v_pk_fma_f32 v[104:105], v[36:37], v[96:97], v[104:105]
	v_pk_fma_f32 v[106:107], v[36:37], v[100:101], v[106:107]
	v_pk_fma_f32 v[104:105], v[38:39], v[98:99], v[104:105]
	v_pk_fma_f32 v[106:107], v[38:39], v[102:103], v[106:107]
	v_cvt_pk_f32_fp8_e32 v[96:97], v82
	v_cvt_pk_f32_fp8_e32 v[100:101], v86
	v_cvt_pk_f32_fp8_sdwa v[98:99], v82 src0_sel:WORD_1
	v_cvt_pk_f32_fp8_sdwa v[102:103], v86 src0_sel:WORD_1
	v_pk_fma_f32 v[104:105], v[40:41], v[96:97], v[104:105]
	v_pk_fma_f32 v[106:107], v[40:41], v[100:101], v[106:107]
	v_pk_fma_f32 v[104:105], v[42:43], v[98:99], v[104:105]
	v_pk_fma_f32 v[106:107], v[42:43], v[102:103], v[106:107]
	v_cvt_pk_f32_fp8_e32 v[96:97], v83
	v_cvt_pk_f32_fp8_e32 v[100:101], v87
	v_cvt_pk_f32_fp8_sdwa v[98:99], v83 src0_sel:WORD_1
	v_cvt_pk_f32_fp8_sdwa v[102:103], v87 src0_sel:WORD_1
	global_load_dwordx4 v[80:83], v138, s[80:81]
	global_load_dwordx4 v[84:87], v139, s[80:81]
	v_pk_fma_f32 v[104:105], v[44:45], v[96:97], v[104:105]
	v_pk_fma_f32 v[106:107], v[44:45], v[100:101], v[106:107]
	v_pk_fma_f32 v[104:105], v[46:47], v[98:99], v[104:105]
	v_pk_fma_f32 v[106:107], v[46:47], v[102:103], v[106:107]
	s_nop 0
	v_add_f32_e32 v112, v104, v105
	v_add_f32_e32 v113, v106, v107
	s_waitcnt vmcnt(6)
; #define PG_ISSUE(BUF, TAB, e0_) do { const int isrc_ = ((e0_) < 64) ? myi0 : myi1; \
;       _Pragma("unroll") for (int e = 0; e < 8; ++e) { const int idx_ = __builtin_amdgcn_readlane(isrc_, ((e0_) + e) & 63); \
;         BUF[e] = *(const u32x4*)((TAB) + (size_t)idx_ * 1024 + lane * 16); } } while (0)
; DEV void peer_gather(const Params& P, int l, int m0, const int* idxs, const float* gs) {
;     ...
;     PG_ISSUE(b0, U, 0);
; #pragma nounroll
;     for (int e0 = 0; e0 < 128; e0 += 16) {
;       PG_ISSUE(b1, U, e0 + 8);
;       PG_U8(b0, 0, e0);
;       if (e0 + 16 < 128) PG_ISSUE(b0, U, e0 + 16); else PG_ISSUE(b0, V, 0);
;       PG_U8(b1, 0, e0 + 8);
;     }
	v_cvt_pk_f32_fp8_e32 v[96:97], v88
	v_cvt_pk_f32_fp8_e32 v[100:101], v92
	v_cvt_pk_f32_fp8_sdwa v[98:99], v88 src0_sel:WORD_1
	v_cvt_pk_f32_fp8_sdwa v[102:103], v92 src0_sel:WORD_1
	v_pk_mul_f32 v[104:105], v[32:33], v[96:97]
	v_pk_mul_f32 v[106:107], v[32:33], v[100:101]
	v_pk_fma_f32 v[104:105], v[34:35], v[98:99], v[104:105]
	v_pk_fma_f32 v[106:107], v[34:35], v[102:103], v[106:107]
	v_cvt_pk_f32_fp8_e32 v[96:97], v89
	v_cvt_pk_f32_fp8_e32 v[100:101], v93
	v_cvt_pk_f32_fp8_sdwa v[98:99], v89 src0_sel:WORD_1
	v_cvt_pk_f32_fp8_sdwa v[102:103], v93 src0_sel:WORD_1
	v_pk_fma_f32 v[104:105], v[36:37], v[96:97], v[104:105]
	v_pk_fma_f32 v[106:107], v[36:37], v[100:101], v[106:107]
	v_pk_fma_f32 v[104:105], v[38:39], v[98:99], v[104:105]
	v_pk_fma_f32 v[106:107], v[38:39], v[102:103], v[106:107]
	v_cvt_pk_f32_fp8_e32 v[96:97], v90
	v_cvt_pk_f32_fp8_e32 v[100:101], v94
	v_cvt_pk_f32_fp8_sdwa v[98:99], v90 src0_sel:WORD_1
	v_cvt_pk_f32_fp8_sdwa v[102:103], v94 src0_sel:WORD_1
	v_pk_fma_f32 v[104:105], v[40:41], v[96:97], v[104:105]
	v_pk_fma_f32 v[106:107], v[40:41], v[100:101], v[106:107]
	v_pk_fma_f32 v[104:105], v[42:43], v[98:99], v[104:105]
	v_pk_fma_f32 v[106:107], v[42:43], v[102:103], v[106:107]
	v_cvt_pk_f32_fp8_e32 v[96:97], v91
	v_cvt_pk_f32_fp8_e32 v[100:101], v95
	v_cvt_pk_f32_fp8_sdwa v[98:99], v91 src0_sel:WORD_1
	v_cvt_pk_f32_fp8_sdwa v[102:103], v95 src0_sel:WORD_1
	global_load_dwordx4 v[88:91], v140, s[80:81]
	global_load_dwordx4 v[92:95], v141, s[80:81]
	v_pk_fma_f32 v[104:105], v[44:45], v[96:97], v[104:105]
	v_pk_fma_f32 v[106:107], v[44:45], v[100:101], v[106:107]
	v_pk_fma_f32 v[104:105], v[46:47], v[98:99], v[104:105]
	v_pk_fma_f32 v[106:107], v[46:47], v[102:103], v[106:107]
	s_nop 0
	v_add_f32_e32 v114, v104, v105
	v_add_f32_e32 v115, v106, v107
	s_nop 1
	v_permlane32_swap_b32_e32 v108, v109
	v_permlane32_swap_b32_e32 v110, v111
	v_permlane32_swap_b32_e32 v112, v113
	v_permlane32_swap_b32_e32 v114, v115
	v_add_f32_e32 v108, v108, v109
	v_add_f32_e32 v110, v110, v111
	v_add_f32_e32 v112, v112, v113
	v_add_f32_e32 v114, v114, v115
	s_nop 1
	v_permlane16_swap_b32_e32 v108, v110
	v_permlane16_swap_b32_e32 v112, v114
	v_add_f32_e32 v108, v108, v110
	v_add_f32_e32 v112, v112, v114
	s_mov_b32 s88, 0xff00ff00
	s_mov_b32 s89, 0xff00ff00
	s_nop 0
	v_cndmask_b32_e64 v109, v108, v112, s[88:89]
	v_cndmask_b32_e64 v111, v112, v108, s[88:89]
	s_nop 1
	v_add_f32_dpp v109, v111, v109 row_ror:8 row_mask:0xf bank_mask:0xf
	s_nop 1
	v_add_f32_dpp v109, v109, v109 quad_perm:[1,0,3,2] row_mask:0xf bank_mask:0xf
	s_nop 1
	v_add_f32_dpp v109, v109, v109 quad_perm:[2,3,0,1] row_mask:0xf bank_mask:0xf
	s_nop 1
	v_add_f32_dpp v109, v109, v109 row_half_mirror row_mask:0xf bank_mask:0xf
	s_nop 0
	ds_bpermute_b32 v110, v251, v109
	s_waitcnt lgkmcnt(0)
	v_cndmask_b32_e64 v245, v245, v110, s[84:85]
	v_cndmask_b32_e64 v246, v246, v110, s[86:87]
	s_add_u32 s98, s100, 1
	s_min_u32 s98, s98, 15
	s_cmp_ge_u32 s98, 8
	s_cselect_b64 s[88:89], -1, 0
	s_lshl_b32 s99, s98, 3
	s_and_b32 s99, s99, 63
	s_mov_b32 vcc_lo, s99
	v_cndmask_b32_e64 v153, v142, v143, s[88:89]
	s_nop 0
	s_add_u32 s98, vcc_lo, 0
	v_readlane_b32 s98, v153, s98
	s_add_u32 s99, vcc_lo, 1
	v_readlane_b32 s99, v153, s99
	s_add_u32 s92, vcc_lo, 2
	v_readlane_b32 s92, v153, s92
	s_add_u32 s93, vcc_lo, 3
	v_readlane_b32 s93, v153, s93
	v_lshl_add_u32 v134, s98, 10, v250
	v_lshl_add_u32 v135, s99, 10, v250
	v_lshl_add_u32 v136, s92, 10, v250
	v_lshl_add_u32 v137, s93, 10, v250
	s_add_u32 s98, vcc_lo, 4
	v_readlane_b32 s98, v153, s98
	s_add_u32 s99, vcc_lo, 5
	v_readlane_b32 s99, v153, s99
	s_add_u32 s92, vcc_lo, 6
	v_readlane_b32 s92, v153, s92
	s_add_u32 s93, vcc_lo, 7
	v_readlane_b32 s93, v153, s93
	v_lshl_add_u32 v138, s98, 10, v250
	v_lshl_add_u32 v139, s99, 10, v250
	v_lshl_add_u32 v140, s92, 10, v250
	v_lshl_add_u32 v141, s93, 10, v250
	s_waitcnt vmcnt(6)
	v_cvt_pk_f32_fp8_e32 v[96:97], v64
	v_cvt_pk_f32_fp8_e32 v[100:101], v68
	v_cvt_pk_f32_fp8_sdwa v[98:99], v64 src0_sel:WORD_1
	v_cvt_pk_f32_fp8_sdwa v[102:103], v68 src0_sel:WORD_1
	v_pk_mul_f32 v[104:105], v[48:49], v[96:97]
	v_pk_mul_f32 v[106:107], v[48:49], v[100:101]
	v_pk_fma_f32 v[104:105], v[50:51], v[98:99], v[104:105]
	v_pk_fma_f32 v[106:107], v[50:51], v[102:103], v[106:107]
	v_cvt_pk_f32_fp8_e32 v[96:97], v65
	v_cvt_pk_f32_fp8_e32 v[100:101], v69
	v_cvt_pk_f32_fp8_sdwa v[98:99], v65 src0_sel:WORD_1
	v_cvt_pk_f32_fp8_sdwa v[102:103], v69 src0_sel:WORD_1
	v_pk_fma_f32 v[104:105], v[52:53], v[96:97], v[104:105]
	v_pk_fma_f32 v[106:107], v[52:53], v[100:101], v[106:107]
	v_pk_fma_f32 v[104:105], v[54:55], v[98:99], v[104:105]
	v_pk_fma_f32 v[106:107], v[54:55], v[102:103], v[106:107]
	v_cvt_pk_f32_fp8_e32 v[96:97], v66
	v_cvt_pk_f32_fp8_e32 v[100:101], v70
	v_cvt_pk_f32_fp8_sdwa v[98:99], v66 src0_sel:WORD_1
	v_cvt_pk_f32_fp8_sdwa v[102:103], v70 src0_sel:WORD_1
	v_pk_fma_f32 v[104:105], v[56:57], v[96:97], v[104:105]
	v_pk_fma_f32 v[106:107], v[56:57], v[100:101], v[106:107]
	v_pk_fma_f32 v[104:105], v[58:59], v[98:99], v[104:105]
	v_pk_fma_f32 v[106:107], v[58:59], v[102:103], v[106:107]
	v_cvt_pk_f32_fp8_e32 v[96:97], v67
	v_cvt_pk_f32_fp8_e32 v[100:101], v71
	v_cvt_pk_f32_fp8_sdwa v[98:99], v67 src0_sel:WORD_1
	v_cvt_pk_f32_fp8_sdwa v[102:103], v71 src0_sel:WORD_1
	global_load_dwordx4 v[64:67], v134, s[80:81]
	global_load_dwordx4 v[68:71], v135, s[80:81]
	v_pk_fma_f32 v[104:105], v[60:61], v[96:97], v[104:105]
	v_pk_fma_f32 v[106:107], v[60:61], v[100:101], v[106:107]
	v_pk_fma_f32 v[104:105], v[62:63], v[98:99], v[104:105]
	v_pk_fma_f32 v[106:107], v[62:63], v[102:103], v[106:107]
	s_nop 0
	v_add_f32_e32 v108, v104, v105
	v_add_f32_e32 v109, v106, v107
	s_waitcnt vmcnt(6)
; #define PG_ISSUE(BUF, TAB, e0_) do { const int isrc_ = ((e0_) < 64) ? myi0 : myi1; \
;       _Pragma("unroll") for (int e = 0; e < 8; ++e) { const int idx_ = __builtin_amdgcn_readlane(isrc_, ((e0_) + e) & 63); \
;         BUF[e] = *(const u32x4*)((TAB) + (size_t)idx_ * 1024 + lane * 16); } } while (0)
; DEV void peer_gather(const Params& P, int l, int m0, const int* idxs, const float* gs) {
;     ...
;     PG_ISSUE(b0, U, 0);
; #pragma nounroll
;     for (int e0 = 0; e0 < 128; e0 += 16) {
;       PG_ISSUE(b1, U, e0 + 8);
;       PG_U8(b0, 0, e0);
;       if (e0 + 16 < 128) PG_ISSUE(b0, U, e0 + 16); else PG_ISSUE(b0, V, 0);
;       PG_U8(b1, 0, e0 + 8);
;     }
	v_cvt_pk_f32_fp8_e32 v[96:97], v72
	v_cvt_pk_f32_fp8_e32 v[100:101], v76
	v_cvt_pk_f32_fp8_sdwa v[98:99], v72 src0_sel:WORD_1
	v_cvt_pk_f32_fp8_sdwa v[102:103], v76 src0_sel:WORD_1
	v_pk_mul_f32 v[104:105], v[48:49], v[96:97]
	v_pk_mul_f32 v[106:107], v[48:49], v[100:101]
	v_pk_fma_f32 v[104:105], v[50:51], v[98:99], v[104:105]
	v_pk_fma_f32 v[106:107], v[50:51], v[102:103], v[106:107]
	v_cvt_pk_f32_fp8_e32 v[96:97], v73
	v_cvt_pk_f32_fp8_e32 v[100:101], v77
	v_cvt_pk_f32_fp8_sdwa v[98:99], v73 src0_sel:WORD_1
	v_cvt_pk_f32_fp8_sdwa v[102:103], v77 src0_sel:WORD_1
	v_pk_fma_f32 v[104:105], v[52:53], v[96:97], v[104:105]
	v_pk_fma_f32 v[106:107], v[52:53], v[100:101], v[106:107]
	v_pk_fma_f32 v[104:105], v[54:55], v[98:99], v[104:105]
	v_pk_fma_f32 v[106:107], v[54:55], v[102:103], v[106:107]
	v_cvt_pk_f32_fp8_e32 v[96:97], v74
	v_cvt_pk_f32_fp8_e32 v[100:101], v78
	v_cvt_pk_f32_fp8_sdwa v[98:99], v74 src0_sel:WORD_1
	v_cvt_pk_f32_fp8_sdwa v[102:103], v78 src0_sel:WORD_1
	v_pk_fma_f32 v[104:105], v[56:57], v[96:97], v[104:105]
	v_pk_fma_f32 v[106:107], v[56:57], v[100:101], v[106:107]
	v_pk_fma_f32 v[104:105], v[58:59], v[98:99], v[104:105]
	v_pk_fma_f32 v[106:107], v[58:59], v[102:103], v[106:107]
	v_cvt_pk_f32_fp8_e32 v[96:97], v75
	v_cvt_pk_f32_fp8_e32 v[100:101], v79
	v_cvt_pk_f32_fp8_sdwa v[98:99], v75 src0_sel:WORD_1
	v_cvt_pk_f32_fp8_sdwa v[102:103], v79 src0_sel:WORD_1
	global_load_dwordx4 v[72:75], v136, s[80:81]
	global_load_dwordx4 v[76:79], v137, s[80:81]
	v_pk_fma_f32 v[104:105], v[60:61], v[96:97], v[104:105]
	v_pk_fma_f32 v[106:107], v[60:61], v[100:101], v[106:107]
	v_pk_fma_f32 v[104:105], v[62:63], v[98:99], v[104:105]
	v_pk_fma_f32 v[106:107], v[62:63], v[102:103], v[106:107]
	s_nop 0
	v_add_f32_e32 v110, v104, v105
	v_add_f32_e32 v111, v106, v107
	s_waitcnt vmcnt(6)
	v_cvt_pk_f32_fp8_e32 v[96:97], v80
	v_cvt_pk_f32_fp8_e32 v[100:101], v84
	v_cvt_pk_f32_fp8_sdwa v[98:99], v80 src0_sel:WORD_1
	v_cvt_pk_f32_fp8_sdwa v[102:103], v84 src0_sel:WORD_1
	v_pk_mul_f32 v[104:105], v[48:49], v[96:97]
	v_pk_mul_f32 v[106:107], v[48:49], v[100:101]
	v_pk_fma_f32 v[104:105], v[50:51], v[98:99], v[104:105]
	v_pk_fma_f32 v[106:107], v[50:51], v[102:103], v[106:107]
	v_cvt_pk_f32_fp8_e32 v[96:97], v81
	v_cvt_pk_f32_fp8_e32 v[100:101], v85
	v_cvt_pk_f32_fp8_sdwa v[98:99], v81 src0_sel:WORD_1
	v_cvt_pk_f32_fp8_sdwa v[102:103], v85 src0_sel:WORD_1
	v_pk_fma_f32 v[104:105], v[52:53], v[96:97], v[104:105]
	v_pk_fma_f32 v[106:107], v[52:53], v[100:101], v[106:107]
	v_pk_fma_f32 v[104:105], v[54:55], v[98:99], v[104:105]
	v_pk_fma_f32 v[106:107], v[54:55], v[102:103], v[106:107]
	v_cvt_pk_f32_fp8_e32 v[96:97], v82
	v_cvt_pk_f32_fp8_e32 v[100:101], v86
	v_cvt_pk_f32_fp8_sdwa v[98:99], v82 src0_sel:WORD_1
	v_cvt_pk_f32_fp8_sdwa v[102:103], v86 src0_sel:WORD_1
	v_pk_fma_f32 v[104:105], v[56:57], v[96:97], v[104:105]
	v_pk_fma_f32 v[106:107], v[56:57], v[100:101], v[106:107]
	v_pk_fma_f32 v[104:105], v[58:59], v[98:99], v[104:105]
	v_pk_fma_f32 v[106:107], v[58:59], v[102:103], v[106:107]
	v_cvt_pk_f32_fp8_e32 v[96:97], v83
	v_cvt_pk_f32_fp8_e32 v[100:101], v87
	v_cvt_pk_f32_fp8_sdwa v[98:99], v83 src0_sel:WORD_1
	v_cvt_pk_f32_fp8_sdwa v[102:103], v87 src0_sel:WORD_1
	global_load_dwordx4 v[80:83], v138, s[80:81]
	global_load_dwordx4 v[84:87], v139, s[80:81]
	v_pk_fma_f32 v[104:105], v[60:61], v[96:97], v[104:105]
	v_pk_fma_f32 v[106:107], v[60:61], v[100:101], v[106:107]
	v_pk_fma_f32 v[104:105], v[62:63], v[98:99], v[104:105]
	v_pk_fma_f32 v[106:107], v[62:63], v[102:103], v[106:107]
	s_nop 0
	v_add_f32_e32 v112, v104, v105
	v_add_f32_e32 v113, v106, v107
	s_waitcnt vmcnt(6)
	v_cvt_pk_f32_fp8_e32 v[96:97], v88
	v_cvt_pk_f32_fp8_e32 v[100:101], v92
	v_cvt_pk_f32_fp8_sdwa v[98:99], v88 src0_sel:WORD_1
	v_cvt_pk_f32_fp8_sdwa v[102:103], v92 src0_sel:WORD_1
	v_pk_mul_f32 v[104:105], v[48:49], v[96:97]
	v_pk_mul_f32 v[106:107], v[48:49], v[100:101]
	v_pk_fma_f32 v[104:105], v[50:51], v[98:99], v[104:105]
	v_pk_fma_f32 v[106:107], v[50:51], v[102:103], v[106:107]
	v_cvt_pk_f32_fp8_e32 v[96:97], v89
	v_cvt_pk_f32_fp8_e32 v[100:101], v93
	v_cvt_pk_f32_fp8_sdwa v[98:99], v89 src0_sel:WORD_1
	v_cvt_pk_f32_fp8_sdwa v[102:103], v93 src0_sel:WORD_1
	v_pk_fma_f32 v[104:105], v[52:53], v[96:97], v[104:105]
	v_pk_fma_f32 v[106:107], v[52:53], v[100:101], v[106:107]
	v_pk_fma_f32 v[104:105], v[54:55], v[98:99], v[104:105]
	v_pk_fma_f32 v[106:107], v[54:55], v[102:103], v[106:107]
	v_cvt_pk_f32_fp8_e32 v[96:97], v90
	v_cvt_pk_f32_fp8_e32 v[100:101], v94
	v_cvt_pk_f32_fp8_sdwa v[98:99], v90 src0_sel:WORD_1
	v_cvt_pk_f32_fp8_sdwa v[102:103], v94 src0_sel:WORD_1
	v_pk_fma_f32 v[104:105], v[56:57], v[96:97], v[104:105]
	v_pk_fma_f32 v[106:107], v[56:57], v[100:101], v[106:107]
	v_pk_fma_f32 v[104:105], v[58:59], v[98:99], v[104:105]
	v_pk_fma_f32 v[106:107], v[58:59], v[102:103], v[106:107]
	v_cvt_pk_f32_fp8_e32 v[96:97], v91
	v_cvt_pk_f32_fp8_e32 v[100:101], v95
	v_cvt_pk_f32_fp8_sdwa v[98:99], v91 src0_sel:WORD_1
	v_cvt_pk_f32_fp8_sdwa v[102:103], v95 src0_sel:WORD_1
	global_load_dwordx4 v[88:91], v140, s[80:81]
	global_load_dwordx4 v[92:95], v141, s[80:81]
	v_pk_fma_f32 v[104:105], v[60:61], v[96:97], v[104:105]
	v_pk_fma_f32 v[106:107], v[60:61], v[100:101], v[106:107]
	v_pk_fma_f32 v[104:105], v[62:63], v[98:99], v[104:105]
	v_pk_fma_f32 v[106:107], v[62:63], v[102:103], v[106:107]
	s_nop 0
	v_add_f32_e32 v114, v104, v105
	v_add_f32_e32 v115, v106, v107
	s_nop 1
	v_permlane32_swap_b32_e32 v108, v109
	v_permlane32_swap_b32_e32 v110, v111
	v_permlane32_swap_b32_e32 v112, v113
	v_permlane32_swap_b32_e32 v114, v115
	v_add_f32_e32 v108, v108, v109
	v_add_f32_e32 v110, v110, v111
	v_add_f32_e32 v112, v112, v113
	v_add_f32_e32 v114, v114, v115
	s_nop 1
	v_permlane16_swap_b32_e32 v108, v110
	v_permlane16_swap_b32_e32 v112, v114
	v_add_f32_e32 v108, v108, v110
	v_add_f32_e32 v112, v112, v114
	s_mov_b32 s88, 0xff00ff00
	s_mov_b32 s89, 0xff00ff00
	s_nop 0
	v_cndmask_b32_e64 v109, v108, v112, s[88:89]
	v_cndmask_b32_e64 v111, v112, v108, s[88:89]
	s_nop 1
	v_add_f32_dpp v109, v111, v109 row_ror:8 row_mask:0xf bank_mask:0xf
	s_nop 1
	v_add_f32_dpp v109, v109, v109 quad_perm:[1,0,3,2] row_mask:0xf bank_mask:0xf
	s_nop 1
	v_add_f32_dpp v109, v109, v109 quad_perm:[2,3,0,1] row_mask:0xf bank_mask:0xf
	s_nop 1
	v_add_f32_dpp v109, v109, v109 row_half_mirror row_mask:0xf bank_mask:0xf
	s_nop 0
	ds_bpermute_b32 v110, v251, v109
	s_waitcnt lgkmcnt(0)
	v_cndmask_b32_e64 v247, v247, v110, s[84:85]
	v_cndmask_b32_e64 v248, v248, v110, s[86:87]
	s_add_u32 s100, s100, 1
	s_add_u32 s101, s101, 8
	s_and_b32 s101, s101, 63
	s_cmp_lt_u32 s100, 16
	s_cbranch_scc1 .Lpg1_Uloop
; #define PG_ISSUE(BUF, TAB, e0_) do { const int isrc_ = ((e0_) < 64) ? myi0 : myi1; \
;       _Pragma("unroll") for (int e = 0; e < 8; ++e) { const int idx_ = __builtin_amdgcn_readlane(isrc_, ((e0_) + e) & 63); \
;         BUF[e] = *(const u32x4*)((TAB) + (size_t)idx_ * 1024 + lane * 16); } } while (0)
; DEV void peer_gather(const Params& P, int l, int m0, const int* idxs, const float* gs) {
;     ...
;     PG_ISSUE(b0, U, 0);
; #pragma nounroll
;     for (int e0 = 0; e0 < 128; e0 += 16) {
;       PG_ISSUE(b1, U, e0 + 8);
;       PG_U8(b0, 0, e0);
;       if (e0 + 16 < 128) PG_ISSUE(b0, U, e0 + 16); else PG_ISSUE(b0, V, 0);
;       PG_U8(b1, 0, e0 + 8);
;     }
;     float* hrow = P.out + tok * DM + lane * 16;
;     f32x4 hv[4];
; #pragma unroll
;     for (int q = 0; q < 4; ++q) hv[q] = *(const f32x4*)(hrow + 4 * q);
;     if (i + 1 < 16) {
;       const int tn = tt + 1;
;       nxa = *(const u32x4*)(hn + (size_t)(m0 + tn) * DM + lane * 16); nxb = *(const u32x4*)(hn + (size_t)(m0 + tn) * DM + lane * 16 + 8);
;       ni0 = idxs[tn * 128 + lane]; ni1 = idxs[tn * 128 + 64 + lane]; ng0 = gs[tn * 128 + lane]; ng1 = gs[tn * 128 + 64 + lane];
;     }
; #pragma nounroll
;     for (int e0 = 0; e0 < 128; e0 += 16) {
;       PG_ISSUE(b1, V, e0 + 8);
	s_waitcnt vmcnt(0)
	s_waitcnt vmcnt(0)
	v_mul_f32_e32 v72, 0x3c800000, v241
	v_mul_f32_e32 v73, 0x3c800000, v242
	v_mul_f32_e32 v74, 0x3c800000, v243
	v_mul_f32_e32 v75, 0x3c800000, v244
	v_mul_f32_e32 v76, 0x3c800000, v245
	v_mul_f32_e32 v77, 0x3c800000, v246
	v_mul_f32_e32 v78, 0x3c800000, v247
	v_mul_f32_e32 v79, 0x3c800000, v248
	v_mul_f32_e32 v64, 0x3d372713, v72
	v_mul_f32_e32 v65, 0x3d372713, v73
	v_mul_f32_e32 v66, 0x3d372713, v74
	v_mul_f32_e32 v67, 0x3d372713, v75
	v_mul_f32_e32 v68, 0x3d372713, v76
	v_mul_f32_e32 v69, 0x3d372713, v77
	v_mul_f32_e32 v70, 0x3d372713, v78
	v_mul_f32_e32 v71, 0x3d372713, v79
	v_mul_f32_e32 v64, v72, v64
	v_mul_f32_e32 v65, v73, v65
	v_mul_f32_e32 v66, v74, v66
	v_mul_f32_e32 v67, v75, v67
	v_mul_f32_e32 v68, v76, v68
	v_mul_f32_e32 v69, v77, v69
	v_mul_f32_e32 v70, v78, v70
	v_mul_f32_e32 v71, v79, v71
	v_fma_f32 v64, v72, v64, v72
	v_fma_f32 v65, v73, v65, v73
	v_fma_f32 v66, v74, v66, v74
	v_fma_f32 v67, v75, v67, v75
	v_fma_f32 v68, v76, v68, v76
	v_fma_f32 v69, v77, v69, v77
	v_fma_f32 v70, v78, v70, v78
	v_fma_f32 v71, v79, v71, v79
	v_mul_f32_e32 v64, 0xbfcc422a, v64
	v_mul_f32_e32 v65, 0xbfcc422a, v65
	v_mul_f32_e32 v66, 0xbfcc422a, v66
	v_mul_f32_e32 v67, 0xbfcc422a, v67
	v_mul_f32_e32 v68, 0xbfcc422a, v68
	v_mul_f32_e32 v69, 0xbfcc422a, v69
	v_mul_f32_e32 v70, 0xbfcc422a, v70
	v_mul_f32_e32 v71, 0xbfcc422a, v71
	v_mul_f32_e32 v64, 0x3fb8aa3b, v64
	v_mul_f32_e32 v65, 0x3fb8aa3b, v65
	v_mul_f32_e32 v66, 0x3fb8aa3b, v66
	v_mul_f32_e32 v67, 0x3fb8aa3b, v67
	v_mul_f32_e32 v68, 0x3fb8aa3b, v68
	v_mul_f32_e32 v69, 0x3fb8aa3b, v69
	v_mul_f32_e32 v70, 0x3fb8aa3b, v70
	v_mul_f32_e32 v71, 0x3fb8aa3b, v71
	v_exp_f32_e32 v64, v64
	v_exp_f32_e32 v65, v65
	v_exp_f32_e32 v66, v66
	v_exp_f32_e32 v67, v67
	v_exp_f32_e32 v68, v68
	v_exp_f32_e32 v69, v69
	v_exp_f32_e32 v70, v70
	v_exp_f32_e32 v71, v71
	s_nop 0
	v_add_f32_e32 v64, 1.0, v64
	v_add_f32_e32 v65, 1.0, v65
	v_add_f32_e32 v66, 1.0, v66
	v_add_f32_e32 v67, 1.0, v67
	v_add_f32_e32 v68, 1.0, v68
	v_add_f32_e32 v69, 1.0, v69
	v_add_f32_e32 v70, 1.0, v70
	v_add_f32_e32 v71, 1.0, v71
	v_rcp_f32_e32 v64, v64
	v_rcp_f32_e32 v65, v65
	v_rcp_f32_e32 v66, v66
	v_rcp_f32_e32 v67, v67
	v_rcp_f32_e32 v68, v68
	v_rcp_f32_e32 v69, v69
	v_rcp_f32_e32 v70, v70
	v_rcp_f32_e32 v71, v71
	s_nop 0
	v_mul_f32_e32 v64, v72, v64
	v_mul_f32_e32 v65, v73, v65
	v_mul_f32_e32 v66, v74, v66
	v_mul_f32_e32 v67, v75, v67
	v_mul_f32_e32 v68, v76, v68
	v_mul_f32_e32 v69, v77, v69
	v_mul_f32_e32 v70, v78, v70
	v_mul_f32_e32 v71, v79, v71
	v_mul_f32_e32 v241, v64, v233
	v_mul_f32_e32 v242, v65, v234
	v_mul_f32_e32 v243, v66, v235
	v_mul_f32_e32 v244, v67, v236
	v_mul_f32_e32 v245, v68, v237
	v_mul_f32_e32 v246, v69, v238
	v_mul_f32_e32 v247, v70, v239
	v_mul_f32_e32 v248, v71, v240
	v_readfirstlane_b32 s80, v128
	v_readfirstlane_b32 s81, v129
	s_nop 4
	v_mov_b32_e32 v0, 0
	v_mov_b32_e32 v1, 0
	v_mov_b32_e32 v2, 0
	v_mov_b32_e32 v3, 0
	v_mov_b32_e32 v4, 0
	v_mov_b32_e32 v5, 0
	v_mov_b32_e32 v6, 0
	v_mov_b32_e32 v7, 0
	v_mov_b32_e32 v8, 0
	v_mov_b32_e32 v9, 0
	v_mov_b32_e32 v10, 0
	v_mov_b32_e32 v11, 0
	v_mov_b32_e32 v12, 0
	v_mov_b32_e32 v13, 0
	v_mov_b32_e32 v14, 0
	v_mov_b32_e32 v15, 0
	v_mov_b32_e32 v16, 0
	v_mov_b32_e32 v17, 0
	v_mov_b32_e32 v18, 0
	v_mov_b32_e32 v19, 0
	v_mov_b32_e32 v20, 0
	v_mov_b32_e32 v21, 0
	v_mov_b32_e32 v22, 0
	v_mov_b32_e32 v23, 0
	v_mov_b32_e32 v24, 0
	v_mov_b32_e32 v25, 0
	v_mov_b32_e32 v26, 0
	v_mov_b32_e32 v27, 0
	v_mov_b32_e32 v28, 0
	v_mov_b32_e32 v29, 0
	v_mov_b32_e32 v30, 0
	v_mov_b32_e32 v31, 0
	v_mov_b32_e32 v32, 0
	v_mov_b32_e32 v33, 0
	v_mov_b32_e32 v34, 0
	v_mov_b32_e32 v35, 0
	v_mov_b32_e32 v36, 0
	v_mov_b32_e32 v37, 0
	v_mov_b32_e32 v38, 0
	v_mov_b32_e32 v39, 0
	v_mov_b32_e32 v40, 0
	v_mov_b32_e32 v41, 0
	v_mov_b32_e32 v42, 0
	v_mov_b32_e32 v43, 0
	v_mov_b32_e32 v44, 0
	v_mov_b32_e32 v45, 0
	v_mov_b32_e32 v46, 0
	v_mov_b32_e32 v47, 0
	v_mov_b32_e32 v48, 0
	v_mov_b32_e32 v49, 0
	v_mov_b32_e32 v50, 0
	v_mov_b32_e32 v51, 0
	v_mov_b32_e32 v52, 0
	v_mov_b32_e32 v53, 0
	v_mov_b32_e32 v54, 0
	v_mov_b32_e32 v55, 0
	v_mov_b32_e32 v56, 0
	v_mov_b32_e32 v57, 0
	v_mov_b32_e32 v58, 0
	v_mov_b32_e32 v59, 0
	v_mov_b32_e32 v60, 0
	v_mov_b32_e32 v61, 0
	v_mov_b32_e32 v62, 0
	v_mov_b32_e32 v63, 0
	s_mov_b32 s100, 0
	s_mov_b32 s101, 0
	s_mov_b64 s[90:91], 0
	v_cndmask_b32_e64 v153, v142, v143, s[90:91]
	s_nop 0
	s_add_u32 s98, s101, 0
	v_readlane_b32 s98, v153, s98
	s_add_u32 s99, s101, 1
	v_readlane_b32 s99, v153, s99
	s_add_u32 s92, s101, 2
	v_readlane_b32 s92, v153, s92
	s_add_u32 s93, s101, 3
	v_readlane_b32 s93, v153, s93
	v_lshl_add_u32 v134, s98, 10, v250
	v_lshl_add_u32 v135, s99, 10, v250
	v_lshl_add_u32 v136, s92, 10, v250
	v_lshl_add_u32 v137, s93, 10, v250
	s_add_u32 s98, s101, 4
	v_readlane_b32 s98, v153, s98
	s_add_u32 s99, s101, 5
	v_readlane_b32 s99, v153, s99
	s_add_u32 s92, s101, 6
	v_readlane_b32 s92, v153, s92
	s_add_u32 s93, s101, 7
	v_readlane_b32 s93, v153, s93
	v_lshl_add_u32 v138, s98, 10, v250
	v_lshl_add_u32 v139, s99, 10, v250
	v_lshl_add_u32 v140, s92, 10, v250
	v_lshl_add_u32 v141, s93, 10, v250
	global_load_dwordx4 v[64:67], v134, s[80:81]
	global_load_dwordx4 v[68:71], v135, s[80:81]
	global_load_dwordx4 v[72:75], v136, s[80:81]
	global_load_dwordx4 v[76:79], v137, s[80:81]
	global_load_dwordx4 v[80:83], v138, s[80:81]
	global_load_dwordx4 v[84:87], v139, s[80:81]
	global_load_dwordx4 v[88:91], v140, s[80:81]
	global_load_dwordx4 v[92:95], v141, s[80:81]
; #define PG_ISSUE(BUF, TAB, e0_) do { const int isrc_ = ((e0_) < 64) ? myi0 : myi1; \
;       _Pragma("unroll") for (int e = 0; e < 8; ++e) { const int idx_ = __builtin_amdgcn_readlane(isrc_, ((e0_) + e) & 63); \
;         BUF[e] = *(const u32x4*)((TAB) + (size_t)idx_ * 1024 + lane * 16); } } while (0)
; DEV void peer_gather(const Params& P, int l, int m0, const int* idxs, const float* gs) {
;     ...
;     PG_ISSUE(b0, U, 0);
; #pragma nounroll
;     for (int e0 = 0; e0 < 128; e0 += 16) {
;       PG_ISSUE(b1, U, e0 + 8);
;       PG_U8(b0, 0, e0);
;       if (e0 + 16 < 128) PG_ISSUE(b0, U, e0 + 16); else PG_ISSUE(b0, V, 0);
;       PG_U8(b1, 0, e0 + 8);
;     }
;     float* hrow = P.out + tok * DM + lane * 16;
;     f32x4 hv[4];
; #pragma unroll
;     for (int q = 0; q < 4; ++q) hv[q] = *(const f32x4*)(hrow + 4 * q);
;     if (i + 1 < 16) {
;       const int tn = tt + 1;
;       nxa = *(const u32x4*)(hn + (size_t)(m0 + tn) * DM + lane * 16); nxb = *(const u32x4*)(hn + (size_t)(m0 + tn) * DM + lane * 16 + 8);
;       ni0 = idxs[tn * 128 + lane]; ni1 = idxs[tn * 128 + 64 + lane]; ng0 = gs[tn * 128 + lane]; ng1 = gs[tn * 128 + 64 + lane];
;     }
; #pragma nounroll
;     for (int e0 = 0; e0 < 128; e0 += 16) {
;       PG_ISSUE(b1, V, e0 + 8);
;       if (e0 == 64 && i + 1 < 16) sort_lists(lane, ni0, ni1, ng0, ng1);
;       PG_V16(b0, e0);
;       if (e0 + 16 < 128) PG_ISSUE(b0, V, e0 + 16);
;       PG_V16(b1, e0 + 8);
;     }
.Lpg1_Vloop:
	s_cmp_ge_u32 s100, 8
	s_cselect_b64 s[90:91], -1, 0
	v_cndmask_b32_e64 v153, v144, v145, s[90:91]
	s_nop 0
	s_add_u32 s98, s101, 0
	v_readlane_b32 s98, v153, s98
	s_add_u32 s99, s101, 1
	v_readlane_b32 s99, v153, s99
	s_add_u32 s92, s101, 2
	v_readlane_b32 s92, v153, s92
	s_add_u32 s93, s101, 3
	v_readlane_b32 s93, v153, s93
	v_lshl_add_u32 v134, s98, 10, v250
	v_lshl_add_u32 v135, s99, 10, v250
	v_lshl_add_u32 v136, s92, 10, v250
	v_lshl_add_u32 v137, s93, 10, v250
	s_add_u32 s98, s101, 4
	v_readlane_b32 s98, v153, s98
	s_add_u32 s99, s101, 5
	v_readlane_b32 s99, v153, s99
	s_add_u32 s92, s101, 6
	v_readlane_b32 s92, v153, s92
	s_add_u32 s93, s101, 7
	v_readlane_b32 s93, v153, s93
	v_lshl_add_u32 v138, s98, 10, v250
	v_lshl_add_u32 v139, s99, 10, v250
	v_lshl_add_u32 v140, s92, 10, v250
	v_lshl_add_u32 v141, s93, 10, v250
	v_cndmask_b32_e64 v152, v241, v242, s[90:91]
	s_add_u32 s98, s101, 0
	s_add_u32 s99, s101, 1
	v_readlane_b32 s84, v152, s98
	v_readlane_b32 s86, v152, s99
	s_waitcnt vmcnt(6)
	v_cvt_pk_f32_fp8_e32 v[96:97], v64
	v_cvt_pk_f32_fp8_sdwa v[98:99], v64 src0_sel:WORD_1
	v_cvt_pk_f32_fp8_e32 v[100:101], v68
	v_cvt_pk_f32_fp8_sdwa v[102:103], v68 src0_sel:WORD_1
	v_pk_fma_f32 v[0:1], v[96:97], s[84:85], v[0:1] op_sel_hi:[1,0,1]
	v_pk_fma_f32 v[2:3], v[98:99], s[84:85], v[2:3] op_sel_hi:[1,0,1]
	v_pk_fma_f32 v[0:1], v[100:101], s[86:87], v[0:1] op_sel_hi:[1,0,1]
	v_pk_fma_f32 v[2:3], v[102:103], s[86:87], v[2:3] op_sel_hi:[1,0,1]
	v_cvt_pk_f32_fp8_e32 v[96:97], v65
	v_cvt_pk_f32_fp8_sdwa v[98:99], v65 src0_sel:WORD_1
	v_cvt_pk_f32_fp8_e32 v[100:101], v69
	v_cvt_pk_f32_fp8_sdwa v[102:103], v69 src0_sel:WORD_1
	v_pk_fma_f32 v[4:5], v[96:97], s[84:85], v[4:5] op_sel_hi:[1,0,1]
	v_pk_fma_f32 v[6:7], v[98:99], s[84:85], v[6:7] op_sel_hi:[1,0,1]
	v_pk_fma_f32 v[4:5], v[100:101], s[86:87], v[4:5] op_sel_hi:[1,0,1]
	v_pk_fma_f32 v[6:7], v[102:103], s[86:87], v[6:7] op_sel_hi:[1,0,1]
	v_cvt_pk_f32_fp8_e32 v[96:97], v66
	v_cvt_pk_f32_fp8_sdwa v[98:99], v66 src0_sel:WORD_1
	v_cvt_pk_f32_fp8_e32 v[100:101], v70
	v_cvt_pk_f32_fp8_sdwa v[102:103], v70 src0_sel:WORD_1
	v_pk_fma_f32 v[8:9], v[96:97], s[84:85], v[8:9] op_sel_hi:[1,0,1]
	v_pk_fma_f32 v[10:11], v[98:99], s[84:85], v[10:11] op_sel_hi:[1,0,1]
	v_pk_fma_f32 v[8:9], v[100:101], s[86:87], v[8:9] op_sel_hi:[1,0,1]
	v_pk_fma_f32 v[10:11], v[102:103], s[86:87], v[10:11] op_sel_hi:[1,0,1]
	v_cvt_pk_f32_fp8_e32 v[96:97], v67
	v_cvt_pk_f32_fp8_sdwa v[98:99], v67 src0_sel:WORD_1
	v_cvt_pk_f32_fp8_e32 v[100:101], v71
	v_cvt_pk_f32_fp8_sdwa v[102:103], v71 src0_sel:WORD_1
	global_load_dwordx4 v[64:67], v134, s[80:81]
	global_load_dwordx4 v[68:71], v135, s[80:81]
	v_pk_fma_f32 v[12:13], v[96:97], s[84:85], v[12:13] op_sel_hi:[1,0,1]
	v_pk_fma_f32 v[14:15], v[98:99], s[84:85], v[14:15] op_sel_hi:[1,0,1]
	v_pk_fma_f32 v[12:13], v[100:101], s[86:87], v[12:13] op_sel_hi:[1,0,1]
	v_pk_fma_f32 v[14:15], v[102:103], s[86:87], v[14:15] op_sel_hi:[1,0,1]
	s_add_u32 s98, s101, 2
	s_add_u32 s99, s101, 3
	v_readlane_b32 s84, v152, s98
	v_readlane_b32 s86, v152, s99
	s_waitcnt vmcnt(6)
	v_cvt_pk_f32_fp8_e32 v[96:97], v72
	v_cvt_pk_f32_fp8_sdwa v[98:99], v72 src0_sel:WORD_1
	v_cvt_pk_f32_fp8_e32 v[100:101], v76
	v_cvt_pk_f32_fp8_sdwa v[102:103], v76 src0_sel:WORD_1
	v_pk_fma_f32 v[0:1], v[96:97], s[84:85], v[0:1] op_sel_hi:[1,0,1]
	v_pk_fma_f32 v[2:3], v[98:99], s[84:85], v[2:3] op_sel_hi:[1,0,1]
	v_pk_fma_f32 v[0:1], v[100:101], s[86:87], v[0:1] op_sel_hi:[1,0,1]
	v_pk_fma_f32 v[2:3], v[102:103], s[86:87], v[2:3] op_sel_hi:[1,0,1]
	v_cvt_pk_f32_fp8_e32 v[96:97], v73
	v_cvt_pk_f32_fp8_sdwa v[98:99], v73 src0_sel:WORD_1
	v_cvt_pk_f32_fp8_e32 v[100:101], v77
	v_cvt_pk_f32_fp8_sdwa v[102:103], v77 src0_sel:WORD_1
	v_pk_fma_f32 v[4:5], v[96:97], s[84:85], v[4:5] op_sel_hi:[1,0,1]
	v_pk_fma_f32 v[6:7], v[98:99], s[84:85], v[6:7] op_sel_hi:[1,0,1]
	v_pk_fma_f32 v[4:5], v[100:101], s[86:87], v[4:5] op_sel_hi:[1,0,1]
	v_pk_fma_f32 v[6:7], v[102:103], s[86:87], v[6:7] op_sel_hi:[1,0,1]
	v_cvt_pk_f32_fp8_e32 v[96:97], v74
	v_cvt_pk_f32_fp8_sdwa v[98:99], v74 src0_sel:WORD_1
	v_cvt_pk_f32_fp8_e32 v[100:101], v78
	v_cvt_pk_f32_fp8_sdwa v[102:103], v78 src0_sel:WORD_1
	v_pk_fma_f32 v[8:9], v[96:97], s[84:85], v[8:9] op_sel_hi:[1,0,1]
	v_pk_fma_f32 v[10:11], v[98:99], s[84:85], v[10:11] op_sel_hi:[1,0,1]
	v_pk_fma_f32 v[8:9], v[100:101], s[86:87], v[8:9] op_sel_hi:[1,0,1]
	v_pk_fma_f32 v[10:11], v[102:103], s[86:87], v[10:11] op_sel_hi:[1,0,1]
	v_cvt_pk_f32_fp8_e32 v[96:97], v75
	v_cvt_pk_f32_fp8_sdwa v[98:99], v75 src0_sel:WORD_1
	v_cvt_pk_f32_fp8_e32 v[100:101], v79
	v_cvt_pk_f32_fp8_sdwa v[102:103], v79 src0_sel:WORD_1
	global_load_dwordx4 v[72:75], v136, s[80:81]
	global_load_dwordx4 v[76:79], v137, s[80:81]
	v_pk_fma_f32 v[12:13], v[96:97], s[84:85], v[12:13] op_sel_hi:[1,0,1]
	v_pk_fma_f32 v[14:15], v[98:99], s[84:85], v[14:15] op_sel_hi:[1,0,1]
	v_pk_fma_f32 v[12:13], v[100:101], s[86:87], v[12:13] op_sel_hi:[1,0,1]
	v_pk_fma_f32 v[14:15], v[102:103], s[86:87], v[14:15] op_sel_hi:[1,0,1]
	s_add_u32 s98, s101, 4
	s_add_u32 s99, s101, 5
	v_readlane_b32 s84, v152, s98
	v_readlane_b32 s86, v152, s99
	s_waitcnt vmcnt(6)
; #define PG_ISSUE(BUF, TAB, e0_) do { const int isrc_ = ((e0_) < 64) ? myi0 : myi1; \
;       _Pragma("unroll") for (int e = 0; e < 8; ++e) { const int idx_ = __builtin_amdgcn_readlane(isrc_, ((e0_) + e) & 63); \
;         BUF[e] = *(const u32x4*)((TAB) + (size_t)idx_ * 1024 + lane * 16); } } while (0)
; DEV void peer_gather(const Params& P, int l, int m0, const int* idxs, const float* gs) {
;     ...
;     PG_ISSUE(b0, U, 0);
; #pragma nounroll
;     for (int e0 = 0; e0 < 128; e0 += 16) {
;       PG_ISSUE(b1, U, e0 + 8);
;       PG_U8(b0, 0, e0);
;       if (e0 + 16 < 128) PG_ISSUE(b0, U, e0 + 16); else PG_ISSUE(b0, V, 0);
;       PG_U8(b1, 0, e0 + 8);
;     }
;     float* hrow = P.out + tok * DM + lane * 16;
;     f32x4 hv[4];
; #pragma unroll
;     for (int q = 0; q < 4; ++q) hv[q] = *(const f32x4*)(hrow + 4 * q);
;     if (i + 1 < 16) {
;       const int tn = tt + 1;
;       nxa = *(const u32x4*)(hn + (size_t)(m0 + tn) * DM + lane * 16); nxb = *(const u32x4*)(hn + (size_t)(m0 + tn) * DM + lane * 16 + 8);
;       ni0 = idxs[tn * 128 + lane]; ni1 = idxs[tn * 128 + 64 + lane]; ng0 = gs[tn * 128 + lane]; ng1 = gs[tn * 128 + 64 + lane];
;     }
; #pragma nounroll
;     for (int e0 = 0; e0 < 128; e0 += 16) {
;       PG_ISSUE(b1, V, e0 + 8);
;       if (e0 == 64 && i + 1 < 16) sort_lists(lane, ni0, ni1, ng0, ng1);
;       PG_V16(b0, e0);
;       if (e0 + 16 < 128) PG_ISSUE(b0, V, e0 + 16);
;       PG_V16(b1, e0 + 8);
;     }
	v_cvt_pk_f32_fp8_e32 v[96:97], v80
	v_cvt_pk_f32_fp8_sdwa v[98:99], v80 src0_sel:WORD_1
	v_cvt_pk_f32_fp8_e32 v[100:101], v84
	v_cvt_pk_f32_fp8_sdwa v[102:103], v84 src0_sel:WORD_1
	v_pk_fma_f32 v[0:1], v[96:97], s[84:85], v[0:1] op_sel_hi:[1,0,1]
	v_pk_fma_f32 v[2:3], v[98:99], s[84:85], v[2:3] op_sel_hi:[1,0,1]
	v_pk_fma_f32 v[0:1], v[100:101], s[86:87], v[0:1] op_sel_hi:[1,0,1]
	v_pk_fma_f32 v[2:3], v[102:103], s[86:87], v[2:3] op_sel_hi:[1,0,1]
	v_cvt_pk_f32_fp8_e32 v[96:97], v81
	v_cvt_pk_f32_fp8_sdwa v[98:99], v81 src0_sel:WORD_1
	v_cvt_pk_f32_fp8_e32 v[100:101], v85
	v_cvt_pk_f32_fp8_sdwa v[102:103], v85 src0_sel:WORD_1
	v_pk_fma_f32 v[4:5], v[96:97], s[84:85], v[4:5] op_sel_hi:[1,0,1]
	v_pk_fma_f32 v[6:7], v[98:99], s[84:85], v[6:7] op_sel_hi:[1,0,1]
	v_pk_fma_f32 v[4:5], v[100:101], s[86:87], v[4:5] op_sel_hi:[1,0,1]
	v_pk_fma_f32 v[6:7], v[102:103], s[86:87], v[6:7] op_sel_hi:[1,0,1]
	v_cvt_pk_f32_fp8_e32 v[96:97], v82
	v_cvt_pk_f32_fp8_sdwa v[98:99], v82 src0_sel:WORD_1
	v_cvt_pk_f32_fp8_e32 v[100:101], v86
	v_cvt_pk_f32_fp8_sdwa v[102:103], v86 src0_sel:WORD_1
	v_pk_fma_f32 v[8:9], v[96:97], s[84:85], v[8:9] op_sel_hi:[1,0,1]
	v_pk_fma_f32 v[10:11], v[98:99], s[84:85], v[10:11] op_sel_hi:[1,0,1]
	v_pk_fma_f32 v[8:9], v[100:101], s[86:87], v[8:9] op_sel_hi:[1,0,1]
	v_pk_fma_f32 v[10:11], v[102:103], s[86:87], v[10:11] op_sel_hi:[1,0,1]
	v_cvt_pk_f32_fp8_e32 v[96:97], v83
	v_cvt_pk_f32_fp8_sdwa v[98:99], v83 src0_sel:WORD_1
	v_cvt_pk_f32_fp8_e32 v[100:101], v87
	v_cvt_pk_f32_fp8_sdwa v[102:103], v87 src0_sel:WORD_1
	global_load_dwordx4 v[80:83], v138, s[80:81]
	global_load_dwordx4 v[84:87], v139, s[80:81]
	v_pk_fma_f32 v[12:13], v[96:97], s[84:85], v[12:13] op_sel_hi:[1,0,1]
	v_pk_fma_f32 v[14:15], v[98:99], s[84:85], v[14:15] op_sel_hi:[1,0,1]
	v_pk_fma_f32 v[12:13], v[100:101], s[86:87], v[12:13] op_sel_hi:[1,0,1]
	v_pk_fma_f32 v[14:15], v[102:103], s[86:87], v[14:15] op_sel_hi:[1,0,1]
	s_add_u32 s98, s101, 6
	s_add_u32 s99, s101, 7
	v_readlane_b32 s84, v152, s98
	v_readlane_b32 s86, v152, s99
	s_waitcnt vmcnt(6)
	v_cvt_pk_f32_fp8_e32 v[96:97], v88
	v_cvt_pk_f32_fp8_sdwa v[98:99], v88 src0_sel:WORD_1
	v_cvt_pk_f32_fp8_e32 v[100:101], v92
	v_cvt_pk_f32_fp8_sdwa v[102:103], v92 src0_sel:WORD_1
	v_pk_fma_f32 v[0:1], v[96:97], s[84:85], v[0:1] op_sel_hi:[1,0,1]
	v_pk_fma_f32 v[2:3], v[98:99], s[84:85], v[2:3] op_sel_hi:[1,0,1]
	v_pk_fma_f32 v[0:1], v[100:101], s[86:87], v[0:1] op_sel_hi:[1,0,1]
	v_pk_fma_f32 v[2:3], v[102:103], s[86:87], v[2:3] op_sel_hi:[1,0,1]
	v_cvt_pk_f32_fp8_e32 v[96:97], v89
	v_cvt_pk_f32_fp8_sdwa v[98:99], v89 src0_sel:WORD_1
	v_cvt_pk_f32_fp8_e32 v[100:101], v93
	v_cvt_pk_f32_fp8_sdwa v[102:103], v93 src0_sel:WORD_1
	v_pk_fma_f32 v[4:5], v[96:97], s[84:85], v[4:5] op_sel_hi:[1,0,1]
	v_pk_fma_f32 v[6:7], v[98:99], s[84:85], v[6:7] op_sel_hi:[1,0,1]
	v_pk_fma_f32 v[4:5], v[100:101], s[86:87], v[4:5] op_sel_hi:[1,0,1]
	v_pk_fma_f32 v[6:7], v[102:103], s[86:87], v[6:7] op_sel_hi:[1,0,1]
	v_cvt_pk_f32_fp8_e32 v[96:97], v90
	v_cvt_pk_f32_fp8_sdwa v[98:99], v90 src0_sel:WORD_1
	v_cvt_pk_f32_fp8_e32 v[100:101], v94
	v_cvt_pk_f32_fp8_sdwa v[102:103], v94 src0_sel:WORD_1
	v_pk_fma_f32 v[8:9], v[96:97], s[84:85], v[8:9] op_sel_hi:[1,0,1]
	v_pk_fma_f32 v[10:11], v[98:99], s[84:85], v[10:11] op_sel_hi:[1,0,1]
	v_pk_fma_f32 v[8:9], v[100:101], s[86:87], v[8:9] op_sel_hi:[1,0,1]
	v_pk_fma_f32 v[10:11], v[102:103], s[86:87], v[10:11] op_sel_hi:[1,0,1]
	v_cvt_pk_f32_fp8_e32 v[96:97], v91
	v_cvt_pk_f32_fp8_sdwa v[98:99], v91 src0_sel:WORD_1
	v_cvt_pk_f32_fp8_e32 v[100:101], v95
	v_cvt_pk_f32_fp8_sdwa v[102:103], v95 src0_sel:WORD_1
	global_load_dwordx4 v[88:91], v140, s[80:81]
	global_load_dwordx4 v[92:95], v141, s[80:81]
	v_pk_fma_f32 v[12:13], v[96:97], s[84:85], v[12:13] op_sel_hi:[1,0,1]
	v_pk_fma_f32 v[14:15], v[98:99], s[84:85], v[14:15] op_sel_hi:[1,0,1]
	v_pk_fma_f32 v[12:13], v[100:101], s[86:87], v[12:13] op_sel_hi:[1,0,1]
	v_pk_fma_f32 v[14:15], v[102:103], s[86:87], v[14:15] op_sel_hi:[1,0,1]
	v_cndmask_b32_e64 v153, v146, v147, s[90:91]
	s_nop 0
	s_add_u32 s98, s101, 0
	v_readlane_b32 s98, v153, s98
	s_add_u32 s99, s101, 1
	v_readlane_b32 s99, v153, s99
	s_add_u32 s92, s101, 2
	v_readlane_b32 s92, v153, s92
	s_add_u32 s93, s101, 3
	v_readlane_b32 s93, v153, s93
	v_lshl_add_u32 v134, s98, 10, v250
	v_lshl_add_u32 v135, s99, 10, v250
	v_lshl_add_u32 v136, s92, 10, v250
	v_lshl_add_u32 v137, s93, 10, v250
	s_add_u32 s98, s101, 4
	v_readlane_b32 s98, v153, s98
	s_add_u32 s99, s101, 5
	v_readlane_b32 s99, v153, s99
	s_add_u32 s92, s101, 6
	v_readlane_b32 s92, v153, s92
	s_add_u32 s93, s101, 7
	v_readlane_b32 s93, v153, s93
	v_lshl_add_u32 v138, s98, 10, v250
	v_lshl_add_u32 v139, s99, 10, v250
	v_lshl_add_u32 v140, s92, 10, v250
	v_lshl_add_u32 v141, s93, 10, v250
	v_cndmask_b32_e64 v152, v243, v244, s[90:91]
	s_add_u32 s98, s101, 0
	s_add_u32 s99, s101, 1
	v_readlane_b32 s84, v152, s98
	v_readlane_b32 s86, v152, s99
	s_waitcnt vmcnt(6)
; #define PG_ISSUE(BUF, TAB, e0_) do { const int isrc_ = ((e0_) < 64) ? myi0 : myi1; \
;       _Pragma("unroll") for (int e = 0; e < 8; ++e) { const int idx_ = __builtin_amdgcn_readlane(isrc_, ((e0_) + e) & 63); \
;         BUF[e] = *(const u32x4*)((TAB) + (size_t)idx_ * 1024 + lane * 16); } } while (0)
; DEV void peer_gather(const Params& P, int l, int m0, const int* idxs, const float* gs) {
;     ...
; #pragma nounroll
;     for (int e0 = 0; e0 < 128; e0 += 16) {
;       PG_ISSUE(b1, V, e0 + 8);
;       if (e0 == 64 && i + 1 < 16) sort_lists(lane, ni0, ni1, ng0, ng1);
;       PG_V16(b0, e0);
;       if (e0 + 16 < 128) PG_ISSUE(b0, V, e0 + 16);
;       PG_V16(b1, e0 + 8);
;     }
	v_cvt_pk_f32_fp8_e32 v[96:97], v64
	v_cvt_pk_f32_fp8_sdwa v[98:99], v64 src0_sel:WORD_1
	v_cvt_pk_f32_fp8_e32 v[100:101], v68
	v_cvt_pk_f32_fp8_sdwa v[102:103], v68 src0_sel:WORD_1
	v_pk_fma_f32 v[16:17], v[96:97], s[84:85], v[16:17] op_sel_hi:[1,0,1]
	v_pk_fma_f32 v[18:19], v[98:99], s[84:85], v[18:19] op_sel_hi:[1,0,1]
	v_pk_fma_f32 v[16:17], v[100:101], s[86:87], v[16:17] op_sel_hi:[1,0,1]
	v_pk_fma_f32 v[18:19], v[102:103], s[86:87], v[18:19] op_sel_hi:[1,0,1]
	v_cvt_pk_f32_fp8_e32 v[96:97], v65
	v_cvt_pk_f32_fp8_sdwa v[98:99], v65 src0_sel:WORD_1
	v_cvt_pk_f32_fp8_e32 v[100:101], v69
	v_cvt_pk_f32_fp8_sdwa v[102:103], v69 src0_sel:WORD_1
	v_pk_fma_f32 v[20:21], v[96:97], s[84:85], v[20:21] op_sel_hi:[1,0,1]
	v_pk_fma_f32 v[22:23], v[98:99], s[84:85], v[22:23] op_sel_hi:[1,0,1]
	v_pk_fma_f32 v[20:21], v[100:101], s[86:87], v[20:21] op_sel_hi:[1,0,1]
	v_pk_fma_f32 v[22:23], v[102:103], s[86:87], v[22:23] op_sel_hi:[1,0,1]
	v_cvt_pk_f32_fp8_e32 v[96:97], v66
	v_cvt_pk_f32_fp8_sdwa v[98:99], v66 src0_sel:WORD_1
	v_cvt_pk_f32_fp8_e32 v[100:101], v70
	v_cvt_pk_f32_fp8_sdwa v[102:103], v70 src0_sel:WORD_1
	v_pk_fma_f32 v[24:25], v[96:97], s[84:85], v[24:25] op_sel_hi:[1,0,1]
	v_pk_fma_f32 v[26:27], v[98:99], s[84:85], v[26:27] op_sel_hi:[1,0,1]
	v_pk_fma_f32 v[24:25], v[100:101], s[86:87], v[24:25] op_sel_hi:[1,0,1]
	v_pk_fma_f32 v[26:27], v[102:103], s[86:87], v[26:27] op_sel_hi:[1,0,1]
	v_cvt_pk_f32_fp8_e32 v[96:97], v67
	v_cvt_pk_f32_fp8_sdwa v[98:99], v67 src0_sel:WORD_1
	v_cvt_pk_f32_fp8_e32 v[100:101], v71
	v_cvt_pk_f32_fp8_sdwa v[102:103], v71 src0_sel:WORD_1
	global_load_dwordx4 v[64:67], v134, s[80:81]
	global_load_dwordx4 v[68:71], v135, s[80:81]
	v_pk_fma_f32 v[28:29], v[96:97], s[84:85], v[28:29] op_sel_hi:[1,0,1]
	v_pk_fma_f32 v[30:31], v[98:99], s[84:85], v[30:31] op_sel_hi:[1,0,1]
	v_pk_fma_f32 v[28:29], v[100:101], s[86:87], v[28:29] op_sel_hi:[1,0,1]
	v_pk_fma_f32 v[30:31], v[102:103], s[86:87], v[30:31] op_sel_hi:[1,0,1]
	s_add_u32 s98, s101, 2
	s_add_u32 s99, s101, 3
	v_readlane_b32 s84, v152, s98
	v_readlane_b32 s86, v152, s99
	s_waitcnt vmcnt(6)
	v_cvt_pk_f32_fp8_e32 v[96:97], v72
	v_cvt_pk_f32_fp8_sdwa v[98:99], v72 src0_sel:WORD_1
	v_cvt_pk_f32_fp8_e32 v[100:101], v76
	v_cvt_pk_f32_fp8_sdwa v[102:103], v76 src0_sel:WORD_1
	v_pk_fma_f32 v[16:17], v[96:97], s[84:85], v[16:17] op_sel_hi:[1,0,1]
	v_pk_fma_f32 v[18:19], v[98:99], s[84:85], v[18:19] op_sel_hi:[1,0,1]
	v_pk_fma_f32 v[16:17], v[100:101], s[86:87], v[16:17] op_sel_hi:[1,0,1]
	v_pk_fma_f32 v[18:19], v[102:103], s[86:87], v[18:19] op_sel_hi:[1,0,1]
	v_cvt_pk_f32_fp8_e32 v[96:97], v73
	v_cvt_pk_f32_fp8_sdwa v[98:99], v73 src0_sel:WORD_1
	v_cvt_pk_f32_fp8_e32 v[100:101], v77
	v_cvt_pk_f32_fp8_sdwa v[102:103], v77 src0_sel:WORD_1
	v_pk_fma_f32 v[20:21], v[96:97], s[84:85], v[20:21] op_sel_hi:[1,0,1]
	v_pk_fma_f32 v[22:23], v[98:99], s[84:85], v[22:23] op_sel_hi:[1,0,1]
	v_pk_fma_f32 v[20:21], v[100:101], s[86:87], v[20:21] op_sel_hi:[1,0,1]
	v_pk_fma_f32 v[22:23], v[102:103], s[86:87], v[22:23] op_sel_hi:[1,0,1]
	v_cvt_pk_f32_fp8_e32 v[96:97], v74
	v_cvt_pk_f32_fp8_sdwa v[98:99], v74 src0_sel:WORD_1
	v_cvt_pk_f32_fp8_e32 v[100:101], v78
	v_cvt_pk_f32_fp8_sdwa v[102:103], v78 src0_sel:WORD_1
	v_pk_fma_f32 v[24:25], v[96:97], s[84:85], v[24:25] op_sel_hi:[1,0,1]
	v_pk_fma_f32 v[26:27], v[98:99], s[84:85], v[26:27] op_sel_hi:[1,0,1]
	v_pk_fma_f32 v[24:25], v[100:101], s[86:87], v[24:25] op_sel_hi:[1,0,1]
	v_pk_fma_f32 v[26:27], v[102:103], s[86:87], v[26:27] op_sel_hi:[1,0,1]
	v_cvt_pk_f32_fp8_e32 v[96:97], v75
	v_cvt_pk_f32_fp8_sdwa v[98:99], v75 src0_sel:WORD_1
	v_cvt_pk_f32_fp8_e32 v[100:101], v79
	v_cvt_pk_f32_fp8_sdwa v[102:103], v79 src0_sel:WORD_1
	global_load_dwordx4 v[72:75], v136, s[80:81]
	global_load_dwordx4 v[76:79], v137, s[80:81]
	v_pk_fma_f32 v[28:29], v[96:97], s[84:85], v[28:29] op_sel_hi:[1,0,1]
	v_pk_fma_f32 v[30:31], v[98:99], s[84:85], v[30:31] op_sel_hi:[1,0,1]
	v_pk_fma_f32 v[28:29], v[100:101], s[86:87], v[28:29] op_sel_hi:[1,0,1]
	v_pk_fma_f32 v[30:31], v[102:103], s[86:87], v[30:31] op_sel_hi:[1,0,1]
	s_add_u32 s98, s101, 4
	s_add_u32 s99, s101, 5
	v_readlane_b32 s84, v152, s98
	v_readlane_b32 s86, v152, s99
	s_waitcnt vmcnt(6)
	v_cvt_pk_f32_fp8_e32 v[96:97], v80
	v_cvt_pk_f32_fp8_sdwa v[98:99], v80 src0_sel:WORD_1
	v_cvt_pk_f32_fp8_e32 v[100:101], v84
	v_cvt_pk_f32_fp8_sdwa v[102:103], v84 src0_sel:WORD_1
	v_pk_fma_f32 v[16:17], v[96:97], s[84:85], v[16:17] op_sel_hi:[1,0,1]
	v_pk_fma_f32 v[18:19], v[98:99], s[84:85], v[18:19] op_sel_hi:[1,0,1]
	v_pk_fma_f32 v[16:17], v[100:101], s[86:87], v[16:17] op_sel_hi:[1,0,1]
	v_pk_fma_f32 v[18:19], v[102:103], s[86:87], v[18:19] op_sel_hi:[1,0,1]
	v_cvt_pk_f32_fp8_e32 v[96:97], v81
	v_cvt_pk_f32_fp8_sdwa v[98:99], v81 src0_sel:WORD_1
	v_cvt_pk_f32_fp8_e32 v[100:101], v85
	v_cvt_pk_f32_fp8_sdwa v[102:103], v85 src0_sel:WORD_1
	v_pk_fma_f32 v[20:21], v[96:97], s[84:85], v[20:21] op_sel_hi:[1,0,1]
	v_pk_fma_f32 v[22:23], v[98:99], s[84:85], v[22:23] op_sel_hi:[1,0,1]
	v_pk_fma_f32 v[20:21], v[100:101], s[86:87], v[20:21] op_sel_hi:[1,0,1]
	v_pk_fma_f32 v[22:23], v[102:103], s[86:87], v[22:23] op_sel_hi:[1,0,1]
	v_cvt_pk_f32_fp8_e32 v[96:97], v82
	v_cvt_pk_f32_fp8_sdwa v[98:99], v82 src0_sel:WORD_1
	v_cvt_pk_f32_fp8_e32 v[100:101], v86
	v_cvt_pk_f32_fp8_sdwa v[102:103], v86 src0_sel:WORD_1
	v_pk_fma_f32 v[24:25], v[96:97], s[84:85], v[24:25] op_sel_hi:[1,0,1]
	v_pk_fma_f32 v[26:27], v[98:99], s[84:85], v[26:27] op_sel_hi:[1,0,1]
	v_pk_fma_f32 v[24:25], v[100:101], s[86:87], v[24:25] op_sel_hi:[1,0,1]
	v_pk_fma_f32 v[26:27], v[102:103], s[86:87], v[26:27] op_sel_hi:[1,0,1]
	v_cvt_pk_f32_fp8_e32 v[96:97], v83
	v_cvt_pk_f32_fp8_sdwa v[98:99], v83 src0_sel:WORD_1
	v_cvt_pk_f32_fp8_e32 v[100:101], v87
	v_cvt_pk_f32_fp8_sdwa v[102:103], v87 src0_sel:WORD_1
	global_load_dwordx4 v[80:83], v138, s[80:81]
	global_load_dwordx4 v[84:87], v139, s[80:81]
	v_pk_fma_f32 v[28:29], v[96:97], s[84:85], v[28:29] op_sel_hi:[1,0,1]
	v_pk_fma_f32 v[30:31], v[98:99], s[84:85], v[30:31] op_sel_hi:[1,0,1]
	v_pk_fma_f32 v[28:29], v[100:101], s[86:87], v[28:29] op_sel_hi:[1,0,1]
	v_pk_fma_f32 v[30:31], v[102:103], s[86:87], v[30:31] op_sel_hi:[1,0,1]
	s_add_u32 s98, s101, 6
	s_add_u32 s99, s101, 7
	v_readlane_b32 s84, v152, s98
	v_readlane_b32 s86, v152, s99
	s_waitcnt vmcnt(6)
; #define PG_ISSUE(BUF, TAB, e0_) do { const int isrc_ = ((e0_) < 64) ? myi0 : myi1; \
;       _Pragma("unroll") for (int e = 0; e < 8; ++e) { const int idx_ = __builtin_amdgcn_readlane(isrc_, ((e0_) + e) & 63); \
;         BUF[e] = *(const u32x4*)((TAB) + (size_t)idx_ * 1024 + lane * 16); } } while (0)
; DEV void peer_gather(const Params& P, int l, int m0, const int* idxs, const float* gs) {
;     ...
; #pragma nounroll
;     for (int e0 = 0; e0 < 128; e0 += 16) {
;       PG_ISSUE(b1, V, e0 + 8);
;       if (e0 == 64 && i + 1 < 16) sort_lists(lane, ni0, ni1, ng0, ng1);
;       PG_V16(b0, e0);
;       if (e0 + 16 < 128) PG_ISSUE(b0, V, e0 + 16);
;       PG_V16(b1, e0 + 8);
;     }
	v_cvt_pk_f32_fp8_e32 v[96:97], v88
	v_cvt_pk_f32_fp8_sdwa v[98:99], v88 src0_sel:WORD_1
	v_cvt_pk_f32_fp8_e32 v[100:101], v92
	v_cvt_pk_f32_fp8_sdwa v[102:103], v92 src0_sel:WORD_1
	v_pk_fma_f32 v[16:17], v[96:97], s[84:85], v[16:17] op_sel_hi:[1,0,1]
	v_pk_fma_f32 v[18:19], v[98:99], s[84:85], v[18:19] op_sel_hi:[1,0,1]
	v_pk_fma_f32 v[16:17], v[100:101], s[86:87], v[16:17] op_sel_hi:[1,0,1]
	v_pk_fma_f32 v[18:19], v[102:103], s[86:87], v[18:19] op_sel_hi:[1,0,1]
	v_cvt_pk_f32_fp8_e32 v[96:97], v89
	v_cvt_pk_f32_fp8_sdwa v[98:99], v89 src0_sel:WORD_1
	v_cvt_pk_f32_fp8_e32 v[100:101], v93
	v_cvt_pk_f32_fp8_sdwa v[102:103], v93 src0_sel:WORD_1
	v_pk_fma_f32 v[20:21], v[96:97], s[84:85], v[20:21] op_sel_hi:[1,0,1]
	v_pk_fma_f32 v[22:23], v[98:99], s[84:85], v[22:23] op_sel_hi:[1,0,1]
	v_pk_fma_f32 v[20:21], v[100:101], s[86:87], v[20:21] op_sel_hi:[1,0,1]
	v_pk_fma_f32 v[22:23], v[102:103], s[86:87], v[22:23] op_sel_hi:[1,0,1]
	v_cvt_pk_f32_fp8_e32 v[96:97], v90
	v_cvt_pk_f32_fp8_sdwa v[98:99], v90 src0_sel:WORD_1
	v_cvt_pk_f32_fp8_e32 v[100:101], v94
	v_cvt_pk_f32_fp8_sdwa v[102:103], v94 src0_sel:WORD_1
	v_pk_fma_f32 v[24:25], v[96:97], s[84:85], v[24:25] op_sel_hi:[1,0,1]
	v_pk_fma_f32 v[26:27], v[98:99], s[84:85], v[26:27] op_sel_hi:[1,0,1]
	v_pk_fma_f32 v[24:25], v[100:101], s[86:87], v[24:25] op_sel_hi:[1,0,1]
	v_pk_fma_f32 v[26:27], v[102:103], s[86:87], v[26:27] op_sel_hi:[1,0,1]
	v_cvt_pk_f32_fp8_e32 v[96:97], v91
	v_cvt_pk_f32_fp8_sdwa v[98:99], v91 src0_sel:WORD_1
	v_cvt_pk_f32_fp8_e32 v[100:101], v95
	v_cvt_pk_f32_fp8_sdwa v[102:103], v95 src0_sel:WORD_1
	global_load_dwordx4 v[88:91], v140, s[80:81]
	global_load_dwordx4 v[92:95], v141, s[80:81]
	v_pk_fma_f32 v[28:29], v[96:97], s[84:85], v[28:29] op_sel_hi:[1,0,1]
	v_pk_fma_f32 v[30:31], v[98:99], s[84:85], v[30:31] op_sel_hi:[1,0,1]
	v_pk_fma_f32 v[28:29], v[100:101], s[86:87], v[28:29] op_sel_hi:[1,0,1]
	v_pk_fma_f32 v[30:31], v[102:103], s[86:87], v[30:31] op_sel_hi:[1,0,1]
	v_cndmask_b32_e64 v153, v148, v149, s[90:91]
	s_nop 0
	s_add_u32 s98, s101, 0
	v_readlane_b32 s98, v153, s98
	s_add_u32 s99, s101, 1
	v_readlane_b32 s99, v153, s99
	s_add_u32 s92, s101, 2
	v_readlane_b32 s92, v153, s92
	s_add_u32 s93, s101, 3
	v_readlane_b32 s93, v153, s93
	v_lshl_add_u32 v134, s98, 10, v250
	v_lshl_add_u32 v135, s99, 10, v250
	v_lshl_add_u32 v136, s92, 10, v250
	v_lshl_add_u32 v137, s93, 10, v250
	s_add_u32 s98, s101, 4
	v_readlane_b32 s98, v153, s98
	s_add_u32 s99, s101, 5
	v_readlane_b32 s99, v153, s99
	s_add_u32 s92, s101, 6
	v_readlane_b32 s92, v153, s92
	s_add_u32 s93, s101, 7
	v_readlane_b32 s93, v153, s93
	v_lshl_add_u32 v138, s98, 10, v250
	v_lshl_add_u32 v139, s99, 10, v250
	v_lshl_add_u32 v140, s92, 10, v250
	v_lshl_add_u32 v141, s93, 10, v250
	v_cndmask_b32_e64 v152, v245, v246, s[90:91]
	s_add_u32 s98, s101, 0
	s_add_u32 s99, s101, 1
	v_readlane_b32 s84, v152, s98
	v_readlane_b32 s86, v152, s99
	s_waitcnt vmcnt(6)
	v_cvt_pk_f32_fp8_e32 v[96:97], v64
	v_cvt_pk_f32_fp8_sdwa v[98:99], v64 src0_sel:WORD_1
	v_cvt_pk_f32_fp8_e32 v[100:101], v68
	v_cvt_pk_f32_fp8_sdwa v[102:103], v68 src0_sel:WORD_1
	v_pk_fma_f32 v[32:33], v[96:97], s[84:85], v[32:33] op_sel_hi:[1,0,1]
	v_pk_fma_f32 v[34:35], v[98:99], s[84:85], v[34:35] op_sel_hi:[1,0,1]
	v_pk_fma_f32 v[32:33], v[100:101], s[86:87], v[32:33] op_sel_hi:[1,0,1]
	v_pk_fma_f32 v[34:35], v[102:103], s[86:87], v[34:35] op_sel_hi:[1,0,1]
	v_cvt_pk_f32_fp8_e32 v[96:97], v65
	v_cvt_pk_f32_fp8_sdwa v[98:99], v65 src0_sel:WORD_1
	v_cvt_pk_f32_fp8_e32 v[100:101], v69
	v_cvt_pk_f32_fp8_sdwa v[102:103], v69 src0_sel:WORD_1
	v_pk_fma_f32 v[36:37], v[96:97], s[84:85], v[36:37] op_sel_hi:[1,0,1]
	v_pk_fma_f32 v[38:39], v[98:99], s[84:85], v[38:39] op_sel_hi:[1,0,1]
	v_pk_fma_f32 v[36:37], v[100:101], s[86:87], v[36:37] op_sel_hi:[1,0,1]
	v_pk_fma_f32 v[38:39], v[102:103], s[86:87], v[38:39] op_sel_hi:[1,0,1]
	v_cvt_pk_f32_fp8_e32 v[96:97], v66
	v_cvt_pk_f32_fp8_sdwa v[98:99], v66 src0_sel:WORD_1
	v_cvt_pk_f32_fp8_e32 v[100:101], v70
	v_cvt_pk_f32_fp8_sdwa v[102:103], v70 src0_sel:WORD_1
	v_pk_fma_f32 v[40:41], v[96:97], s[84:85], v[40:41] op_sel_hi:[1,0,1]
	v_pk_fma_f32 v[42:43], v[98:99], s[84:85], v[42:43] op_sel_hi:[1,0,1]
	v_pk_fma_f32 v[40:41], v[100:101], s[86:87], v[40:41] op_sel_hi:[1,0,1]
	v_pk_fma_f32 v[42:43], v[102:103], s[86:87], v[42:43] op_sel_hi:[1,0,1]
	v_cvt_pk_f32_fp8_e32 v[96:97], v67
	v_cvt_pk_f32_fp8_sdwa v[98:99], v67 src0_sel:WORD_1
	v_cvt_pk_f32_fp8_e32 v[100:101], v71
	v_cvt_pk_f32_fp8_sdwa v[102:103], v71 src0_sel:WORD_1
	global_load_dwordx4 v[64:67], v134, s[80:81]
	global_load_dwordx4 v[68:71], v135, s[80:81]
	v_pk_fma_f32 v[44:45], v[96:97], s[84:85], v[44:45] op_sel_hi:[1,0,1]
	v_pk_fma_f32 v[46:47], v[98:99], s[84:85], v[46:47] op_sel_hi:[1,0,1]
	v_pk_fma_f32 v[44:45], v[100:101], s[86:87], v[44:45] op_sel_hi:[1,0,1]
	v_pk_fma_f32 v[46:47], v[102:103], s[86:87], v[46:47] op_sel_hi:[1,0,1]
	s_add_u32 s98, s101, 2
	s_add_u32 s99, s101, 3
	v_readlane_b32 s84, v152, s98
	v_readlane_b32 s86, v152, s99
	s_waitcnt vmcnt(6)
; #define PG_ISSUE(BUF, TAB, e0_) do { const int isrc_ = ((e0_) < 64) ? myi0 : myi1; \
;       _Pragma("unroll") for (int e = 0; e < 8; ++e) { const int idx_ = __builtin_amdgcn_readlane(isrc_, ((e0_) + e) & 63); \
;         BUF[e] = *(const u32x4*)((TAB) + (size_t)idx_ * 1024 + lane * 16); } } while (0)
; DEV void peer_gather(const Params& P, int l, int m0, const int* idxs, const float* gs) {
;     ...
; #pragma nounroll
;     for (int e0 = 0; e0 < 128; e0 += 16) {
;       PG_ISSUE(b1, V, e0 + 8);
;       if (e0 == 64 && i + 1 < 16) sort_lists(lane, ni0, ni1, ng0, ng1);
;       PG_V16(b0, e0);
;       if (e0 + 16 < 128) PG_ISSUE(b0, V, e0 + 16);
;       PG_V16(b1, e0 + 8);
;     }
	v_cvt_pk_f32_fp8_e32 v[96:97], v72
	v_cvt_pk_f32_fp8_sdwa v[98:99], v72 src0_sel:WORD_1
	v_cvt_pk_f32_fp8_e32 v[100:101], v76
	v_cvt_pk_f32_fp8_sdwa v[102:103], v76 src0_sel:WORD_1
	v_pk_fma_f32 v[32:33], v[96:97], s[84:85], v[32:33] op_sel_hi:[1,0,1]
	v_pk_fma_f32 v[34:35], v[98:99], s[84:85], v[34:35] op_sel_hi:[1,0,1]
	v_pk_fma_f32 v[32:33], v[100:101], s[86:87], v[32:33] op_sel_hi:[1,0,1]
	v_pk_fma_f32 v[34:35], v[102:103], s[86:87], v[34:35] op_sel_hi:[1,0,1]
	v_cvt_pk_f32_fp8_e32 v[96:97], v73
	v_cvt_pk_f32_fp8_sdwa v[98:99], v73 src0_sel:WORD_1
	v_cvt_pk_f32_fp8_e32 v[100:101], v77
	v_cvt_pk_f32_fp8_sdwa v[102:103], v77 src0_sel:WORD_1
	v_pk_fma_f32 v[36:37], v[96:97], s[84:85], v[36:37] op_sel_hi:[1,0,1]
	v_pk_fma_f32 v[38:39], v[98:99], s[84:85], v[38:39] op_sel_hi:[1,0,1]
	v_pk_fma_f32 v[36:37], v[100:101], s[86:87], v[36:37] op_sel_hi:[1,0,1]
	v_pk_fma_f32 v[38:39], v[102:103], s[86:87], v[38:39] op_sel_hi:[1,0,1]
	v_cvt_pk_f32_fp8_e32 v[96:97], v74
	v_cvt_pk_f32_fp8_sdwa v[98:99], v74 src0_sel:WORD_1
	v_cvt_pk_f32_fp8_e32 v[100:101], v78
	v_cvt_pk_f32_fp8_sdwa v[102:103], v78 src0_sel:WORD_1
	v_pk_fma_f32 v[40:41], v[96:97], s[84:85], v[40:41] op_sel_hi:[1,0,1]
	v_pk_fma_f32 v[42:43], v[98:99], s[84:85], v[42:43] op_sel_hi:[1,0,1]
	v_pk_fma_f32 v[40:41], v[100:101], s[86:87], v[40:41] op_sel_hi:[1,0,1]
	v_pk_fma_f32 v[42:43], v[102:103], s[86:87], v[42:43] op_sel_hi:[1,0,1]
	v_cvt_pk_f32_fp8_e32 v[96:97], v75
	v_cvt_pk_f32_fp8_sdwa v[98:99], v75 src0_sel:WORD_1
	v_cvt_pk_f32_fp8_e32 v[100:101], v79
	v_cvt_pk_f32_fp8_sdwa v[102:103], v79 src0_sel:WORD_1
	global_load_dwordx4 v[72:75], v136, s[80:81]
	global_load_dwordx4 v[76:79], v137, s[80:81]
	v_pk_fma_f32 v[44:45], v[96:97], s[84:85], v[44:45] op_sel_hi:[1,0,1]
	v_pk_fma_f32 v[46:47], v[98:99], s[84:85], v[46:47] op_sel_hi:[1,0,1]
	v_pk_fma_f32 v[44:45], v[100:101], s[86:87], v[44:45] op_sel_hi:[1,0,1]
	v_pk_fma_f32 v[46:47], v[102:103], s[86:87], v[46:47] op_sel_hi:[1,0,1]
	s_add_u32 s98, s101, 4
	s_add_u32 s99, s101, 5
	v_readlane_b32 s84, v152, s98
	v_readlane_b32 s86, v152, s99
	s_waitcnt vmcnt(6)
	v_cvt_pk_f32_fp8_e32 v[96:97], v80
	v_cvt_pk_f32_fp8_sdwa v[98:99], v80 src0_sel:WORD_1
	v_cvt_pk_f32_fp8_e32 v[100:101], v84
	v_cvt_pk_f32_fp8_sdwa v[102:103], v84 src0_sel:WORD_1
	v_pk_fma_f32 v[32:33], v[96:97], s[84:85], v[32:33] op_sel_hi:[1,0,1]
	v_pk_fma_f32 v[34:35], v[98:99], s[84:85], v[34:35] op_sel_hi:[1,0,1]
	v_pk_fma_f32 v[32:33], v[100:101], s[86:87], v[32:33] op_sel_hi:[1,0,1]
	v_pk_fma_f32 v[34:35], v[102:103], s[86:87], v[34:35] op_sel_hi:[1,0,1]
	v_cvt_pk_f32_fp8_e32 v[96:97], v81
	v_cvt_pk_f32_fp8_sdwa v[98:99], v81 src0_sel:WORD_1
	v_cvt_pk_f32_fp8_e32 v[100:101], v85
	v_cvt_pk_f32_fp8_sdwa v[102:103], v85 src0_sel:WORD_1
	v_pk_fma_f32 v[36:37], v[96:97], s[84:85], v[36:37] op_sel_hi:[1,0,1]
	v_pk_fma_f32 v[38:39], v[98:99], s[84:85], v[38:39] op_sel_hi:[1,0,1]
	v_pk_fma_f32 v[36:37], v[100:101], s[86:87], v[36:37] op_sel_hi:[1,0,1]
	v_pk_fma_f32 v[38:39], v[102:103], s[86:87], v[38:39] op_sel_hi:[1,0,1]
	v_cvt_pk_f32_fp8_e32 v[96:97], v82
	v_cvt_pk_f32_fp8_sdwa v[98:99], v82 src0_sel:WORD_1
	v_cvt_pk_f32_fp8_e32 v[100:101], v86
	v_cvt_pk_f32_fp8_sdwa v[102:103], v86 src0_sel:WORD_1
	v_pk_fma_f32 v[40:41], v[96:97], s[84:85], v[40:41] op_sel_hi:[1,0,1]
	v_pk_fma_f32 v[42:43], v[98:99], s[84:85], v[42:43] op_sel_hi:[1,0,1]
	v_pk_fma_f32 v[40:41], v[100:101], s[86:87], v[40:41] op_sel_hi:[1,0,1]
	v_pk_fma_f32 v[42:43], v[102:103], s[86:87], v[42:43] op_sel_hi:[1,0,1]
	v_cvt_pk_f32_fp8_e32 v[96:97], v83
	v_cvt_pk_f32_fp8_sdwa v[98:99], v83 src0_sel:WORD_1
	v_cvt_pk_f32_fp8_e32 v[100:101], v87
	v_cvt_pk_f32_fp8_sdwa v[102:103], v87 src0_sel:WORD_1
	global_load_dwordx4 v[80:83], v138, s[80:81]
	global_load_dwordx4 v[84:87], v139, s[80:81]
	v_pk_fma_f32 v[44:45], v[96:97], s[84:85], v[44:45] op_sel_hi:[1,0,1]
	v_pk_fma_f32 v[46:47], v[98:99], s[84:85], v[46:47] op_sel_hi:[1,0,1]
	v_pk_fma_f32 v[44:45], v[100:101], s[86:87], v[44:45] op_sel_hi:[1,0,1]
	v_pk_fma_f32 v[46:47], v[102:103], s[86:87], v[46:47] op_sel_hi:[1,0,1]
	s_add_u32 s98, s101, 6
	s_add_u32 s99, s101, 7
	v_readlane_b32 s84, v152, s98
	v_readlane_b32 s86, v152, s99
	s_waitcnt vmcnt(6)
	v_cvt_pk_f32_fp8_e32 v[96:97], v88
	v_cvt_pk_f32_fp8_sdwa v[98:99], v88 src0_sel:WORD_1
	v_cvt_pk_f32_fp8_e32 v[100:101], v92
	v_cvt_pk_f32_fp8_sdwa v[102:103], v92 src0_sel:WORD_1
	v_pk_fma_f32 v[32:33], v[96:97], s[84:85], v[32:33] op_sel_hi:[1,0,1]
	v_pk_fma_f32 v[34:35], v[98:99], s[84:85], v[34:35] op_sel_hi:[1,0,1]
	v_pk_fma_f32 v[32:33], v[100:101], s[86:87], v[32:33] op_sel_hi:[1,0,1]
	v_pk_fma_f32 v[34:35], v[102:103], s[86:87], v[34:35] op_sel_hi:[1,0,1]
	v_cvt_pk_f32_fp8_e32 v[96:97], v89
	v_cvt_pk_f32_fp8_sdwa v[98:99], v89 src0_sel:WORD_1
	v_cvt_pk_f32_fp8_e32 v[100:101], v93
	v_cvt_pk_f32_fp8_sdwa v[102:103], v93 src0_sel:WORD_1
	v_pk_fma_f32 v[36:37], v[96:97], s[84:85], v[36:37] op_sel_hi:[1,0,1]
	v_pk_fma_f32 v[38:39], v[98:99], s[84:85], v[38:39] op_sel_hi:[1,0,1]
	v_pk_fma_f32 v[36:37], v[100:101], s[86:87], v[36:37] op_sel_hi:[1,0,1]
	v_pk_fma_f32 v[38:39], v[102:103], s[86:87], v[38:39] op_sel_hi:[1,0,1]
	v_cvt_pk_f32_fp8_e32 v[96:97], v90
	v_cvt_pk_f32_fp8_sdwa v[98:99], v90 src0_sel:WORD_1
	v_cvt_pk_f32_fp8_e32 v[100:101], v94
	v_cvt_pk_f32_fp8_sdwa v[102:103], v94 src0_sel:WORD_1
	v_pk_fma_f32 v[40:41], v[96:97], s[84:85], v[40:41] op_sel_hi:[1,0,1]
	v_pk_fma_f32 v[42:43], v[98:99], s[84:85], v[42:43] op_sel_hi:[1,0,1]
	v_pk_fma_f32 v[40:41], v[100:101], s[86:87], v[40:41] op_sel_hi:[1,0,1]
	v_pk_fma_f32 v[42:43], v[102:103], s[86:87], v[42:43] op_sel_hi:[1,0,1]
	v_cvt_pk_f32_fp8_e32 v[96:97], v91
; #define PG_ISSUE(BUF, TAB, e0_) do { const int isrc_ = ((e0_) < 64) ? myi0 : myi1; \
;       _Pragma("unroll") for (int e = 0; e < 8; ++e) { const int idx_ = __builtin_amdgcn_readlane(isrc_, ((e0_) + e) & 63); \
;         BUF[e] = *(const u32x4*)((TAB) + (size_t)idx_ * 1024 + lane * 16); } } while (0)
; DEV void peer_gather(const Params& P, int l, int m0, const int* idxs, const float* gs) {
;     ...
; #pragma nounroll
;     for (int e0 = 0; e0 < 128; e0 += 16) {
;       PG_ISSUE(b1, V, e0 + 8);
;       if (e0 == 64 && i + 1 < 16) sort_lists(lane, ni0, ni1, ng0, ng1);
;       PG_V16(b0, e0);
;       if (e0 + 16 < 128) PG_ISSUE(b0, V, e0 + 16);
;       PG_V16(b1, e0 + 8);
;     }
	v_cvt_pk_f32_fp8_sdwa v[98:99], v91 src0_sel:WORD_1
	v_cvt_pk_f32_fp8_e32 v[100:101], v95
	v_cvt_pk_f32_fp8_sdwa v[102:103], v95 src0_sel:WORD_1
	global_load_dwordx4 v[88:91], v140, s[80:81]
	global_load_dwordx4 v[92:95], v141, s[80:81]
	v_pk_fma_f32 v[44:45], v[96:97], s[84:85], v[44:45] op_sel_hi:[1,0,1]
	v_pk_fma_f32 v[46:47], v[98:99], s[84:85], v[46:47] op_sel_hi:[1,0,1]
	v_pk_fma_f32 v[44:45], v[100:101], s[86:87], v[44:45] op_sel_hi:[1,0,1]
	v_pk_fma_f32 v[46:47], v[102:103], s[86:87], v[46:47] op_sel_hi:[1,0,1]
	s_add_u32 s98, s100, 1
	s_min_u32 s98, s98, 15
	s_cmp_ge_u32 s98, 8
	s_cselect_b64 s[88:89], -1, 0
	s_lshl_b32 s99, s98, 3
	s_and_b32 s99, s99, 63
	s_mov_b32 vcc_lo, s99
	v_cndmask_b32_e64 v153, v142, v143, s[88:89]
	s_nop 0
	s_add_u32 s98, vcc_lo, 0
	v_readlane_b32 s98, v153, s98
	s_add_u32 s99, vcc_lo, 1
	v_readlane_b32 s99, v153, s99
	s_add_u32 s92, vcc_lo, 2
	v_readlane_b32 s92, v153, s92
	s_add_u32 s93, vcc_lo, 3
	v_readlane_b32 s93, v153, s93
	v_lshl_add_u32 v134, s98, 10, v250
	v_lshl_add_u32 v135, s99, 10, v250
	v_lshl_add_u32 v136, s92, 10, v250
	v_lshl_add_u32 v137, s93, 10, v250
	s_add_u32 s98, vcc_lo, 4
	v_readlane_b32 s98, v153, s98
	s_add_u32 s99, vcc_lo, 5
	v_readlane_b32 s99, v153, s99
	s_add_u32 s92, vcc_lo, 6
	v_readlane_b32 s92, v153, s92
	s_add_u32 s93, vcc_lo, 7
	v_readlane_b32 s93, v153, s93
	v_lshl_add_u32 v138, s98, 10, v250
	v_lshl_add_u32 v139, s99, 10, v250
	v_lshl_add_u32 v140, s92, 10, v250
	v_lshl_add_u32 v141, s93, 10, v250
	v_cndmask_b32_e64 v152, v247, v248, s[90:91]
	s_add_u32 s98, s101, 0
	s_add_u32 s99, s101, 1
	v_readlane_b32 s84, v152, s98
	v_readlane_b32 s86, v152, s99
	s_waitcnt vmcnt(6)
	v_cvt_pk_f32_fp8_e32 v[96:97], v64
	v_cvt_pk_f32_fp8_sdwa v[98:99], v64 src0_sel:WORD_1
	v_cvt_pk_f32_fp8_e32 v[100:101], v68
	v_cvt_pk_f32_fp8_sdwa v[102:103], v68 src0_sel:WORD_1
	v_pk_fma_f32 v[48:49], v[96:97], s[84:85], v[48:49] op_sel_hi:[1,0,1]
	v_pk_fma_f32 v[50:51], v[98:99], s[84:85], v[50:51] op_sel_hi:[1,0,1]
	v_pk_fma_f32 v[48:49], v[100:101], s[86:87], v[48:49] op_sel_hi:[1,0,1]
	v_pk_fma_f32 v[50:51], v[102:103], s[86:87], v[50:51] op_sel_hi:[1,0,1]
	v_cvt_pk_f32_fp8_e32 v[96:97], v65
	v_cvt_pk_f32_fp8_sdwa v[98:99], v65 src0_sel:WORD_1
	v_cvt_pk_f32_fp8_e32 v[100:101], v69
	v_cvt_pk_f32_fp8_sdwa v[102:103], v69 src0_sel:WORD_1
	v_pk_fma_f32 v[52:53], v[96:97], s[84:85], v[52:53] op_sel_hi:[1,0,1]
	v_pk_fma_f32 v[54:55], v[98:99], s[84:85], v[54:55] op_sel_hi:[1,0,1]
	v_pk_fma_f32 v[52:53], v[100:101], s[86:87], v[52:53] op_sel_hi:[1,0,1]
	v_pk_fma_f32 v[54:55], v[102:103], s[86:87], v[54:55] op_sel_hi:[1,0,1]
	v_cvt_pk_f32_fp8_e32 v[96:97], v66
	v_cvt_pk_f32_fp8_sdwa v[98:99], v66 src0_sel:WORD_1
	v_cvt_pk_f32_fp8_e32 v[100:101], v70
	v_cvt_pk_f32_fp8_sdwa v[102:103], v70 src0_sel:WORD_1
	v_pk_fma_f32 v[56:57], v[96:97], s[84:85], v[56:57] op_sel_hi:[1,0,1]
	v_pk_fma_f32 v[58:59], v[98:99], s[84:85], v[58:59] op_sel_hi:[1,0,1]
	v_pk_fma_f32 v[56:57], v[100:101], s[86:87], v[56:57] op_sel_hi:[1,0,1]
	v_pk_fma_f32 v[58:59], v[102:103], s[86:87], v[58:59] op_sel_hi:[1,0,1]
	v_cvt_pk_f32_fp8_e32 v[96:97], v67
	v_cvt_pk_f32_fp8_sdwa v[98:99], v67 src0_sel:WORD_1
	v_cvt_pk_f32_fp8_e32 v[100:101], v71
	v_cvt_pk_f32_fp8_sdwa v[102:103], v71 src0_sel:WORD_1
	global_load_dwordx4 v[64:67], v134, s[80:81]
	global_load_dwordx4 v[68:71], v135, s[80:81]
	v_pk_fma_f32 v[60:61], v[96:97], s[84:85], v[60:61] op_sel_hi:[1,0,1]
	v_pk_fma_f32 v[62:63], v[98:99], s[84:85], v[62:63] op_sel_hi:[1,0,1]
	v_pk_fma_f32 v[60:61], v[100:101], s[86:87], v[60:61] op_sel_hi:[1,0,1]
	v_pk_fma_f32 v[62:63], v[102:103], s[86:87], v[62:63] op_sel_hi:[1,0,1]
	s_add_u32 s98, s101, 2
	s_add_u32 s99, s101, 3
	v_readlane_b32 s84, v152, s98
	v_readlane_b32 s86, v152, s99
	s_waitcnt vmcnt(6)
	v_cvt_pk_f32_fp8_e32 v[96:97], v72
	v_cvt_pk_f32_fp8_sdwa v[98:99], v72 src0_sel:WORD_1
	v_cvt_pk_f32_fp8_e32 v[100:101], v76
	v_cvt_pk_f32_fp8_sdwa v[102:103], v76 src0_sel:WORD_1
	v_pk_fma_f32 v[48:49], v[96:97], s[84:85], v[48:49] op_sel_hi:[1,0,1]
	v_pk_fma_f32 v[50:51], v[98:99], s[84:85], v[50:51] op_sel_hi:[1,0,1]
	v_pk_fma_f32 v[48:49], v[100:101], s[86:87], v[48:49] op_sel_hi:[1,0,1]
	v_pk_fma_f32 v[50:51], v[102:103], s[86:87], v[50:51] op_sel_hi:[1,0,1]
	v_cvt_pk_f32_fp8_e32 v[96:97], v73
	v_cvt_pk_f32_fp8_sdwa v[98:99], v73 src0_sel:WORD_1
	v_cvt_pk_f32_fp8_e32 v[100:101], v77
	v_cvt_pk_f32_fp8_sdwa v[102:103], v77 src0_sel:WORD_1
	v_pk_fma_f32 v[52:53], v[96:97], s[84:85], v[52:53] op_sel_hi:[1,0,1]
	v_pk_fma_f32 v[54:55], v[98:99], s[84:85], v[54:55] op_sel_hi:[1,0,1]
	v_pk_fma_f32 v[52:53], v[100:101], s[86:87], v[52:53] op_sel_hi:[1,0,1]
	v_pk_fma_f32 v[54:55], v[102:103], s[86:87], v[54:55] op_sel_hi:[1,0,1]
	v_cvt_pk_f32_fp8_e32 v[96:97], v74
	v_cvt_pk_f32_fp8_sdwa v[98:99], v74 src0_sel:WORD_1
	v_cvt_pk_f32_fp8_e32 v[100:101], v78
	v_cvt_pk_f32_fp8_sdwa v[102:103], v78 src0_sel:WORD_1
	v_pk_fma_f32 v[56:57], v[96:97], s[84:85], v[56:57] op_sel_hi:[1,0,1]
	v_pk_fma_f32 v[58:59], v[98:99], s[84:85], v[58:59] op_sel_hi:[1,0,1]
	v_pk_fma_f32 v[56:57], v[100:101], s[86:87], v[56:57] op_sel_hi:[1,0,1]
	v_pk_fma_f32 v[58:59], v[102:103], s[86:87], v[58:59] op_sel_hi:[1,0,1]
	v_cvt_pk_f32_fp8_e32 v[96:97], v75
	v_cvt_pk_f32_fp8_sdwa v[98:99], v75 src0_sel:WORD_1
	v_cvt_pk_f32_fp8_e32 v[100:101], v79
	v_cvt_pk_f32_fp8_sdwa v[102:103], v79 src0_sel:WORD_1
	global_load_dwordx4 v[72:75], v136, s[80:81]
	global_load_dwordx4 v[76:79], v137, s[80:81]
	v_pk_fma_f32 v[60:61], v[96:97], s[84:85], v[60:61] op_sel_hi:[1,0,1]
	v_pk_fma_f32 v[62:63], v[98:99], s[84:85], v[62:63] op_sel_hi:[1,0,1]
	v_pk_fma_f32 v[60:61], v[100:101], s[86:87], v[60:61] op_sel_hi:[1,0,1]
	v_pk_fma_f32 v[62:63], v[102:103], s[86:87], v[62:63] op_sel_hi:[1,0,1]
	s_add_u32 s98, s101, 4
	s_add_u32 s99, s101, 5
	v_readlane_b32 s84, v152, s98
	v_readlane_b32 s86, v152, s99
	s_waitcnt vmcnt(6)
; #define PG_ISSUE(BUF, TAB, e0_) do { const int isrc_ = ((e0_) < 64) ? myi0 : myi1; \
;       _Pragma("unroll") for (int e = 0; e < 8; ++e) { const int idx_ = __builtin_amdgcn_readlane(isrc_, ((e0_) + e) & 63); \
;         BUF[e] = *(const u32x4*)((TAB) + (size_t)idx_ * 1024 + lane * 16); } } while (0)
; DEV void peer_gather(const Params& P, int l, int m0, const int* idxs, const float* gs) {
;     ...
;     float* hrow = P.out + tok * DM + lane * 16;
;     f32x4 hv[4];
; #pragma unroll
;     for (int q = 0; q < 4; ++q) hv[q] = *(const f32x4*)(hrow + 4 * q);
;     ...
; #pragma nounroll
;     for (int e0 = 0; e0 < 128; e0 += 16) {
;       PG_ISSUE(b1, V, e0 + 8);
;       if (e0 == 64 && i + 1 < 16) sort_lists(lane, ni0, ni1, ng0, ng1);
;       PG_V16(b0, e0);
;       if (e0 + 16 < 128) PG_ISSUE(b0, V, e0 + 16);
;       PG_V16(b1, e0 + 8);
;     }
	v_cvt_pk_f32_fp8_e32 v[96:97], v80
	v_cvt_pk_f32_fp8_sdwa v[98:99], v80 src0_sel:WORD_1
	v_cvt_pk_f32_fp8_e32 v[100:101], v84
	v_cvt_pk_f32_fp8_sdwa v[102:103], v84 src0_sel:WORD_1
	v_pk_fma_f32 v[48:49], v[96:97], s[84:85], v[48:49] op_sel_hi:[1,0,1]
	v_pk_fma_f32 v[50:51], v[98:99], s[84:85], v[50:51] op_sel_hi:[1,0,1]
	v_pk_fma_f32 v[48:49], v[100:101], s[86:87], v[48:49] op_sel_hi:[1,0,1]
	v_pk_fma_f32 v[50:51], v[102:103], s[86:87], v[50:51] op_sel_hi:[1,0,1]
	v_cvt_pk_f32_fp8_e32 v[96:97], v81
	v_cvt_pk_f32_fp8_sdwa v[98:99], v81 src0_sel:WORD_1
	v_cvt_pk_f32_fp8_e32 v[100:101], v85
	v_cvt_pk_f32_fp8_sdwa v[102:103], v85 src0_sel:WORD_1
	v_pk_fma_f32 v[52:53], v[96:97], s[84:85], v[52:53] op_sel_hi:[1,0,1]
	v_pk_fma_f32 v[54:55], v[98:99], s[84:85], v[54:55] op_sel_hi:[1,0,1]
	v_pk_fma_f32 v[52:53], v[100:101], s[86:87], v[52:53] op_sel_hi:[1,0,1]
	v_pk_fma_f32 v[54:55], v[102:103], s[86:87], v[54:55] op_sel_hi:[1,0,1]
	v_cvt_pk_f32_fp8_e32 v[96:97], v82
	v_cvt_pk_f32_fp8_sdwa v[98:99], v82 src0_sel:WORD_1
	v_cvt_pk_f32_fp8_e32 v[100:101], v86
	v_cvt_pk_f32_fp8_sdwa v[102:103], v86 src0_sel:WORD_1
	v_pk_fma_f32 v[56:57], v[96:97], s[84:85], v[56:57] op_sel_hi:[1,0,1]
	v_pk_fma_f32 v[58:59], v[98:99], s[84:85], v[58:59] op_sel_hi:[1,0,1]
	v_pk_fma_f32 v[56:57], v[100:101], s[86:87], v[56:57] op_sel_hi:[1,0,1]
	v_pk_fma_f32 v[58:59], v[102:103], s[86:87], v[58:59] op_sel_hi:[1,0,1]
	v_cvt_pk_f32_fp8_e32 v[96:97], v83
	v_cvt_pk_f32_fp8_sdwa v[98:99], v83 src0_sel:WORD_1
	v_cvt_pk_f32_fp8_e32 v[100:101], v87
	v_cvt_pk_f32_fp8_sdwa v[102:103], v87 src0_sel:WORD_1
	global_load_dwordx4 v[80:83], v138, s[80:81]
	global_load_dwordx4 v[84:87], v139, s[80:81]
	v_pk_fma_f32 v[60:61], v[96:97], s[84:85], v[60:61] op_sel_hi:[1,0,1]
	v_pk_fma_f32 v[62:63], v[98:99], s[84:85], v[62:63] op_sel_hi:[1,0,1]
	v_pk_fma_f32 v[60:61], v[100:101], s[86:87], v[60:61] op_sel_hi:[1,0,1]
	v_pk_fma_f32 v[62:63], v[102:103], s[86:87], v[62:63] op_sel_hi:[1,0,1]
	s_add_u32 s98, s101, 6
	s_add_u32 s99, s101, 7
	v_readlane_b32 s84, v152, s98
	v_readlane_b32 s86, v152, s99
	s_waitcnt vmcnt(6)
	v_cvt_pk_f32_fp8_e32 v[96:97], v88
	v_cvt_pk_f32_fp8_sdwa v[98:99], v88 src0_sel:WORD_1
	v_cvt_pk_f32_fp8_e32 v[100:101], v92
	v_cvt_pk_f32_fp8_sdwa v[102:103], v92 src0_sel:WORD_1
	v_pk_fma_f32 v[48:49], v[96:97], s[84:85], v[48:49] op_sel_hi:[1,0,1]
	v_pk_fma_f32 v[50:51], v[98:99], s[84:85], v[50:51] op_sel_hi:[1,0,1]
	v_pk_fma_f32 v[48:49], v[100:101], s[86:87], v[48:49] op_sel_hi:[1,0,1]
	v_pk_fma_f32 v[50:51], v[102:103], s[86:87], v[50:51] op_sel_hi:[1,0,1]
	v_cvt_pk_f32_fp8_e32 v[96:97], v89
	v_cvt_pk_f32_fp8_sdwa v[98:99], v89 src0_sel:WORD_1
	v_cvt_pk_f32_fp8_e32 v[100:101], v93
	v_cvt_pk_f32_fp8_sdwa v[102:103], v93 src0_sel:WORD_1
	v_pk_fma_f32 v[52:53], v[96:97], s[84:85], v[52:53] op_sel_hi:[1,0,1]
	v_pk_fma_f32 v[54:55], v[98:99], s[84:85], v[54:55] op_sel_hi:[1,0,1]
	v_pk_fma_f32 v[52:53], v[100:101], s[86:87], v[52:53] op_sel_hi:[1,0,1]
	v_pk_fma_f32 v[54:55], v[102:103], s[86:87], v[54:55] op_sel_hi:[1,0,1]
	v_cvt_pk_f32_fp8_e32 v[96:97], v90
	v_cvt_pk_f32_fp8_sdwa v[98:99], v90 src0_sel:WORD_1
	v_cvt_pk_f32_fp8_e32 v[100:101], v94
	v_cvt_pk_f32_fp8_sdwa v[102:103], v94 src0_sel:WORD_1
	v_pk_fma_f32 v[56:57], v[96:97], s[84:85], v[56:57] op_sel_hi:[1,0,1]
	v_pk_fma_f32 v[58:59], v[98:99], s[84:85], v[58:59] op_sel_hi:[1,0,1]
	v_pk_fma_f32 v[56:57], v[100:101], s[86:87], v[56:57] op_sel_hi:[1,0,1]
	v_pk_fma_f32 v[58:59], v[102:103], s[86:87], v[58:59] op_sel_hi:[1,0,1]
	v_cvt_pk_f32_fp8_e32 v[96:97], v91
	v_cvt_pk_f32_fp8_sdwa v[98:99], v91 src0_sel:WORD_1
	v_cvt_pk_f32_fp8_e32 v[100:101], v95
	v_cvt_pk_f32_fp8_sdwa v[102:103], v95 src0_sel:WORD_1
	global_load_dwordx4 v[88:91], v140, s[80:81]
	global_load_dwordx4 v[92:95], v141, s[80:81]
	v_pk_fma_f32 v[60:61], v[96:97], s[84:85], v[60:61] op_sel_hi:[1,0,1]
	v_pk_fma_f32 v[62:63], v[98:99], s[84:85], v[62:63] op_sel_hi:[1,0,1]
	v_pk_fma_f32 v[60:61], v[100:101], s[86:87], v[60:61] op_sel_hi:[1,0,1]
	v_pk_fma_f32 v[62:63], v[102:103], s[86:87], v[62:63] op_sel_hi:[1,0,1]
	s_add_u32 s100, s100, 1
	s_add_u32 s101, s101, 8
	s_and_b32 s101, s101, 63
	s_cmp_lt_u32 s100, 16
	s_cbranch_scc1 .Lpg1_Vloop
	s_waitcnt vmcnt(0)
	v_readfirstlane_b32 s82, v132
	v_readfirstlane_b32 s83, v133
	s_nop 4
	s_add_u32 s98, s3, 0
	s_lshl_b32 s99, s98, 12
	v_lshl_add_u32 v116, v249, 6, s99
	global_load_dwordx4 v[64:67], v116, s[82:83] offset:0
	global_load_dwordx4 v[68:71], v116, s[82:83] offset:16
	global_load_dwordx4 v[72:75], v116, s[82:83] offset:32
	global_load_dwordx4 v[76:79], v116, s[82:83] offset:48
	v_readfirstlane_b32 s88, v130
	v_readfirstlane_b32 s89, v131
	s_nop 4
	v_lshlrev_b32_e32 v117, 6, v249
	global_load_dwordx4 v[80:83], v117, s[88:89] offset:0
	global_load_dwordx4 v[84:87], v117, s[88:89] offset:16
	global_load_dwordx4 v[88:91], v117, s[88:89] offset:32
	global_load_dwordx4 v[92:95], v117, s[88:89] offset:48
	s_mov_b32 s90, 0x3c800000
	s_waitcnt vmcnt(4)
; DEV unsigned pk2(float lo, float hi) { f32x2_t v = {lo, hi}; bf16x2_t b = __builtin_convertvector(v, bf16x2_t); return __builtin_bit_cast(unsigned, b); }
; DEV void peer_gather(const Params& P, int l, int m0, const int* idxs, const float* gs) {
;     ...
;     float ss = 0.f;
; #pragma unroll
;     for (int q = 0; q < 4; ++q) {
;       hv[q][0] += acc[2 * q][0] * TAB_INV; hv[q][1] += acc[2 * q][1] * TAB_INV; hv[q][2] += acc[2 * q + 1][0] * TAB_INV; hv[q][3] += acc[2 * q + 1][1] * TAB_INV;
;       ss += hv[q][0] * hv[q][0] + hv[q][1] * hv[q][1] + hv[q][2] * hv[q][2] + hv[q][3] * hv[q][3];
;       *(f32x4*)(hrow + 4 * q) = hv[q];
;     }
;     const float rstd = rsqrtf(wave_sum(ss) * (1.f / DM) + EPS);
;     u32x4 oa, ob;
; #pragma unroll
;     for (int q = 0; q < 4; ++q) {
;       const f32x4 g = *(const f32x4*)(gp + lane * 16 + 4 * q);
;       const unsigned p0 = pk2(hv[q][0] * rstd * g[0], hv[q][1] * rstd * g[1]), p1 = pk2(hv[q][2] * rstd * g[2], hv[q][3] * rstd * g[3]);
;       if (q < 2) { oa[2 * q] = p0; oa[2 * q + 1] = p1; } else { ob[2 * (q - 2)] = p0; ob[2 * (q - 2) + 1] = p1; }
;     }
;     *(u32x4*)(hn + tok * DM + lane * 16) = oa; *(u32x4*)(hn + tok * DM + lane * 16 + 8) = ob;
	v_pk_fma_f32 v[64:65], v[0:1], s[90:91], v[64:65] op_sel_hi:[1,0,1]
	v_pk_fma_f32 v[66:67], v[2:3], s[90:91], v[66:67] op_sel_hi:[1,0,1]
	v_pk_fma_f32 v[68:69], v[4:5], s[90:91], v[68:69] op_sel_hi:[1,0,1]
	v_pk_fma_f32 v[70:71], v[6:7], s[90:91], v[70:71] op_sel_hi:[1,0,1]
	v_pk_fma_f32 v[72:73], v[8:9], s[90:91], v[72:73] op_sel_hi:[1,0,1]
	v_pk_fma_f32 v[74:75], v[10:11], s[90:91], v[74:75] op_sel_hi:[1,0,1]
	v_pk_fma_f32 v[76:77], v[12:13], s[90:91], v[76:77] op_sel_hi:[1,0,1]
	v_pk_fma_f32 v[78:79], v[14:15], s[90:91], v[78:79] op_sel_hi:[1,0,1]
	global_store_dwordx4 v116, v[64:67], s[82:83] offset:0
	global_store_dwordx4 v116, v[68:71], s[82:83] offset:16
	global_store_dwordx4 v116, v[72:75], s[82:83] offset:32
	global_store_dwordx4 v116, v[76:79], s[82:83] offset:48
	v_pk_mul_f32 v[96:97], v[64:65], v[64:65]
	v_pk_fma_f32 v[96:97], v[66:67], v[66:67], v[96:97]
	v_pk_fma_f32 v[96:97], v[68:69], v[68:69], v[96:97]
	v_pk_fma_f32 v[96:97], v[70:71], v[70:71], v[96:97]
	v_pk_fma_f32 v[96:97], v[72:73], v[72:73], v[96:97]
	v_pk_fma_f32 v[96:97], v[74:75], v[74:75], v[96:97]
	v_pk_fma_f32 v[96:97], v[76:77], v[76:77], v[96:97]
	v_pk_fma_f32 v[96:97], v[78:79], v[78:79], v[96:97]
	s_nop 0
	v_add_f32_e32 v118, v96, v97
	s_nop 1
	v_add_f32_dpp v118, v118, v118 quad_perm:[1,0,3,2] row_mask:0xf bank_mask:0xf
	s_nop 1
	v_add_f32_dpp v118, v118, v118 quad_perm:[2,3,0,1] row_mask:0xf bank_mask:0xf
	s_nop 1
	v_add_f32_dpp v118, v118, v118 row_half_mirror row_mask:0xf bank_mask:0xf
	s_nop 1
	v_add_f32_dpp v118, v118, v118 row_mirror row_mask:0xf bank_mask:0xf
	v_xor_b32_e32 v119, 64, v252
	ds_bpermute_b32 v119, v119, v118
	s_waitcnt lgkmcnt(0)
	v_add_f32_e32 v118, v118, v119
	v_xor_b32_e32 v119, 128, v252
	ds_bpermute_b32 v119, v119, v118
	s_waitcnt lgkmcnt(0)
	v_add_f32_e32 v118, v118, v119
	v_mov_b32_e32 v119, 0x358637bd
	v_fmac_f32_e32 v119, 0x3a800000, v118
	v_rsq_f32_e32 v98, v119
	s_waitcnt vmcnt(4)
	s_nop 0
	v_pk_mul_f32 v[64:65], v[64:65], v[98:99] op_sel_hi:[1,0]
	v_pk_mul_f32 v[66:67], v[66:67], v[98:99] op_sel_hi:[1,0]
	v_pk_mul_f32 v[68:69], v[68:69], v[98:99] op_sel_hi:[1,0]
	v_pk_mul_f32 v[70:71], v[70:71], v[98:99] op_sel_hi:[1,0]
	v_pk_mul_f32 v[72:73], v[72:73], v[98:99] op_sel_hi:[1,0]
	v_pk_mul_f32 v[74:75], v[74:75], v[98:99] op_sel_hi:[1,0]
	v_pk_mul_f32 v[76:77], v[76:77], v[98:99] op_sel_hi:[1,0]
	v_pk_mul_f32 v[78:79], v[78:79], v[98:99] op_sel_hi:[1,0]
	v_pk_mul_f32 v[64:65], v[80:81], v[64:65]
	v_pk_mul_f32 v[66:67], v[82:83], v[66:67]
	v_pk_mul_f32 v[68:69], v[84:85], v[68:69]
	v_pk_mul_f32 v[70:71], v[86:87], v[70:71]
	v_pk_mul_f32 v[72:73], v[88:89], v[72:73]
	v_pk_mul_f32 v[74:75], v[90:91], v[74:75]
	v_pk_mul_f32 v[76:77], v[92:93], v[76:77]
	v_pk_mul_f32 v[78:79], v[94:95], v[78:79]
	v_cvt_pk_bf16_f32 v80, v64, v65
	v_cvt_pk_bf16_f32 v81, v66, v67
	v_cvt_pk_bf16_f32 v82, v68, v69
	v_cvt_pk_bf16_f32 v83, v70, v71
	v_cvt_pk_bf16_f32 v84, v72, v73
	v_cvt_pk_bf16_f32 v85, v74, v75
	v_cvt_pk_bf16_f32 v86, v76, v77
	v_cvt_pk_bf16_f32 v87, v78, v79
	v_readfirstlane_b32 s82, v122
	v_readfirstlane_b32 s83, v123
	s_nop 4
	s_lshl_b32 s99, s98, 11
	v_lshl_add_u32 v116, v249, 5, s99
	global_store_dwordx4 v116, v[80:83], s[82:83]
	global_store_dwordx4 v116, v[84:87], s[82:83] offset:16
	s_nop 1
	v_readfirstlane_b32 s82, v132
	v_readfirstlane_b32 s83, v133
	s_nop 4
	s_add_u32 s98, s3, 1
	s_lshl_b32 s99, s98, 12
	v_lshl_add_u32 v116, v249, 6, s99
	global_load_dwordx4 v[64:67], v116, s[82:83] offset:0
	global_load_dwordx4 v[68:71], v116, s[82:83] offset:16
	global_load_dwordx4 v[72:75], v116, s[82:83] offset:32
	global_load_dwordx4 v[76:79], v116, s[82:83] offset:48
	v_readfirstlane_b32 s88, v130
	v_readfirstlane_b32 s89, v131
	s_nop 4
	v_lshlrev_b32_e32 v117, 6, v249
	global_load_dwordx4 v[80:83], v117, s[88:89] offset:0
	global_load_dwordx4 v[84:87], v117, s[88:89] offset:16
	global_load_dwordx4 v[88:91], v117, s[88:89] offset:32
	global_load_dwordx4 v[92:95], v117, s[88:89] offset:48
	s_mov_b32 s90, 0x3c800000
	s_waitcnt vmcnt(4)
	v_pk_fma_f32 v[64:65], v[16:17], s[90:91], v[64:65] op_sel_hi:[1,0,1]
	v_pk_fma_f32 v[66:67], v[18:19], s[90:91], v[66:67] op_sel_hi:[1,0,1]
	v_pk_fma_f32 v[68:69], v[20:21], s[90:91], v[68:69] op_sel_hi:[1,0,1]
	v_pk_fma_f32 v[70:71], v[22:23], s[90:91], v[70:71] op_sel_hi:[1,0,1]
	v_pk_fma_f32 v[72:73], v[24:25], s[90:91], v[72:73] op_sel_hi:[1,0,1]
	v_pk_fma_f32 v[74:75], v[26:27], s[90:91], v[74:75] op_sel_hi:[1,0,1]
	v_pk_fma_f32 v[76:77], v[28:29], s[90:91], v[76:77] op_sel_hi:[1,0,1]
	v_pk_fma_f32 v[78:79], v[30:31], s[90:91], v[78:79] op_sel_hi:[1,0,1]
	global_store_dwordx4 v116, v[64:67], s[82:83] offset:0
	global_store_dwordx4 v116, v[68:71], s[82:83] offset:16
	global_store_dwordx4 v116, v[72:75], s[82:83] offset:32
	global_store_dwordx4 v116, v[76:79], s[82:83] offset:48
	v_pk_mul_f32 v[96:97], v[64:65], v[64:65]
	v_pk_fma_f32 v[96:97], v[66:67], v[66:67], v[96:97]
	v_pk_fma_f32 v[96:97], v[68:69], v[68:69], v[96:97]
	v_pk_fma_f32 v[96:97], v[70:71], v[70:71], v[96:97]
	v_pk_fma_f32 v[96:97], v[72:73], v[72:73], v[96:97]
	v_pk_fma_f32 v[96:97], v[74:75], v[74:75], v[96:97]
	v_pk_fma_f32 v[96:97], v[76:77], v[76:77], v[96:97]
	v_pk_fma_f32 v[96:97], v[78:79], v[78:79], v[96:97]
	s_nop 0
	v_add_f32_e32 v118, v96, v97
	s_nop 1
	v_add_f32_dpp v118, v118, v118 quad_perm:[1,0,3,2] row_mask:0xf bank_mask:0xf
	s_nop 1
	v_add_f32_dpp v118, v118, v118 quad_perm:[2,3,0,1] row_mask:0xf bank_mask:0xf
	s_nop 1
	v_add_f32_dpp v118, v118, v118 row_half_mirror row_mask:0xf bank_mask:0xf
	s_nop 1
	v_add_f32_dpp v118, v118, v118 row_mirror row_mask:0xf bank_mask:0xf
	v_xor_b32_e32 v119, 64, v252
	ds_bpermute_b32 v119, v119, v118
	s_waitcnt lgkmcnt(0)
; DEV unsigned pk2(float lo, float hi) { f32x2_t v = {lo, hi}; bf16x2_t b = __builtin_convertvector(v, bf16x2_t); return __builtin_bit_cast(unsigned, b); }
; DEV void peer_gather(const Params& P, int l, int m0, const int* idxs, const float* gs) {
;     ...
;     float ss = 0.f;
; #pragma unroll
;     for (int q = 0; q < 4; ++q) {
;       hv[q][0] += acc[2 * q][0] * TAB_INV; hv[q][1] += acc[2 * q][1] * TAB_INV; hv[q][2] += acc[2 * q + 1][0] * TAB_INV; hv[q][3] += acc[2 * q + 1][1] * TAB_INV;
;       ss += hv[q][0] * hv[q][0] + hv[q][1] * hv[q][1] + hv[q][2] * hv[q][2] + hv[q][3] * hv[q][3];
;       *(f32x4*)(hrow + 4 * q) = hv[q];
;     }
;     const float rstd = rsqrtf(wave_sum(ss) * (1.f / DM) + EPS);
;     u32x4 oa, ob;
; #pragma unroll
;     for (int q = 0; q < 4; ++q) {
;       const f32x4 g = *(const f32x4*)(gp + lane * 16 + 4 * q);
;       const unsigned p0 = pk2(hv[q][0] * rstd * g[0], hv[q][1] * rstd * g[1]), p1 = pk2(hv[q][2] * rstd * g[2], hv[q][3] * rstd * g[3]);
;       if (q < 2) { oa[2 * q] = p0; oa[2 * q + 1] = p1; } else { ob[2 * (q - 2)] = p0; ob[2 * (q - 2) + 1] = p1; }
;     }
;     *(u32x4*)(hn + tok * DM + lane * 16) = oa; *(u32x4*)(hn + tok * DM + lane * 16 + 8) = ob;
	v_add_f32_e32 v118, v118, v119
	v_xor_b32_e32 v119, 128, v252
	ds_bpermute_b32 v119, v119, v118
	s_waitcnt lgkmcnt(0)
	v_add_f32_e32 v118, v118, v119
	v_mov_b32_e32 v119, 0x358637bd
	v_fmac_f32_e32 v119, 0x3a800000, v118
	v_rsq_f32_e32 v98, v119
	s_waitcnt vmcnt(4)
	s_nop 0
	v_pk_mul_f32 v[64:65], v[64:65], v[98:99] op_sel_hi:[1,0]
	v_pk_mul_f32 v[66:67], v[66:67], v[98:99] op_sel_hi:[1,0]
	v_pk_mul_f32 v[68:69], v[68:69], v[98:99] op_sel_hi:[1,0]
	v_pk_mul_f32 v[70:71], v[70:71], v[98:99] op_sel_hi:[1,0]
	v_pk_mul_f32 v[72:73], v[72:73], v[98:99] op_sel_hi:[1,0]
	v_pk_mul_f32 v[74:75], v[74:75], v[98:99] op_sel_hi:[1,0]
	v_pk_mul_f32 v[76:77], v[76:77], v[98:99] op_sel_hi:[1,0]
	v_pk_mul_f32 v[78:79], v[78:79], v[98:99] op_sel_hi:[1,0]
	v_pk_mul_f32 v[64:65], v[80:81], v[64:65]
	v_pk_mul_f32 v[66:67], v[82:83], v[66:67]
	v_pk_mul_f32 v[68:69], v[84:85], v[68:69]
	v_pk_mul_f32 v[70:71], v[86:87], v[70:71]
	v_pk_mul_f32 v[72:73], v[88:89], v[72:73]
	v_pk_mul_f32 v[74:75], v[90:91], v[74:75]
	v_pk_mul_f32 v[76:77], v[92:93], v[76:77]
	v_pk_mul_f32 v[78:79], v[94:95], v[78:79]
	v_cvt_pk_bf16_f32 v80, v64, v65
	v_cvt_pk_bf16_f32 v81, v66, v67
	v_cvt_pk_bf16_f32 v82, v68, v69
	v_cvt_pk_bf16_f32 v83, v70, v71
	v_cvt_pk_bf16_f32 v84, v72, v73
	v_cvt_pk_bf16_f32 v85, v74, v75
	v_cvt_pk_bf16_f32 v86, v76, v77
	v_cvt_pk_bf16_f32 v87, v78, v79
	v_readfirstlane_b32 s82, v122
	v_readfirstlane_b32 s83, v123
	s_nop 4
	s_lshl_b32 s99, s98, 11
	v_lshl_add_u32 v116, v249, 5, s99
	global_store_dwordx4 v116, v[80:83], s[82:83]
	global_store_dwordx4 v116, v[84:87], s[82:83] offset:16
	s_nop 1
	v_readfirstlane_b32 s82, v132
	v_readfirstlane_b32 s83, v133
	s_nop 4
	s_add_u32 s98, s3, 2
	s_lshl_b32 s99, s98, 12
	v_lshl_add_u32 v116, v249, 6, s99
	global_load_dwordx4 v[64:67], v116, s[82:83] offset:0
	global_load_dwordx4 v[68:71], v116, s[82:83] offset:16
	global_load_dwordx4 v[72:75], v116, s[82:83] offset:32
	global_load_dwordx4 v[76:79], v116, s[82:83] offset:48
	v_readfirstlane_b32 s88, v130
	v_readfirstlane_b32 s89, v131
	s_nop 4
	v_lshlrev_b32_e32 v117, 6, v249
	global_load_dwordx4 v[80:83], v117, s[88:89] offset:0
	global_load_dwordx4 v[84:87], v117, s[88:89] offset:16
	global_load_dwordx4 v[88:91], v117, s[88:89] offset:32
	global_load_dwordx4 v[92:95], v117, s[88:89] offset:48
	s_mov_b32 s90, 0x3c800000
	s_waitcnt vmcnt(4)
	v_pk_fma_f32 v[64:65], v[32:33], s[90:91], v[64:65] op_sel_hi:[1,0,1]
	v_pk_fma_f32 v[66:67], v[34:35], s[90:91], v[66:67] op_sel_hi:[1,0,1]
	v_pk_fma_f32 v[68:69], v[36:37], s[90:91], v[68:69] op_sel_hi:[1,0,1]
	v_pk_fma_f32 v[70:71], v[38:39], s[90:91], v[70:71] op_sel_hi:[1,0,1]
	v_pk_fma_f32 v[72:73], v[40:41], s[90:91], v[72:73] op_sel_hi:[1,0,1]
	v_pk_fma_f32 v[74:75], v[42:43], s[90:91], v[74:75] op_sel_hi:[1,0,1]
	v_pk_fma_f32 v[76:77], v[44:45], s[90:91], v[76:77] op_sel_hi:[1,0,1]
	v_pk_fma_f32 v[78:79], v[46:47], s[90:91], v[78:79] op_sel_hi:[1,0,1]
	global_store_dwordx4 v116, v[64:67], s[82:83] offset:0
	global_store_dwordx4 v116, v[68:71], s[82:83] offset:16
	global_store_dwordx4 v116, v[72:75], s[82:83] offset:32
	global_store_dwordx4 v116, v[76:79], s[82:83] offset:48
	v_pk_mul_f32 v[96:97], v[64:65], v[64:65]
	v_pk_fma_f32 v[96:97], v[66:67], v[66:67], v[96:97]
	v_pk_fma_f32 v[96:97], v[68:69], v[68:69], v[96:97]
	v_pk_fma_f32 v[96:97], v[70:71], v[70:71], v[96:97]
	v_pk_fma_f32 v[96:97], v[72:73], v[72:73], v[96:97]
	v_pk_fma_f32 v[96:97], v[74:75], v[74:75], v[96:97]
	v_pk_fma_f32 v[96:97], v[76:77], v[76:77], v[96:97]
	v_pk_fma_f32 v[96:97], v[78:79], v[78:79], v[96:97]
	s_nop 0
	v_add_f32_e32 v118, v96, v97
	s_nop 1
	v_add_f32_dpp v118, v118, v118 quad_perm:[1,0,3,2] row_mask:0xf bank_mask:0xf
	s_nop 1
	v_add_f32_dpp v118, v118, v118 quad_perm:[2,3,0,1] row_mask:0xf bank_mask:0xf
	s_nop 1
	v_add_f32_dpp v118, v118, v118 row_half_mirror row_mask:0xf bank_mask:0xf
	s_nop 1
	v_add_f32_dpp v118, v118, v118 row_mirror row_mask:0xf bank_mask:0xf
	v_xor_b32_e32 v119, 64, v252
	ds_bpermute_b32 v119, v119, v118
	s_waitcnt lgkmcnt(0)
	v_add_f32_e32 v118, v118, v119
	v_xor_b32_e32 v119, 128, v252
	ds_bpermute_b32 v119, v119, v118
	s_waitcnt lgkmcnt(0)
	v_add_f32_e32 v118, v118, v119
	v_mov_b32_e32 v119, 0x358637bd
	v_fmac_f32_e32 v119, 0x3a800000, v118
	v_rsq_f32_e32 v98, v119
	s_waitcnt vmcnt(4)
; DEV unsigned pk2(float lo, float hi) { f32x2_t v = {lo, hi}; bf16x2_t b = __builtin_convertvector(v, bf16x2_t); return __builtin_bit_cast(unsigned, b); }
; DEV void peer_gather(const Params& P, int l, int m0, const int* idxs, const float* gs) {
;     ...
;     float ss = 0.f;
; #pragma unroll
;     for (int q = 0; q < 4; ++q) {
;       hv[q][0] += acc[2 * q][0] * TAB_INV; hv[q][1] += acc[2 * q][1] * TAB_INV; hv[q][2] += acc[2 * q + 1][0] * TAB_INV; hv[q][3] += acc[2 * q + 1][1] * TAB_INV;
;       ss += hv[q][0] * hv[q][0] + hv[q][1] * hv[q][1] + hv[q][2] * hv[q][2] + hv[q][3] * hv[q][3];
;       *(f32x4*)(hrow + 4 * q) = hv[q];
;     }
;     const float rstd = rsqrtf(wave_sum(ss) * (1.f / DM) + EPS);
;     u32x4 oa, ob;
; #pragma unroll
;     for (int q = 0; q < 4; ++q) {
;       const f32x4 g = *(const f32x4*)(gp + lane * 16 + 4 * q);
;       const unsigned p0 = pk2(hv[q][0] * rstd * g[0], hv[q][1] * rstd * g[1]), p1 = pk2(hv[q][2] * rstd * g[2], hv[q][3] * rstd * g[3]);
;       if (q < 2) { oa[2 * q] = p0; oa[2 * q + 1] = p1; } else { ob[2 * (q - 2)] = p0; ob[2 * (q - 2) + 1] = p1; }
;     }
;     *(u32x4*)(hn + tok * DM + lane * 16) = oa; *(u32x4*)(hn + tok * DM + lane * 16 + 8) = ob;
	s_nop 0
	v_pk_mul_f32 v[64:65], v[64:65], v[98:99] op_sel_hi:[1,0]
	v_pk_mul_f32 v[66:67], v[66:67], v[98:99] op_sel_hi:[1,0]
	v_pk_mul_f32 v[68:69], v[68:69], v[98:99] op_sel_hi:[1,0]
	v_pk_mul_f32 v[70:71], v[70:71], v[98:99] op_sel_hi:[1,0]
	v_pk_mul_f32 v[72:73], v[72:73], v[98:99] op_sel_hi:[1,0]
	v_pk_mul_f32 v[74:75], v[74:75], v[98:99] op_sel_hi:[1,0]
	v_pk_mul_f32 v[76:77], v[76:77], v[98:99] op_sel_hi:[1,0]
	v_pk_mul_f32 v[78:79], v[78:79], v[98:99] op_sel_hi:[1,0]
	v_pk_mul_f32 v[64:65], v[80:81], v[64:65]
	v_pk_mul_f32 v[66:67], v[82:83], v[66:67]
	v_pk_mul_f32 v[68:69], v[84:85], v[68:69]
	v_pk_mul_f32 v[70:71], v[86:87], v[70:71]
	v_pk_mul_f32 v[72:73], v[88:89], v[72:73]
	v_pk_mul_f32 v[74:75], v[90:91], v[74:75]
	v_pk_mul_f32 v[76:77], v[92:93], v[76:77]
	v_pk_mul_f32 v[78:79], v[94:95], v[78:79]
	v_cvt_pk_bf16_f32 v80, v64, v65
	v_cvt_pk_bf16_f32 v81, v66, v67
	v_cvt_pk_bf16_f32 v82, v68, v69
	v_cvt_pk_bf16_f32 v83, v70, v71
	v_cvt_pk_bf16_f32 v84, v72, v73
	v_cvt_pk_bf16_f32 v85, v74, v75
	v_cvt_pk_bf16_f32 v86, v76, v77
	v_cvt_pk_bf16_f32 v87, v78, v79
	v_readfirstlane_b32 s82, v122
	v_readfirstlane_b32 s83, v123
	s_nop 4
	s_lshl_b32 s99, s98, 11
	v_lshl_add_u32 v116, v249, 5, s99
	global_store_dwordx4 v116, v[80:83], s[82:83]
	global_store_dwordx4 v116, v[84:87], s[82:83] offset:16
	s_nop 1
	v_readfirstlane_b32 s82, v132
	v_readfirstlane_b32 s83, v133
	s_nop 4
	s_add_u32 s98, s3, 3
	s_lshl_b32 s99, s98, 12
	v_lshl_add_u32 v116, v249, 6, s99
	global_load_dwordx4 v[64:67], v116, s[82:83] offset:0
	global_load_dwordx4 v[68:71], v116, s[82:83] offset:16
	global_load_dwordx4 v[72:75], v116, s[82:83] offset:32
	global_load_dwordx4 v[76:79], v116, s[82:83] offset:48
	v_readfirstlane_b32 s88, v130
	v_readfirstlane_b32 s89, v131
	s_nop 4
	v_lshlrev_b32_e32 v117, 6, v249
	global_load_dwordx4 v[80:83], v117, s[88:89] offset:0
	global_load_dwordx4 v[84:87], v117, s[88:89] offset:16
	global_load_dwordx4 v[88:91], v117, s[88:89] offset:32
	global_load_dwordx4 v[92:95], v117, s[88:89] offset:48
	s_mov_b32 s90, 0x3c800000
	s_waitcnt vmcnt(4)
	v_pk_fma_f32 v[64:65], v[48:49], s[90:91], v[64:65] op_sel_hi:[1,0,1]
	v_pk_fma_f32 v[66:67], v[50:51], s[90:91], v[66:67] op_sel_hi:[1,0,1]
	v_pk_fma_f32 v[68:69], v[52:53], s[90:91], v[68:69] op_sel_hi:[1,0,1]
	v_pk_fma_f32 v[70:71], v[54:55], s[90:91], v[70:71] op_sel_hi:[1,0,1]
	v_pk_fma_f32 v[72:73], v[56:57], s[90:91], v[72:73] op_sel_hi:[1,0,1]
	v_pk_fma_f32 v[74:75], v[58:59], s[90:91], v[74:75] op_sel_hi:[1,0,1]
	v_pk_fma_f32 v[76:77], v[60:61], s[90:91], v[76:77] op_sel_hi:[1,0,1]
	v_pk_fma_f32 v[78:79], v[62:63], s[90:91], v[78:79] op_sel_hi:[1,0,1]
	global_store_dwordx4 v116, v[64:67], s[82:83] offset:0
	global_store_dwordx4 v116, v[68:71], s[82:83] offset:16
	global_store_dwordx4 v116, v[72:75], s[82:83] offset:32
	global_store_dwordx4 v116, v[76:79], s[82:83] offset:48
	v_pk_mul_f32 v[96:97], v[64:65], v[64:65]
	v_pk_fma_f32 v[96:97], v[66:67], v[66:67], v[96:97]
	v_pk_fma_f32 v[96:97], v[68:69], v[68:69], v[96:97]
	v_pk_fma_f32 v[96:97], v[70:71], v[70:71], v[96:97]
	v_pk_fma_f32 v[96:97], v[72:73], v[72:73], v[96:97]
	v_pk_fma_f32 v[96:97], v[74:75], v[74:75], v[96:97]
	v_pk_fma_f32 v[96:97], v[76:77], v[76:77], v[96:97]
	v_pk_fma_f32 v[96:97], v[78:79], v[78:79], v[96:97]
	s_nop 0
	v_add_f32_e32 v118, v96, v97
	s_nop 1
	v_add_f32_dpp v118, v118, v118 quad_perm:[1,0,3,2] row_mask:0xf bank_mask:0xf
	s_nop 1
	v_add_f32_dpp v118, v118, v118 quad_perm:[2,3,0,1] row_mask:0xf bank_mask:0xf
	s_nop 1
	v_add_f32_dpp v118, v118, v118 row_half_mirror row_mask:0xf bank_mask:0xf
	s_nop 1
	v_add_f32_dpp v118, v118, v118 row_mirror row_mask:0xf bank_mask:0xf
	v_xor_b32_e32 v119, 64, v252
	ds_bpermute_b32 v119, v119, v118
	s_waitcnt lgkmcnt(0)
	v_add_f32_e32 v118, v118, v119
	v_xor_b32_e32 v119, 128, v252
	ds_bpermute_b32 v119, v119, v118
	s_waitcnt lgkmcnt(0)
	v_add_f32_e32 v118, v118, v119
	v_mov_b32_e32 v119, 0x358637bd
	v_fmac_f32_e32 v119, 0x3a800000, v118
	v_rsq_f32_e32 v98, v119
	s_waitcnt vmcnt(4)
	s_nop 0
	v_pk_mul_f32 v[64:65], v[64:65], v[98:99] op_sel_hi:[1,0]
	v_pk_mul_f32 v[66:67], v[66:67], v[98:99] op_sel_hi:[1,0]
	v_pk_mul_f32 v[68:69], v[68:69], v[98:99] op_sel_hi:[1,0]
	v_pk_mul_f32 v[70:71], v[70:71], v[98:99] op_sel_hi:[1,0]
	v_pk_mul_f32 v[72:73], v[72:73], v[98:99] op_sel_hi:[1,0]
	v_pk_mul_f32 v[74:75], v[74:75], v[98:99] op_sel_hi:[1,0]
	v_pk_mul_f32 v[76:77], v[76:77], v[98:99] op_sel_hi:[1,0]
	v_pk_mul_f32 v[78:79], v[78:79], v[98:99] op_sel_hi:[1,0]
	v_pk_mul_f32 v[64:65], v[80:81], v[64:65]
	v_pk_mul_f32 v[66:67], v[82:83], v[66:67]
	v_pk_mul_f32 v[68:69], v[84:85], v[68:69]
	v_pk_mul_f32 v[70:71], v[86:87], v[70:71]
	v_pk_mul_f32 v[72:73], v[88:89], v[72:73]
	v_pk_mul_f32 v[74:75], v[90:91], v[74:75]
	v_pk_mul_f32 v[76:77], v[92:93], v[76:77]
	v_pk_mul_f32 v[78:79], v[94:95], v[78:79]
	v_cvt_pk_bf16_f32 v80, v64, v65
	v_cvt_pk_bf16_f32 v81, v66, v67
	v_cvt_pk_bf16_f32 v82, v68, v69
	v_cvt_pk_bf16_f32 v83, v70, v71
	v_cvt_pk_bf16_f32 v84, v72, v73
	v_cvt_pk_bf16_f32 v85, v74, v75
	v_cvt_pk_bf16_f32 v86, v76, v77
	v_cvt_pk_bf16_f32 v87, v78, v79
	v_readfirstlane_b32 s82, v122
	v_readfirstlane_b32 s83, v123
	s_nop 4
	s_lshl_b32 s99, s98, 11
	v_lshl_add_u32 v116, v249, 5, s99
	global_store_dwordx4 v116, v[80:83], s[82:83]
	global_store_dwordx4 v116, v[84:87], s[82:83] offset:16
	s_nop 1
	s_add_u32 s3, s3, 4
	s_add_u32 s33, s33, 4
	s_add_u32 s2, s2, 1
	s_cmp_lt_u32 s2, 4
	s_cbranch_scc1 .Lpg1_pass
	s_waitcnt vmcnt(0) lgkmcnt(0)
	v_readlane_b32 s92, v231, 15
	v_readlane_b32 s93, v231, 16

; __global__ void __launch_bounds__(512) mega(Params P) {
	.amdhsa_kernel _Z4mega6Params
		.amdhsa_group_segment_fixed_size 0
		.amdhsa_private_segment_fixed_size 0
		.amdhsa_kernarg_size 480
		.amdhsa_user_sgpr_count 2
		.amdhsa_user_sgpr_dispatch_ptr 0
		.amdhsa_user_sgpr_queue_ptr 0
		.amdhsa_user_sgpr_kernarg_segment_ptr 1
		.amdhsa_user_sgpr_dispatch_id 0
		.amdhsa_user_sgpr_kernarg_preload_length 0
		.amdhsa_user_sgpr_kernarg_preload_offset 0
		.amdhsa_user_sgpr_private_segment_size 0
		.amdhsa_uses_dynamic_stack 0
		.amdhsa_enable_private_segment 0
		.amdhsa_system_sgpr_workgroup_id_x 1
		.amdhsa_system_sgpr_workgroup_id_y 0
		.amdhsa_system_sgpr_workgroup_id_z 0
		.amdhsa_system_sgpr_workgroup_info 0
		.amdhsa_system_vgpr_workitem_id 2
		.amdhsa_next_free_vgpr 256
		.amdhsa_next_free_sgpr 102
		.amdhsa_accum_offset 256
		.amdhsa_reserve_vcc 1
		.amdhsa_float_round_mode_32 0
		.amdhsa_float_round_mode_16_64 0
		.amdhsa_float_denorm_mode_32 3
		.amdhsa_float_denorm_mode_16_64 3
		.amdhsa_dx10_clamp 1
		.amdhsa_ieee_mode 1
		.amdhsa_fp16_overflow 0
		.amdhsa_tg_split 0
		.amdhsa_exception_fp_ieee_invalid_op 0
		.amdhsa_exception_fp_denorm_src 0
		.amdhsa_exception_fp_ieee_div_zero 0
		.amdhsa_exception_fp_ieee_overflow 0
		.amdhsa_exception_fp_ieee_underflow 0
		.amdhsa_exception_fp_ieee_inexact 0
		.amdhsa_exception_int_div_zero 0
	.end_amdhsa_kernel

; __global__ void __launch_bounds__(512) mega(Params P) {
amdhsa.kernels:
  - .agpr_count:     0
    .args:
      - .offset:         0
        .size:           224
        .value_kind:     by_value
      - .offset:         224
        .size:           4
        .value_kind:     hidden_block_count_x
      - .offset:         228
        .size:           4
        .value_kind:     hidden_block_count_y
      - .offset:         232
        .size:           4
        .value_kind:     hidden_block_count_z
      - .offset:         236
        .size:           2
        .value_kind:     hidden_group_size_x
      - .offset:         238
        .size:           2
        .value_kind:     hidden_group_size_y
      - .offset:         240
        .size:           2
        .value_kind:     hidden_group_size_z
      - .offset:         242
        .size:           2
        .value_kind:     hidden_remainder_x
      - .offset:         244
        .size:           2
        .value_kind:     hidden_remainder_y
      - .offset:         246
        .size:           2
        .value_kind:     hidden_remainder_z
      - .offset:         264
        .size:           8
        .value_kind:     hidden_global_offset_x
      - .offset:         272
        .size:           8
        .value_kind:     hidden_global_offset_y
      - .offset:         280
        .size:           8
        .value_kind:     hidden_global_offset_z
      - .offset:         288
        .size:           2
        .value_kind:     hidden_grid_dims
      - .offset:         312
        .size:           8
        .value_kind:     hidden_multigrid_sync_arg
      - .offset:         344
        .size:           4
        .value_kind:     hidden_dynamic_lds_size
    .group_segment_fixed_size: 0
    .kernarg_segment_align: 8
    .kernarg_segment_size: 480
    .language:       OpenCL C
    .language_version:
      - 2
      - 0
    .max_flat_workgroup_size: 512
    .name:           _Z4mega6Params
    .private_segment_fixed_size: 0
    .sgpr_count:     108
    .sgpr_spill_count: 123
    .symbol:         _Z4mega6Params.kd
    .uniform_work_group_size: 1
    .uses_dynamic_stack: false
    .vgpr_count:     256
    .vgpr_spill_count: 0
    .wavefront_size: 64
